# v10 + every 16-byte global store made write-through (sc1) so the grid barrier's L2 writeback has less dirty data
# baseline (speedup 1.0000x reference)
.LBB0_21:
	s_lshl_b32 s14, s23, 6
	v_readlane_b32 s56, v234, 7
	s_ashr_i32 s15, s14, 31
	s_mul_i32 s23, s23, 0x180000
	v_readlane_b32 s58, v234, 9
	s_mul_hi_i32 s16, s14, 0x6000
	v_readlane_b32 s59, v234, 10
	s_add_u32 s17, s58, s23
	s_addc_u32 s16, s59, s16
	s_lshl_b64 s[12:13], s[12:13], 2
	s_add_u32 s12, s17, s12
	s_addc_u32 s13, s16, s13
	v_lshl_add_u64 v[78:79], s[12:13], 0, v[74:75]
	v_lshlrev_b32_e32 v4, 2, v2
	v_lshl_add_u64 v[134:135], v[78:79], 0, v[4:5]
	v_add_co_u32_e32 v82, vcc, s28, v134
	s_lshl_b64 s[12:13], s[14:15], 1
	s_nop 0
	v_addc_co_u32_e32 v83, vcc, 0, v135, vcc
	global_load_dwordx4 v[78:81], v[134:135], off nt
	s_nop 0
	global_load_dwordx4 v[82:85], v[82:83], off nt
	v_add_co_u32_e32 v86, vcc, s36, v134
	s_add_u32 s10, s10, s12
	s_nop 0
	v_addc_co_u32_e32 v87, vcc, 0, v135, vcc
	v_add_co_u32_e32 v90, vcc, s49, v134
	s_mov_b32 s12, 0x90000
	s_nop 0
	v_addc_co_u32_e32 v91, vcc, 0, v135, vcc
	global_load_dwordx4 v[86:89], v[86:87], off nt
	s_nop 0
	global_load_dwordx4 v[90:93], v[90:91], off nt
	v_add_co_u32_e32 v94, vcc, s50, v134
	v_add_u32_e32 v4, 0x410, v1
	s_nop 0
	v_addc_co_u32_e32 v95, vcc, 0, v135, vcc
	v_add_co_u32_e32 v98, vcc, s51, v134
	v_add_u32_e32 v77, 0x400, v33
	s_nop 0
	v_addc_co_u32_e32 v99, vcc, 0, v135, vcc
	global_load_dwordx4 v[94:97], v[94:95], off nt
	s_nop 0
	global_load_dwordx4 v[98:101], v[98:99], off nt
	v_add_co_u32_e32 v102, vcc, s12, v134
	s_mov_b32 s12, 0xc0000
	s_nop 0
	v_addc_co_u32_e32 v103, vcc, 0, v135, vcc
	v_add_co_u32_e32 v106, vcc, s42, v134
	s_addc_u32 s11, s11, s13
	s_nop 0
	v_addc_co_u32_e32 v107, vcc, 0, v135, vcc
	global_load_dwordx4 v[102:105], v[102:103], off nt
	s_nop 0
	global_load_dwordx4 v[106:109], v[106:107], off nt
	v_add_co_u32_e32 v110, vcc, s12, v134
	s_mov_b32 s12, 0xd8000
	s_nop 0
	v_addc_co_u32_e32 v111, vcc, 0, v135, vcc
	v_add_co_u32_e32 v114, vcc, s12, v134
	s_mov_b32 s12, 0xf0000
	s_nop 0
	v_addc_co_u32_e32 v115, vcc, 0, v135, vcc
	global_load_dwordx4 v[110:113], v[110:111], off nt
	s_nop 0
	global_load_dwordx4 v[114:117], v[114:115], off nt
	v_add_co_u32_e32 v118, vcc, s12, v134
	s_mov_b32 s12, 0x120000
	s_nop 0
	v_addc_co_u32_e32 v119, vcc, 0, v135, vcc
	v_add_co_u32_e32 v122, vcc, s48, v134
	v_readlane_b32 s57, v234, 8
	s_nop 0
	v_addc_co_u32_e32 v123, vcc, 0, v135, vcc
	global_load_dwordx4 v[118:121], v[118:119], off nt
	s_nop 0
	global_load_dwordx4 v[122:125], v[122:123], off nt
	v_add_co_u32_e32 v126, vcc, s12, v134
	s_mov_b32 s12, 0x138000
	s_nop 0
	v_addc_co_u32_e32 v127, vcc, 0, v135, vcc
	v_add_co_u32_e32 v130, vcc, s12, v134
	s_mov_b32 s12, 0x168000
	s_nop 0
	v_addc_co_u32_e32 v131, vcc, 0, v135, vcc
	global_load_dwordx4 v[126:129], v[126:127], off nt
	s_nop 0
	global_load_dwordx4 v[130:133], v[130:131], off nt
	v_add_co_u32_e32 v136, vcc, s44, v134
	v_readlane_b32 s60, v234, 11
	s_nop 0
	v_addc_co_u32_e32 v137, vcc, 0, v135, vcc
	v_add_co_u32_e32 v138, vcc, s12, v134
	v_readlane_b32 s61, v234, 12
	s_nop 0
	v_addc_co_u32_e32 v139, vcc, 0, v135, vcc
	global_load_dwordx4 v[134:137], v[136:137], off nt
	s_nop 0
	global_load_dwordx4 v[138:141], v[138:139], off nt
	v_readlane_b32 s62, v234, 13
	s_waitcnt vmcnt(15)
	v_pk_mul_f32 v[78:79], s[0:1], v[78:79] op_sel_hi:[0,1]
	ds_write2_b32 v1, v78, v79 offset1:1
	v_pk_mul_f32 v[78:79], s[0:1], v[80:81] op_sel_hi:[0,1]
	ds_write2_b32 v1, v78, v79 offset0:2 offset1:3
	s_waitcnt vmcnt(14)
	v_pk_mul_f32 v[78:79], s[0:1], v[82:83] op_sel_hi:[0,1]
	ds_write2_b32 v4, v78, v79 offset1:1
	v_pk_mul_f32 v[78:79], s[0:1], v[84:85] op_sel_hi:[0,1]
	v_add_u32_e32 v4, 0x418, v1
	ds_write2_b32 v4, v78, v79 offset1:1
	v_add_u32_e32 v4, 0x820, v1
	v_readlane_b32 s63, v234, 14
	s_waitcnt vmcnt(13)
	v_pk_mul_f32 v[78:79], s[0:1], v[86:87] op_sel_hi:[0,1]
	ds_write2_b32 v4, v78, v79 offset1:1
	v_pk_mul_f32 v[78:79], s[0:1], v[88:89] op_sel_hi:[0,1]
	v_add_u32_e32 v4, 0x828, v1
	ds_write2_b32 v4, v78, v79 offset1:1
	s_waitcnt vmcnt(12)
	v_pk_mul_f32 v[78:79], s[0:1], v[90:91] op_sel_hi:[0,1]
	v_add_u32_e32 v4, 0xc30, v1
	ds_write2_b32 v4, v78, v79 offset1:1
	v_pk_mul_f32 v[78:79], s[0:1], v[92:93] op_sel_hi:[0,1]
	v_add_u32_e32 v4, 0xc38, v1
	ds_write2_b32 v4, v78, v79 offset1:1
	s_waitcnt vmcnt(11)
	v_pk_mul_f32 v[78:79], s[0:1], v[94:95] op_sel_hi:[0,1]
	v_add_u32_e32 v4, 0x1040, v1
	ds_write2_b32 v4, v78, v79 offset1:1
	v_pk_mul_f32 v[78:79], s[0:1], v[96:97] op_sel_hi:[0,1]
	v_add_u32_e32 v4, 0x1048, v1
	ds_write2_b32 v4, v78, v79 offset1:1
	s_waitcnt vmcnt(10)
	v_pk_mul_f32 v[78:79], s[0:1], v[98:99] op_sel_hi:[0,1]
	v_add_u32_e32 v4, 0x1450, v1
	ds_write2_b32 v4, v78, v79 offset1:1
	v_pk_mul_f32 v[78:79], s[0:1], v[100:101] op_sel_hi:[0,1]
	v_add_u32_e32 v4, 0x1458, v1
	ds_write2_b32 v4, v78, v79 offset1:1
	s_waitcnt vmcnt(9)
	v_pk_mul_f32 v[78:79], s[0:1], v[102:103] op_sel_hi:[0,1]
	v_add_u32_e32 v4, 0x1860, v1
	ds_write2_b32 v4, v78, v79 offset1:1
	v_pk_mul_f32 v[78:79], s[0:1], v[104:105] op_sel_hi:[0,1]
	v_add_u32_e32 v4, 0x1868, v1
	ds_write2_b32 v4, v78, v79 offset1:1
	s_waitcnt vmcnt(8)
	v_pk_mul_f32 v[78:79], s[0:1], v[106:107] op_sel_hi:[0,1]
	v_add_u32_e32 v4, 0x1c70, v1
	ds_write2_b32 v4, v78, v79 offset1:1
	v_pk_mul_f32 v[78:79], s[0:1], v[108:109] op_sel_hi:[0,1]
	v_add_u32_e32 v4, 0x1c78, v1
	ds_write2_b32 v4, v78, v79 offset1:1
	s_waitcnt vmcnt(7)
	v_pk_mul_f32 v[78:79], s[0:1], v[110:111] op_sel_hi:[0,1]
	v_add_u32_e32 v4, 0x2080, v1
	ds_write2_b32 v4, v78, v79 offset1:1
	v_pk_mul_f32 v[78:79], s[0:1], v[112:113] op_sel_hi:[0,1]
	v_add_u32_e32 v4, 0x2088, v1
	ds_write2_b32 v4, v78, v79 offset1:1
	s_waitcnt vmcnt(6)
	v_pk_mul_f32 v[78:79], s[0:1], v[114:115] op_sel_hi:[0,1]
	v_add_u32_e32 v4, 0x2490, v1
	ds_write2_b32 v4, v78, v79 offset1:1
	v_pk_mul_f32 v[78:79], s[0:1], v[116:117] op_sel_hi:[0,1]
	v_add_u32_e32 v4, 0x2498, v1
	ds_write2_b32 v4, v78, v79 offset1:1
	s_waitcnt vmcnt(5)
	v_pk_mul_f32 v[78:79], s[0:1], v[118:119] op_sel_hi:[0,1]
	v_add_u32_e32 v4, 0x28a0, v1
	ds_write2_b32 v4, v78, v79 offset1:1
	v_pk_mul_f32 v[78:79], s[0:1], v[120:121] op_sel_hi:[0,1]
	v_add_u32_e32 v4, 0x28a8, v1
	ds_write2_b32 v4, v78, v79 offset1:1
	s_waitcnt vmcnt(4)
	v_pk_mul_f32 v[78:79], s[0:1], v[122:123] op_sel_hi:[0,1]
	v_add_u32_e32 v4, 0x2cb0, v1
	ds_write2_b32 v4, v78, v79 offset1:1
	v_pk_mul_f32 v[78:79], s[0:1], v[124:125] op_sel_hi:[0,1]
	v_add_u32_e32 v4, 0x2cb8, v1
	ds_write2_b32 v4, v78, v79 offset1:1
	s_waitcnt vmcnt(3)
	v_pk_mul_f32 v[78:79], s[0:1], v[126:127] op_sel_hi:[0,1]
	v_add_u32_e32 v4, 0x30c0, v1
	ds_write2_b32 v4, v78, v79 offset1:1
	v_pk_mul_f32 v[78:79], s[0:1], v[128:129] op_sel_hi:[0,1]
	v_add_u32_e32 v4, 0x30c8, v1
	ds_write2_b32 v4, v78, v79 offset1:1
	s_waitcnt vmcnt(2)
	v_pk_mul_f32 v[78:79], s[0:1], v[130:131] op_sel_hi:[0,1]
	v_add_u32_e32 v4, 0x34d0, v1
	ds_write2_b32 v4, v78, v79 offset1:1
	v_pk_mul_f32 v[78:79], s[0:1], v[132:133] op_sel_hi:[0,1]
	v_add_u32_e32 v4, 0x34d8, v1
	ds_write2_b32 v4, v78, v79 offset1:1
	s_waitcnt vmcnt(1)
	v_pk_mul_f32 v[78:79], s[0:1], v[134:135] op_sel_hi:[0,1]
	v_add_u32_e32 v4, 0x38e0, v1
	ds_write2_b32 v4, v78, v79 offset1:1
	v_pk_mul_f32 v[78:79], s[0:1], v[136:137] op_sel_hi:[0,1]
	v_add_u32_e32 v4, 0x38e8, v1
	ds_write2_b32 v4, v78, v79 offset1:1
	s_waitcnt vmcnt(0)
	v_pk_mul_f32 v[78:79], s[0:1], v[138:139] op_sel_hi:[0,1]
	v_add_u32_e32 v4, 0x3cf0, v1
	ds_write2_b32 v4, v78, v79 offset1:1
	v_pk_mul_f32 v[78:79], s[0:1], v[140:141] op_sel_hi:[0,1]
	v_add_u32_e32 v4, 0x3cf8, v1
	ds_write2_b32 v4, v78, v79 offset1:1
	s_waitcnt lgkmcnt(0)
	ds_read2_b32 v[82:83], v33 offset0:65 offset1:73
	ds_read2_b32 v[84:85], v33 offset1:8
	ds_read2_b32 v[86:87], v33 offset0:130 offset1:138
	ds_read2_b32 v[88:89], v33 offset0:195 offset1:203
	ds_read2_b32 v[90:91], v77 offset0:4 offset1:12
	ds_read2_b32 v[92:93], v77 offset0:69 offset1:77
	ds_read2_b32 v[94:95], v77 offset0:134 offset1:142
	ds_read2_b32 v[96:97], v77 offset0:199 offset1:207
	v_lshlrev_b32_e32 v4, 1, v32
	v_lshl_add_u64 v[98:99], s[10:11], 0, v[4:5]
	s_waitcnt lgkmcnt(6)
	v_cvt_pk_bf16_f32 v78, v84, v82
	s_waitcnt lgkmcnt(4)
	v_cvt_pk_bf16_f32 v79, v86, v88
	s_waitcnt lgkmcnt(2)
	v_cvt_pk_bf16_f32 v80, v90, v92
	s_waitcnt lgkmcnt(0)
	v_cvt_pk_bf16_f32 v81, v94, v96
	v_lshl_add_u64 v[100:101], v[98:99], 0, v[34:35]
	global_store_dwordx4 v[100:101], v[78:81], off sc1
	v_readlane_b32 s64, v234, 15
	v_readlane_b32 s65, v234, 16
	v_cvt_pk_bf16_f32 v78, v85, v83
	v_cvt_pk_bf16_f32 v79, v87, v89
	v_cvt_pk_bf16_f32 v80, v91, v93
	v_cvt_pk_bf16_f32 v81, v95, v97
	ds_read2_b32 v[84:85], v33 offset0:81 offset1:89
	ds_read2_b32 v[86:87], v33 offset0:16 offset1:24
	ds_read2_b32 v[88:89], v33 offset0:146 offset1:154
	ds_read2_b32 v[90:91], v33 offset0:211 offset1:219
	ds_read2_b32 v[92:93], v77 offset0:20 offset1:28
	ds_read2_b32 v[94:95], v77 offset0:85 offset1:93
	ds_read2_b32 v[96:97], v77 offset0:150 offset1:158
	ds_read2_b32 v[100:101], v77 offset0:215 offset1:223
	v_lshl_add_u64 v[82:83], v[98:99], 0, v[36:37]
	global_store_dwordx4 v[82:83], v[78:81], off sc1
	v_lshl_add_u64 v[82:83], v[98:99], 0, v[38:39]
	v_readlane_b32 s66, v234, 17
	s_waitcnt lgkmcnt(6)
	v_cvt_pk_bf16_f32 v78, v86, v84
	s_waitcnt lgkmcnt(4)
	v_cvt_pk_bf16_f32 v79, v88, v90
	s_waitcnt lgkmcnt(2)
	v_cvt_pk_bf16_f32 v80, v92, v94
	s_waitcnt lgkmcnt(0)
	v_cvt_pk_bf16_f32 v81, v96, v100
	global_store_dwordx4 v[82:83], v[78:81], off sc1
	v_lshl_add_u64 v[82:83], v[98:99], 0, v[46:47]
	v_readlane_b32 s67, v234, 18
	v_cvt_pk_bf16_f32 v78, v87, v85
	v_cvt_pk_bf16_f32 v79, v89, v91
	v_cvt_pk_bf16_f32 v80, v93, v95
	v_cvt_pk_bf16_f32 v81, v97, v101
	ds_read2_b32 v[84:85], v33 offset0:32 offset1:40
	ds_read2_b32 v[86:87], v33 offset0:97 offset1:105
	ds_read2_b32 v[88:89], v33 offset0:162 offset1:170
	ds_read2_b32 v[90:91], v33 offset0:227 offset1:235
	ds_read2_b32 v[92:93], v77 offset0:36 offset1:44
	ds_read2_b32 v[94:95], v77 offset0:101 offset1:109
	ds_read2_b32 v[96:97], v77 offset0:166 offset1:174
	ds_read2_b32 v[100:101], v77 offset0:231 offset1:239
	global_store_dwordx4 v[82:83], v[78:81], off sc1
	v_lshl_add_u64 v[82:83], v[98:99], 0, v[50:51]
	v_readlane_b32 s68, v234, 19
	s_waitcnt lgkmcnt(6)
	v_cvt_pk_bf16_f32 v78, v84, v86
	s_waitcnt lgkmcnt(4)
	v_cvt_pk_bf16_f32 v79, v88, v90
	s_waitcnt lgkmcnt(2)
	v_cvt_pk_bf16_f32 v80, v92, v94
	s_waitcnt lgkmcnt(0)
	v_cvt_pk_bf16_f32 v81, v96, v100
	global_store_dwordx4 v[82:83], v[78:81], off sc1
	v_lshl_add_u64 v[82:83], v[98:99], 0, v[54:55]
	v_readlane_b32 s69, v234, 20
	v_cvt_pk_bf16_f32 v78, v85, v87
	v_cvt_pk_bf16_f32 v79, v89, v91
	v_cvt_pk_bf16_f32 v80, v93, v95
	v_cvt_pk_bf16_f32 v81, v97, v101
	ds_read2_b32 v[84:85], v33 offset0:48 offset1:56
	ds_read2_b32 v[86:87], v33 offset0:113 offset1:121
	ds_read2_b32 v[88:89], v33 offset0:178 offset1:186
	ds_read2_b32 v[90:91], v33 offset0:243 offset1:251
	ds_read2_b32 v[92:93], v77 offset0:52 offset1:60
	ds_read2_b32 v[94:95], v77 offset0:117 offset1:125
	ds_read2_b32 v[96:97], v77 offset0:182 offset1:190
	ds_read2_b32 v[100:101], v77 offset0:247 offset1:255
	global_store_dwordx4 v[82:83], v[78:81], off sc1
	v_lshl_add_u64 v[82:83], v[98:99], 0, v[58:59]
	v_readlane_b32 s70, v234, 21
	s_waitcnt lgkmcnt(6)
	v_cvt_pk_bf16_f32 v78, v84, v86
	s_waitcnt lgkmcnt(4)
	v_cvt_pk_bf16_f32 v79, v88, v90
	s_waitcnt lgkmcnt(2)
	v_cvt_pk_bf16_f32 v80, v92, v94
	s_waitcnt lgkmcnt(0)
	v_cvt_pk_bf16_f32 v81, v96, v100
	global_store_dwordx4 v[82:83], v[78:81], off sc1
	v_lshl_add_u64 v[82:83], v[98:99], 0, v[62:63]
	v_readlane_b32 s71, v234, 22
	v_cvt_pk_bf16_f32 v78, v85, v87
	v_cvt_pk_bf16_f32 v79, v89, v91
	v_cvt_pk_bf16_f32 v80, v93, v95
	v_cvt_pk_bf16_f32 v81, v97, v101
	global_store_dwordx4 v[82:83], v[78:81], off sc1
	s_waitcnt lgkmcnt(0)

.LBB0_23:
	s_cmpk_gt_i32 s52, 0x5ff
	s_mov_b64 s[10:11], -1
	s_cbranch_scc0 .LBB0_65
	s_cmpk_gt_u32 s52, 0x7ff
	s_cbranch_scc0 .LBB0_62
	s_cmpk_gt_u32 s52, 0x9ff
	s_cbranch_scc0 .LBB0_55
	s_cmpk_gt_u32 s52, 0xaff
	s_cbranch_scc0 .LBB0_52
	s_cmpk_gt_u32 s52, 0xbff
	s_cbranch_scc0 .LBB0_49
	s_cmpk_gt_u32 s52, 0x117f
	s_cbranch_scc0 .LBB0_42
	s_cmpk_gt_u32 s52, 0x143f
	s_cbranch_scc0 .LBB0_39
	s_cmpk_gt_u32 s52, 0x4c3f
	s_cbranch_scc0 .LBB0_32
	s_add_i32 s0, s52, 0xb3c0
	s_bfe_u32 s10, s0, 0x90007
	s_mulk_i32 s10, 0x2493
	s_lshr_b32 s12, s10, 16
	s_mul_i32 s10, s12, 0x380
	s_sub_i32 s0, s0, s10
	s_and_b32 s10, s0, 0xffff
	s_lshl_b32 s0, s10, 2
	s_lshl_b32 s10, s10, 6
	v_readlane_b32 s56, v234, 23
	s_and_b32 s0, s0, 0xfc0
	s_and_b32 s13, s10, 0x3c0
	s_mul_i32 s10, s12, 0xe00000
	v_readlane_b32 s68, v234, 35
	v_readlane_b32 s69, v234, 36
	s_add_u32 s10, s68, s10
	s_addc_u32 s11, s69, 0
	s_lshl_b32 s14, s0, 12
	s_add_u32 s10, s10, s14
	s_addc_u32 s11, s11, 0
	s_lshl_b32 s14, s13, 2
	s_add_u32 s10, s10, s14
	s_addc_u32 s11, s11, 0
	v_lshl_add_u64 v[78:79], s[10:11], 0, v[66:67]
	v_lshlrev_b32_e32 v4, 2, v2
	v_lshl_add_u64 v[134:135], v[78:79], 0, v[4:5]
	v_add_co_u32_e32 v82, vcc, s21, v134
	global_load_dwordx4 v[78:81], v[134:135], off nt
	s_nop 0
	v_addc_co_u32_e32 v83, vcc, 0, v135, vcc
	v_add_co_u32_e32 v86, vcc, s24, v134
	global_load_dwordx4 v[82:85], v[82:83], off nt
	s_nop 0
	v_addc_co_u32_e32 v87, vcc, 0, v135, vcc
	v_add_co_u32_e32 v90, vcc, s25, v134
	global_load_dwordx4 v[86:89], v[86:87], off nt
	s_nop 0
	v_addc_co_u32_e32 v91, vcc, 0, v135, vcc
	v_add_co_u32_e32 v94, vcc, s26, v134
	global_load_dwordx4 v[90:93], v[90:91], off nt
	s_nop 0
	v_addc_co_u32_e32 v95, vcc, 0, v135, vcc
	v_add_co_u32_e32 v98, vcc, s27, v134
	global_load_dwordx4 v[94:97], v[94:95], off nt
	s_nop 0
	v_addc_co_u32_e32 v99, vcc, 0, v135, vcc
	v_add_co_u32_e32 v102, vcc, s28, v134
	global_load_dwordx4 v[98:101], v[98:99], off nt
	s_nop 0
	v_addc_co_u32_e32 v103, vcc, 0, v135, vcc
	v_add_co_u32_e32 v106, vcc, s29, v134
	global_load_dwordx4 v[102:105], v[102:103], off nt
	s_nop 0
	v_addc_co_u32_e32 v107, vcc, 0, v135, vcc
	v_add_co_u32_e32 v110, vcc, s30, v134
	global_load_dwordx4 v[106:109], v[106:107], off nt
	s_nop 0
	v_addc_co_u32_e32 v111, vcc, 0, v135, vcc
	v_add_co_u32_e32 v114, vcc, s31, v134
	global_load_dwordx4 v[110:113], v[110:111], off nt
	s_nop 0
	v_addc_co_u32_e32 v115, vcc, 0, v135, vcc
	v_add_co_u32_e32 v118, vcc, s34, v134
	global_load_dwordx4 v[114:117], v[114:115], off nt
	s_nop 0
	v_addc_co_u32_e32 v119, vcc, 0, v135, vcc
	v_add_co_u32_e32 v122, vcc, s35, v134
	v_add_u32_e32 v4, 0x410, v1
	s_nop 0
	v_addc_co_u32_e32 v123, vcc, 0, v135, vcc
	global_load_dwordx4 v[118:121], v[118:119], off nt
	s_nop 0
	global_load_dwordx4 v[122:125], v[122:123], off nt
	v_add_co_u32_e32 v126, vcc, s36, v134
	s_lshl_b32 s10, s12, 10
	s_nop 0
	v_addc_co_u32_e32 v127, vcc, 0, v135, vcc
	v_add_co_u32_e32 v130, vcc, s37, v134
	s_or_b32 s10, s10, s13
	s_nop 0
	v_addc_co_u32_e32 v131, vcc, 0, v135, vcc
	global_load_dwordx4 v[126:129], v[126:127], off nt
	s_nop 0
	global_load_dwordx4 v[130:133], v[130:131], off nt
	v_add_co_u32_e32 v136, vcc, s38, v134
	s_mulk_i32 s10, 0xe00
	s_nop 0
	v_addc_co_u32_e32 v137, vcc, 0, v135, vcc
	v_add_co_u32_e32 v138, vcc, s39, v134
	v_readlane_b32 s11, v234, 40
	s_nop 0
	v_addc_co_u32_e32 v139, vcc, 0, v135, vcc
	global_load_dwordx4 v[134:137], v[136:137], off nt
	s_nop 0
	global_load_dwordx4 v[138:141], v[138:139], off nt
	s_add_u32 s10, s11, s10
	v_readlane_b32 s11, v234, 41
	s_addc_u32 s11, s11, 0
	s_add_u32 s10, s10, s0
	s_waitcnt vmcnt(15)
	v_pk_mul_f32 v[78:79], v[78:79], s[4:5] op_sel_hi:[1,0]
	ds_write2_b32 v1, v78, v79 offset1:1
	v_pk_mul_f32 v[78:79], v[80:81], s[4:5] op_sel_hi:[1,0]
	ds_write2_b32 v1, v78, v79 offset0:2 offset1:3
	s_addc_u32 s11, s11, 0
	s_waitcnt vmcnt(14)
	v_pk_mul_f32 v[78:79], v[82:83], s[4:5] op_sel_hi:[1,0]
	ds_write2_b32 v4, v78, v79 offset1:1
	v_pk_mul_f32 v[78:79], v[84:85], s[4:5] op_sel_hi:[1,0]
	v_add_u32_e32 v4, 0x418, v1
	ds_write2_b32 v4, v78, v79 offset1:1
	s_waitcnt vmcnt(13)
	v_pk_mul_f32 v[78:79], v[86:87], s[4:5] op_sel_hi:[1,0]
	v_add_u32_e32 v4, 0x820, v1
	ds_write2_b32 v4, v78, v79 offset1:1
	v_pk_mul_f32 v[78:79], v[88:89], s[4:5] op_sel_hi:[1,0]
	v_add_u32_e32 v4, 0x828, v1
	ds_write2_b32 v4, v78, v79 offset1:1
	s_waitcnt vmcnt(12)
	v_pk_mul_f32 v[78:79], v[90:91], s[4:5] op_sel_hi:[1,0]
	v_add_u32_e32 v4, 0xc30, v1
	ds_write2_b32 v4, v78, v79 offset1:1
	v_pk_mul_f32 v[78:79], v[92:93], s[4:5] op_sel_hi:[1,0]
	v_add_u32_e32 v4, 0xc38, v1
	ds_write2_b32 v4, v78, v79 offset1:1
	s_waitcnt vmcnt(11)
	v_pk_mul_f32 v[78:79], v[94:95], s[4:5] op_sel_hi:[1,0]
	v_add_u32_e32 v4, 0x1040, v1
	ds_write2_b32 v4, v78, v79 offset1:1
	v_pk_mul_f32 v[78:79], v[96:97], s[4:5] op_sel_hi:[1,0]
	v_add_u32_e32 v4, 0x1048, v1
	ds_write2_b32 v4, v78, v79 offset1:1
	s_waitcnt vmcnt(10)
	v_pk_mul_f32 v[78:79], v[98:99], s[4:5] op_sel_hi:[1,0]
	v_add_u32_e32 v4, 0x1450, v1
	ds_write2_b32 v4, v78, v79 offset1:1
	v_pk_mul_f32 v[78:79], v[100:101], s[4:5] op_sel_hi:[1,0]
	v_add_u32_e32 v4, 0x1458, v1
	ds_write2_b32 v4, v78, v79 offset1:1
	s_waitcnt vmcnt(9)
	v_pk_mul_f32 v[78:79], v[102:103], s[4:5] op_sel_hi:[1,0]
	v_add_u32_e32 v4, 0x1860, v1
	ds_write2_b32 v4, v78, v79 offset1:1
	v_pk_mul_f32 v[78:79], v[104:105], s[4:5] op_sel_hi:[1,0]
	v_add_u32_e32 v4, 0x1868, v1
	ds_write2_b32 v4, v78, v79 offset1:1
	s_waitcnt vmcnt(8)
	v_pk_mul_f32 v[78:79], v[106:107], s[4:5] op_sel_hi:[1,0]
	v_add_u32_e32 v4, 0x1c70, v1
	ds_write2_b32 v4, v78, v79 offset1:1
	v_pk_mul_f32 v[78:79], v[108:109], s[4:5] op_sel_hi:[1,0]
	v_add_u32_e32 v4, 0x1c78, v1
	ds_write2_b32 v4, v78, v79 offset1:1
	s_waitcnt vmcnt(7)
	v_pk_mul_f32 v[78:79], v[110:111], s[4:5] op_sel_hi:[1,0]
	v_add_u32_e32 v4, 0x2080, v1
	ds_write2_b32 v4, v78, v79 offset1:1
	v_pk_mul_f32 v[78:79], v[112:113], s[4:5] op_sel_hi:[1,0]
	v_add_u32_e32 v4, 0x2088, v1
	ds_write2_b32 v4, v78, v79 offset1:1
	s_waitcnt vmcnt(6)
	v_pk_mul_f32 v[78:79], v[114:115], s[4:5] op_sel_hi:[1,0]
	v_add_u32_e32 v4, 0x2490, v1
	ds_write2_b32 v4, v78, v79 offset1:1
	v_pk_mul_f32 v[78:79], v[116:117], s[4:5] op_sel_hi:[1,0]
	v_add_u32_e32 v4, 0x2498, v1
	ds_write2_b32 v4, v78, v79 offset1:1
	s_waitcnt vmcnt(5)
	v_pk_mul_f32 v[78:79], v[118:119], s[4:5] op_sel_hi:[1,0]
	v_add_u32_e32 v4, 0x28a0, v1
	ds_write2_b32 v4, v78, v79 offset1:1
	v_pk_mul_f32 v[78:79], v[120:121], s[4:5] op_sel_hi:[1,0]
	v_add_u32_e32 v4, 0x28a8, v1
	ds_write2_b32 v4, v78, v79 offset1:1
	s_waitcnt vmcnt(4)
	v_pk_mul_f32 v[78:79], v[122:123], s[4:5] op_sel_hi:[1,0]
	v_add_u32_e32 v4, 0x2cb0, v1
	ds_write2_b32 v4, v78, v79 offset1:1
	v_pk_mul_f32 v[78:79], v[124:125], s[4:5] op_sel_hi:[1,0]
	v_add_u32_e32 v4, 0x2cb8, v1
	ds_write2_b32 v4, v78, v79 offset1:1
	s_waitcnt vmcnt(3)
	v_pk_mul_f32 v[78:79], v[126:127], s[4:5] op_sel_hi:[1,0]
	v_add_u32_e32 v4, 0x30c0, v1
	ds_write2_b32 v4, v78, v79 offset1:1
	v_pk_mul_f32 v[78:79], v[128:129], s[4:5] op_sel_hi:[1,0]
	v_add_u32_e32 v4, 0x30c8, v1
	ds_write2_b32 v4, v78, v79 offset1:1
	s_waitcnt vmcnt(2)
	v_pk_mul_f32 v[78:79], v[130:131], s[4:5] op_sel_hi:[1,0]
	v_add_u32_e32 v4, 0x34d0, v1
	ds_write2_b32 v4, v78, v79 offset1:1
	v_pk_mul_f32 v[78:79], v[132:133], s[4:5] op_sel_hi:[1,0]
	v_add_u32_e32 v4, 0x34d8, v1
	ds_write2_b32 v4, v78, v79 offset1:1
	s_waitcnt vmcnt(1)
	v_pk_mul_f32 v[78:79], v[134:135], s[4:5] op_sel_hi:[1,0]
	v_add_u32_e32 v4, 0x38e0, v1
	ds_write2_b32 v4, v78, v79 offset1:1
	v_pk_mul_f32 v[78:79], v[136:137], s[4:5] op_sel_hi:[1,0]
	v_add_u32_e32 v4, 0x38e8, v1
	ds_write2_b32 v4, v78, v79 offset1:1
	s_waitcnt vmcnt(0)
	v_pk_mul_f32 v[78:79], v[138:139], s[4:5] op_sel_hi:[1,0]
	v_add_u32_e32 v4, 0x3cf0, v1
	ds_write2_b32 v4, v78, v79 offset1:1
	v_pk_mul_f32 v[78:79], v[140:141], s[4:5] op_sel_hi:[1,0]
	v_add_u32_e32 v4, 0x3cf8, v1
	ds_write2_b32 v4, v78, v79 offset1:1
	s_waitcnt lgkmcnt(0)
	ds_read2_b32 v[82:83], v3 offset1:16
	ds_read2_b32 v[84:85], v3 offset0:65 offset1:81
	v_mov_b32_e32 v78, v5
	ds_read2_b32 v[88:89], v3 offset0:130 offset1:146
	ds_read2_b32 v[90:91], v3 offset0:195 offset1:211
	v_add_u32_e32 v118, 0xc00, v3
	s_waitcnt lgkmcnt(3)
	v_med3_f32 v4, v82, s40, v76
	s_waitcnt lgkmcnt(2)
	v_med3_f32 v77, v84, s40, v76
	v_cvt_pk_fp8_f32 v78, v4, v77
	v_add_u32_e32 v4, 0x400, v3
	ds_read2_b32 v[92:93], v4 offset0:4 offset1:20
	ds_read2_b32 v[94:95], v4 offset0:69 offset1:85
	s_waitcnt lgkmcnt(3)
	v_med3_f32 v77, v88, s40, v76
	s_waitcnt lgkmcnt(2)
	v_med3_f32 v79, v90, s40, v76
	v_cvt_pk_fp8_f32 v78, v77, v79 op_sel:[0,0,1]
	s_waitcnt lgkmcnt(1)
	v_med3_f32 v77, v92, s40, v76
	s_waitcnt lgkmcnt(0)
	v_med3_f32 v80, v94, s40, v76
	v_mov_b32_e32 v79, v5
	v_cvt_pk_fp8_f32 v79, v77, v80
	ds_read2_b32 v[96:97], v4 offset0:134 offset1:150
	ds_read2_b32 v[98:99], v4 offset0:199 offset1:215
	v_add_u32_e32 v77, 0x800, v3
	ds_read2_b32 v[100:101], v77 offset0:8 offset1:24
	ds_read2_b32 v[102:103], v77 offset0:73 offset1:89
	ds_read2_b32 v[104:105], v77 offset0:138 offset1:154
	ds_read2_b32 v[106:107], v77 offset0:203 offset1:219
	ds_read2_b32 v[108:109], v118 offset0:12 offset1:28
	ds_read2_b32 v[110:111], v118 offset0:77 offset1:93
	s_waitcnt lgkmcnt(7)
	v_med3_f32 v80, v96, s40, v76
	s_waitcnt lgkmcnt(6)
	v_med3_f32 v81, v98, s40, v76
	v_cvt_pk_fp8_f32 v79, v80, v81 op_sel:[0,0,1]
	s_waitcnt lgkmcnt(5)
	v_med3_f32 v81, v100, s40, v76
	s_waitcnt lgkmcnt(4)
	v_med3_f32 v82, v102, s40, v76
	v_mov_b32_e32 v80, v5
	ds_read2_b32 v[112:113], v118 offset0:142 offset1:158
	ds_read2_b32 v[114:115], v118 offset0:207 offset1:223
	v_cvt_pk_fp8_f32 v80, v81, v82
	s_waitcnt lgkmcnt(3)
	v_med3_f32 v88, v108, s40, v76
	s_waitcnt lgkmcnt(2)
	v_med3_f32 v90, v110, s40, v76
	v_mov_b32_e32 v81, v5
	v_cvt_pk_fp8_f32 v81, v88, v90
	v_med3_f32 v82, v104, s40, v76
	v_med3_f32 v84, v106, s40, v76
	v_cvt_pk_fp8_f32 v80, v82, v84 op_sel:[0,0,1]
	s_waitcnt lgkmcnt(1)
	v_med3_f32 v82, v112, s40, v76
	s_waitcnt lgkmcnt(0)
	v_med3_f32 v84, v114, s40, v76
	v_cvt_pk_fp8_f32 v81, v82, v84 op_sel:[0,0,1]
	v_med3_f32 v83, v83, s40, v76
	v_med3_f32 v84, v85, s40, v76
	v_mov_b32_e32 v82, v5
	v_cvt_pk_fp8_f32 v82, v83, v84
	v_med3_f32 v84, v89, s40, v76
	v_med3_f32 v88, v93, s40, v76
	v_med3_f32 v89, v95, s40, v76
	v_mov_b32_e32 v83, v5
	v_cvt_pk_fp8_f32 v83, v88, v89
	v_med3_f32 v85, v91, s40, v76
	v_cvt_pk_fp8_f32 v82, v84, v85 op_sel:[0,0,1]
	v_med3_f32 v84, v97, s40, v76
	v_med3_f32 v85, v99, s40, v76
	v_cvt_pk_fp8_f32 v83, v84, v85 op_sel:[0,0,1]
	v_med3_f32 v85, v101, s40, v76
	v_med3_f32 v88, v103, s40, v76
	v_mov_b32_e32 v84, v5
	v_cvt_pk_fp8_f32 v84, v85, v88
	v_med3_f32 v90, v109, s40, v76
	v_med3_f32 v91, v111, s40, v76
	v_mov_b32_e32 v85, v5
	v_cvt_pk_fp8_f32 v85, v90, v91
	v_med3_f32 v88, v105, s40, v76
	v_med3_f32 v89, v107, s40, v76
	v_cvt_pk_fp8_f32 v84, v88, v89 op_sel:[0,0,1]
	v_med3_f32 v88, v113, s40, v76
	v_med3_f32 v89, v115, s40, v76
	v_cvt_pk_fp8_f32 v85, v88, v89 op_sel:[0,0,1]
	v_lshl_add_u64 v[86:87], s[10:11], 0, v[6:7]
	ds_read2_b32 v[88:89], v3 offset0:32 offset1:48
	ds_read2_b32 v[90:91], v3 offset0:97 offset1:113
	v_lshl_add_u64 v[116:117], v[86:87], 0, v[8:9]
	global_store_dwordx4 v[116:117], v[78:81], off sc1
	v_readlane_b32 s57, v234, 24
	v_readlane_b32 s58, v234, 25
	v_lshl_add_u64 v[78:79], v[86:87], 0, v[10:11]
	global_store_dwordx4 v[78:79], v[82:85], off sc1
	ds_read2_b32 v[82:83], v3 offset0:162 offset1:178
	ds_read2_b32 v[84:85], v3 offset0:227 offset1:243
	s_waitcnt lgkmcnt(3)
	v_med3_f32 v79, v88, s40, v76
	s_waitcnt lgkmcnt(2)
	v_med3_f32 v80, v90, s40, v76
	v_mov_b32_e32 v78, v5
	ds_read2_b32 v[92:93], v4 offset0:36 offset1:52
	ds_read2_b32 v[94:95], v4 offset0:101 offset1:117
	v_cvt_pk_fp8_f32 v78, v79, v80
	s_waitcnt lgkmcnt(3)
	v_med3_f32 v79, v82, s40, v76
	s_waitcnt lgkmcnt(2)
	v_med3_f32 v80, v84, s40, v76
	ds_read2_b32 v[96:97], v4 offset0:166 offset1:182
	ds_read2_b32 v[98:99], v4 offset0:231 offset1:247
	v_cvt_pk_fp8_f32 v78, v79, v80 op_sel:[0,0,1]
	s_waitcnt lgkmcnt(3)
	v_med3_f32 v80, v92, s40, v76
	s_waitcnt lgkmcnt(2)
	v_med3_f32 v81, v94, s40, v76
	v_mov_b32_e32 v79, v5
	ds_read2_b32 v[100:101], v77 offset0:40 offset1:56
	ds_read2_b32 v[102:103], v77 offset0:105 offset1:121
	v_cvt_pk_fp8_f32 v79, v80, v81
	ds_read2_b32 v[104:105], v77 offset0:170 offset1:186
	ds_read2_b32 v[106:107], v77 offset0:235 offset1:251
	ds_read2_b32 v[108:109], v118 offset0:44 offset1:60
	ds_read2_b32 v[110:111], v118 offset0:109 offset1:125
	s_waitcnt lgkmcnt(7)
	v_med3_f32 v4, v96, s40, v76
	s_waitcnt lgkmcnt(6)
	v_med3_f32 v80, v98, s40, v76
	v_cvt_pk_fp8_f32 v79, v4, v80 op_sel:[0,0,1]
	s_waitcnt lgkmcnt(5)
	v_med3_f32 v4, v100, s40, v76
	s_waitcnt lgkmcnt(4)
	v_med3_f32 v81, v102, s40, v76
	v_mov_b32_e32 v80, v5
	ds_read2_b32 v[112:113], v118 offset0:174 offset1:190
	ds_read2_b32 v[114:115], v118 offset0:239 offset1:255
	v_cvt_pk_fp8_f32 v80, v4, v81
	s_waitcnt lgkmcnt(3)
	v_med3_f32 v82, v108, s40, v76
	s_waitcnt lgkmcnt(2)
	v_med3_f32 v84, v110, s40, v76
	v_mov_b32_e32 v81, v5
	v_cvt_pk_fp8_f32 v81, v82, v84
	v_med3_f32 v4, v104, s40, v76
	v_med3_f32 v77, v106, s40, v76
	v_cvt_pk_fp8_f32 v80, v4, v77 op_sel:[0,0,1]
	s_waitcnt lgkmcnt(1)
	v_med3_f32 v4, v112, s40, v76
	s_waitcnt lgkmcnt(0)
	v_med3_f32 v77, v114, s40, v76
	v_cvt_pk_fp8_f32 v81, v4, v77 op_sel:[0,0,1]
	v_med3_f32 v4, v89, s40, v76
	v_med3_f32 v77, v91, s40, v76
	v_mov_b32_e32 v82, v5
	v_cvt_pk_fp8_f32 v82, v4, v77
	v_med3_f32 v4, v83, s40, v76
	v_med3_f32 v77, v85, s40, v76
	v_med3_f32 v84, v93, s40, v76
	v_med3_f32 v85, v95, s40, v76
	v_mov_b32_e32 v83, v5
	v_cvt_pk_fp8_f32 v83, v84, v85
	v_cvt_pk_fp8_f32 v82, v4, v77 op_sel:[0,0,1]
	v_med3_f32 v4, v97, s40, v76
	v_med3_f32 v77, v99, s40, v76
	v_cvt_pk_fp8_f32 v83, v4, v77 op_sel:[0,0,1]
	v_med3_f32 v4, v101, s40, v76
	v_med3_f32 v77, v103, s40, v76
	v_mov_b32_e32 v84, v5
	v_cvt_pk_fp8_f32 v84, v4, v77
	v_med3_f32 v88, v109, s40, v76
	v_med3_f32 v89, v111, s40, v76
	v_mov_b32_e32 v85, v5
	v_cvt_pk_fp8_f32 v85, v88, v89
	v_med3_f32 v4, v105, s40, v76
	v_med3_f32 v77, v107, s40, v76
	v_cvt_pk_fp8_f32 v84, v4, v77 op_sel:[0,0,1]
	v_med3_f32 v4, v113, s40, v76
	v_med3_f32 v77, v115, s40, v76
	v_cvt_pk_fp8_f32 v85, v4, v77 op_sel:[0,0,1]
	v_lshl_add_u64 v[88:89], v[86:87], 0, v[12:13]
	global_store_dwordx4 v[88:89], v[78:81], off sc1
	v_readlane_b32 s59, v234, 26
	v_readlane_b32 s60, v234, 27
	v_lshl_add_u64 v[78:79], v[86:87], 0, v[14:15]
	global_store_dwordx4 v[78:79], v[82:85], off sc1
	s_waitcnt lgkmcnt(0)
	v_readlane_b32 s61, v234, 28
	v_readlane_b32 s62, v234, 29
	v_readlane_b32 s63, v234, 30
	v_readlane_b32 s64, v234, 31
	v_readlane_b32 s65, v234, 32
	v_readlane_b32 s66, v234, 33
	v_readlane_b32 s67, v234, 34
	v_readlane_b32 s70, v234, 37
	v_readlane_b32 s71, v234, 38
	s_mov_b64 s[10:11], 0

.LBB0_37:
	v_readlane_b32 s56, v234, 23
	s_lshl_b32 s10, s13, 6
	s_mul_i32 s12, s12, 0x1c00000
	v_readlane_b32 s66, v234, 33
	v_readlane_b32 s67, v234, 34
	s_add_u32 s12, s66, s12
	s_addc_u32 s15, s67, 0
	s_and_b32 s10, s10, 0xffc0
	s_mul_i32 s13, s13, 0x1c0000
	s_add_u32 s12, s12, s13
	s_addc_u32 s13, s15, 0
	s_and_b32 s14, 0xffff, s14
	s_lshl_b32 s14, s14, 2
	s_add_u32 s12, s12, s14
	s_addc_u32 s13, s13, 0
	v_lshl_add_u64 v[78:79], s[12:13], 0, v[68:69]
	v_lshlrev_b32_e32 v4, 2, v2
	v_lshl_add_u64 v[134:135], v[78:79], 0, v[4:5]
	v_add_co_u32_e32 v82, vcc, s29, v134
	s_add_i32 s0, s11, s0
	s_nop 0
	v_addc_co_u32_e32 v83, vcc, 0, v135, vcc
	global_load_dwordx4 v[78:81], v[134:135], off nt
	s_nop 0
	global_load_dwordx4 v[82:85], v[82:83], off nt
	v_add_co_u32_e32 v86, vcc, s38, v134
	s_mov_b32 s11, 0x54000
	s_nop 0
	v_addc_co_u32_e32 v87, vcc, 0, v135, vcc
	v_add_co_u32_e32 v90, vcc, s11, v134
	s_mov_b32 s11, 0x8c000
	s_nop 0
	v_addc_co_u32_e32 v91, vcc, 0, v135, vcc
	global_load_dwordx4 v[86:89], v[86:87], off nt
	s_nop 0
	global_load_dwordx4 v[90:93], v[90:91], off nt
	v_add_co_u32_e32 v94, vcc, s41, v134
	s_lshl_b64 s[12:13], s[0:1], 10
	s_nop 0
	v_addc_co_u32_e32 v95, vcc, 0, v135, vcc
	v_add_co_u32_e32 v98, vcc, s11, v134
	s_add_u32 s0, s77, s12
	s_nop 0
	v_addc_co_u32_e32 v99, vcc, 0, v135, vcc
	global_load_dwordx4 v[94:97], v[94:95], off nt
	s_nop 0
	global_load_dwordx4 v[98:101], v[98:99], off nt
	v_add_co_u32_e32 v102, vcc, s42, v134
	s_mov_b32 s12, 0xc4000
	s_nop 0
	v_addc_co_u32_e32 v103, vcc, 0, v135, vcc
	v_add_co_u32_e32 v106, vcc, s12, v134
	s_mov_b32 s12, 0xe0000
	s_nop 0
	v_addc_co_u32_e32 v107, vcc, 0, v135, vcc
	global_load_dwordx4 v[102:105], v[102:103], off nt
	s_nop 0
	global_load_dwordx4 v[106:109], v[106:107], off nt
	v_add_co_u32_e32 v110, vcc, s12, v134
	s_mov_b32 s12, 0xfc000
	s_nop 0
	v_addc_co_u32_e32 v111, vcc, 0, v135, vcc
	v_add_co_u32_e32 v114, vcc, s12, v134
	s_mov_b32 s12, 0x118000
	s_nop 0
	v_addc_co_u32_e32 v115, vcc, 0, v135, vcc
	global_load_dwordx4 v[110:113], v[110:111], off nt
	s_nop 0
	global_load_dwordx4 v[114:117], v[114:115], off nt
	v_add_co_u32_e32 v118, vcc, s12, v134
	s_mov_b32 s12, 0x16c000
	s_nop 0
	v_addc_co_u32_e32 v119, vcc, 0, v135, vcc
	v_add_co_u32_e32 v122, vcc, s43, v134
	v_add_u32_e32 v4, 0x410, v1
	s_nop 0
	v_addc_co_u32_e32 v123, vcc, 0, v135, vcc
	global_load_dwordx4 v[118:121], v[118:119], off nt
	s_nop 0
	global_load_dwordx4 v[122:125], v[122:123], off nt
	v_add_co_u32_e32 v126, vcc, s44, v134
	v_readlane_b32 s11, v234, 42
	s_nop 0
	v_addc_co_u32_e32 v127, vcc, 0, v135, vcc
	v_add_co_u32_e32 v130, vcc, s12, v134
	s_mov_b32 s12, 0x188000
	s_nop 0
	v_addc_co_u32_e32 v131, vcc, 0, v135, vcc
	global_load_dwordx4 v[126:129], v[126:127], off nt
	s_nop 0
	global_load_dwordx4 v[130:133], v[130:131], off nt
	v_add_co_u32_e32 v136, vcc, s12, v134
	s_mov_b32 s12, 0x1a4000
	s_nop 0
	v_addc_co_u32_e32 v137, vcc, 0, v135, vcc
	v_add_co_u32_e32 v138, vcc, s12, v134
	s_addc_u32 s11, s11, s13
	s_nop 0
	v_addc_co_u32_e32 v139, vcc, 0, v135, vcc
	global_load_dwordx4 v[134:137], v[136:137], off nt
	s_nop 0
	global_load_dwordx4 v[138:141], v[138:139], off nt
	s_add_u32 s10, s0, s10
	s_waitcnt vmcnt(15)
	v_pk_mul_f32 v[78:79], v[78:79], s[6:7] op_sel_hi:[1,0]
	ds_write2_b32 v1, v78, v79 offset1:1
	v_pk_mul_f32 v[78:79], v[80:81], s[6:7] op_sel_hi:[1,0]
	ds_write2_b32 v1, v78, v79 offset0:2 offset1:3
	s_waitcnt vmcnt(14)
	v_pk_mul_f32 v[78:79], v[82:83], s[6:7] op_sel_hi:[1,0]
	ds_write2_b32 v4, v78, v79 offset1:1
	v_pk_mul_f32 v[78:79], v[84:85], s[6:7] op_sel_hi:[1,0]
	v_add_u32_e32 v4, 0x418, v1
	ds_write2_b32 v4, v78, v79 offset1:1
	v_add_u32_e32 v4, 0x820, v1
	s_addc_u32 s11, s11, 0
	s_waitcnt vmcnt(13)
	v_pk_mul_f32 v[78:79], v[86:87], s[6:7] op_sel_hi:[1,0]
	ds_write2_b32 v4, v78, v79 offset1:1
	v_pk_mul_f32 v[78:79], v[88:89], s[6:7] op_sel_hi:[1,0]
	v_add_u32_e32 v4, 0x828, v1
	ds_write2_b32 v4, v78, v79 offset1:1
	s_waitcnt vmcnt(12)
	v_pk_mul_f32 v[78:79], v[90:91], s[6:7] op_sel_hi:[1,0]
	v_add_u32_e32 v4, 0xc30, v1
	ds_write2_b32 v4, v78, v79 offset1:1
	v_pk_mul_f32 v[78:79], v[92:93], s[6:7] op_sel_hi:[1,0]
	v_add_u32_e32 v4, 0xc38, v1
	ds_write2_b32 v4, v78, v79 offset1:1
	s_waitcnt vmcnt(11)
	v_pk_mul_f32 v[78:79], v[94:95], s[6:7] op_sel_hi:[1,0]
	v_add_u32_e32 v4, 0x1040, v1
	ds_write2_b32 v4, v78, v79 offset1:1
	v_pk_mul_f32 v[78:79], v[96:97], s[6:7] op_sel_hi:[1,0]
	v_add_u32_e32 v4, 0x1048, v1
	ds_write2_b32 v4, v78, v79 offset1:1
	s_waitcnt vmcnt(10)
	v_pk_mul_f32 v[78:79], v[98:99], s[6:7] op_sel_hi:[1,0]
	v_add_u32_e32 v4, 0x1450, v1
	ds_write2_b32 v4, v78, v79 offset1:1
	v_pk_mul_f32 v[78:79], v[100:101], s[6:7] op_sel_hi:[1,0]
	v_add_u32_e32 v4, 0x1458, v1
	ds_write2_b32 v4, v78, v79 offset1:1
	s_waitcnt vmcnt(9)
	v_pk_mul_f32 v[78:79], v[102:103], s[6:7] op_sel_hi:[1,0]
	v_add_u32_e32 v4, 0x1860, v1
	ds_write2_b32 v4, v78, v79 offset1:1
	v_pk_mul_f32 v[78:79], v[104:105], s[6:7] op_sel_hi:[1,0]
	v_add_u32_e32 v4, 0x1868, v1
	ds_write2_b32 v4, v78, v79 offset1:1
	s_waitcnt vmcnt(8)
	v_pk_mul_f32 v[78:79], v[106:107], s[6:7] op_sel_hi:[1,0]
	v_add_u32_e32 v4, 0x1c70, v1
	ds_write2_b32 v4, v78, v79 offset1:1
	v_pk_mul_f32 v[78:79], v[108:109], s[6:7] op_sel_hi:[1,0]
	v_add_u32_e32 v4, 0x1c78, v1
	ds_write2_b32 v4, v78, v79 offset1:1
	s_waitcnt vmcnt(7)
	v_pk_mul_f32 v[78:79], v[110:111], s[6:7] op_sel_hi:[1,0]
	v_add_u32_e32 v4, 0x2080, v1
	ds_write2_b32 v4, v78, v79 offset1:1
	v_pk_mul_f32 v[78:79], v[112:113], s[6:7] op_sel_hi:[1,0]
	v_add_u32_e32 v4, 0x2088, v1
	ds_write2_b32 v4, v78, v79 offset1:1
	s_waitcnt vmcnt(6)
	v_pk_mul_f32 v[78:79], v[114:115], s[6:7] op_sel_hi:[1,0]
	v_add_u32_e32 v4, 0x2490, v1
	ds_write2_b32 v4, v78, v79 offset1:1
	v_pk_mul_f32 v[78:79], v[116:117], s[6:7] op_sel_hi:[1,0]
	v_add_u32_e32 v4, 0x2498, v1
	ds_write2_b32 v4, v78, v79 offset1:1
	s_waitcnt vmcnt(5)
	v_pk_mul_f32 v[78:79], v[118:119], s[6:7] op_sel_hi:[1,0]
	v_add_u32_e32 v4, 0x28a0, v1
	ds_write2_b32 v4, v78, v79 offset1:1
	v_pk_mul_f32 v[78:79], v[120:121], s[6:7] op_sel_hi:[1,0]
	v_add_u32_e32 v4, 0x28a8, v1
	ds_write2_b32 v4, v78, v79 offset1:1
	s_waitcnt vmcnt(4)
	v_pk_mul_f32 v[78:79], v[122:123], s[6:7] op_sel_hi:[1,0]
	v_add_u32_e32 v4, 0x2cb0, v1
	ds_write2_b32 v4, v78, v79 offset1:1
	v_pk_mul_f32 v[78:79], v[124:125], s[6:7] op_sel_hi:[1,0]
	v_add_u32_e32 v4, 0x2cb8, v1
	ds_write2_b32 v4, v78, v79 offset1:1
	s_waitcnt vmcnt(3)
	v_pk_mul_f32 v[78:79], v[126:127], s[6:7] op_sel_hi:[1,0]
	v_add_u32_e32 v4, 0x30c0, v1
	ds_write2_b32 v4, v78, v79 offset1:1
	v_pk_mul_f32 v[78:79], v[128:129], s[6:7] op_sel_hi:[1,0]
	v_add_u32_e32 v4, 0x30c8, v1
	ds_write2_b32 v4, v78, v79 offset1:1
	s_waitcnt vmcnt(2)
	v_pk_mul_f32 v[78:79], v[130:131], s[6:7] op_sel_hi:[1,0]
	v_add_u32_e32 v4, 0x34d0, v1
	ds_write2_b32 v4, v78, v79 offset1:1
	v_pk_mul_f32 v[78:79], v[132:133], s[6:7] op_sel_hi:[1,0]
	v_add_u32_e32 v4, 0x34d8, v1
	ds_write2_b32 v4, v78, v79 offset1:1
	s_waitcnt vmcnt(1)
	v_pk_mul_f32 v[78:79], v[134:135], s[6:7] op_sel_hi:[1,0]
	v_add_u32_e32 v4, 0x38e0, v1
	ds_write2_b32 v4, v78, v79 offset1:1
	v_pk_mul_f32 v[78:79], v[136:137], s[6:7] op_sel_hi:[1,0]
	v_add_u32_e32 v4, 0x38e8, v1
	ds_write2_b32 v4, v78, v79 offset1:1
	s_waitcnt vmcnt(0)
	v_pk_mul_f32 v[78:79], v[138:139], s[6:7] op_sel_hi:[1,0]
	v_add_u32_e32 v4, 0x3cf0, v1
	ds_write2_b32 v4, v78, v79 offset1:1
	v_pk_mul_f32 v[78:79], v[140:141], s[6:7] op_sel_hi:[1,0]
	v_add_u32_e32 v4, 0x3cf8, v1
	ds_write2_b32 v4, v78, v79 offset1:1
	s_waitcnt lgkmcnt(0)
	ds_read2_b32 v[82:83], v3 offset1:16
	ds_read2_b32 v[84:85], v3 offset0:65 offset1:81
	v_mov_b32_e32 v78, v5
	ds_read2_b32 v[88:89], v3 offset0:130 offset1:146
	ds_read2_b32 v[90:91], v3 offset0:195 offset1:211
	v_add_u32_e32 v118, 0xc00, v3
	s_waitcnt lgkmcnt(3)
	v_med3_f32 v4, v82, s40, v76
	s_waitcnt lgkmcnt(2)
	v_med3_f32 v77, v84, s40, v76
	v_cvt_pk_fp8_f32 v78, v4, v77
	v_add_u32_e32 v4, 0x400, v3
	ds_read2_b32 v[92:93], v4 offset0:4 offset1:20
	ds_read2_b32 v[94:95], v4 offset0:69 offset1:85
	s_waitcnt lgkmcnt(3)
	v_med3_f32 v77, v88, s40, v76
	s_waitcnt lgkmcnt(2)
	v_med3_f32 v79, v90, s40, v76
	v_cvt_pk_fp8_f32 v78, v77, v79 op_sel:[0,0,1]
	s_waitcnt lgkmcnt(1)
	v_med3_f32 v77, v92, s40, v76
	s_waitcnt lgkmcnt(0)
	v_med3_f32 v80, v94, s40, v76
	v_mov_b32_e32 v79, v5
	v_cvt_pk_fp8_f32 v79, v77, v80
	ds_read2_b32 v[96:97], v4 offset0:134 offset1:150
	ds_read2_b32 v[98:99], v4 offset0:199 offset1:215
	v_add_u32_e32 v77, 0x800, v3
	ds_read2_b32 v[100:101], v77 offset0:8 offset1:24
	ds_read2_b32 v[102:103], v77 offset0:73 offset1:89
	ds_read2_b32 v[104:105], v77 offset0:138 offset1:154
	ds_read2_b32 v[106:107], v77 offset0:203 offset1:219
	ds_read2_b32 v[108:109], v118 offset0:12 offset1:28
	ds_read2_b32 v[110:111], v118 offset0:77 offset1:93
	s_waitcnt lgkmcnt(7)
	v_med3_f32 v80, v96, s40, v76
	s_waitcnt lgkmcnt(6)
	v_med3_f32 v81, v98, s40, v76
	v_cvt_pk_fp8_f32 v79, v80, v81 op_sel:[0,0,1]
	s_waitcnt lgkmcnt(5)
	v_med3_f32 v81, v100, s40, v76
	s_waitcnt lgkmcnt(4)
	v_med3_f32 v82, v102, s40, v76
	v_mov_b32_e32 v80, v5
	ds_read2_b32 v[112:113], v118 offset0:142 offset1:158
	ds_read2_b32 v[114:115], v118 offset0:207 offset1:223
	v_cvt_pk_fp8_f32 v80, v81, v82
	s_waitcnt lgkmcnt(3)
	v_med3_f32 v88, v108, s40, v76
	s_waitcnt lgkmcnt(2)
	v_med3_f32 v90, v110, s40, v76
	v_mov_b32_e32 v81, v5
	v_cvt_pk_fp8_f32 v81, v88, v90
	v_med3_f32 v82, v104, s40, v76
	v_med3_f32 v84, v106, s40, v76
	v_cvt_pk_fp8_f32 v80, v82, v84 op_sel:[0,0,1]
	s_waitcnt lgkmcnt(1)
	v_med3_f32 v82, v112, s40, v76
	s_waitcnt lgkmcnt(0)
	v_med3_f32 v84, v114, s40, v76
	v_cvt_pk_fp8_f32 v81, v82, v84 op_sel:[0,0,1]
	v_med3_f32 v83, v83, s40, v76
	v_med3_f32 v84, v85, s40, v76
	v_mov_b32_e32 v82, v5
	v_cvt_pk_fp8_f32 v82, v83, v84
	v_med3_f32 v84, v89, s40, v76
	v_med3_f32 v88, v93, s40, v76
	v_med3_f32 v89, v95, s40, v76
	v_mov_b32_e32 v83, v5
	v_cvt_pk_fp8_f32 v83, v88, v89
	v_med3_f32 v85, v91, s40, v76
	v_cvt_pk_fp8_f32 v82, v84, v85 op_sel:[0,0,1]
	v_med3_f32 v84, v97, s40, v76
	v_med3_f32 v85, v99, s40, v76
	v_cvt_pk_fp8_f32 v83, v84, v85 op_sel:[0,0,1]
	v_med3_f32 v85, v101, s40, v76
	v_med3_f32 v88, v103, s40, v76
	v_mov_b32_e32 v84, v5
	v_cvt_pk_fp8_f32 v84, v85, v88
	v_med3_f32 v90, v109, s40, v76
	v_med3_f32 v91, v111, s40, v76
	v_mov_b32_e32 v85, v5
	v_cvt_pk_fp8_f32 v85, v90, v91
	v_med3_f32 v88, v105, s40, v76
	v_med3_f32 v89, v107, s40, v76
	v_cvt_pk_fp8_f32 v84, v88, v89 op_sel:[0,0,1]
	v_med3_f32 v88, v113, s40, v76
	v_med3_f32 v89, v115, s40, v76
	v_cvt_pk_fp8_f32 v85, v88, v89 op_sel:[0,0,1]
	v_lshl_add_u64 v[86:87], s[10:11], 0, v[6:7]
	ds_read2_b32 v[88:89], v3 offset0:32 offset1:48
	ds_read2_b32 v[90:91], v3 offset0:97 offset1:113
	v_lshl_add_u64 v[116:117], v[86:87], 0, v[16:17]
	global_store_dwordx4 v[116:117], v[78:81], off sc1
	v_readlane_b32 s57, v234, 24
	v_readlane_b32 s58, v234, 25
	v_lshl_add_u64 v[78:79], v[86:87], 0, v[18:19]
	global_store_dwordx4 v[78:79], v[82:85], off sc1
	ds_read2_b32 v[82:83], v3 offset0:162 offset1:178
	ds_read2_b32 v[84:85], v3 offset0:227 offset1:243
	s_waitcnt lgkmcnt(3)
	v_med3_f32 v79, v88, s40, v76
	s_waitcnt lgkmcnt(2)
	v_med3_f32 v80, v90, s40, v76
	v_mov_b32_e32 v78, v5
	ds_read2_b32 v[92:93], v4 offset0:36 offset1:52
	ds_read2_b32 v[94:95], v4 offset0:101 offset1:117
	v_cvt_pk_fp8_f32 v78, v79, v80
	s_waitcnt lgkmcnt(3)
	v_med3_f32 v79, v82, s40, v76
	s_waitcnt lgkmcnt(2)
	v_med3_f32 v80, v84, s40, v76
	ds_read2_b32 v[96:97], v4 offset0:166 offset1:182
	ds_read2_b32 v[98:99], v4 offset0:231 offset1:247
	v_cvt_pk_fp8_f32 v78, v79, v80 op_sel:[0,0,1]
	s_waitcnt lgkmcnt(3)
	v_med3_f32 v80, v92, s40, v76
	s_waitcnt lgkmcnt(2)
	v_med3_f32 v81, v94, s40, v76
	v_mov_b32_e32 v79, v5
	ds_read2_b32 v[100:101], v77 offset0:40 offset1:56
	ds_read2_b32 v[102:103], v77 offset0:105 offset1:121
	v_cvt_pk_fp8_f32 v79, v80, v81
	ds_read2_b32 v[104:105], v77 offset0:170 offset1:186
	ds_read2_b32 v[106:107], v77 offset0:235 offset1:251
	ds_read2_b32 v[108:109], v118 offset0:44 offset1:60
	ds_read2_b32 v[110:111], v118 offset0:109 offset1:125
	s_waitcnt lgkmcnt(7)
	v_med3_f32 v4, v96, s40, v76
	s_waitcnt lgkmcnt(6)
	v_med3_f32 v80, v98, s40, v76
	v_cvt_pk_fp8_f32 v79, v4, v80 op_sel:[0,0,1]
	s_waitcnt lgkmcnt(5)
	v_med3_f32 v4, v100, s40, v76
	s_waitcnt lgkmcnt(4)
	v_med3_f32 v81, v102, s40, v76
	v_mov_b32_e32 v80, v5
	ds_read2_b32 v[112:113], v118 offset0:174 offset1:190
	ds_read2_b32 v[114:115], v118 offset0:239 offset1:255
	v_cvt_pk_fp8_f32 v80, v4, v81
	s_waitcnt lgkmcnt(3)
	v_med3_f32 v82, v108, s40, v76
	s_waitcnt lgkmcnt(2)
	v_med3_f32 v84, v110, s40, v76
	v_mov_b32_e32 v81, v5
	v_cvt_pk_fp8_f32 v81, v82, v84
	v_med3_f32 v4, v104, s40, v76
	v_med3_f32 v77, v106, s40, v76
	v_cvt_pk_fp8_f32 v80, v4, v77 op_sel:[0,0,1]
	s_waitcnt lgkmcnt(1)
	v_med3_f32 v4, v112, s40, v76
	s_waitcnt lgkmcnt(0)
	v_med3_f32 v77, v114, s40, v76
	v_cvt_pk_fp8_f32 v81, v4, v77 op_sel:[0,0,1]
	v_med3_f32 v4, v89, s40, v76
	v_med3_f32 v77, v91, s40, v76
	v_mov_b32_e32 v82, v5
	v_cvt_pk_fp8_f32 v82, v4, v77
	v_med3_f32 v4, v83, s40, v76
	v_med3_f32 v77, v85, s40, v76
	v_med3_f32 v84, v93, s40, v76
	v_med3_f32 v85, v95, s40, v76
	v_mov_b32_e32 v83, v5
	v_cvt_pk_fp8_f32 v83, v84, v85
	v_cvt_pk_fp8_f32 v82, v4, v77 op_sel:[0,0,1]
	v_med3_f32 v4, v97, s40, v76
	v_med3_f32 v77, v99, s40, v76
	v_cvt_pk_fp8_f32 v83, v4, v77 op_sel:[0,0,1]
	v_med3_f32 v4, v101, s40, v76
	v_med3_f32 v77, v103, s40, v76
	v_mov_b32_e32 v84, v5
	v_cvt_pk_fp8_f32 v84, v4, v77
	v_med3_f32 v88, v109, s40, v76
	v_med3_f32 v89, v111, s40, v76
	v_mov_b32_e32 v85, v5
	v_cvt_pk_fp8_f32 v85, v88, v89
	v_med3_f32 v4, v105, s40, v76
	v_med3_f32 v77, v107, s40, v76
	v_cvt_pk_fp8_f32 v84, v4, v77 op_sel:[0,0,1]
	v_med3_f32 v4, v113, s40, v76
	v_med3_f32 v77, v115, s40, v76
	v_cvt_pk_fp8_f32 v85, v4, v77 op_sel:[0,0,1]
	v_lshl_add_u64 v[88:89], v[86:87], 0, v[20:21]
	global_store_dwordx4 v[88:89], v[78:81], off sc1
	v_readlane_b32 s59, v234, 26
	v_readlane_b32 s60, v234, 27
	v_lshl_add_u64 v[78:79], v[86:87], 0, v[22:23]
	global_store_dwordx4 v[78:79], v[82:85], off sc1
	s_waitcnt lgkmcnt(0)
	v_readlane_b32 s61, v234, 28
	v_readlane_b32 s62, v234, 29
	v_readlane_b32 s63, v234, 30
	v_readlane_b32 s64, v234, 31
	v_readlane_b32 s65, v234, 32
	v_readlane_b32 s68, v234, 35
	v_readlane_b32 s69, v234, 36
	v_readlane_b32 s70, v234, 37
	v_readlane_b32 s71, v234, 38

.LBB0_39:
	s_andn2_b64 vcc, exec, s[10:11]
	s_cbranch_vccnz .LBB0_41
	s_and_b32 s0, s9, 0x7fc0
	s_addk_i32 s0, 0xba00
	v_readlane_b32 s56, v234, 23
	s_and_b32 s12, s5, 0x3c0
	s_lshl_b64 s[10:11], s[0:1], 12
	v_readlane_b32 s62, v234, 29
	v_readlane_b32 s63, v234, 30
	s_add_u32 s10, s62, s10
	s_addc_u32 s11, s63, s11
	s_lshl_b32 s13, s12, 2
	s_add_u32 s10, s10, s13
	s_addc_u32 s11, s11, 0
	v_lshl_add_u64 v[78:79], s[10:11], 0, v[66:67]
	v_lshlrev_b32_e32 v4, 2, v2
	v_lshl_add_u64 v[134:135], v[78:79], 0, v[4:5]
	v_add_co_u32_e32 v82, vcc, s21, v134
	global_load_dwordx4 v[78:81], v[134:135], off nt
	s_nop 0
	v_addc_co_u32_e32 v83, vcc, 0, v135, vcc
	v_add_co_u32_e32 v86, vcc, s24, v134
	global_load_dwordx4 v[82:85], v[82:83], off nt
	s_nop 0
	v_addc_co_u32_e32 v87, vcc, 0, v135, vcc
	v_add_co_u32_e32 v90, vcc, s25, v134
	global_load_dwordx4 v[86:89], v[86:87], off nt
	s_nop 0
	v_addc_co_u32_e32 v91, vcc, 0, v135, vcc
	v_add_co_u32_e32 v94, vcc, s26, v134
	global_load_dwordx4 v[90:93], v[90:91], off nt
	s_nop 0
	v_addc_co_u32_e32 v95, vcc, 0, v135, vcc
	v_add_co_u32_e32 v98, vcc, s27, v134
	global_load_dwordx4 v[94:97], v[94:95], off nt
	s_nop 0
	v_addc_co_u32_e32 v99, vcc, 0, v135, vcc
	v_add_co_u32_e32 v102, vcc, s28, v134
	global_load_dwordx4 v[98:101], v[98:99], off nt
	s_nop 0
	v_addc_co_u32_e32 v103, vcc, 0, v135, vcc
	v_add_co_u32_e32 v106, vcc, s29, v134
	global_load_dwordx4 v[102:105], v[102:103], off nt
	s_nop 0
	v_addc_co_u32_e32 v107, vcc, 0, v135, vcc
	v_add_co_u32_e32 v110, vcc, s30, v134
	global_load_dwordx4 v[106:109], v[106:107], off nt
	s_nop 0
	v_addc_co_u32_e32 v111, vcc, 0, v135, vcc
	v_add_co_u32_e32 v114, vcc, s31, v134
	global_load_dwordx4 v[110:113], v[110:111], off nt
	s_nop 0
	v_addc_co_u32_e32 v115, vcc, 0, v135, vcc
	v_add_co_u32_e32 v118, vcc, s34, v134
	global_load_dwordx4 v[114:117], v[114:115], off nt
	s_nop 0
	v_addc_co_u32_e32 v119, vcc, 0, v135, vcc
	v_add_co_u32_e32 v122, vcc, s35, v134
	v_add_u32_e32 v4, 0x410, v1
	s_nop 0
	v_addc_co_u32_e32 v123, vcc, 0, v135, vcc
	global_load_dwordx4 v[118:121], v[118:119], off nt
	s_nop 0
	global_load_dwordx4 v[122:125], v[122:123], off nt
	v_add_co_u32_e32 v126, vcc, s36, v134
	s_mulk_i32 s12, 0xb00
	s_nop 0
	v_addc_co_u32_e32 v127, vcc, 0, v135, vcc
	v_add_co_u32_e32 v130, vcc, s37, v134
	v_readlane_b32 s10, v234, 43
	s_nop 0
	v_addc_co_u32_e32 v131, vcc, 0, v135, vcc
	global_load_dwordx4 v[126:129], v[126:127], off nt
	s_nop 0
	global_load_dwordx4 v[130:133], v[130:131], off nt
	v_add_co_u32_e32 v136, vcc, s38, v134
	s_add_u32 s10, s10, s12
	s_nop 0
	v_addc_co_u32_e32 v137, vcc, 0, v135, vcc
	v_add_co_u32_e32 v138, vcc, s39, v134
	v_readlane_b32 s11, v234, 44
	s_nop 0
	v_addc_co_u32_e32 v139, vcc, 0, v135, vcc
	global_load_dwordx4 v[134:137], v[136:137], off nt
	s_nop 0
	global_load_dwordx4 v[138:141], v[138:139], off nt
	s_addc_u32 s11, s11, 0
	s_add_u32 s10, s10, s0
	s_addc_u32 s11, s11, 0
	v_readlane_b32 s57, v234, 24
	s_waitcnt vmcnt(15)
	v_pk_mul_f32 v[78:79], v[78:79], s[4:5] op_sel_hi:[1,0]
	ds_write2_b32 v1, v78, v79 offset1:1
	v_pk_mul_f32 v[78:79], v[80:81], s[4:5] op_sel_hi:[1,0]
	ds_write2_b32 v1, v78, v79 offset0:2 offset1:3
	v_readlane_b32 s58, v234, 25
	s_waitcnt vmcnt(14)
	v_pk_mul_f32 v[78:79], v[82:83], s[4:5] op_sel_hi:[1,0]
	ds_write2_b32 v4, v78, v79 offset1:1
	v_pk_mul_f32 v[78:79], v[84:85], s[4:5] op_sel_hi:[1,0]
	v_add_u32_e32 v4, 0x418, v1
	ds_write2_b32 v4, v78, v79 offset1:1
	s_waitcnt vmcnt(13)
	v_pk_mul_f32 v[78:79], v[86:87], s[4:5] op_sel_hi:[1,0]
	v_add_u32_e32 v4, 0x820, v1
	ds_write2_b32 v4, v78, v79 offset1:1
	v_pk_mul_f32 v[78:79], v[88:89], s[4:5] op_sel_hi:[1,0]
	v_add_u32_e32 v4, 0x828, v1
	ds_write2_b32 v4, v78, v79 offset1:1
	s_waitcnt vmcnt(12)
	v_pk_mul_f32 v[78:79], v[90:91], s[4:5] op_sel_hi:[1,0]
	v_add_u32_e32 v4, 0xc30, v1
	ds_write2_b32 v4, v78, v79 offset1:1
	v_pk_mul_f32 v[78:79], v[92:93], s[4:5] op_sel_hi:[1,0]
	v_add_u32_e32 v4, 0xc38, v1
	ds_write2_b32 v4, v78, v79 offset1:1
	s_waitcnt vmcnt(11)
	v_pk_mul_f32 v[78:79], v[94:95], s[4:5] op_sel_hi:[1,0]
	v_add_u32_e32 v4, 0x1040, v1
	ds_write2_b32 v4, v78, v79 offset1:1
	v_pk_mul_f32 v[78:79], v[96:97], s[4:5] op_sel_hi:[1,0]
	v_add_u32_e32 v4, 0x1048, v1
	ds_write2_b32 v4, v78, v79 offset1:1
	s_waitcnt vmcnt(10)
	v_pk_mul_f32 v[78:79], v[98:99], s[4:5] op_sel_hi:[1,0]
	v_add_u32_e32 v4, 0x1450, v1
	ds_write2_b32 v4, v78, v79 offset1:1
	v_pk_mul_f32 v[78:79], v[100:101], s[4:5] op_sel_hi:[1,0]
	v_add_u32_e32 v4, 0x1458, v1
	ds_write2_b32 v4, v78, v79 offset1:1
	s_waitcnt vmcnt(9)
	v_pk_mul_f32 v[78:79], v[102:103], s[4:5] op_sel_hi:[1,0]
	v_add_u32_e32 v4, 0x1860, v1
	ds_write2_b32 v4, v78, v79 offset1:1
	v_pk_mul_f32 v[78:79], v[104:105], s[4:5] op_sel_hi:[1,0]
	v_add_u32_e32 v4, 0x1868, v1
	ds_write2_b32 v4, v78, v79 offset1:1
	s_waitcnt vmcnt(8)
	v_pk_mul_f32 v[78:79], v[106:107], s[4:5] op_sel_hi:[1,0]
	v_add_u32_e32 v4, 0x1c70, v1
	ds_write2_b32 v4, v78, v79 offset1:1
	v_pk_mul_f32 v[78:79], v[108:109], s[4:5] op_sel_hi:[1,0]
	v_add_u32_e32 v4, 0x1c78, v1
	ds_write2_b32 v4, v78, v79 offset1:1
	s_waitcnt vmcnt(7)
	v_pk_mul_f32 v[78:79], v[110:111], s[4:5] op_sel_hi:[1,0]
	v_add_u32_e32 v4, 0x2080, v1
	ds_write2_b32 v4, v78, v79 offset1:1
	v_pk_mul_f32 v[78:79], v[112:113], s[4:5] op_sel_hi:[1,0]
	v_add_u32_e32 v4, 0x2088, v1
	ds_write2_b32 v4, v78, v79 offset1:1
	s_waitcnt vmcnt(6)
	v_pk_mul_f32 v[78:79], v[114:115], s[4:5] op_sel_hi:[1,0]
	v_add_u32_e32 v4, 0x2490, v1
	ds_write2_b32 v4, v78, v79 offset1:1
	v_pk_mul_f32 v[78:79], v[116:117], s[4:5] op_sel_hi:[1,0]
	v_add_u32_e32 v4, 0x2498, v1
	ds_write2_b32 v4, v78, v79 offset1:1
	s_waitcnt vmcnt(5)
	v_pk_mul_f32 v[78:79], v[118:119], s[4:5] op_sel_hi:[1,0]
	v_add_u32_e32 v4, 0x28a0, v1
	ds_write2_b32 v4, v78, v79 offset1:1
	v_pk_mul_f32 v[78:79], v[120:121], s[4:5] op_sel_hi:[1,0]
	v_add_u32_e32 v4, 0x28a8, v1
	ds_write2_b32 v4, v78, v79 offset1:1
	s_waitcnt vmcnt(4)
	v_pk_mul_f32 v[78:79], v[122:123], s[4:5] op_sel_hi:[1,0]
	v_add_u32_e32 v4, 0x2cb0, v1
	ds_write2_b32 v4, v78, v79 offset1:1
	v_pk_mul_f32 v[78:79], v[124:125], s[4:5] op_sel_hi:[1,0]
	v_add_u32_e32 v4, 0x2cb8, v1
	ds_write2_b32 v4, v78, v79 offset1:1
	s_waitcnt vmcnt(3)
	v_pk_mul_f32 v[78:79], v[126:127], s[4:5] op_sel_hi:[1,0]
	v_add_u32_e32 v4, 0x30c0, v1
	ds_write2_b32 v4, v78, v79 offset1:1
	v_pk_mul_f32 v[78:79], v[128:129], s[4:5] op_sel_hi:[1,0]
	v_add_u32_e32 v4, 0x30c8, v1
	ds_write2_b32 v4, v78, v79 offset1:1
	s_waitcnt vmcnt(2)
	v_pk_mul_f32 v[78:79], v[130:131], s[4:5] op_sel_hi:[1,0]
	v_add_u32_e32 v4, 0x34d0, v1
	ds_write2_b32 v4, v78, v79 offset1:1
	v_pk_mul_f32 v[78:79], v[132:133], s[4:5] op_sel_hi:[1,0]
	v_add_u32_e32 v4, 0x34d8, v1
	ds_write2_b32 v4, v78, v79 offset1:1
	s_waitcnt vmcnt(1)
	v_pk_mul_f32 v[78:79], v[134:135], s[4:5] op_sel_hi:[1,0]
	v_add_u32_e32 v4, 0x38e0, v1
	ds_write2_b32 v4, v78, v79 offset1:1
	v_pk_mul_f32 v[78:79], v[136:137], s[4:5] op_sel_hi:[1,0]
	v_add_u32_e32 v4, 0x38e8, v1
	ds_write2_b32 v4, v78, v79 offset1:1
	s_waitcnt vmcnt(0)
	v_pk_mul_f32 v[78:79], v[138:139], s[4:5] op_sel_hi:[1,0]
	v_add_u32_e32 v4, 0x3cf0, v1
	ds_write2_b32 v4, v78, v79 offset1:1
	v_pk_mul_f32 v[78:79], v[140:141], s[4:5] op_sel_hi:[1,0]
	v_add_u32_e32 v4, 0x3cf8, v1
	ds_write2_b32 v4, v78, v79 offset1:1
	s_waitcnt lgkmcnt(0)
	ds_read2_b32 v[82:83], v3 offset1:16
	ds_read2_b32 v[84:85], v3 offset0:65 offset1:81
	v_mov_b32_e32 v78, v5
	ds_read2_b32 v[88:89], v3 offset0:130 offset1:146
	ds_read2_b32 v[90:91], v3 offset0:195 offset1:211
	v_add_u32_e32 v118, 0xc00, v3
	s_waitcnt lgkmcnt(3)
	v_med3_f32 v4, v82, s40, v76
	s_waitcnt lgkmcnt(2)
	v_med3_f32 v77, v84, s40, v76
	v_cvt_pk_fp8_f32 v78, v4, v77
	v_add_u32_e32 v4, 0x400, v3
	ds_read2_b32 v[92:93], v4 offset0:4 offset1:20
	ds_read2_b32 v[94:95], v4 offset0:69 offset1:85
	s_waitcnt lgkmcnt(3)
	v_med3_f32 v77, v88, s40, v76
	s_waitcnt lgkmcnt(2)
	v_med3_f32 v79, v90, s40, v76
	v_cvt_pk_fp8_f32 v78, v77, v79 op_sel:[0,0,1]
	s_waitcnt lgkmcnt(1)
	v_med3_f32 v77, v92, s40, v76
	s_waitcnt lgkmcnt(0)
	v_med3_f32 v80, v94, s40, v76
	v_mov_b32_e32 v79, v5
	v_cvt_pk_fp8_f32 v79, v77, v80
	ds_read2_b32 v[96:97], v4 offset0:134 offset1:150
	ds_read2_b32 v[98:99], v4 offset0:199 offset1:215
	v_add_u32_e32 v77, 0x800, v3
	ds_read2_b32 v[100:101], v77 offset0:8 offset1:24
	ds_read2_b32 v[102:103], v77 offset0:73 offset1:89
	ds_read2_b32 v[104:105], v77 offset0:138 offset1:154
	ds_read2_b32 v[106:107], v77 offset0:203 offset1:219
	ds_read2_b32 v[108:109], v118 offset0:12 offset1:28
	ds_read2_b32 v[110:111], v118 offset0:77 offset1:93
	s_waitcnt lgkmcnt(7)
	v_med3_f32 v80, v96, s40, v76
	s_waitcnt lgkmcnt(6)
	v_med3_f32 v81, v98, s40, v76
	v_cvt_pk_fp8_f32 v79, v80, v81 op_sel:[0,0,1]
	s_waitcnt lgkmcnt(5)
	v_med3_f32 v81, v100, s40, v76
	s_waitcnt lgkmcnt(4)
	v_med3_f32 v82, v102, s40, v76
	v_mov_b32_e32 v80, v5
	ds_read2_b32 v[112:113], v118 offset0:142 offset1:158
	ds_read2_b32 v[114:115], v118 offset0:207 offset1:223
	v_cvt_pk_fp8_f32 v80, v81, v82
	s_waitcnt lgkmcnt(3)
	v_med3_f32 v88, v108, s40, v76
	s_waitcnt lgkmcnt(2)
	v_med3_f32 v90, v110, s40, v76
	v_mov_b32_e32 v81, v5
	v_cvt_pk_fp8_f32 v81, v88, v90
	v_med3_f32 v82, v104, s40, v76
	v_med3_f32 v84, v106, s40, v76
	v_cvt_pk_fp8_f32 v80, v82, v84 op_sel:[0,0,1]
	s_waitcnt lgkmcnt(1)
	v_med3_f32 v82, v112, s40, v76
	s_waitcnt lgkmcnt(0)
	v_med3_f32 v84, v114, s40, v76
	v_cvt_pk_fp8_f32 v81, v82, v84 op_sel:[0,0,1]
	v_med3_f32 v83, v83, s40, v76
	v_med3_f32 v84, v85, s40, v76
	v_mov_b32_e32 v82, v5
	v_cvt_pk_fp8_f32 v82, v83, v84
	v_med3_f32 v84, v89, s40, v76
	v_med3_f32 v88, v93, s40, v76
	v_med3_f32 v89, v95, s40, v76
	v_mov_b32_e32 v83, v5
	v_cvt_pk_fp8_f32 v83, v88, v89
	v_med3_f32 v85, v91, s40, v76
	v_cvt_pk_fp8_f32 v82, v84, v85 op_sel:[0,0,1]
	v_med3_f32 v84, v97, s40, v76
	v_med3_f32 v85, v99, s40, v76
	v_cvt_pk_fp8_f32 v83, v84, v85 op_sel:[0,0,1]
	v_med3_f32 v85, v101, s40, v76
	v_med3_f32 v88, v103, s40, v76
	v_mov_b32_e32 v84, v5
	v_cvt_pk_fp8_f32 v84, v85, v88
	v_med3_f32 v90, v109, s40, v76
	v_med3_f32 v91, v111, s40, v76
	v_mov_b32_e32 v85, v5
	v_cvt_pk_fp8_f32 v85, v90, v91
	v_med3_f32 v88, v105, s40, v76
	v_med3_f32 v89, v107, s40, v76
	v_cvt_pk_fp8_f32 v84, v88, v89 op_sel:[0,0,1]
	v_med3_f32 v88, v113, s40, v76
	v_med3_f32 v89, v115, s40, v76
	v_cvt_pk_fp8_f32 v85, v88, v89 op_sel:[0,0,1]
	v_lshl_add_u64 v[86:87], s[10:11], 0, v[6:7]
	ds_read2_b32 v[88:89], v3 offset0:32 offset1:48
	ds_read2_b32 v[90:91], v3 offset0:97 offset1:113
	v_lshl_add_u64 v[116:117], v[86:87], 0, v[24:25]
	global_store_dwordx4 v[116:117], v[78:81], off sc1
	v_readlane_b32 s59, v234, 26
	v_readlane_b32 s60, v234, 27
	v_lshl_add_u64 v[78:79], v[86:87], 0, v[26:27]
	global_store_dwordx4 v[78:79], v[82:85], off sc1
	ds_read2_b32 v[82:83], v3 offset0:162 offset1:178
	ds_read2_b32 v[84:85], v3 offset0:227 offset1:243
	s_waitcnt lgkmcnt(3)
	v_med3_f32 v79, v88, s40, v76
	s_waitcnt lgkmcnt(2)
	v_med3_f32 v80, v90, s40, v76
	v_mov_b32_e32 v78, v5
	ds_read2_b32 v[92:93], v4 offset0:36 offset1:52
	ds_read2_b32 v[94:95], v4 offset0:101 offset1:117
	v_cvt_pk_fp8_f32 v78, v79, v80
	s_waitcnt lgkmcnt(3)
	v_med3_f32 v79, v82, s40, v76
	s_waitcnt lgkmcnt(2)
	v_med3_f32 v80, v84, s40, v76
	ds_read2_b32 v[96:97], v4 offset0:166 offset1:182
	ds_read2_b32 v[98:99], v4 offset0:231 offset1:247
	v_cvt_pk_fp8_f32 v78, v79, v80 op_sel:[0,0,1]
	s_waitcnt lgkmcnt(3)
	v_med3_f32 v80, v92, s40, v76
	s_waitcnt lgkmcnt(2)
	v_med3_f32 v81, v94, s40, v76
	v_mov_b32_e32 v79, v5
	ds_read2_b32 v[100:101], v77 offset0:40 offset1:56
	ds_read2_b32 v[102:103], v77 offset0:105 offset1:121
	v_cvt_pk_fp8_f32 v79, v80, v81
	ds_read2_b32 v[104:105], v77 offset0:170 offset1:186
	ds_read2_b32 v[106:107], v77 offset0:235 offset1:251
	ds_read2_b32 v[108:109], v118 offset0:44 offset1:60
	ds_read2_b32 v[110:111], v118 offset0:109 offset1:125
	s_waitcnt lgkmcnt(7)
	v_med3_f32 v4, v96, s40, v76
	s_waitcnt lgkmcnt(6)
	v_med3_f32 v80, v98, s40, v76
	v_cvt_pk_fp8_f32 v79, v4, v80 op_sel:[0,0,1]
	s_waitcnt lgkmcnt(5)
	v_med3_f32 v4, v100, s40, v76
	s_waitcnt lgkmcnt(4)
	v_med3_f32 v81, v102, s40, v76
	v_mov_b32_e32 v80, v5
	ds_read2_b32 v[112:113], v118 offset0:174 offset1:190
	ds_read2_b32 v[114:115], v118 offset0:239 offset1:255
	v_cvt_pk_fp8_f32 v80, v4, v81
	s_waitcnt lgkmcnt(3)
	v_med3_f32 v82, v108, s40, v76
	s_waitcnt lgkmcnt(2)
	v_med3_f32 v84, v110, s40, v76
	v_mov_b32_e32 v81, v5
	v_cvt_pk_fp8_f32 v81, v82, v84
	v_med3_f32 v4, v104, s40, v76
	v_med3_f32 v77, v106, s40, v76
	v_cvt_pk_fp8_f32 v80, v4, v77 op_sel:[0,0,1]
	s_waitcnt lgkmcnt(1)
	v_med3_f32 v4, v112, s40, v76
	s_waitcnt lgkmcnt(0)
	v_med3_f32 v77, v114, s40, v76
	v_cvt_pk_fp8_f32 v81, v4, v77 op_sel:[0,0,1]
	v_med3_f32 v4, v89, s40, v76
	v_med3_f32 v77, v91, s40, v76
	v_mov_b32_e32 v82, v5
	v_cvt_pk_fp8_f32 v82, v4, v77
	v_med3_f32 v4, v83, s40, v76
	v_med3_f32 v77, v85, s40, v76
	v_med3_f32 v84, v93, s40, v76
	v_med3_f32 v85, v95, s40, v76
	v_mov_b32_e32 v83, v5
	v_cvt_pk_fp8_f32 v83, v84, v85
	v_cvt_pk_fp8_f32 v82, v4, v77 op_sel:[0,0,1]
	v_med3_f32 v4, v97, s40, v76
	v_med3_f32 v77, v99, s40, v76
	v_cvt_pk_fp8_f32 v83, v4, v77 op_sel:[0,0,1]
	v_med3_f32 v4, v101, s40, v76
	v_med3_f32 v77, v103, s40, v76
	v_mov_b32_e32 v84, v5
	v_cvt_pk_fp8_f32 v84, v4, v77
	v_med3_f32 v88, v109, s40, v76
	v_med3_f32 v89, v111, s40, v76
	v_mov_b32_e32 v85, v5
	v_cvt_pk_fp8_f32 v85, v88, v89
	v_med3_f32 v4, v105, s40, v76
	v_med3_f32 v77, v107, s40, v76
	v_cvt_pk_fp8_f32 v84, v4, v77 op_sel:[0,0,1]
	v_med3_f32 v4, v113, s40, v76
	v_med3_f32 v77, v115, s40, v76
	v_cvt_pk_fp8_f32 v85, v4, v77 op_sel:[0,0,1]
	v_lshl_add_u64 v[88:89], v[86:87], 0, v[28:29]
	global_store_dwordx4 v[88:89], v[78:81], off sc1
	v_readlane_b32 s61, v234, 28
	v_readlane_b32 s64, v234, 31
	v_lshl_add_u64 v[78:79], v[86:87], 0, v[30:31]
	global_store_dwordx4 v[78:79], v[82:85], off sc1
	s_waitcnt lgkmcnt(0)
	v_readlane_b32 s65, v234, 32
	v_readlane_b32 s66, v234, 33
	v_readlane_b32 s67, v234, 34
	v_readlane_b32 s68, v234, 35
	v_readlane_b32 s69, v234, 36
	v_readlane_b32 s70, v234, 37
	v_readlane_b32 s71, v234, 38

.LBB0_47:
	s_lshl_b32 s10, s12, 6
	v_readlane_b32 s56, v234, 23
	s_and_b32 s10, s10, 0xffc0
	s_mul_i32 s12, s12, 0x160000
	v_readlane_b32 s60, v234, 27
	v_readlane_b32 s61, v234, 28
	s_add_u32 s11, s60, s12
	s_addc_u32 s14, s61, 0
	s_and_b32 s12, 0xffff, s13
	s_lshl_b32 s12, s12, 2
	s_add_u32 s12, s11, s12
	s_addc_u32 s13, s14, 0
	v_lshl_add_u64 v[78:79], s[12:13], 0, v[70:71]
	v_lshlrev_b32_e32 v4, 2, v2
	v_lshl_add_u64 v[134:135], v[78:79], 0, v[4:5]
	s_mov_b32 s11, 0x16000
	v_add_co_u32_e32 v82, vcc, s11, v134
	s_mov_b32 s11, 0x42000
	s_nop 0
	v_addc_co_u32_e32 v83, vcc, 0, v135, vcc
	global_load_dwordx4 v[78:81], v[134:135], off nt
	s_nop 0
	global_load_dwordx4 v[82:85], v[82:83], off nt
	v_add_co_u32_e32 v86, vcc, s35, v134
	s_lshl_b64 s[12:13], s[0:1], 10
	s_nop 0
	v_addc_co_u32_e32 v87, vcc, 0, v135, vcc
	v_add_co_u32_e32 v90, vcc, s11, v134
	s_mov_b32 s11, 0x6e000
	s_nop 0
	v_addc_co_u32_e32 v91, vcc, 0, v135, vcc
	global_load_dwordx4 v[86:89], v[86:87], off nt
	s_nop 0
	global_load_dwordx4 v[90:93], v[90:91], off nt
	v_add_co_u32_e32 v94, vcc, s45, v134
	v_readlane_b32 s0, v234, 45
	s_nop 0
	v_addc_co_u32_e32 v95, vcc, 0, v135, vcc
	v_add_co_u32_e32 v98, vcc, s11, v134
	s_add_u32 s0, s0, s12
	s_nop 0
	v_addc_co_u32_e32 v99, vcc, 0, v135, vcc
	s_mov_b32 s12, 0x84000
	global_load_dwordx4 v[94:97], v[94:95], off nt
	s_nop 0
	global_load_dwordx4 v[98:101], v[98:99], off nt
	v_add_co_u32_e32 v102, vcc, s12, v134
	s_mov_b32 s12, 0x9a000
	s_nop 0
	v_addc_co_u32_e32 v103, vcc, 0, v135, vcc
	v_add_co_u32_e32 v106, vcc, s12, v134
	s_mov_b32 s12, 0xb0000
	s_nop 0
	v_addc_co_u32_e32 v107, vcc, 0, v135, vcc
	global_load_dwordx4 v[102:105], v[102:103], off nt
	s_nop 0
	global_load_dwordx4 v[106:109], v[106:107], off nt
	v_add_co_u32_e32 v110, vcc, s12, v134
	s_mov_b32 s12, 0xc6000
	s_nop 0
	v_addc_co_u32_e32 v111, vcc, 0, v135, vcc
	v_add_co_u32_e32 v114, vcc, s12, v134
	s_mov_b32 s12, 0xdc000
	s_nop 0
	v_addc_co_u32_e32 v115, vcc, 0, v135, vcc
	global_load_dwordx4 v[110:113], v[110:111], off nt
	s_nop 0
	global_load_dwordx4 v[114:117], v[114:115], off nt
	v_add_co_u32_e32 v118, vcc, s12, v134
	s_mov_b32 s12, 0xf2000
	s_nop 0
	v_addc_co_u32_e32 v119, vcc, 0, v135, vcc
	v_add_co_u32_e32 v122, vcc, s12, v134
	s_mov_b32 s12, 0x11e000
	s_nop 0
	v_addc_co_u32_e32 v123, vcc, 0, v135, vcc
	global_load_dwordx4 v[118:121], v[118:119], off nt
	s_nop 0
	global_load_dwordx4 v[122:125], v[122:123], off nt
	v_add_co_u32_e32 v126, vcc, s48, v134
	v_add_u32_e32 v4, 0x410, v1
	s_nop 0
	v_addc_co_u32_e32 v127, vcc, 0, v135, vcc
	v_add_co_u32_e32 v130, vcc, s12, v134
	s_mov_b32 s12, 0x14a000
	s_nop 0
	v_addc_co_u32_e32 v131, vcc, 0, v135, vcc
	global_load_dwordx4 v[126:129], v[126:127], off nt
	s_nop 0
	global_load_dwordx4 v[130:133], v[130:131], off nt
	v_add_co_u32_e32 v136, vcc, s43, v134
	v_readlane_b32 s11, v234, 46
	s_nop 0
	v_addc_co_u32_e32 v137, vcc, 0, v135, vcc
	v_add_co_u32_e32 v138, vcc, s12, v134
	s_addc_u32 s11, s11, s13
	s_nop 0
	v_addc_co_u32_e32 v139, vcc, 0, v135, vcc
	global_load_dwordx4 v[134:137], v[136:137], off nt
	s_nop 0
	global_load_dwordx4 v[138:141], v[138:139], off nt
	s_waitcnt vmcnt(15)
	v_pk_mul_f32 v[78:79], v[78:79], s[6:7] op_sel_hi:[1,0]
	ds_write2_b32 v1, v78, v79 offset1:1
	v_pk_mul_f32 v[78:79], v[80:81], s[6:7] op_sel_hi:[1,0]
	ds_write2_b32 v1, v78, v79 offset0:2 offset1:3
	s_waitcnt vmcnt(14)
	v_pk_mul_f32 v[78:79], v[82:83], s[6:7] op_sel_hi:[1,0]
	ds_write2_b32 v4, v78, v79 offset1:1
	v_pk_mul_f32 v[78:79], v[84:85], s[6:7] op_sel_hi:[1,0]
	v_add_u32_e32 v4, 0x418, v1
	ds_write2_b32 v4, v78, v79 offset1:1
	v_add_u32_e32 v4, 0x820, v1
	s_add_u32 s10, s0, s10
	s_waitcnt vmcnt(13)
	v_pk_mul_f32 v[78:79], v[86:87], s[6:7] op_sel_hi:[1,0]
	ds_write2_b32 v4, v78, v79 offset1:1
	v_pk_mul_f32 v[78:79], v[88:89], s[6:7] op_sel_hi:[1,0]
	v_add_u32_e32 v4, 0x828, v1
	ds_write2_b32 v4, v78, v79 offset1:1
	s_waitcnt vmcnt(12)
	v_pk_mul_f32 v[78:79], v[90:91], s[6:7] op_sel_hi:[1,0]
	v_add_u32_e32 v4, 0xc30, v1
	ds_write2_b32 v4, v78, v79 offset1:1
	v_pk_mul_f32 v[78:79], v[92:93], s[6:7] op_sel_hi:[1,0]
	v_add_u32_e32 v4, 0xc38, v1
	ds_write2_b32 v4, v78, v79 offset1:1
	v_add_u32_e32 v4, 0x1040, v1
	s_waitcnt vmcnt(11)
	v_pk_mul_f32 v[78:79], v[94:95], s[6:7] op_sel_hi:[1,0]
	ds_write2_b32 v4, v78, v79 offset1:1
	v_pk_mul_f32 v[78:79], v[96:97], s[6:7] op_sel_hi:[1,0]
	v_add_u32_e32 v4, 0x1048, v1
	ds_write2_b32 v4, v78, v79 offset1:1
	s_waitcnt vmcnt(10)
	v_pk_mul_f32 v[78:79], v[98:99], s[6:7] op_sel_hi:[1,0]
	v_add_u32_e32 v4, 0x1450, v1
	ds_write2_b32 v4, v78, v79 offset1:1
	v_pk_mul_f32 v[78:79], v[100:101], s[6:7] op_sel_hi:[1,0]
	v_add_u32_e32 v4, 0x1458, v1
	ds_write2_b32 v4, v78, v79 offset1:1
	s_waitcnt vmcnt(9)
	v_pk_mul_f32 v[78:79], v[102:103], s[6:7] op_sel_hi:[1,0]
	v_add_u32_e32 v4, 0x1860, v1
	ds_write2_b32 v4, v78, v79 offset1:1
	v_pk_mul_f32 v[78:79], v[104:105], s[6:7] op_sel_hi:[1,0]
	v_add_u32_e32 v4, 0x1868, v1
	ds_write2_b32 v4, v78, v79 offset1:1
	s_waitcnt vmcnt(8)
	v_pk_mul_f32 v[78:79], v[106:107], s[6:7] op_sel_hi:[1,0]
	v_add_u32_e32 v4, 0x1c70, v1
	ds_write2_b32 v4, v78, v79 offset1:1
	v_pk_mul_f32 v[78:79], v[108:109], s[6:7] op_sel_hi:[1,0]
	v_add_u32_e32 v4, 0x1c78, v1
	ds_write2_b32 v4, v78, v79 offset1:1
	s_waitcnt vmcnt(7)
	v_pk_mul_f32 v[78:79], v[110:111], s[6:7] op_sel_hi:[1,0]
	v_add_u32_e32 v4, 0x2080, v1
	ds_write2_b32 v4, v78, v79 offset1:1
	v_pk_mul_f32 v[78:79], v[112:113], s[6:7] op_sel_hi:[1,0]
	v_add_u32_e32 v4, 0x2088, v1
	ds_write2_b32 v4, v78, v79 offset1:1
	s_waitcnt vmcnt(6)
	v_pk_mul_f32 v[78:79], v[114:115], s[6:7] op_sel_hi:[1,0]
	v_add_u32_e32 v4, 0x2490, v1
	ds_write2_b32 v4, v78, v79 offset1:1
	v_pk_mul_f32 v[78:79], v[116:117], s[6:7] op_sel_hi:[1,0]
	v_add_u32_e32 v4, 0x2498, v1
	ds_write2_b32 v4, v78, v79 offset1:1
	s_waitcnt vmcnt(5)
	v_pk_mul_f32 v[78:79], v[118:119], s[6:7] op_sel_hi:[1,0]
	v_add_u32_e32 v4, 0x28a0, v1
	ds_write2_b32 v4, v78, v79 offset1:1
	v_pk_mul_f32 v[78:79], v[120:121], s[6:7] op_sel_hi:[1,0]
	v_add_u32_e32 v4, 0x28a8, v1
	ds_write2_b32 v4, v78, v79 offset1:1
	s_waitcnt vmcnt(4)
	v_pk_mul_f32 v[78:79], v[122:123], s[6:7] op_sel_hi:[1,0]
	v_add_u32_e32 v4, 0x2cb0, v1
	ds_write2_b32 v4, v78, v79 offset1:1
	v_pk_mul_f32 v[78:79], v[124:125], s[6:7] op_sel_hi:[1,0]
	v_add_u32_e32 v4, 0x2cb8, v1
	ds_write2_b32 v4, v78, v79 offset1:1
	s_waitcnt vmcnt(3)
	v_pk_mul_f32 v[78:79], v[126:127], s[6:7] op_sel_hi:[1,0]
	v_add_u32_e32 v4, 0x30c0, v1
	ds_write2_b32 v4, v78, v79 offset1:1
	v_pk_mul_f32 v[78:79], v[128:129], s[6:7] op_sel_hi:[1,0]
	v_add_u32_e32 v4, 0x30c8, v1
	ds_write2_b32 v4, v78, v79 offset1:1
	s_waitcnt vmcnt(2)
	v_pk_mul_f32 v[78:79], v[130:131], s[6:7] op_sel_hi:[1,0]
	v_add_u32_e32 v4, 0x34d0, v1
	ds_write2_b32 v4, v78, v79 offset1:1
	v_pk_mul_f32 v[78:79], v[132:133], s[6:7] op_sel_hi:[1,0]
	v_add_u32_e32 v4, 0x34d8, v1
	ds_write2_b32 v4, v78, v79 offset1:1
	s_waitcnt vmcnt(1)
	v_pk_mul_f32 v[78:79], v[134:135], s[6:7] op_sel_hi:[1,0]
	v_add_u32_e32 v4, 0x38e0, v1
	ds_write2_b32 v4, v78, v79 offset1:1
	v_pk_mul_f32 v[78:79], v[136:137], s[6:7] op_sel_hi:[1,0]
	v_add_u32_e32 v4, 0x38e8, v1
	ds_write2_b32 v4, v78, v79 offset1:1
	s_waitcnt vmcnt(0)
	v_pk_mul_f32 v[78:79], v[138:139], s[6:7] op_sel_hi:[1,0]
	v_add_u32_e32 v4, 0x3cf0, v1
	ds_write2_b32 v4, v78, v79 offset1:1
	v_pk_mul_f32 v[78:79], v[140:141], s[6:7] op_sel_hi:[1,0]
	v_add_u32_e32 v4, 0x3cf8, v1
	ds_write2_b32 v4, v78, v79 offset1:1
	s_waitcnt lgkmcnt(0)
	ds_read2_b32 v[82:83], v3 offset1:16
	ds_read2_b32 v[84:85], v3 offset0:65 offset1:81
	v_mov_b32_e32 v78, v5
	ds_read2_b32 v[88:89], v3 offset0:130 offset1:146
	ds_read2_b32 v[90:91], v3 offset0:195 offset1:211
	v_add_u32_e32 v118, 0xc00, v3
	s_waitcnt lgkmcnt(3)
	v_med3_f32 v4, v82, s40, v76
	s_waitcnt lgkmcnt(2)
	v_med3_f32 v77, v84, s40, v76
	v_cvt_pk_fp8_f32 v78, v4, v77
	v_add_u32_e32 v4, 0x400, v3
	ds_read2_b32 v[92:93], v4 offset0:4 offset1:20
	ds_read2_b32 v[94:95], v4 offset0:69 offset1:85
	s_waitcnt lgkmcnt(3)
	v_med3_f32 v77, v88, s40, v76
	s_waitcnt lgkmcnt(2)
	v_med3_f32 v79, v90, s40, v76
	v_cvt_pk_fp8_f32 v78, v77, v79 op_sel:[0,0,1]
	s_waitcnt lgkmcnt(1)
	v_med3_f32 v77, v92, s40, v76
	s_waitcnt lgkmcnt(0)
	v_med3_f32 v80, v94, s40, v76
	v_mov_b32_e32 v79, v5
	v_cvt_pk_fp8_f32 v79, v77, v80
	ds_read2_b32 v[96:97], v4 offset0:134 offset1:150
	ds_read2_b32 v[98:99], v4 offset0:199 offset1:215
	v_add_u32_e32 v77, 0x800, v3
	ds_read2_b32 v[100:101], v77 offset0:8 offset1:24
	ds_read2_b32 v[102:103], v77 offset0:73 offset1:89
	ds_read2_b32 v[104:105], v77 offset0:138 offset1:154
	ds_read2_b32 v[106:107], v77 offset0:203 offset1:219
	ds_read2_b32 v[108:109], v118 offset0:12 offset1:28
	ds_read2_b32 v[110:111], v118 offset0:77 offset1:93
	s_waitcnt lgkmcnt(7)
	v_med3_f32 v80, v96, s40, v76
	s_waitcnt lgkmcnt(6)
	v_med3_f32 v81, v98, s40, v76
	v_cvt_pk_fp8_f32 v79, v80, v81 op_sel:[0,0,1]
	s_waitcnt lgkmcnt(5)
	v_med3_f32 v81, v100, s40, v76
	s_waitcnt lgkmcnt(4)
	v_med3_f32 v82, v102, s40, v76
	v_mov_b32_e32 v80, v5
	ds_read2_b32 v[112:113], v118 offset0:142 offset1:158
	ds_read2_b32 v[114:115], v118 offset0:207 offset1:223
	v_cvt_pk_fp8_f32 v80, v81, v82
	s_waitcnt lgkmcnt(3)
	v_med3_f32 v88, v108, s40, v76
	s_waitcnt lgkmcnt(2)
	v_med3_f32 v90, v110, s40, v76
	v_mov_b32_e32 v81, v5
	v_cvt_pk_fp8_f32 v81, v88, v90
	v_med3_f32 v82, v104, s40, v76
	v_med3_f32 v84, v106, s40, v76
	v_cvt_pk_fp8_f32 v80, v82, v84 op_sel:[0,0,1]
	s_waitcnt lgkmcnt(1)
	v_med3_f32 v82, v112, s40, v76
	s_waitcnt lgkmcnt(0)
	v_med3_f32 v84, v114, s40, v76
	v_cvt_pk_fp8_f32 v81, v82, v84 op_sel:[0,0,1]
	v_med3_f32 v83, v83, s40, v76
	v_med3_f32 v84, v85, s40, v76
	v_mov_b32_e32 v82, v5
	v_cvt_pk_fp8_f32 v82, v83, v84
	v_med3_f32 v84, v89, s40, v76
	v_med3_f32 v88, v93, s40, v76
	v_med3_f32 v89, v95, s40, v76
	v_mov_b32_e32 v83, v5
	v_cvt_pk_fp8_f32 v83, v88, v89
	v_med3_f32 v85, v91, s40, v76
	v_cvt_pk_fp8_f32 v82, v84, v85 op_sel:[0,0,1]
	v_med3_f32 v84, v97, s40, v76
	v_med3_f32 v85, v99, s40, v76
	v_cvt_pk_fp8_f32 v83, v84, v85 op_sel:[0,0,1]
	v_med3_f32 v85, v101, s40, v76
	v_med3_f32 v88, v103, s40, v76
	v_mov_b32_e32 v84, v5
	v_cvt_pk_fp8_f32 v84, v85, v88
	v_med3_f32 v90, v109, s40, v76
	v_med3_f32 v91, v111, s40, v76
	v_mov_b32_e32 v85, v5
	v_cvt_pk_fp8_f32 v85, v90, v91
	v_med3_f32 v88, v105, s40, v76
	v_med3_f32 v89, v107, s40, v76
	v_cvt_pk_fp8_f32 v84, v88, v89 op_sel:[0,0,1]
	v_med3_f32 v88, v113, s40, v76
	v_med3_f32 v89, v115, s40, v76
	s_addc_u32 s11, s11, 0
	v_cvt_pk_fp8_f32 v85, v88, v89 op_sel:[0,0,1]
	v_lshl_add_u64 v[86:87], s[10:11], 0, v[6:7]
	ds_read2_b32 v[88:89], v3 offset0:32 offset1:48
	ds_read2_b32 v[90:91], v3 offset0:97 offset1:113
	v_lshl_add_u64 v[116:117], v[86:87], 0, v[16:17]
	global_store_dwordx4 v[116:117], v[78:81], off sc1
	v_readlane_b32 s57, v234, 24
	v_readlane_b32 s58, v234, 25
	v_lshl_add_u64 v[78:79], v[86:87], 0, v[18:19]
	global_store_dwordx4 v[78:79], v[82:85], off sc1
	ds_read2_b32 v[82:83], v3 offset0:162 offset1:178
	ds_read2_b32 v[84:85], v3 offset0:227 offset1:243
	s_waitcnt lgkmcnt(3)
	v_med3_f32 v79, v88, s40, v76
	s_waitcnt lgkmcnt(2)
	v_med3_f32 v80, v90, s40, v76
	v_mov_b32_e32 v78, v5
	ds_read2_b32 v[92:93], v4 offset0:36 offset1:52
	ds_read2_b32 v[94:95], v4 offset0:101 offset1:117
	v_cvt_pk_fp8_f32 v78, v79, v80
	s_waitcnt lgkmcnt(3)
	v_med3_f32 v79, v82, s40, v76
	s_waitcnt lgkmcnt(2)
	v_med3_f32 v80, v84, s40, v76
	ds_read2_b32 v[96:97], v4 offset0:166 offset1:182
	ds_read2_b32 v[98:99], v4 offset0:231 offset1:247
	v_cvt_pk_fp8_f32 v78, v79, v80 op_sel:[0,0,1]
	s_waitcnt lgkmcnt(3)
	v_med3_f32 v80, v92, s40, v76
	s_waitcnt lgkmcnt(2)
	v_med3_f32 v81, v94, s40, v76
	v_mov_b32_e32 v79, v5
	ds_read2_b32 v[100:101], v77 offset0:40 offset1:56
	ds_read2_b32 v[102:103], v77 offset0:105 offset1:121
	v_cvt_pk_fp8_f32 v79, v80, v81
	ds_read2_b32 v[104:105], v77 offset0:170 offset1:186
	ds_read2_b32 v[106:107], v77 offset0:235 offset1:251
	ds_read2_b32 v[108:109], v118 offset0:44 offset1:60
	ds_read2_b32 v[110:111], v118 offset0:109 offset1:125
	s_waitcnt lgkmcnt(7)
	v_med3_f32 v4, v96, s40, v76
	s_waitcnt lgkmcnt(6)
	v_med3_f32 v80, v98, s40, v76
	v_cvt_pk_fp8_f32 v79, v4, v80 op_sel:[0,0,1]
	s_waitcnt lgkmcnt(5)
	v_med3_f32 v4, v100, s40, v76
	s_waitcnt lgkmcnt(4)
	v_med3_f32 v81, v102, s40, v76
	v_mov_b32_e32 v80, v5
	ds_read2_b32 v[112:113], v118 offset0:174 offset1:190
	ds_read2_b32 v[114:115], v118 offset0:239 offset1:255
	v_cvt_pk_fp8_f32 v80, v4, v81
	s_waitcnt lgkmcnt(3)
	v_med3_f32 v82, v108, s40, v76
	s_waitcnt lgkmcnt(2)
	v_med3_f32 v84, v110, s40, v76
	v_mov_b32_e32 v81, v5
	v_cvt_pk_fp8_f32 v81, v82, v84
	v_med3_f32 v4, v104, s40, v76
	v_med3_f32 v77, v106, s40, v76
	v_cvt_pk_fp8_f32 v80, v4, v77 op_sel:[0,0,1]
	s_waitcnt lgkmcnt(1)
	v_med3_f32 v4, v112, s40, v76
	s_waitcnt lgkmcnt(0)
	v_med3_f32 v77, v114, s40, v76
	v_cvt_pk_fp8_f32 v81, v4, v77 op_sel:[0,0,1]
	v_med3_f32 v4, v89, s40, v76
	v_med3_f32 v77, v91, s40, v76
	v_mov_b32_e32 v82, v5
	v_cvt_pk_fp8_f32 v82, v4, v77
	v_med3_f32 v4, v83, s40, v76
	v_med3_f32 v77, v85, s40, v76
	v_med3_f32 v84, v93, s40, v76
	v_med3_f32 v85, v95, s40, v76
	v_mov_b32_e32 v83, v5
	v_cvt_pk_fp8_f32 v83, v84, v85
	v_cvt_pk_fp8_f32 v82, v4, v77 op_sel:[0,0,1]
	v_med3_f32 v4, v97, s40, v76
	v_med3_f32 v77, v99, s40, v76
	v_cvt_pk_fp8_f32 v83, v4, v77 op_sel:[0,0,1]
	v_med3_f32 v4, v101, s40, v76
	v_med3_f32 v77, v103, s40, v76
	v_mov_b32_e32 v84, v5
	v_cvt_pk_fp8_f32 v84, v4, v77
	v_med3_f32 v88, v109, s40, v76
	v_med3_f32 v89, v111, s40, v76
	v_mov_b32_e32 v85, v5
	v_cvt_pk_fp8_f32 v85, v88, v89
	v_med3_f32 v4, v105, s40, v76
	v_med3_f32 v77, v107, s40, v76
	v_cvt_pk_fp8_f32 v84, v4, v77 op_sel:[0,0,1]
	v_med3_f32 v4, v113, s40, v76
	v_med3_f32 v77, v115, s40, v76
	v_cvt_pk_fp8_f32 v85, v4, v77 op_sel:[0,0,1]
	v_lshl_add_u64 v[88:89], v[86:87], 0, v[20:21]
	global_store_dwordx4 v[88:89], v[78:81], off sc1
	v_readlane_b32 s59, v234, 26
	v_readlane_b32 s62, v234, 29
	v_lshl_add_u64 v[78:79], v[86:87], 0, v[22:23]
	global_store_dwordx4 v[78:79], v[82:85], off sc1
	s_waitcnt lgkmcnt(0)
	v_readlane_b32 s63, v234, 30
	v_readlane_b32 s64, v234, 31
	v_readlane_b32 s65, v234, 32
	v_readlane_b32 s66, v234, 33
	v_readlane_b32 s67, v234, 34
	v_readlane_b32 s68, v234, 35
	v_readlane_b32 s69, v234, 36
	v_readlane_b32 s70, v234, 37
	v_readlane_b32 s71, v234, 38

.LBB0_49:
	s_andn2_b64 vcc, exec, s[10:11]
	s_cbranch_vccnz .LBB0_51
	s_and_b32 s0, s9, 0x3fc0
	s_addk_i32 s0, 0xd400
	v_readlane_b32 s56, v234, 7
	s_and_b32 s12, s5, 0x3c0
	s_lshl_b64 s[10:11], s[0:1], 12
	v_readlane_b32 s66, v234, 17
	v_readlane_b32 s67, v234, 18
	s_add_u32 s10, s66, s10
	s_addc_u32 s11, s67, s11
	s_lshl_b32 s13, s12, 2
	s_add_u32 s10, s10, s13
	s_addc_u32 s11, s11, 0
	v_lshl_add_u64 v[78:79], s[10:11], 0, v[66:67]
	v_lshlrev_b32_e32 v4, 2, v2
	v_lshl_add_u64 v[138:139], v[78:79], 0, v[4:5]
	v_add_co_u32_e32 v82, vcc, s21, v138
	v_add_u32_e32 v4, 0x410, v1
	s_nop 0
	v_addc_co_u32_e32 v83, vcc, 0, v139, vcc
	v_add_co_u32_e32 v86, vcc, s24, v138
	global_load_dwordx4 v[78:81], v[138:139], off nt
	s_nop 0
	global_load_dwordx4 v[82:85], v[82:83], off nt
	v_addc_co_u32_e32 v87, vcc, 0, v139, vcc
	v_add_co_u32_e32 v90, vcc, s25, v138
	s_lshl_b32 s10, s12, 11
	s_nop 0
	v_addc_co_u32_e32 v91, vcc, 0, v139, vcc
	global_load_dwordx4 v[86:89], v[86:87], off nt
	s_nop 0
	global_load_dwordx4 v[90:93], v[90:91], off nt
	v_add_co_u32_e32 v94, vcc, s26, v138
	v_readlane_b32 s11, v234, 47
	s_nop 0
	v_addc_co_u32_e32 v95, vcc, 0, v139, vcc
	v_add_co_u32_e32 v98, vcc, s27, v138
	v_add_u32_e32 v77, 0x400, v33
	s_nop 0
	v_addc_co_u32_e32 v99, vcc, 0, v139, vcc
	global_load_dwordx4 v[94:97], v[94:95], off nt
	s_nop 0
	global_load_dwordx4 v[98:101], v[98:99], off nt
	v_add_co_u32_e32 v102, vcc, s28, v138
	s_add_u32 s12, s11, s10
	s_nop 0
	v_addc_co_u32_e32 v103, vcc, 0, v139, vcc
	v_add_co_u32_e32 v106, vcc, s29, v138
	v_readlane_b32 s10, v234, 48
	s_nop 0
	v_addc_co_u32_e32 v107, vcc, 0, v139, vcc
	global_load_dwordx4 v[102:105], v[102:103], off nt
	s_nop 0
	global_load_dwordx4 v[106:109], v[106:107], off nt
	v_add_co_u32_e32 v110, vcc, s30, v138
	s_addc_u32 s13, s10, 0
	s_nop 0
	v_addc_co_u32_e32 v111, vcc, 0, v139, vcc
	v_add_co_u32_e32 v114, vcc, s31, v138
	s_lshl_b64 s[10:11], s[0:1], 1
	s_nop 0
	v_addc_co_u32_e32 v115, vcc, 0, v139, vcc
	global_load_dwordx4 v[110:113], v[110:111], off nt
	s_nop 0
	global_load_dwordx4 v[114:117], v[114:115], off nt
	v_add_co_u32_e32 v118, vcc, s34, v138
	s_add_u32 s10, s12, s10
	s_nop 0
	v_addc_co_u32_e32 v119, vcc, 0, v139, vcc
	v_add_co_u32_e32 v122, vcc, s35, v138
	s_addc_u32 s11, s13, s11
	s_nop 0
	v_addc_co_u32_e32 v123, vcc, 0, v139, vcc
	global_load_dwordx4 v[118:121], v[118:119], off nt
	s_nop 0
	global_load_dwordx4 v[122:125], v[122:123], off nt
	v_add_co_u32_e32 v126, vcc, s36, v138
	v_readlane_b32 s57, v234, 8
	s_nop 0
	v_addc_co_u32_e32 v127, vcc, 0, v139, vcc
	global_load_dwordx4 v[126:129], v[126:127], off nt
	v_add_co_u32_e32 v130, vcc, s37, v138
	v_readlane_b32 s58, v234, 9
	s_nop 0
	v_addc_co_u32_e32 v131, vcc, 0, v139, vcc
	global_load_dwordx4 v[130:133], v[130:131], off nt
	v_add_co_u32_e32 v134, vcc, s38, v138
	v_readlane_b32 s59, v234, 10
	s_nop 0
	v_addc_co_u32_e32 v135, vcc, 0, v139, vcc
	global_load_dwordx4 v[134:137], v[134:135], off nt
	v_add_co_u32_e32 v138, vcc, s39, v138
	v_readlane_b32 s60, v234, 11
	s_nop 0
	v_addc_co_u32_e32 v139, vcc, 0, v139, vcc
	global_load_dwordx4 v[138:141], v[138:139], off nt
	s_waitcnt vmcnt(15)
	ds_write2_b32 v1, v78, v79 offset1:1
	ds_write2_b32 v1, v80, v81 offset0:2 offset1:3
	s_waitcnt vmcnt(14)
	ds_write2_b32 v4, v82, v83 offset1:1
	v_add_u32_e32 v4, 0x418, v1
	ds_write2_b32 v4, v84, v85 offset1:1
	v_add_u32_e32 v4, 0x820, v1
	v_readlane_b32 s61, v234, 12
	v_readlane_b32 s62, v234, 13
	v_readlane_b32 s63, v234, 14
	s_waitcnt vmcnt(13)
	ds_write2_b32 v4, v86, v87 offset1:1
	v_add_u32_e32 v4, 0x828, v1
	ds_write2_b32 v4, v88, v89 offset1:1
	v_add_u32_e32 v4, 0xc30, v1
	s_waitcnt vmcnt(12)
	ds_write2_b32 v4, v90, v91 offset1:1
	v_add_u32_e32 v4, 0xc38, v1
	ds_write2_b32 v4, v92, v93 offset1:1
	v_add_u32_e32 v4, 0x1040, v1
	v_readlane_b32 s64, v234, 15
	v_readlane_b32 s65, v234, 16
	v_readlane_b32 s68, v234, 19
	s_waitcnt vmcnt(11)
	ds_write2_b32 v4, v94, v95 offset1:1
	v_add_u32_e32 v4, 0x1048, v1
	ds_write2_b32 v4, v96, v97 offset1:1
	v_add_u32_e32 v4, 0x1450, v1
	s_waitcnt vmcnt(10)
	ds_write2_b32 v4, v98, v99 offset1:1
	v_add_u32_e32 v4, 0x1458, v1
	ds_write2_b32 v4, v100, v101 offset1:1
	v_add_u32_e32 v4, 0x1860, v1
	v_readlane_b32 s69, v234, 20
	v_readlane_b32 s70, v234, 21
	v_readlane_b32 s71, v234, 22
	s_waitcnt vmcnt(9)
	ds_write2_b32 v4, v102, v103 offset1:1
	v_add_u32_e32 v4, 0x1868, v1
	ds_write2_b32 v4, v104, v105 offset1:1
	v_add_u32_e32 v4, 0x1c70, v1
	s_waitcnt vmcnt(8)
	ds_write2_b32 v4, v106, v107 offset1:1
	v_add_u32_e32 v4, 0x1c78, v1
	ds_write2_b32 v4, v108, v109 offset1:1
	v_add_u32_e32 v4, 0x2080, v1
	s_waitcnt vmcnt(7)
	ds_write2_b32 v4, v110, v111 offset1:1
	v_add_u32_e32 v4, 0x2088, v1
	ds_write2_b32 v4, v112, v113 offset1:1
	v_add_u32_e32 v4, 0x2490, v1
	s_waitcnt vmcnt(6)
	ds_write2_b32 v4, v114, v115 offset1:1
	v_add_u32_e32 v4, 0x2498, v1
	ds_write2_b32 v4, v116, v117 offset1:1
	v_add_u32_e32 v4, 0x28a0, v1
	s_waitcnt vmcnt(5)
	ds_write2_b32 v4, v118, v119 offset1:1
	v_add_u32_e32 v4, 0x28a8, v1
	ds_write2_b32 v4, v120, v121 offset1:1
	v_add_u32_e32 v4, 0x2cb0, v1
	s_waitcnt vmcnt(4)
	ds_write2_b32 v4, v122, v123 offset1:1
	v_add_u32_e32 v4, 0x2cb8, v1
	ds_write2_b32 v4, v124, v125 offset1:1
	v_add_u32_e32 v4, 0x30c0, v1
	s_waitcnt vmcnt(3)
	ds_write2_b32 v4, v126, v127 offset1:1
	v_add_u32_e32 v4, 0x30c8, v1
	ds_write2_b32 v4, v128, v129 offset1:1
	v_add_u32_e32 v4, 0x34d0, v1
	s_waitcnt vmcnt(2)
	ds_write2_b32 v4, v130, v131 offset1:1
	v_add_u32_e32 v4, 0x34d8, v1
	ds_write2_b32 v4, v132, v133 offset1:1
	v_add_u32_e32 v4, 0x38e0, v1
	s_waitcnt vmcnt(1)
	ds_write2_b32 v4, v134, v135 offset1:1
	v_add_u32_e32 v4, 0x38e8, v1
	ds_write2_b32 v4, v136, v137 offset1:1
	v_add_u32_e32 v4, 0x3cf0, v1
	s_waitcnt vmcnt(0)
	ds_write2_b32 v4, v138, v139 offset1:1
	v_add_u32_e32 v4, 0x3cf8, v1
	ds_write2_b32 v4, v140, v141 offset1:1
	s_waitcnt lgkmcnt(0)
	ds_read2_b32 v[82:83], v33 offset0:65 offset1:73
	ds_read2_b32 v[84:85], v33 offset1:8
	ds_read2_b32 v[86:87], v33 offset0:130 offset1:138
	ds_read2_b32 v[88:89], v33 offset0:195 offset1:203
	ds_read2_b32 v[90:91], v77 offset0:4 offset1:12
	ds_read2_b32 v[92:93], v77 offset0:69 offset1:77
	ds_read2_b32 v[94:95], v77 offset0:134 offset1:142
	ds_read2_b32 v[96:97], v77 offset0:199 offset1:207
	v_lshlrev_b32_e32 v4, 1, v32
	v_lshl_add_u64 v[98:99], s[10:11], 0, v[4:5]
	s_waitcnt lgkmcnt(6)
	v_cvt_pk_bf16_f32 v78, v84, v82
	s_waitcnt lgkmcnt(4)
	v_cvt_pk_bf16_f32 v79, v86, v88
	s_waitcnt lgkmcnt(2)
	v_cvt_pk_bf16_f32 v80, v90, v92
	s_waitcnt lgkmcnt(0)
	v_cvt_pk_bf16_f32 v81, v94, v96
	v_lshl_add_u64 v[100:101], v[98:99], 0, v[34:35]
	global_store_dwordx4 v[100:101], v[78:81], off sc1
	s_nop 1
	v_cvt_pk_bf16_f32 v78, v85, v83
	v_cvt_pk_bf16_f32 v79, v87, v89
	v_cvt_pk_bf16_f32 v80, v91, v93
	v_cvt_pk_bf16_f32 v81, v95, v97
	ds_read2_b32 v[84:85], v33 offset0:81 offset1:89
	ds_read2_b32 v[86:87], v33 offset0:16 offset1:24
	ds_read2_b32 v[88:89], v33 offset0:146 offset1:154
	ds_read2_b32 v[90:91], v33 offset0:211 offset1:219
	ds_read2_b32 v[92:93], v77 offset0:20 offset1:28
	ds_read2_b32 v[94:95], v77 offset0:85 offset1:93
	ds_read2_b32 v[96:97], v77 offset0:150 offset1:158
	ds_read2_b32 v[100:101], v77 offset0:215 offset1:223
	v_lshl_add_u64 v[82:83], v[98:99], 0, v[36:37]
	global_store_dwordx4 v[82:83], v[78:81], off sc1
	v_lshl_add_u64 v[82:83], v[98:99], 0, v[38:39]
	s_waitcnt lgkmcnt(6)
	v_cvt_pk_bf16_f32 v78, v86, v84
	s_waitcnt lgkmcnt(4)
	v_cvt_pk_bf16_f32 v79, v88, v90
	s_waitcnt lgkmcnt(2)
	v_cvt_pk_bf16_f32 v80, v92, v94
	s_waitcnt lgkmcnt(0)
	v_cvt_pk_bf16_f32 v81, v96, v100
	global_store_dwordx4 v[82:83], v[78:81], off sc1
	v_lshl_add_u64 v[82:83], v[98:99], 0, v[46:47]
	s_nop 0
	v_cvt_pk_bf16_f32 v78, v87, v85
	v_cvt_pk_bf16_f32 v79, v89, v91
	v_cvt_pk_bf16_f32 v80, v93, v95
	v_cvt_pk_bf16_f32 v81, v97, v101
	ds_read2_b32 v[84:85], v33 offset0:32 offset1:40
	ds_read2_b32 v[86:87], v33 offset0:97 offset1:105
	ds_read2_b32 v[88:89], v33 offset0:162 offset1:170
	ds_read2_b32 v[90:91], v33 offset0:227 offset1:235
	ds_read2_b32 v[92:93], v77 offset0:36 offset1:44
	ds_read2_b32 v[94:95], v77 offset0:101 offset1:109
	ds_read2_b32 v[96:97], v77 offset0:166 offset1:174
	ds_read2_b32 v[100:101], v77 offset0:231 offset1:239
	global_store_dwordx4 v[82:83], v[78:81], off sc1
	v_lshl_add_u64 v[82:83], v[98:99], 0, v[50:51]
	s_waitcnt lgkmcnt(6)
	v_cvt_pk_bf16_f32 v78, v84, v86
	s_waitcnt lgkmcnt(4)
	v_cvt_pk_bf16_f32 v79, v88, v90
	s_waitcnt lgkmcnt(2)
	v_cvt_pk_bf16_f32 v80, v92, v94
	s_waitcnt lgkmcnt(0)
	v_cvt_pk_bf16_f32 v81, v96, v100
	global_store_dwordx4 v[82:83], v[78:81], off sc1
	v_lshl_add_u64 v[82:83], v[98:99], 0, v[54:55]
	s_nop 0
	v_cvt_pk_bf16_f32 v78, v85, v87
	v_cvt_pk_bf16_f32 v79, v89, v91
	v_cvt_pk_bf16_f32 v80, v93, v95
	v_cvt_pk_bf16_f32 v81, v97, v101
	ds_read2_b32 v[84:85], v33 offset0:48 offset1:56
	ds_read2_b32 v[86:87], v33 offset0:113 offset1:121
	ds_read2_b32 v[88:89], v33 offset0:178 offset1:186
	ds_read2_b32 v[90:91], v33 offset0:243 offset1:251
	ds_read2_b32 v[92:93], v77 offset0:52 offset1:60
	ds_read2_b32 v[94:95], v77 offset0:117 offset1:125
	ds_read2_b32 v[96:97], v77 offset0:182 offset1:190
	ds_read2_b32 v[100:101], v77 offset0:247 offset1:255
	global_store_dwordx4 v[82:83], v[78:81], off sc1
	v_lshl_add_u64 v[82:83], v[98:99], 0, v[58:59]
	s_waitcnt lgkmcnt(6)
	v_cvt_pk_bf16_f32 v78, v84, v86
	s_waitcnt lgkmcnt(4)
	v_cvt_pk_bf16_f32 v79, v88, v90
	s_waitcnt lgkmcnt(2)
	v_cvt_pk_bf16_f32 v80, v92, v94
	s_waitcnt lgkmcnt(0)
	v_cvt_pk_bf16_f32 v81, v96, v100
	global_store_dwordx4 v[82:83], v[78:81], off sc1
	v_lshl_add_u64 v[82:83], v[98:99], 0, v[62:63]
	s_nop 0
	v_cvt_pk_bf16_f32 v78, v85, v87
	v_cvt_pk_bf16_f32 v79, v89, v91
	v_cvt_pk_bf16_f32 v80, v93, v95
	v_cvt_pk_bf16_f32 v81, v97, v101
	global_store_dwordx4 v[82:83], v[78:81], off sc1
	s_waitcnt lgkmcnt(0)

.LBB0_52:
	s_andn2_b64 vcc, exec, s[10:11]
	s_cbranch_vccnz .LBB0_54
	s_and_b32 s0, s9, 0x3fc0
	s_addk_i32 s0, 0xd800
	v_readlane_b32 s56, v234, 7
	s_and_b32 s12, s5, 0x3c0
	s_lshl_b64 s[10:11], s[0:1], 12
	v_readlane_b32 s64, v234, 15
	v_readlane_b32 s65, v234, 16
	s_add_u32 s10, s64, s10
	s_addc_u32 s11, s65, s11
	s_lshl_b32 s13, s12, 2
	s_add_u32 s10, s10, s13
	s_addc_u32 s11, s11, 0
	v_lshl_add_u64 v[78:79], s[10:11], 0, v[66:67]
	v_lshlrev_b32_e32 v4, 2, v2
	v_lshl_add_u64 v[134:135], v[78:79], 0, v[4:5]
	v_add_co_u32_e32 v82, vcc, s21, v134
	global_load_dwordx4 v[78:81], v[134:135], off nt
	s_nop 0
	v_addc_co_u32_e32 v83, vcc, 0, v135, vcc
	v_add_co_u32_e32 v86, vcc, s24, v134
	global_load_dwordx4 v[82:85], v[82:83], off nt
	s_nop 0
	v_addc_co_u32_e32 v87, vcc, 0, v135, vcc
	v_add_co_u32_e32 v90, vcc, s25, v134
	global_load_dwordx4 v[86:89], v[86:87], off nt
	s_nop 0
	v_addc_co_u32_e32 v91, vcc, 0, v135, vcc
	v_add_co_u32_e32 v94, vcc, s26, v134
	global_load_dwordx4 v[90:93], v[90:91], off nt
	s_nop 0
	v_addc_co_u32_e32 v95, vcc, 0, v135, vcc
	v_add_co_u32_e32 v98, vcc, s27, v134
	global_load_dwordx4 v[94:97], v[94:95], off nt
	s_nop 0
	v_addc_co_u32_e32 v99, vcc, 0, v135, vcc
	v_add_co_u32_e32 v102, vcc, s28, v134
	global_load_dwordx4 v[98:101], v[98:99], off nt
	s_nop 0
	v_addc_co_u32_e32 v103, vcc, 0, v135, vcc
	v_add_co_u32_e32 v106, vcc, s29, v134
	global_load_dwordx4 v[102:105], v[102:103], off nt
	s_nop 0
	v_addc_co_u32_e32 v107, vcc, 0, v135, vcc
	v_add_co_u32_e32 v110, vcc, s30, v134
	global_load_dwordx4 v[106:109], v[106:107], off nt
	s_nop 0
	v_addc_co_u32_e32 v111, vcc, 0, v135, vcc
	v_add_co_u32_e32 v114, vcc, s31, v134
	global_load_dwordx4 v[110:113], v[110:111], off nt
	s_nop 0
	v_addc_co_u32_e32 v115, vcc, 0, v135, vcc
	v_add_co_u32_e32 v118, vcc, s34, v134
	global_load_dwordx4 v[114:117], v[114:115], off nt
	s_nop 0
	v_addc_co_u32_e32 v119, vcc, 0, v135, vcc
	v_add_co_u32_e32 v122, vcc, s35, v134
	v_add_u32_e32 v4, 0x410, v1
	s_nop 0
	v_addc_co_u32_e32 v123, vcc, 0, v135, vcc
	global_load_dwordx4 v[118:121], v[118:119], off nt
	s_nop 0
	global_load_dwordx4 v[122:125], v[122:123], off nt
	v_add_co_u32_e32 v126, vcc, s36, v134
	s_lshl_b32 s12, s12, 11
	s_nop 0
	v_addc_co_u32_e32 v127, vcc, 0, v135, vcc
	v_add_co_u32_e32 v130, vcc, s37, v134
	s_add_u32 s12, s84, s12
	s_nop 0
	v_addc_co_u32_e32 v131, vcc, 0, v135, vcc
	global_load_dwordx4 v[126:129], v[126:127], off nt
	s_nop 0
	global_load_dwordx4 v[130:133], v[130:131], off nt
	v_add_co_u32_e32 v136, vcc, s38, v134
	s_addc_u32 s13, s85, 0
	s_nop 0
	v_addc_co_u32_e32 v137, vcc, 0, v135, vcc
	v_add_co_u32_e32 v138, vcc, s39, v134
	s_lshl_b64 s[10:11], s[0:1], 1
	s_nop 0
	v_addc_co_u32_e32 v139, vcc, 0, v135, vcc
	global_load_dwordx4 v[134:137], v[136:137], off nt
	s_nop 0
	global_load_dwordx4 v[138:141], v[138:139], off nt
	s_add_u32 s10, s12, s10
	s_addc_u32 s11, s13, s11
	v_readlane_b32 s57, v234, 8
	v_readlane_b32 s58, v234, 9
	s_waitcnt vmcnt(15)
	v_pk_mul_f32 v[78:79], v[78:79], s[8:9] op_sel_hi:[1,0]
	ds_write2_b32 v1, v78, v79 offset1:1
	v_pk_mul_f32 v[78:79], v[80:81], s[8:9] op_sel_hi:[1,0]
	ds_write2_b32 v1, v78, v79 offset0:2 offset1:3
	v_readlane_b32 s59, v234, 10
	s_waitcnt vmcnt(14)
	v_pk_mul_f32 v[78:79], v[82:83], s[8:9] op_sel_hi:[1,0]
	ds_write2_b32 v4, v78, v79 offset1:1
	v_pk_mul_f32 v[78:79], v[84:85], s[8:9] op_sel_hi:[1,0]
	v_add_u32_e32 v4, 0x418, v1
	ds_write2_b32 v4, v78, v79 offset1:1
	s_waitcnt vmcnt(13)
	v_pk_mul_f32 v[78:79], v[86:87], s[8:9] op_sel_hi:[1,0]
	v_add_u32_e32 v4, 0x820, v1
	ds_write2_b32 v4, v78, v79 offset1:1
	v_pk_mul_f32 v[78:79], v[88:89], s[8:9] op_sel_hi:[1,0]
	v_add_u32_e32 v4, 0x828, v1
	ds_write2_b32 v4, v78, v79 offset1:1
	s_waitcnt vmcnt(12)
	v_pk_mul_f32 v[78:79], v[90:91], s[8:9] op_sel_hi:[1,0]
	v_add_u32_e32 v4, 0xc30, v1
	ds_write2_b32 v4, v78, v79 offset1:1
	v_pk_mul_f32 v[78:79], v[92:93], s[8:9] op_sel_hi:[1,0]
	v_add_u32_e32 v4, 0xc38, v1
	ds_write2_b32 v4, v78, v79 offset1:1
	s_waitcnt vmcnt(11)
	v_pk_mul_f32 v[78:79], v[94:95], s[8:9] op_sel_hi:[1,0]
	v_add_u32_e32 v4, 0x1040, v1
	ds_write2_b32 v4, v78, v79 offset1:1
	v_pk_mul_f32 v[78:79], v[96:97], s[8:9] op_sel_hi:[1,0]
	v_add_u32_e32 v4, 0x1048, v1
	ds_write2_b32 v4, v78, v79 offset1:1
	s_waitcnt vmcnt(10)
	v_pk_mul_f32 v[78:79], v[98:99], s[8:9] op_sel_hi:[1,0]
	v_add_u32_e32 v4, 0x1450, v1
	ds_write2_b32 v4, v78, v79 offset1:1
	v_pk_mul_f32 v[78:79], v[100:101], s[8:9] op_sel_hi:[1,0]
	v_add_u32_e32 v4, 0x1458, v1
	ds_write2_b32 v4, v78, v79 offset1:1
	s_waitcnt vmcnt(9)
	v_pk_mul_f32 v[78:79], v[102:103], s[8:9] op_sel_hi:[1,0]
	v_add_u32_e32 v4, 0x1860, v1
	ds_write2_b32 v4, v78, v79 offset1:1
	v_pk_mul_f32 v[78:79], v[104:105], s[8:9] op_sel_hi:[1,0]
	v_add_u32_e32 v4, 0x1868, v1
	ds_write2_b32 v4, v78, v79 offset1:1
	s_waitcnt vmcnt(8)
	v_pk_mul_f32 v[78:79], v[106:107], s[8:9] op_sel_hi:[1,0]
	v_add_u32_e32 v4, 0x1c70, v1
	ds_write2_b32 v4, v78, v79 offset1:1
	v_pk_mul_f32 v[78:79], v[108:109], s[8:9] op_sel_hi:[1,0]
	v_add_u32_e32 v4, 0x1c78, v1
	ds_write2_b32 v4, v78, v79 offset1:1
	s_waitcnt vmcnt(7)
	v_pk_mul_f32 v[78:79], v[110:111], s[8:9] op_sel_hi:[1,0]
	v_add_u32_e32 v4, 0x2080, v1
	ds_write2_b32 v4, v78, v79 offset1:1
	v_pk_mul_f32 v[78:79], v[112:113], s[8:9] op_sel_hi:[1,0]
	v_add_u32_e32 v4, 0x2088, v1
	ds_write2_b32 v4, v78, v79 offset1:1
	s_waitcnt vmcnt(6)
	v_pk_mul_f32 v[78:79], v[114:115], s[8:9] op_sel_hi:[1,0]
	v_add_u32_e32 v4, 0x2490, v1
	ds_write2_b32 v4, v78, v79 offset1:1
	v_pk_mul_f32 v[78:79], v[116:117], s[8:9] op_sel_hi:[1,0]
	v_add_u32_e32 v4, 0x2498, v1
	ds_write2_b32 v4, v78, v79 offset1:1
	s_waitcnt vmcnt(5)
	v_pk_mul_f32 v[78:79], v[118:119], s[8:9] op_sel_hi:[1,0]
	v_add_u32_e32 v4, 0x28a0, v1
	ds_write2_b32 v4, v78, v79 offset1:1
	v_pk_mul_f32 v[78:79], v[120:121], s[8:9] op_sel_hi:[1,0]
	v_add_u32_e32 v4, 0x28a8, v1
	ds_write2_b32 v4, v78, v79 offset1:1
	s_waitcnt vmcnt(4)
	v_pk_mul_f32 v[78:79], v[122:123], s[8:9] op_sel_hi:[1,0]
	v_add_u32_e32 v4, 0x2cb0, v1
	ds_write2_b32 v4, v78, v79 offset1:1
	v_pk_mul_f32 v[78:79], v[124:125], s[8:9] op_sel_hi:[1,0]
	v_add_u32_e32 v4, 0x2cb8, v1
	ds_write2_b32 v4, v78, v79 offset1:1
	s_waitcnt vmcnt(3)
	v_pk_mul_f32 v[78:79], v[126:127], s[8:9] op_sel_hi:[1,0]
	v_add_u32_e32 v4, 0x30c0, v1
	ds_write2_b32 v4, v78, v79 offset1:1
	v_pk_mul_f32 v[78:79], v[128:129], s[8:9] op_sel_hi:[1,0]
	v_add_u32_e32 v4, 0x30c8, v1
	ds_write2_b32 v4, v78, v79 offset1:1
	s_waitcnt vmcnt(2)
	v_pk_mul_f32 v[78:79], v[130:131], s[8:9] op_sel_hi:[1,0]
	v_add_u32_e32 v4, 0x34d0, v1
	ds_write2_b32 v4, v78, v79 offset1:1
	v_pk_mul_f32 v[78:79], v[132:133], s[8:9] op_sel_hi:[1,0]
	v_add_u32_e32 v4, 0x34d8, v1
	ds_write2_b32 v4, v78, v79 offset1:1
	s_waitcnt vmcnt(1)
	v_pk_mul_f32 v[78:79], v[134:135], s[8:9] op_sel_hi:[1,0]
	v_add_u32_e32 v4, 0x38e0, v1
	ds_write2_b32 v4, v78, v79 offset1:1
	v_pk_mul_f32 v[78:79], v[136:137], s[8:9] op_sel_hi:[1,0]
	v_add_u32_e32 v4, 0x38e8, v1
	ds_write2_b32 v4, v78, v79 offset1:1
	s_waitcnt vmcnt(0)
	v_pk_mul_f32 v[78:79], v[138:139], s[8:9] op_sel_hi:[1,0]
	v_add_u32_e32 v4, 0x3cf0, v1
	ds_write2_b32 v4, v78, v79 offset1:1
	v_pk_mul_f32 v[78:79], v[140:141], s[8:9] op_sel_hi:[1,0]
	v_add_u32_e32 v4, 0x3cf8, v1
	ds_write2_b32 v4, v78, v79 offset1:1
	v_lshlrev_b32_e32 v4, 1, v32
	s_waitcnt lgkmcnt(0)
	v_lshl_add_u64 v[78:79], s[10:11], 0, v[4:5]
	v_add_u32_e32 v4, 0x400, v33
	ds_read2_b32 v[82:83], v33 offset0:65 offset1:73
	ds_read2_b32 v[84:85], v33 offset1:8
	ds_read2_b32 v[86:87], v33 offset0:130 offset1:138
	ds_read2_b32 v[88:89], v33 offset0:195 offset1:203
	ds_read2_b32 v[90:91], v4 offset0:4 offset1:12
	ds_read2_b32 v[92:93], v4 offset0:69 offset1:77
	ds_read2_b32 v[94:95], v4 offset0:134 offset1:142
	ds_read2_b32 v[96:97], v4 offset0:199 offset1:207
	s_mov_b64 s[10:11], 0x2400000
	v_lshl_add_u64 v[98:99], v[78:79], 0, s[10:11]
	s_waitcnt lgkmcnt(6)
	v_cvt_pk_bf16_f32 v78, v84, v82
	s_waitcnt lgkmcnt(4)
	v_cvt_pk_bf16_f32 v79, v86, v88
	s_waitcnt lgkmcnt(2)
	v_cvt_pk_bf16_f32 v80, v90, v92
	s_waitcnt lgkmcnt(0)
	v_cvt_pk_bf16_f32 v81, v94, v96
	v_lshl_add_u64 v[100:101], v[98:99], 0, v[34:35]
	global_store_dwordx4 v[100:101], v[78:81], off sc1
	v_readlane_b32 s60, v234, 11
	v_readlane_b32 s61, v234, 12
	v_cvt_pk_bf16_f32 v78, v85, v83
	v_cvt_pk_bf16_f32 v79, v87, v89
	v_cvt_pk_bf16_f32 v80, v91, v93
	v_cvt_pk_bf16_f32 v81, v95, v97
	ds_read2_b32 v[84:85], v33 offset0:81 offset1:89
	ds_read2_b32 v[86:87], v33 offset0:16 offset1:24
	ds_read2_b32 v[88:89], v33 offset0:146 offset1:154
	ds_read2_b32 v[90:91], v33 offset0:211 offset1:219
	ds_read2_b32 v[92:93], v4 offset0:20 offset1:28
	ds_read2_b32 v[94:95], v4 offset0:85 offset1:93
	ds_read2_b32 v[96:97], v4 offset0:150 offset1:158
	ds_read2_b32 v[100:101], v4 offset0:215 offset1:223
	v_lshl_add_u64 v[82:83], v[98:99], 0, v[36:37]
	global_store_dwordx4 v[82:83], v[78:81], off sc1
	v_lshl_add_u64 v[82:83], v[98:99], 0, v[38:39]
	v_readlane_b32 s62, v234, 13
	s_waitcnt lgkmcnt(6)
	v_cvt_pk_bf16_f32 v78, v86, v84
	s_waitcnt lgkmcnt(4)
	v_cvt_pk_bf16_f32 v79, v88, v90
	s_waitcnt lgkmcnt(2)
	v_cvt_pk_bf16_f32 v80, v92, v94
	s_waitcnt lgkmcnt(0)
	v_cvt_pk_bf16_f32 v81, v96, v100
	global_store_dwordx4 v[82:83], v[78:81], off sc1
	v_lshl_add_u64 v[82:83], v[98:99], 0, v[46:47]
	v_readlane_b32 s63, v234, 14
	v_cvt_pk_bf16_f32 v78, v87, v85
	v_cvt_pk_bf16_f32 v79, v89, v91
	v_cvt_pk_bf16_f32 v80, v93, v95
	v_cvt_pk_bf16_f32 v81, v97, v101
	ds_read2_b32 v[84:85], v33 offset0:32 offset1:40
	ds_read2_b32 v[86:87], v33 offset0:97 offset1:105
	ds_read2_b32 v[88:89], v33 offset0:162 offset1:170
	ds_read2_b32 v[90:91], v33 offset0:227 offset1:235
	ds_read2_b32 v[92:93], v4 offset0:36 offset1:44
	ds_read2_b32 v[94:95], v4 offset0:101 offset1:109
	ds_read2_b32 v[96:97], v4 offset0:166 offset1:174
	ds_read2_b32 v[100:101], v4 offset0:231 offset1:239
	global_store_dwordx4 v[82:83], v[78:81], off sc1
	v_lshl_add_u64 v[82:83], v[98:99], 0, v[50:51]
	v_readlane_b32 s66, v234, 17
	s_waitcnt lgkmcnt(6)
	v_cvt_pk_bf16_f32 v78, v84, v86
	s_waitcnt lgkmcnt(4)
	v_cvt_pk_bf16_f32 v79, v88, v90
	s_waitcnt lgkmcnt(2)
	v_cvt_pk_bf16_f32 v80, v92, v94
	s_waitcnt lgkmcnt(0)
	v_cvt_pk_bf16_f32 v81, v96, v100
	global_store_dwordx4 v[82:83], v[78:81], off sc1
	v_lshl_add_u64 v[82:83], v[98:99], 0, v[54:55]
	v_readlane_b32 s67, v234, 18
	v_cvt_pk_bf16_f32 v78, v85, v87
	v_cvt_pk_bf16_f32 v79, v89, v91
	v_cvt_pk_bf16_f32 v80, v93, v95
	v_cvt_pk_bf16_f32 v81, v97, v101
	ds_read2_b32 v[84:85], v33 offset0:48 offset1:56
	ds_read2_b32 v[86:87], v33 offset0:113 offset1:121
	ds_read2_b32 v[88:89], v33 offset0:178 offset1:186
	ds_read2_b32 v[90:91], v33 offset0:243 offset1:251
	ds_read2_b32 v[92:93], v4 offset0:52 offset1:60
	ds_read2_b32 v[94:95], v4 offset0:117 offset1:125
	ds_read2_b32 v[96:97], v4 offset0:182 offset1:190
	ds_read2_b32 v[100:101], v4 offset0:247 offset1:255
	global_store_dwordx4 v[82:83], v[78:81], off sc1
	v_lshl_add_u64 v[82:83], v[98:99], 0, v[58:59]
	v_readlane_b32 s68, v234, 19
	s_waitcnt lgkmcnt(6)
	v_cvt_pk_bf16_f32 v78, v84, v86
	s_waitcnt lgkmcnt(4)
	v_cvt_pk_bf16_f32 v79, v88, v90
	s_waitcnt lgkmcnt(2)
	v_cvt_pk_bf16_f32 v80, v92, v94
	s_waitcnt lgkmcnt(0)
	v_cvt_pk_bf16_f32 v81, v96, v100
	global_store_dwordx4 v[82:83], v[78:81], off sc1
	v_lshl_add_u64 v[82:83], v[98:99], 0, v[62:63]
	v_readlane_b32 s69, v234, 20
	v_cvt_pk_bf16_f32 v78, v85, v87
	v_cvt_pk_bf16_f32 v79, v89, v91
	v_cvt_pk_bf16_f32 v80, v93, v95
	v_cvt_pk_bf16_f32 v81, v97, v101
	global_store_dwordx4 v[82:83], v[78:81], off sc1
	s_waitcnt lgkmcnt(0)
	v_readlane_b32 s70, v234, 21
	v_readlane_b32 s71, v234, 22

.LBB0_60:
	s_and_b32 s0, s19, 0x1fc0
	s_addk_i32 s0, 0xf000
	s_lshl_b64 s[12:13], s[0:1], 1
	s_add_u32 s10, s10, s12
	v_readlane_b32 s56, v234, 7
	s_addc_u32 s11, s11, s13
	s_lshl_b64 s[12:13], s[0:1], 13
	v_readlane_b32 s62, v234, 13
	v_readlane_b32 s63, v234, 14
	s_add_u32 s0, s62, s12
	s_addc_u32 s13, s63, s13
	s_lshl_b32 s12, s14, 2
	s_add_u32 s12, s0, s12
	s_addc_u32 s13, s13, 0
	v_lshl_add_u64 v[78:79], s[12:13], 0, v[72:73]
	v_lshlrev_b32_e32 v4, 2, v2
	v_lshl_add_u64 v[138:139], v[78:79], 0, v[4:5]
	v_add_co_u32_e32 v82, vcc, s24, v138
	s_mov_b32 s0, 0x40000
	s_nop 0
	v_addc_co_u32_e32 v83, vcc, 0, v139, vcc
	v_add_co_u32_e32 v86, vcc, s26, v138
	global_load_dwordx4 v[78:81], v[138:139], off nt
	s_nop 0
	global_load_dwordx4 v[82:85], v[82:83], off nt
	v_addc_co_u32_e32 v87, vcc, 0, v139, vcc
	v_add_co_u32_e32 v90, vcc, s28, v138
	v_add_u32_e32 v4, 0x410, v1
	s_nop 0
	v_addc_co_u32_e32 v91, vcc, 0, v139, vcc
	global_load_dwordx4 v[86:89], v[86:87], off nt
	s_nop 0
	global_load_dwordx4 v[90:93], v[90:91], off nt
	v_add_co_u32_e32 v94, vcc, s30, v138
	v_add_u32_e32 v77, 0x400, v33
	s_nop 0
	v_addc_co_u32_e32 v95, vcc, 0, v139, vcc
	v_add_co_u32_e32 v98, vcc, s34, v138
	v_readlane_b32 s57, v234, 8
	s_nop 0
	v_addc_co_u32_e32 v99, vcc, 0, v139, vcc
	global_load_dwordx4 v[94:97], v[94:95], off nt
	s_nop 0
	global_load_dwordx4 v[98:101], v[98:99], off nt
	v_add_co_u32_e32 v102, vcc, s36, v138
	v_readlane_b32 s58, v234, 9
	s_nop 0
	v_addc_co_u32_e32 v103, vcc, 0, v139, vcc
	v_add_co_u32_e32 v106, vcc, s38, v138
	v_readlane_b32 s59, v234, 10
	s_nop 0
	v_addc_co_u32_e32 v107, vcc, 0, v139, vcc
	global_load_dwordx4 v[102:105], v[102:103], off nt
	s_nop 0
	global_load_dwordx4 v[106:109], v[106:107], off nt
	v_add_co_u32_e32 v110, vcc, s0, v138
	s_mov_b32 s0, 0x50000
	s_nop 0
	v_addc_co_u32_e32 v111, vcc, 0, v139, vcc
	v_add_co_u32_e32 v114, vcc, s49, v138
	v_readlane_b32 s60, v234, 11
	s_nop 0
	v_addc_co_u32_e32 v115, vcc, 0, v139, vcc
	global_load_dwordx4 v[110:113], v[110:111], off nt
	s_nop 0
	global_load_dwordx4 v[114:117], v[114:115], off nt
	v_add_co_u32_e32 v118, vcc, s0, v138
	s_mov_b32 s0, 0x68000
	s_nop 0
	v_addc_co_u32_e32 v119, vcc, 0, v139, vcc
	v_add_co_u32_e32 v122, vcc, s45, v138
	v_readlane_b32 s61, v234, 12
	s_nop 0
	v_addc_co_u32_e32 v123, vcc, 0, v139, vcc
	global_load_dwordx4 v[118:121], v[118:119], off nt
	s_nop 0
	global_load_dwordx4 v[122:125], v[122:123], off nt
	v_add_co_u32_e32 v126, vcc, s50, v138
	v_readlane_b32 s64, v234, 15
	s_nop 0
	v_addc_co_u32_e32 v127, vcc, 0, v139, vcc
	global_load_dwordx4 v[126:129], v[126:127], off nt
	v_add_co_u32_e32 v130, vcc, s0, v138
	v_readlane_b32 s65, v234, 16
	s_nop 0
	v_addc_co_u32_e32 v131, vcc, 0, v139, vcc
	global_load_dwordx4 v[130:133], v[130:131], off nt
	v_add_co_u32_e32 v134, vcc, s41, v138
	v_readlane_b32 s66, v234, 17
	s_nop 0
	v_addc_co_u32_e32 v135, vcc, 0, v139, vcc
	global_load_dwordx4 v[134:137], v[134:135], off nt
	v_add_co_u32_e32 v138, vcc, s51, v138
	v_readlane_b32 s67, v234, 18
	s_nop 0
	v_addc_co_u32_e32 v139, vcc, 0, v139, vcc
	global_load_dwordx4 v[138:141], v[138:139], off nt
	s_waitcnt vmcnt(15)
	ds_write2_b32 v1, v78, v79 offset1:1
	ds_write2_b32 v1, v80, v81 offset0:2 offset1:3
	s_waitcnt vmcnt(14)
	ds_write2_b32 v4, v82, v83 offset1:1
	v_add_u32_e32 v4, 0x418, v1
	ds_write2_b32 v4, v84, v85 offset1:1
	v_add_u32_e32 v4, 0x820, v1
	v_readlane_b32 s68, v234, 19
	v_readlane_b32 s69, v234, 20
	v_readlane_b32 s70, v234, 21
	s_waitcnt vmcnt(13)
	ds_write2_b32 v4, v86, v87 offset1:1
	v_add_u32_e32 v4, 0x828, v1
	ds_write2_b32 v4, v88, v89 offset1:1
	v_add_u32_e32 v4, 0xc30, v1
	s_waitcnt vmcnt(12)
	ds_write2_b32 v4, v90, v91 offset1:1
	v_add_u32_e32 v4, 0xc38, v1
	ds_write2_b32 v4, v92, v93 offset1:1
	v_add_u32_e32 v4, 0x1040, v1
	v_readlane_b32 s71, v234, 22
	s_waitcnt vmcnt(11)
	ds_write2_b32 v4, v94, v95 offset1:1
	v_add_u32_e32 v4, 0x1048, v1
	ds_write2_b32 v4, v96, v97 offset1:1
	v_add_u32_e32 v4, 0x1450, v1
	s_waitcnt vmcnt(10)
	ds_write2_b32 v4, v98, v99 offset1:1
	v_add_u32_e32 v4, 0x1458, v1
	ds_write2_b32 v4, v100, v101 offset1:1
	v_add_u32_e32 v4, 0x1860, v1
	s_waitcnt vmcnt(9)
	ds_write2_b32 v4, v102, v103 offset1:1
	v_add_u32_e32 v4, 0x1868, v1
	ds_write2_b32 v4, v104, v105 offset1:1
	v_add_u32_e32 v4, 0x1c70, v1
	s_waitcnt vmcnt(8)
	ds_write2_b32 v4, v106, v107 offset1:1
	v_add_u32_e32 v4, 0x1c78, v1
	ds_write2_b32 v4, v108, v109 offset1:1
	v_add_u32_e32 v4, 0x2080, v1
	s_waitcnt vmcnt(7)
	ds_write2_b32 v4, v110, v111 offset1:1
	v_add_u32_e32 v4, 0x2088, v1
	ds_write2_b32 v4, v112, v113 offset1:1
	v_add_u32_e32 v4, 0x2490, v1
	s_waitcnt vmcnt(6)
	ds_write2_b32 v4, v114, v115 offset1:1
	v_add_u32_e32 v4, 0x2498, v1
	ds_write2_b32 v4, v116, v117 offset1:1
	v_add_u32_e32 v4, 0x28a0, v1
	s_waitcnt vmcnt(5)
	ds_write2_b32 v4, v118, v119 offset1:1
	v_add_u32_e32 v4, 0x28a8, v1
	ds_write2_b32 v4, v120, v121 offset1:1
	v_add_u32_e32 v4, 0x2cb0, v1
	s_waitcnt vmcnt(4)
	ds_write2_b32 v4, v122, v123 offset1:1
	v_add_u32_e32 v4, 0x2cb8, v1
	ds_write2_b32 v4, v124, v125 offset1:1
	v_add_u32_e32 v4, 0x30c0, v1
	s_waitcnt vmcnt(3)
	ds_write2_b32 v4, v126, v127 offset1:1
	v_add_u32_e32 v4, 0x30c8, v1
	ds_write2_b32 v4, v128, v129 offset1:1
	v_add_u32_e32 v4, 0x34d0, v1
	s_waitcnt vmcnt(2)
	ds_write2_b32 v4, v130, v131 offset1:1
	v_add_u32_e32 v4, 0x34d8, v1
	ds_write2_b32 v4, v132, v133 offset1:1
	v_add_u32_e32 v4, 0x38e0, v1
	s_waitcnt vmcnt(1)
	ds_write2_b32 v4, v134, v135 offset1:1
	v_add_u32_e32 v4, 0x38e8, v1
	ds_write2_b32 v4, v136, v137 offset1:1
	v_add_u32_e32 v4, 0x3cf0, v1
	s_waitcnt vmcnt(0)
	ds_write2_b32 v4, v138, v139 offset1:1
	v_add_u32_e32 v4, 0x3cf8, v1
	ds_write2_b32 v4, v140, v141 offset1:1
	s_waitcnt lgkmcnt(0)
	ds_read2_b32 v[82:83], v33 offset0:65 offset1:73
	ds_read2_b32 v[84:85], v33 offset1:8
	ds_read2_b32 v[86:87], v33 offset0:130 offset1:138
	ds_read2_b32 v[88:89], v33 offset0:195 offset1:203
	ds_read2_b32 v[90:91], v77 offset0:4 offset1:12
	ds_read2_b32 v[92:93], v77 offset0:69 offset1:77
	ds_read2_b32 v[94:95], v77 offset0:134 offset1:142
	ds_read2_b32 v[96:97], v77 offset0:199 offset1:207
	v_lshlrev_b32_e32 v4, 1, v32
	v_lshl_add_u64 v[98:99], s[10:11], 0, v[4:5]
	s_waitcnt lgkmcnt(6)
	v_cvt_pk_bf16_f32 v78, v84, v82
	s_waitcnt lgkmcnt(4)
	v_cvt_pk_bf16_f32 v79, v86, v88
	s_waitcnt lgkmcnt(2)
	v_cvt_pk_bf16_f32 v80, v90, v92
	s_waitcnt lgkmcnt(0)
	v_cvt_pk_bf16_f32 v81, v94, v96
	v_lshl_add_u64 v[100:101], v[98:99], 0, v[34:35]
	global_store_dwordx4 v[100:101], v[78:81], off sc1
	s_nop 1
	v_cvt_pk_bf16_f32 v78, v85, v83
	v_cvt_pk_bf16_f32 v79, v87, v89
	v_cvt_pk_bf16_f32 v80, v91, v93
	v_cvt_pk_bf16_f32 v81, v95, v97
	ds_read2_b32 v[84:85], v33 offset0:81 offset1:89
	ds_read2_b32 v[86:87], v33 offset0:16 offset1:24
	ds_read2_b32 v[88:89], v33 offset0:146 offset1:154
	ds_read2_b32 v[90:91], v33 offset0:211 offset1:219
	ds_read2_b32 v[92:93], v77 offset0:20 offset1:28
	ds_read2_b32 v[94:95], v77 offset0:85 offset1:93
	ds_read2_b32 v[96:97], v77 offset0:150 offset1:158
	ds_read2_b32 v[100:101], v77 offset0:215 offset1:223
	v_lshl_add_u64 v[82:83], v[98:99], 0, v[36:37]
	global_store_dwordx4 v[82:83], v[78:81], off sc1
	v_lshl_add_u64 v[82:83], v[98:99], 0, v[38:39]
	s_waitcnt lgkmcnt(6)
	v_cvt_pk_bf16_f32 v78, v86, v84
	s_waitcnt lgkmcnt(4)
	v_cvt_pk_bf16_f32 v79, v88, v90
	s_waitcnt lgkmcnt(2)
	v_cvt_pk_bf16_f32 v80, v92, v94
	s_waitcnt lgkmcnt(0)
	v_cvt_pk_bf16_f32 v81, v96, v100
	global_store_dwordx4 v[82:83], v[78:81], off sc1
	v_lshl_add_u64 v[82:83], v[98:99], 0, v[46:47]
	s_nop 0
	v_cvt_pk_bf16_f32 v78, v87, v85
	v_cvt_pk_bf16_f32 v79, v89, v91
	v_cvt_pk_bf16_f32 v80, v93, v95
	v_cvt_pk_bf16_f32 v81, v97, v101
	ds_read2_b32 v[84:85], v33 offset0:32 offset1:40
	ds_read2_b32 v[86:87], v33 offset0:97 offset1:105
	ds_read2_b32 v[88:89], v33 offset0:162 offset1:170
	ds_read2_b32 v[90:91], v33 offset0:227 offset1:235
	ds_read2_b32 v[92:93], v77 offset0:36 offset1:44
	ds_read2_b32 v[94:95], v77 offset0:101 offset1:109
	ds_read2_b32 v[96:97], v77 offset0:166 offset1:174
	ds_read2_b32 v[100:101], v77 offset0:231 offset1:239
	global_store_dwordx4 v[82:83], v[78:81], off sc1
	v_lshl_add_u64 v[82:83], v[98:99], 0, v[50:51]
	s_waitcnt lgkmcnt(6)
	v_cvt_pk_bf16_f32 v78, v84, v86
	s_waitcnt lgkmcnt(4)
	v_cvt_pk_bf16_f32 v79, v88, v90
	s_waitcnt lgkmcnt(2)
	v_cvt_pk_bf16_f32 v80, v92, v94
	s_waitcnt lgkmcnt(0)
	v_cvt_pk_bf16_f32 v81, v96, v100
	global_store_dwordx4 v[82:83], v[78:81], off sc1
	v_lshl_add_u64 v[82:83], v[98:99], 0, v[54:55]
	s_nop 0
	v_cvt_pk_bf16_f32 v78, v85, v87
	v_cvt_pk_bf16_f32 v79, v89, v91
	v_cvt_pk_bf16_f32 v80, v93, v95
	v_cvt_pk_bf16_f32 v81, v97, v101
	ds_read2_b32 v[84:85], v33 offset0:48 offset1:56
	ds_read2_b32 v[86:87], v33 offset0:113 offset1:121
	ds_read2_b32 v[88:89], v33 offset0:178 offset1:186
	ds_read2_b32 v[90:91], v33 offset0:243 offset1:251
	ds_read2_b32 v[92:93], v77 offset0:52 offset1:60
	ds_read2_b32 v[94:95], v77 offset0:117 offset1:125
	ds_read2_b32 v[96:97], v77 offset0:182 offset1:190
	ds_read2_b32 v[100:101], v77 offset0:247 offset1:255
	global_store_dwordx4 v[82:83], v[78:81], off sc1
	v_lshl_add_u64 v[82:83], v[98:99], 0, v[58:59]
	s_waitcnt lgkmcnt(6)
	v_cvt_pk_bf16_f32 v78, v84, v86
	s_waitcnt lgkmcnt(4)
	v_cvt_pk_bf16_f32 v79, v88, v90
	s_waitcnt lgkmcnt(2)
	v_cvt_pk_bf16_f32 v80, v92, v94
	s_waitcnt lgkmcnt(0)
	v_cvt_pk_bf16_f32 v81, v96, v100
	global_store_dwordx4 v[82:83], v[78:81], off sc1
	v_lshl_add_u64 v[82:83], v[98:99], 0, v[62:63]
	s_nop 0
	v_cvt_pk_bf16_f32 v78, v85, v87
	v_cvt_pk_bf16_f32 v79, v89, v91
	v_cvt_pk_bf16_f32 v80, v93, v95
	v_cvt_pk_bf16_f32 v81, v97, v101
	global_store_dwordx4 v[82:83], v[78:81], off sc1
	s_waitcnt lgkmcnt(0)

.LBB0_62:
	s_andn2_b64 vcc, exec, s[10:11]
	s_cbranch_vccnz .LBB0_64
	s_and_b32 s0, s9, 0x1fc0
	s_addk_i32 s0, 0xe800
	v_readlane_b32 s56, v234, 7
	s_and_b32 s12, s5, 0x3c0
	s_lshl_b64 s[10:11], s[0:1], 12
	v_readlane_b32 s60, v234, 11
	v_readlane_b32 s61, v234, 12
	s_add_u32 s10, s60, s10
	s_addc_u32 s11, s61, s11
	s_lshl_b32 s13, s12, 2
	s_add_u32 s10, s10, s13
	s_addc_u32 s11, s11, 0
	v_lshl_add_u64 v[78:79], s[10:11], 0, v[66:67]
	v_lshlrev_b32_e32 v4, 2, v2
	v_lshl_add_u64 v[138:139], v[78:79], 0, v[4:5]
	v_add_co_u32_e32 v82, vcc, s21, v138
	v_add_u32_e32 v4, 0x410, v1
	s_nop 0
	v_addc_co_u32_e32 v83, vcc, 0, v139, vcc
	v_add_co_u32_e32 v86, vcc, s24, v138
	global_load_dwordx4 v[78:81], v[138:139], off nt
	s_nop 0
	global_load_dwordx4 v[82:85], v[82:83], off nt
	v_addc_co_u32_e32 v87, vcc, 0, v139, vcc
	v_add_co_u32_e32 v90, vcc, s25, v138
	s_lshl_b32 s10, s12, 12
	s_nop 0
	v_addc_co_u32_e32 v91, vcc, 0, v139, vcc
	global_load_dwordx4 v[86:89], v[86:87], off nt
	s_nop 0
	global_load_dwordx4 v[90:93], v[90:91], off nt
	v_add_co_u32_e32 v94, vcc, s26, v138
	v_readlane_b32 s11, v234, 53
	s_nop 0
	v_addc_co_u32_e32 v95, vcc, 0, v139, vcc
	v_add_co_u32_e32 v98, vcc, s27, v138
	v_add_u32_e32 v77, 0x400, v33
	s_nop 0
	v_addc_co_u32_e32 v99, vcc, 0, v139, vcc
	global_load_dwordx4 v[94:97], v[94:95], off nt
	s_nop 0
	global_load_dwordx4 v[98:101], v[98:99], off nt
	v_add_co_u32_e32 v102, vcc, s28, v138
	s_add_u32 s12, s11, s10
	s_nop 0
	v_addc_co_u32_e32 v103, vcc, 0, v139, vcc
	v_add_co_u32_e32 v106, vcc, s29, v138
	s_addc_u32 s13, s89, 0
	s_nop 0
	v_addc_co_u32_e32 v107, vcc, 0, v139, vcc
	global_load_dwordx4 v[102:105], v[102:103], off nt
	s_nop 0
	global_load_dwordx4 v[106:109], v[106:107], off nt
	v_add_co_u32_e32 v110, vcc, s30, v138
	s_lshl_b64 s[10:11], s[0:1], 1
	s_nop 0
	v_addc_co_u32_e32 v111, vcc, 0, v139, vcc
	v_add_co_u32_e32 v114, vcc, s31, v138
	s_add_u32 s10, s12, s10
	s_nop 0
	v_addc_co_u32_e32 v115, vcc, 0, v139, vcc
	global_load_dwordx4 v[110:113], v[110:111], off nt
	s_nop 0
	global_load_dwordx4 v[114:117], v[114:115], off nt
	v_add_co_u32_e32 v118, vcc, s34, v138
	s_addc_u32 s11, s13, s11
	s_nop 0
	v_addc_co_u32_e32 v119, vcc, 0, v139, vcc
	v_add_co_u32_e32 v122, vcc, s35, v138
	v_readlane_b32 s57, v234, 8
	s_nop 0
	v_addc_co_u32_e32 v123, vcc, 0, v139, vcc
	global_load_dwordx4 v[118:121], v[118:119], off nt
	s_nop 0
	global_load_dwordx4 v[122:125], v[122:123], off nt
	v_add_co_u32_e32 v126, vcc, s36, v138
	v_readlane_b32 s58, v234, 9
	s_nop 0
	v_addc_co_u32_e32 v127, vcc, 0, v139, vcc
	global_load_dwordx4 v[126:129], v[126:127], off nt
	v_add_co_u32_e32 v130, vcc, s37, v138
	v_readlane_b32 s59, v234, 10
	s_nop 0
	v_addc_co_u32_e32 v131, vcc, 0, v139, vcc
	global_load_dwordx4 v[130:133], v[130:131], off nt
	v_add_co_u32_e32 v134, vcc, s38, v138
	v_readlane_b32 s62, v234, 13
	s_nop 0
	v_addc_co_u32_e32 v135, vcc, 0, v139, vcc
	global_load_dwordx4 v[134:137], v[134:135], off nt
	v_add_co_u32_e32 v138, vcc, s39, v138
	v_readlane_b32 s63, v234, 14
	s_nop 0
	v_addc_co_u32_e32 v139, vcc, 0, v139, vcc
	global_load_dwordx4 v[138:141], v[138:139], off nt
	s_waitcnt vmcnt(15)
	ds_write2_b32 v1, v78, v79 offset1:1
	ds_write2_b32 v1, v80, v81 offset0:2 offset1:3
	s_waitcnt vmcnt(14)
	ds_write2_b32 v4, v82, v83 offset1:1
	v_add_u32_e32 v4, 0x418, v1
	ds_write2_b32 v4, v84, v85 offset1:1
	v_add_u32_e32 v4, 0x820, v1
	v_readlane_b32 s64, v234, 15
	v_readlane_b32 s65, v234, 16
	v_readlane_b32 s66, v234, 17
	s_waitcnt vmcnt(13)
	ds_write2_b32 v4, v86, v87 offset1:1
	v_add_u32_e32 v4, 0x828, v1
	ds_write2_b32 v4, v88, v89 offset1:1
	v_add_u32_e32 v4, 0xc30, v1
	s_waitcnt vmcnt(12)
	ds_write2_b32 v4, v90, v91 offset1:1
	v_add_u32_e32 v4, 0xc38, v1
	ds_write2_b32 v4, v92, v93 offset1:1
	v_add_u32_e32 v4, 0x1040, v1
	v_readlane_b32 s67, v234, 18
	v_readlane_b32 s68, v234, 19
	v_readlane_b32 s69, v234, 20
	s_waitcnt vmcnt(11)
	ds_write2_b32 v4, v94, v95 offset1:1
	v_add_u32_e32 v4, 0x1048, v1
	ds_write2_b32 v4, v96, v97 offset1:1
	v_add_u32_e32 v4, 0x1450, v1
	s_waitcnt vmcnt(10)
	ds_write2_b32 v4, v98, v99 offset1:1
	v_add_u32_e32 v4, 0x1458, v1
	ds_write2_b32 v4, v100, v101 offset1:1
	v_add_u32_e32 v4, 0x1860, v1
	v_readlane_b32 s70, v234, 21
	v_readlane_b32 s71, v234, 22
	s_waitcnt vmcnt(9)
	ds_write2_b32 v4, v102, v103 offset1:1
	v_add_u32_e32 v4, 0x1868, v1
	ds_write2_b32 v4, v104, v105 offset1:1
	v_add_u32_e32 v4, 0x1c70, v1
	s_waitcnt vmcnt(8)
	ds_write2_b32 v4, v106, v107 offset1:1
	v_add_u32_e32 v4, 0x1c78, v1
	ds_write2_b32 v4, v108, v109 offset1:1
	v_add_u32_e32 v4, 0x2080, v1
	s_waitcnt vmcnt(7)
	ds_write2_b32 v4, v110, v111 offset1:1
	v_add_u32_e32 v4, 0x2088, v1
	ds_write2_b32 v4, v112, v113 offset1:1
	v_add_u32_e32 v4, 0x2490, v1
	s_waitcnt vmcnt(6)
	ds_write2_b32 v4, v114, v115 offset1:1
	v_add_u32_e32 v4, 0x2498, v1
	ds_write2_b32 v4, v116, v117 offset1:1
	v_add_u32_e32 v4, 0x28a0, v1
	s_waitcnt vmcnt(5)
	ds_write2_b32 v4, v118, v119 offset1:1
	v_add_u32_e32 v4, 0x28a8, v1
	ds_write2_b32 v4, v120, v121 offset1:1
	v_add_u32_e32 v4, 0x2cb0, v1
	s_waitcnt vmcnt(4)
	ds_write2_b32 v4, v122, v123 offset1:1
	v_add_u32_e32 v4, 0x2cb8, v1
	ds_write2_b32 v4, v124, v125 offset1:1
	v_add_u32_e32 v4, 0x30c0, v1
	s_waitcnt vmcnt(3)
	ds_write2_b32 v4, v126, v127 offset1:1
	v_add_u32_e32 v4, 0x30c8, v1
	ds_write2_b32 v4, v128, v129 offset1:1
	v_add_u32_e32 v4, 0x34d0, v1
	s_waitcnt vmcnt(2)
	ds_write2_b32 v4, v130, v131 offset1:1
	v_add_u32_e32 v4, 0x34d8, v1
	ds_write2_b32 v4, v132, v133 offset1:1
	v_add_u32_e32 v4, 0x38e0, v1
	s_waitcnt vmcnt(1)
	ds_write2_b32 v4, v134, v135 offset1:1
	v_add_u32_e32 v4, 0x38e8, v1
	ds_write2_b32 v4, v136, v137 offset1:1
	v_add_u32_e32 v4, 0x3cf0, v1
	s_waitcnt vmcnt(0)
	ds_write2_b32 v4, v138, v139 offset1:1
	v_add_u32_e32 v4, 0x3cf8, v1
	ds_write2_b32 v4, v140, v141 offset1:1
	s_waitcnt lgkmcnt(0)
	ds_read2_b32 v[82:83], v33 offset0:65 offset1:73
	ds_read2_b32 v[84:85], v33 offset1:8
	ds_read2_b32 v[86:87], v33 offset0:130 offset1:138
	ds_read2_b32 v[88:89], v33 offset0:195 offset1:203
	ds_read2_b32 v[90:91], v77 offset0:4 offset1:12
	ds_read2_b32 v[92:93], v77 offset0:69 offset1:77
	ds_read2_b32 v[94:95], v77 offset0:134 offset1:142
	ds_read2_b32 v[96:97], v77 offset0:199 offset1:207
	v_lshlrev_b32_e32 v4, 1, v32
	v_lshl_add_u64 v[98:99], s[10:11], 0, v[4:5]
	s_waitcnt lgkmcnt(6)
	v_cvt_pk_bf16_f32 v78, v84, v82
	s_waitcnt lgkmcnt(4)
	v_cvt_pk_bf16_f32 v79, v86, v88
	s_waitcnt lgkmcnt(2)
	v_cvt_pk_bf16_f32 v80, v90, v92
	s_waitcnt lgkmcnt(0)
	v_cvt_pk_bf16_f32 v81, v94, v96
	v_lshl_add_u64 v[100:101], v[98:99], 0, v[40:41]
	global_store_dwordx4 v[100:101], v[78:81], off sc1
	s_nop 1
	v_cvt_pk_bf16_f32 v78, v85, v83
	v_cvt_pk_bf16_f32 v79, v87, v89
	v_cvt_pk_bf16_f32 v80, v91, v93
	v_cvt_pk_bf16_f32 v81, v95, v97
	ds_read2_b32 v[84:85], v33 offset0:81 offset1:89
	ds_read2_b32 v[86:87], v33 offset0:16 offset1:24
	ds_read2_b32 v[88:89], v33 offset0:146 offset1:154
	ds_read2_b32 v[90:91], v33 offset0:211 offset1:219
	ds_read2_b32 v[92:93], v77 offset0:20 offset1:28
	ds_read2_b32 v[94:95], v77 offset0:85 offset1:93
	ds_read2_b32 v[96:97], v77 offset0:150 offset1:158
	ds_read2_b32 v[100:101], v77 offset0:215 offset1:223
	v_lshl_add_u64 v[82:83], v[98:99], 0, v[42:43]
	global_store_dwordx4 v[82:83], v[78:81], off sc1
	v_lshl_add_u64 v[82:83], v[98:99], 0, v[44:45]
	s_waitcnt lgkmcnt(6)
	v_cvt_pk_bf16_f32 v78, v86, v84
	s_waitcnt lgkmcnt(4)
	v_cvt_pk_bf16_f32 v79, v88, v90
	s_waitcnt lgkmcnt(2)
	v_cvt_pk_bf16_f32 v80, v92, v94
	s_waitcnt lgkmcnt(0)
	v_cvt_pk_bf16_f32 v81, v96, v100
	global_store_dwordx4 v[82:83], v[78:81], off sc1
	v_lshl_add_u64 v[82:83], v[98:99], 0, v[48:49]
	s_nop 0
	v_cvt_pk_bf16_f32 v78, v87, v85
	v_cvt_pk_bf16_f32 v79, v89, v91
	v_cvt_pk_bf16_f32 v80, v93, v95
	v_cvt_pk_bf16_f32 v81, v97, v101
	ds_read2_b32 v[84:85], v33 offset0:32 offset1:40
	ds_read2_b32 v[86:87], v33 offset0:97 offset1:105
	ds_read2_b32 v[88:89], v33 offset0:162 offset1:170
	ds_read2_b32 v[90:91], v33 offset0:227 offset1:235
	ds_read2_b32 v[92:93], v77 offset0:36 offset1:44
	ds_read2_b32 v[94:95], v77 offset0:101 offset1:109
	ds_read2_b32 v[96:97], v77 offset0:166 offset1:174
	ds_read2_b32 v[100:101], v77 offset0:231 offset1:239
	global_store_dwordx4 v[82:83], v[78:81], off sc1
	v_lshl_add_u64 v[82:83], v[98:99], 0, v[52:53]
	s_waitcnt lgkmcnt(6)
	v_cvt_pk_bf16_f32 v78, v84, v86
	s_waitcnt lgkmcnt(4)
	v_cvt_pk_bf16_f32 v79, v88, v90
	s_waitcnt lgkmcnt(2)
	v_cvt_pk_bf16_f32 v80, v92, v94
	s_waitcnt lgkmcnt(0)
	v_cvt_pk_bf16_f32 v81, v96, v100
	global_store_dwordx4 v[82:83], v[78:81], off sc1
	v_lshl_add_u64 v[82:83], v[98:99], 0, v[56:57]
	s_nop 0
	v_cvt_pk_bf16_f32 v78, v85, v87
	v_cvt_pk_bf16_f32 v79, v89, v91
	v_cvt_pk_bf16_f32 v80, v93, v95
	v_cvt_pk_bf16_f32 v81, v97, v101
	ds_read2_b32 v[84:85], v33 offset0:48 offset1:56
	ds_read2_b32 v[86:87], v33 offset0:113 offset1:121
	ds_read2_b32 v[88:89], v33 offset0:178 offset1:186
	ds_read2_b32 v[90:91], v33 offset0:243 offset1:251
	ds_read2_b32 v[92:93], v77 offset0:52 offset1:60
	ds_read2_b32 v[94:95], v77 offset0:117 offset1:125
	ds_read2_b32 v[96:97], v77 offset0:182 offset1:190
	ds_read2_b32 v[100:101], v77 offset0:247 offset1:255
	global_store_dwordx4 v[82:83], v[78:81], off sc1
	v_lshl_add_u64 v[82:83], v[98:99], 0, v[60:61]
	s_waitcnt lgkmcnt(6)
	v_cvt_pk_bf16_f32 v78, v84, v86
	s_waitcnt lgkmcnt(4)
	v_cvt_pk_bf16_f32 v79, v88, v90
	s_waitcnt lgkmcnt(2)
	v_cvt_pk_bf16_f32 v80, v92, v94
	s_waitcnt lgkmcnt(0)
	v_cvt_pk_bf16_f32 v81, v96, v100
	global_store_dwordx4 v[82:83], v[78:81], off sc1
	v_lshl_add_u64 v[82:83], v[98:99], 0, v[64:65]
	s_nop 0
	v_cvt_pk_bf16_f32 v78, v85, v87
	v_cvt_pk_bf16_f32 v79, v89, v91
	v_cvt_pk_bf16_f32 v80, v93, v95
	v_cvt_pk_bf16_f32 v81, v97, v101
	global_store_dwordx4 v[82:83], v[78:81], off sc1
	s_waitcnt lgkmcnt(0)

.Lxcv4_top:
	v_add_u32_e32 v7, s11, v6
	v_cmp_gt_i32_e32 vcc, s16, v7
	s_and_b64 exec, s[14:15], vcc
	s_cbranch_execz .Lxcv4_done
	v_ashrrev_i32_e32 v5, 31, v4
	v_lshl_add_u64 v[46:47], v[4:5], 4, s[12:13]
	v_lshl_add_u64 v[48:49], v[46:47], 0, s[18:19]
	v_lshl_add_u64 v[50:51], v[48:49], 0, s[18:19]
	v_lshl_add_u64 v[52:53], v[50:51], 0, s[18:19]
	global_load_dwordx4 v[8:11], v[46:47], off
	global_load_dwordx4 v[12:15], v[46:47], off offset:16
	global_load_dwordx4 v[16:19], v[48:49], off
	global_load_dwordx4 v[20:23], v[48:49], off offset:16
	global_load_dwordx4 v[24:27], v[50:51], off
	global_load_dwordx4 v[28:31], v[50:51], off offset:16
	global_load_dwordx4 v[32:35], v[52:53], off
	global_load_dwordx4 v[36:39], v[52:53], off offset:16
	v_add_u32_e32 v6, s17, v6
	v_add_u32_e32 v4, s20, v4
	s_waitcnt vmcnt(6)
	v_cvt_pk_bf16_f32 v8, v8, v9
	v_cvt_pk_bf16_f32 v9, v10, v11
	v_cvt_pk_bf16_f32 v10, v12, v13
	v_cvt_pk_bf16_f32 v11, v14, v15
	global_store_dwordx4 v[2:3], v[8:11], off sc1
	v_lshl_add_u64 v[2:3], v[2:3], 0, s[6:7]
	s_waitcnt vmcnt(5)
	v_cvt_pk_bf16_f32 v16, v16, v17
	v_cvt_pk_bf16_f32 v17, v18, v19
	v_cvt_pk_bf16_f32 v18, v20, v21
	v_cvt_pk_bf16_f32 v19, v22, v23
	global_store_dwordx4 v[2:3], v[16:19], off sc1
	v_lshl_add_u64 v[2:3], v[2:3], 0, s[6:7]
	s_waitcnt vmcnt(4)
	v_cvt_pk_bf16_f32 v24, v24, v25
	v_cvt_pk_bf16_f32 v25, v26, v27
	v_cvt_pk_bf16_f32 v26, v28, v29
	v_cvt_pk_bf16_f32 v27, v30, v31
	global_store_dwordx4 v[2:3], v[24:27], off sc1
	v_lshl_add_u64 v[2:3], v[2:3], 0, s[6:7]
	s_waitcnt vmcnt(3)
	v_cvt_pk_bf16_f32 v32, v32, v33
	v_cvt_pk_bf16_f32 v33, v34, v35
	v_cvt_pk_bf16_f32 v34, v36, v37
	v_cvt_pk_bf16_f32 v35, v38, v39
	global_store_dwordx4 v[2:3], v[32:35], off sc1
	v_lshl_add_u64 v[2:3], v[2:3], 0, s[6:7]
	s_branch .Lxcv4_top

.LBB0_80:
	v_ashrrev_i32_e32 v5, 31, v4
	v_lshl_add_u64 v[12:13], v[4:5], 4, s[12:13]
	global_load_dwordx4 v[8:11], v[12:13], off
	s_nop 0
	global_load_dwordx4 v[12:15], v[12:13], off offset:16
	v_add_u32_e32 v6, s4, v6
	v_cmp_lt_i32_e32 vcc, s10, v6
	v_add_u32_e32 v4, s5, v4
	s_or_b64 s[8:9], vcc, s[8:9]
	s_waitcnt vmcnt(1)
	v_cvt_pk_bf16_f32 v8, v8, v9
	v_cvt_pk_bf16_f32 v9, v10, v11
	s_waitcnt vmcnt(0)
	v_cvt_pk_bf16_f32 v10, v12, v13
	v_cvt_pk_bf16_f32 v11, v14, v15
	global_store_dwordx4 v[2:3], v[8:11], off sc1
	v_lshl_add_u64 v[2:3], v[2:3], 0, s[6:7]
	s_andn2_b64 exec, exec, s[8:9]
	s_cbranch_execnz .LBB0_80

.LBB0_172:
	s_waitcnt vmcnt(0)
	v_pk_mul_f32 v[192:193], v[104:105], v[132:133]
	v_pk_mul_f32 v[132:133], v[120:121], v[132:133]
	v_pk_mul_f32 v[180:181], v[106:107], v[134:135]
	v_pk_fma_f32 v[192:193], v[120:121], v[128:129], v[192:193] neg_lo:[0,0,1] neg_hi:[0,0,1]
	v_pk_mul_f32 v[134:135], v[122:123], v[134:135]
	v_pk_fma_f32 v[128:129], v[104:105], v[128:129], v[132:133]
	v_ashrrev_i32_e32 v167, 31, v166
	v_pk_mul_f32 v[172:173], v[110:111], v[142:143]
	v_pk_mul_f32 v[176:177], v[108:109], v[140:141]
	v_pk_fma_f32 v[180:181], v[122:123], v[130:131], v[180:181] neg_lo:[0,0,1] neg_hi:[0,0,1]
	v_pk_mul_f32 v[142:143], v[126:127], v[142:143]
	v_pk_mul_f32 v[140:141], v[124:125], v[140:141]
	v_pk_fma_f32 v[130:131], v[106:107], v[130:131], v[134:135]
	v_pk_mul_f32 v[134:135], v[128:129], v[168:169] op_sel_hi:[1,0]
	v_lshlrev_b64 v[128:129], 12, v[166:167]
	s_lshl_b32 s26, s14, 8
	v_pk_fma_f32 v[172:173], v[126:127], v[138:139], v[172:173] neg_lo:[0,0,1] neg_hi:[0,0,1]
	v_pk_fma_f32 v[176:177], v[124:125], v[136:137], v[176:177] neg_lo:[0,0,1] neg_hi:[0,0,1]
	v_pk_fma_f32 v[138:139], v[110:111], v[138:139], v[142:143]
	v_pk_fma_f32 v[136:137], v[108:109], v[136:137], v[140:141]
	v_lshl_add_u64 v[128:129], s[58:59], 0, v[128:129]
	s_ashr_i32 s27, s26, 31
	v_pk_mul_f32 v[172:173], v[172:173], v[168:169] op_sel_hi:[1,0]
	v_pk_mul_f32 v[176:177], v[176:177], v[168:169] op_sel_hi:[1,0]
	v_pk_mul_f32 v[180:181], v[180:181], v[168:169] op_sel_hi:[1,0]
	v_pk_mul_f32 v[192:193], v[192:193], v[168:169] op_sel_hi:[1,0]
	v_pk_mul_f32 v[138:139], v[138:139], v[168:169] op_sel_hi:[1,0]
	v_pk_mul_f32 v[136:137], v[136:137], v[168:169] op_sel_hi:[1,0]
	v_pk_mul_f32 v[132:133], v[130:131], v[168:169] op_sel_hi:[1,0]
	v_lshl_add_u64 v[128:129], s[26:27], 1, v[128:129]
	v_lshlrev_b32_e32 v168, 1, v152
	v_mov_b32_e32 v169, v145
	v_lshl_add_u64 v[140:141], v[128:129], 0, v[168:169]
	v_cvt_pk_bf16_f32 v128, v176, v177
	v_cvt_pk_bf16_f32 v129, v172, v173
	v_cvt_pk_bf16_f32 v130, v192, v193
	v_cvt_pk_bf16_f32 v131, v180, v181
	global_store_dwordx4 v[140:141], v[128:131], off sc1
	v_or_b32_e32 v176, 16, v166
	v_cndmask_b32_e64 v147, 0, 1, s[28:29]
	v_cvt_pk_bf16_f32 v128, v136, v137
	v_cvt_pk_bf16_f32 v129, v138, v139
	v_cvt_pk_bf16_f32 v130, v134, v135
	v_cvt_pk_bf16_f32 v131, v132, v133
	global_store_dwordx4 v[140:141], v[128:131], off offset:256 sc1
	v_cmp_ne_u32_e64 s[6:7], 1, v147
	s_andn2_b64 vcc, exec, s[28:29]
	v_lshlrev_b32_e32 v128, 9, v176
	v_and_b32_e32 v128, 0x1fbe00, v128
	v_mov_b32_e32 v129, v145
	v_lshl_add_u64 v[132:133], v[154:155], 0, v[128:129]
	v_lshl_add_u64 v[140:141], v[156:157], 0, v[128:129]
	global_load_dwordx4 v[128:131], v[132:133], off offset:16
	global_load_dwordx4 v[136:139], v[132:133], off
	s_nop 0
	global_load_dwordx4 v[132:135], v[140:141], off offset:16
	s_nop 0
	global_load_dwordx4 v[140:143], v[140:141], off
	v_lshl_add_u32 v172, s14, 6, v186
	s_cbranch_vccnz .LBB0_174
	v_mov_b32_e32 v173, v145
	v_lshl_add_u64 v[174:175], v[172:173], 2, s[8:9]
	global_load_dword v174, v[174:175], off
.LBB0_174:
	s_waitcnt vmcnt(1)
	v_pk_mul_f32 v[196:197], v[88:89], v[132:133]
	v_pk_mul_f32 v[132:133], v[112:113], v[132:133]
	v_pk_mul_f32 v[194:195], v[90:91], v[134:135]
	v_pk_fma_f32 v[196:197], v[112:113], v[128:129], v[196:197] neg_lo:[0,0,1] neg_hi:[0,0,1]
	v_pk_mul_f32 v[134:135], v[114:115], v[134:135]
	v_pk_fma_f32 v[128:129], v[88:89], v[128:129], v[132:133]
	v_ashrrev_i32_e32 v177, 31, v176
	s_waitcnt vmcnt(0)
	v_pk_mul_f32 v[180:181], v[94:95], v[142:143]
	v_pk_mul_f32 v[192:193], v[92:93], v[140:141]
	v_pk_fma_f32 v[194:195], v[114:115], v[130:131], v[194:195] neg_lo:[0,0,1] neg_hi:[0,0,1]
	v_pk_fma_f32 v[130:131], v[90:91], v[130:131], v[134:135]
	v_pk_mul_f32 v[134:135], v[128:129], v[174:175] op_sel_hi:[1,0]
	v_lshlrev_b64 v[128:129], 12, v[176:177]
	v_pk_fma_f32 v[180:181], v[118:119], v[138:139], v[180:181] neg_lo:[0,0,1] neg_hi:[0,0,1]
	v_pk_fma_f32 v[192:193], v[116:117], v[136:137], v[192:193] neg_lo:[0,0,1] neg_hi:[0,0,1]
	v_pk_mul_f32 v[142:143], v[118:119], v[142:143]
	v_pk_mul_f32 v[140:141], v[116:117], v[140:141]
	v_lshl_add_u64 v[128:129], s[58:59], 0, v[128:129]
	v_pk_mul_f32 v[180:181], v[180:181], v[174:175] op_sel_hi:[1,0]
	v_pk_mul_f32 v[192:193], v[192:193], v[174:175] op_sel_hi:[1,0]
	v_pk_mul_f32 v[194:195], v[194:195], v[174:175] op_sel_hi:[1,0]
	v_pk_mul_f32 v[196:197], v[196:197], v[174:175] op_sel_hi:[1,0]
	v_pk_fma_f32 v[138:139], v[94:95], v[138:139], v[142:143]
	v_pk_fma_f32 v[136:137], v[92:93], v[136:137], v[140:141]
	v_lshl_add_u64 v[128:129], s[26:27], 1, v[128:129]
	v_pk_mul_f32 v[138:139], v[138:139], v[174:175] op_sel_hi:[1,0]
	v_pk_mul_f32 v[136:137], v[136:137], v[174:175] op_sel_hi:[1,0]
	v_pk_mul_f32 v[132:133], v[130:131], v[174:175] op_sel_hi:[1,0]
	v_lshl_add_u64 v[140:141], v[128:129], 0, v[168:169]
	v_cvt_pk_bf16_f32 v128, v192, v193
	v_cvt_pk_bf16_f32 v129, v180, v181
	v_cvt_pk_bf16_f32 v130, v196, v197
	v_cvt_pk_bf16_f32 v131, v194, v195
	global_store_dwordx4 v[140:141], v[128:131], off sc1
	v_or_b32_e32 v176, 32, v166
	v_mov_b32_e32 v178, 1.0
	v_cvt_pk_bf16_f32 v128, v136, v137
	v_cvt_pk_bf16_f32 v129, v138, v139
	v_cvt_pk_bf16_f32 v130, v134, v135
	v_cvt_pk_bf16_f32 v131, v132, v133
	global_store_dwordx4 v[140:141], v[128:131], off offset:256 sc1
	s_and_b64 vcc, exec, s[6:7]
	v_lshl_add_u32 v174, s14, 6, v187
	v_lshlrev_b32_e32 v128, 9, v176
	v_and_b32_e32 v128, 0x1fde00, v128
	v_mov_b32_e32 v129, v145
	v_lshl_add_u64 v[132:133], v[154:155], 0, v[128:129]
	v_lshl_add_u64 v[140:141], v[156:157], 0, v[128:129]
	global_load_dwordx4 v[128:131], v[132:133], off offset:16
	global_load_dwordx4 v[136:139], v[132:133], off
	s_nop 0
	global_load_dwordx4 v[132:135], v[140:141], off offset:16
	s_nop 0
	global_load_dwordx4 v[140:143], v[140:141], off
	v_mov_b32_e32 v180, 1.0
	s_cbranch_vccnz .LBB0_176
	v_mov_b32_e32 v175, v145
	v_lshl_add_u64 v[180:181], v[174:175], 2, s[8:9]
	global_load_dword v180, v[180:181], off
.LBB0_176:
	s_waitcnt vmcnt(1)
	v_pk_mul_f32 v[198:199], v[72:73], v[132:133]
	v_pk_mul_f32 v[132:133], v[96:97], v[132:133]
	v_pk_mul_f32 v[196:197], v[74:75], v[134:135]
	v_pk_fma_f32 v[198:199], v[96:97], v[128:129], v[198:199] neg_lo:[0,0,1] neg_hi:[0,0,1]
	v_pk_mul_f32 v[134:135], v[98:99], v[134:135]
	v_pk_fma_f32 v[128:129], v[72:73], v[128:129], v[132:133]
	v_ashrrev_i32_e32 v177, 31, v176
	s_waitcnt vmcnt(0)
	v_pk_mul_f32 v[192:193], v[78:79], v[142:143]
	v_pk_mul_f32 v[194:195], v[76:77], v[140:141]
	v_pk_fma_f32 v[196:197], v[98:99], v[130:131], v[196:197] neg_lo:[0,0,1] neg_hi:[0,0,1]
	v_pk_fma_f32 v[130:131], v[74:75], v[130:131], v[134:135]
	v_pk_mul_f32 v[134:135], v[128:129], v[180:181] op_sel_hi:[1,0]
	v_lshlrev_b64 v[128:129], 12, v[176:177]
	v_pk_fma_f32 v[192:193], v[102:103], v[138:139], v[192:193] neg_lo:[0,0,1] neg_hi:[0,0,1]
	v_pk_fma_f32 v[194:195], v[100:101], v[136:137], v[194:195] neg_lo:[0,0,1] neg_hi:[0,0,1]
	v_pk_mul_f32 v[142:143], v[102:103], v[142:143]
	v_pk_mul_f32 v[140:141], v[100:101], v[140:141]
	v_lshl_add_u64 v[128:129], s[58:59], 0, v[128:129]
	v_pk_mul_f32 v[192:193], v[192:193], v[180:181] op_sel_hi:[1,0]
	v_pk_mul_f32 v[194:195], v[194:195], v[180:181] op_sel_hi:[1,0]
	v_pk_mul_f32 v[196:197], v[196:197], v[180:181] op_sel_hi:[1,0]
	v_pk_mul_f32 v[198:199], v[198:199], v[180:181] op_sel_hi:[1,0]
	v_pk_fma_f32 v[138:139], v[78:79], v[138:139], v[142:143]
	v_pk_fma_f32 v[136:137], v[76:77], v[136:137], v[140:141]
	v_lshl_add_u64 v[128:129], s[26:27], 1, v[128:129]
	v_mov_b32_e32 v169, v145
	v_pk_mul_f32 v[138:139], v[138:139], v[180:181] op_sel_hi:[1,0]
	v_pk_mul_f32 v[136:137], v[136:137], v[180:181] op_sel_hi:[1,0]
	v_pk_mul_f32 v[132:133], v[130:131], v[180:181] op_sel_hi:[1,0]
	v_lshl_add_u64 v[140:141], v[128:129], 0, v[168:169]
	v_cvt_pk_bf16_f32 v128, v194, v195
	v_cvt_pk_bf16_f32 v129, v192, v193
	v_cvt_pk_bf16_f32 v130, v198, v199
	v_cvt_pk_bf16_f32 v131, v196, v197
	global_store_dwordx4 v[140:141], v[128:131], off sc1
	v_or_b32_e32 v180, 48, v166
	s_and_b64 vcc, exec, s[6:7]
	v_cvt_pk_bf16_f32 v128, v136, v137
	v_cvt_pk_bf16_f32 v129, v138, v139
	v_cvt_pk_bf16_f32 v130, v134, v135
	v_cvt_pk_bf16_f32 v131, v132, v133
	global_store_dwordx4 v[140:141], v[128:131], off offset:256 sc1
	v_lshl_add_u32 v176, s14, 6, v188
	s_nop 0
	v_lshlrev_b32_e32 v128, 9, v180
	v_and_b32_e32 v128, 0x1ffe00, v128
	v_mov_b32_e32 v129, v145
	v_lshl_add_u64 v[132:133], v[154:155], 0, v[128:129]
	v_lshl_add_u64 v[140:141], v[156:157], 0, v[128:129]
	global_load_dwordx4 v[128:131], v[132:133], off offset:16
	global_load_dwordx4 v[136:139], v[132:133], off
	s_nop 0
	global_load_dwordx4 v[132:135], v[140:141], off offset:16
	s_nop 0
	global_load_dwordx4 v[140:143], v[140:141], off
	s_cbranch_vccnz .LBB0_178
	v_mov_b32_e32 v177, v145
	v_lshl_add_u64 v[192:193], v[176:177], 2, s[8:9]
	global_load_dword v178, v[192:193], off
.LBB0_178:
	s_waitcnt vmcnt(1)
	v_pk_mul_f32 v[198:199], v[64:65], v[132:133]
	v_pk_mul_f32 v[132:133], v[80:81], v[132:133]
	v_pk_mul_f32 v[196:197], v[66:67], v[134:135]
	v_pk_fma_f32 v[198:199], v[80:81], v[128:129], v[198:199] neg_lo:[0,0,1] neg_hi:[0,0,1]
	v_pk_mul_f32 v[134:135], v[82:83], v[134:135]
	v_pk_fma_f32 v[128:129], v[64:65], v[128:129], v[132:133]
	v_ashrrev_i32_e32 v181, 31, v180
	s_waitcnt vmcnt(0)
	v_pk_mul_f32 v[192:193], v[70:71], v[142:143]
	v_pk_mul_f32 v[194:195], v[68:69], v[140:141]
	v_pk_fma_f32 v[196:197], v[82:83], v[130:131], v[196:197] neg_lo:[0,0,1] neg_hi:[0,0,1]
	v_pk_fma_f32 v[130:131], v[66:67], v[130:131], v[134:135]
	v_pk_mul_f32 v[134:135], v[128:129], v[178:179] op_sel_hi:[1,0]
	v_lshlrev_b64 v[128:129], 12, v[180:181]
	v_pk_fma_f32 v[192:193], v[86:87], v[138:139], v[192:193] neg_lo:[0,0,1] neg_hi:[0,0,1]
	v_pk_fma_f32 v[194:195], v[84:85], v[136:137], v[194:195] neg_lo:[0,0,1] neg_hi:[0,0,1]
	v_pk_mul_f32 v[142:143], v[86:87], v[142:143]
	v_pk_mul_f32 v[140:141], v[84:85], v[140:141]
	v_lshl_add_u64 v[128:129], s[58:59], 0, v[128:129]
	v_pk_mul_f32 v[192:193], v[192:193], v[178:179] op_sel_hi:[1,0]
	v_pk_mul_f32 v[194:195], v[194:195], v[178:179] op_sel_hi:[1,0]
	v_pk_mul_f32 v[196:197], v[196:197], v[178:179] op_sel_hi:[1,0]
	v_pk_mul_f32 v[198:199], v[198:199], v[178:179] op_sel_hi:[1,0]
	v_pk_fma_f32 v[138:139], v[70:71], v[138:139], v[142:143]
	v_pk_fma_f32 v[136:137], v[68:69], v[136:137], v[140:141]
	v_lshl_add_u64 v[128:129], s[26:27], 1, v[128:129]
	v_pk_mul_f32 v[138:139], v[138:139], v[178:179] op_sel_hi:[1,0]
	v_pk_mul_f32 v[136:137], v[136:137], v[178:179] op_sel_hi:[1,0]
	v_pk_mul_f32 v[132:133], v[130:131], v[178:179] op_sel_hi:[1,0]
	v_lshl_add_u64 v[140:141], v[128:129], 0, v[168:169]
	v_cvt_pk_bf16_f32 v128, v194, v195
	v_cvt_pk_bf16_f32 v129, v192, v193
	v_cvt_pk_bf16_f32 v130, v198, v199
	v_cvt_pk_bf16_f32 v131, v196, v197
	global_store_dwordx4 v[140:141], v[128:131], off sc1
	v_add_u32_e32 v180, 0x80, v166
	v_mov_b32_e32 v178, 1.0
	v_cvt_pk_bf16_f32 v128, v136, v137
	v_cvt_pk_bf16_f32 v129, v138, v139
	v_cvt_pk_bf16_f32 v130, v134, v135
	v_cvt_pk_bf16_f32 v131, v132, v133
	global_store_dwordx4 v[140:141], v[128:131], off offset:256 sc1
	s_and_b64 vcc, exec, s[6:7]
	v_mov_b32_e32 v182, 1.0
	v_lshlrev_b32_e32 v128, 9, v180
	v_and_b32_e32 v128, 0x1f9e00, v128
	v_mov_b32_e32 v129, v145
	v_lshl_add_u64 v[132:133], v[154:155], 0, v[128:129]
	v_lshl_add_u64 v[140:141], v[156:157], 0, v[128:129]
	global_load_dwordx4 v[128:131], v[132:133], off offset:16
	global_load_dwordx4 v[136:139], v[132:133], off
	s_nop 0
	global_load_dwordx4 v[132:135], v[140:141], off offset:16
	s_nop 0
	global_load_dwordx4 v[140:143], v[140:141], off
	s_cbranch_vccnz .LBB0_180
	v_mov_b32_e32 v171, v145
	v_lshl_add_u64 v[170:171], v[170:171], 2, s[8:9]
	global_load_dword v182, v[170:171], off
.LBB0_180:
	s_waitcnt vmcnt(1)
	v_pk_mul_f32 v[196:197], v[40:41], v[132:133]
	v_pk_mul_f32 v[132:133], v[56:57], v[132:133]
	v_pk_mul_f32 v[194:195], v[42:43], v[134:135]
	v_pk_fma_f32 v[196:197], v[56:57], v[128:129], v[196:197] neg_lo:[0,0,1] neg_hi:[0,0,1]
	v_pk_mul_f32 v[134:135], v[58:59], v[134:135]
	v_pk_fma_f32 v[128:129], v[40:41], v[128:129], v[132:133]
	v_ashrrev_i32_e32 v181, 31, v180
	s_waitcnt vmcnt(0)
	v_pk_mul_f32 v[170:171], v[46:47], v[142:143]
	v_pk_mul_f32 v[192:193], v[44:45], v[140:141]
	v_pk_fma_f32 v[194:195], v[58:59], v[130:131], v[194:195] neg_lo:[0,0,1] neg_hi:[0,0,1]
	v_pk_fma_f32 v[130:131], v[42:43], v[130:131], v[134:135]
	v_pk_mul_f32 v[134:135], v[128:129], v[182:183] op_sel_hi:[1,0]
	v_lshlrev_b64 v[128:129], 12, v[180:181]
	v_pk_fma_f32 v[170:171], v[62:63], v[138:139], v[170:171] neg_lo:[0,0,1] neg_hi:[0,0,1]
	v_pk_fma_f32 v[192:193], v[60:61], v[136:137], v[192:193] neg_lo:[0,0,1] neg_hi:[0,0,1]
	v_pk_mul_f32 v[142:143], v[62:63], v[142:143]
	v_pk_mul_f32 v[140:141], v[60:61], v[140:141]
	v_lshl_add_u64 v[128:129], s[58:59], 0, v[128:129]
	v_pk_mul_f32 v[170:171], v[170:171], v[182:183] op_sel_hi:[1,0]
	v_pk_mul_f32 v[192:193], v[192:193], v[182:183] op_sel_hi:[1,0]
	v_pk_mul_f32 v[194:195], v[194:195], v[182:183] op_sel_hi:[1,0]
	v_pk_mul_f32 v[196:197], v[196:197], v[182:183] op_sel_hi:[1,0]
	v_pk_fma_f32 v[138:139], v[46:47], v[138:139], v[142:143]
	v_pk_fma_f32 v[136:137], v[44:45], v[136:137], v[140:141]
	v_lshl_add_u64 v[128:129], s[26:27], 1, v[128:129]
	v_mov_b32_e32 v169, v145
	v_pk_mul_f32 v[138:139], v[138:139], v[182:183] op_sel_hi:[1,0]
	v_pk_mul_f32 v[136:137], v[136:137], v[182:183] op_sel_hi:[1,0]
	v_pk_mul_f32 v[132:133], v[130:131], v[182:183] op_sel_hi:[1,0]
	v_lshl_add_u64 v[140:141], v[128:129], 0, v[168:169]
	v_cvt_pk_bf16_f32 v128, v192, v193
	v_cvt_pk_bf16_f32 v129, v170, v171
	v_cvt_pk_bf16_f32 v130, v196, v197
	v_cvt_pk_bf16_f32 v131, v194, v195
	global_store_dwordx4 v[140:141], v[128:131], off sc1
	v_add_u32_e32 v170, 0x90, v166
	s_and_b64 vcc, exec, s[6:7]
	v_cvt_pk_bf16_f32 v128, v136, v137
	v_cvt_pk_bf16_f32 v129, v138, v139
	v_cvt_pk_bf16_f32 v130, v134, v135
	v_cvt_pk_bf16_f32 v131, v132, v133
	global_store_dwordx4 v[140:141], v[128:131], off offset:256 sc1
	s_nop 1
	v_lshlrev_b32_e32 v128, 9, v170
	v_and_b32_e32 v128, 0x1fbe00, v128
	v_mov_b32_e32 v129, v145
	v_lshl_add_u64 v[132:133], v[154:155], 0, v[128:129]
	v_lshl_add_u64 v[140:141], v[156:157], 0, v[128:129]
	global_load_dwordx4 v[128:131], v[132:133], off offset:16
	global_load_dwordx4 v[136:139], v[132:133], off
	s_nop 0
	global_load_dwordx4 v[132:135], v[140:141], off offset:16
	s_nop 0
	global_load_dwordx4 v[140:143], v[140:141], off
	s_cbranch_vccnz .LBB0_182
	v_mov_b32_e32 v173, v145
	v_lshl_add_u64 v[172:173], v[172:173], 2, s[8:9]
	global_load_dword v178, v[172:173], off
.LBB0_182:
	s_waitcnt vmcnt(1)
	v_pk_mul_f32 v[194:195], v[24:25], v[132:133]
	v_pk_mul_f32 v[132:133], v[48:49], v[132:133]
	v_pk_mul_f32 v[192:193], v[26:27], v[134:135]
	v_pk_fma_f32 v[194:195], v[48:49], v[128:129], v[194:195] neg_lo:[0,0,1] neg_hi:[0,0,1]
	v_pk_mul_f32 v[134:135], v[50:51], v[134:135]
	v_pk_fma_f32 v[128:129], v[24:25], v[128:129], v[132:133]
	v_ashrrev_i32_e32 v171, 31, v170
	s_waitcnt vmcnt(0)
	v_pk_mul_f32 v[172:173], v[30:31], v[142:143]
	v_pk_mul_f32 v[180:181], v[28:29], v[140:141]
	v_pk_fma_f32 v[192:193], v[50:51], v[130:131], v[192:193] neg_lo:[0,0,1] neg_hi:[0,0,1]
	v_pk_fma_f32 v[130:131], v[26:27], v[130:131], v[134:135]
	v_pk_mul_f32 v[134:135], v[128:129], v[178:179] op_sel_hi:[1,0]
	v_lshlrev_b64 v[128:129], 12, v[170:171]
	v_pk_fma_f32 v[172:173], v[54:55], v[138:139], v[172:173] neg_lo:[0,0,1] neg_hi:[0,0,1]
	v_pk_fma_f32 v[180:181], v[52:53], v[136:137], v[180:181] neg_lo:[0,0,1] neg_hi:[0,0,1]
	v_pk_mul_f32 v[142:143], v[54:55], v[142:143]
	v_pk_mul_f32 v[140:141], v[52:53], v[140:141]
	v_lshl_add_u64 v[128:129], s[58:59], 0, v[128:129]
	v_pk_mul_f32 v[172:173], v[172:173], v[178:179] op_sel_hi:[1,0]
	v_pk_mul_f32 v[180:181], v[180:181], v[178:179] op_sel_hi:[1,0]
	v_pk_mul_f32 v[192:193], v[192:193], v[178:179] op_sel_hi:[1,0]
	v_pk_mul_f32 v[194:195], v[194:195], v[178:179] op_sel_hi:[1,0]
	v_pk_fma_f32 v[138:139], v[30:31], v[138:139], v[142:143]
	v_pk_fma_f32 v[136:137], v[28:29], v[136:137], v[140:141]
	v_lshl_add_u64 v[128:129], s[26:27], 1, v[128:129]
	v_pk_mul_f32 v[138:139], v[138:139], v[178:179] op_sel_hi:[1,0]
	v_pk_mul_f32 v[136:137], v[136:137], v[178:179] op_sel_hi:[1,0]
	v_pk_mul_f32 v[132:133], v[130:131], v[178:179] op_sel_hi:[1,0]
	v_lshl_add_u64 v[140:141], v[128:129], 0, v[168:169]
	v_cvt_pk_bf16_f32 v128, v180, v181
	v_cvt_pk_bf16_f32 v129, v172, v173
	v_cvt_pk_bf16_f32 v130, v194, v195
	v_cvt_pk_bf16_f32 v131, v192, v193
	global_store_dwordx4 v[140:141], v[128:131], off sc1
	v_add_u32_e32 v172, 0xa0, v166
	v_mov_b32_e32 v170, 1.0
	v_cvt_pk_bf16_f32 v128, v136, v137
	v_cvt_pk_bf16_f32 v129, v138, v139
	v_cvt_pk_bf16_f32 v130, v134, v135
	v_cvt_pk_bf16_f32 v131, v132, v133
	global_store_dwordx4 v[140:141], v[128:131], off offset:256 sc1
	s_and_b64 vcc, exec, s[6:7]
	v_mov_b32_e32 v178, 1.0
	v_lshlrev_b32_e32 v128, 9, v172
	v_and_b32_e32 v128, 0x1fde00, v128
	v_mov_b32_e32 v129, v145
	v_lshl_add_u64 v[132:133], v[154:155], 0, v[128:129]
	v_lshl_add_u64 v[140:141], v[156:157], 0, v[128:129]
	global_load_dwordx4 v[128:131], v[132:133], off offset:16
	global_load_dwordx4 v[136:139], v[132:133], off
	s_nop 0
	global_load_dwordx4 v[132:135], v[140:141], off offset:16
	s_nop 0
	global_load_dwordx4 v[140:143], v[140:141], off
	s_cbranch_vccnz .LBB0_184
	v_mov_b32_e32 v175, v145
	v_lshl_add_u64 v[174:175], v[174:175], 2, s[8:9]
	global_load_dword v178, v[174:175], off
.LBB0_184:
	s_waitcnt vmcnt(1)
	v_pk_mul_f32 v[194:195], v[8:9], v[132:133]
	v_pk_mul_f32 v[132:133], v[32:33], v[132:133]
	v_pk_mul_f32 v[192:193], v[10:11], v[134:135]
	v_pk_fma_f32 v[194:195], v[32:33], v[128:129], v[194:195] neg_lo:[0,0,1] neg_hi:[0,0,1]
	v_pk_mul_f32 v[134:135], v[34:35], v[134:135]
	v_pk_fma_f32 v[128:129], v[8:9], v[128:129], v[132:133]
	v_ashrrev_i32_e32 v173, 31, v172
	s_waitcnt vmcnt(0)
	v_pk_mul_f32 v[174:175], v[14:15], v[142:143]
	v_pk_mul_f32 v[180:181], v[12:13], v[140:141]
	v_pk_fma_f32 v[192:193], v[34:35], v[130:131], v[192:193] neg_lo:[0,0,1] neg_hi:[0,0,1]
	v_pk_fma_f32 v[130:131], v[10:11], v[130:131], v[134:135]
	v_pk_mul_f32 v[134:135], v[128:129], v[178:179] op_sel_hi:[1,0]
	v_lshlrev_b64 v[128:129], 12, v[172:173]
	v_pk_fma_f32 v[174:175], v[38:39], v[138:139], v[174:175] neg_lo:[0,0,1] neg_hi:[0,0,1]
	v_pk_fma_f32 v[180:181], v[36:37], v[136:137], v[180:181] neg_lo:[0,0,1] neg_hi:[0,0,1]
	v_pk_mul_f32 v[142:143], v[38:39], v[142:143]
	v_pk_mul_f32 v[140:141], v[36:37], v[140:141]
	v_lshl_add_u64 v[128:129], s[58:59], 0, v[128:129]
	v_pk_mul_f32 v[174:175], v[174:175], v[178:179] op_sel_hi:[1,0]
	v_pk_mul_f32 v[180:181], v[180:181], v[178:179] op_sel_hi:[1,0]
	v_pk_mul_f32 v[192:193], v[192:193], v[178:179] op_sel_hi:[1,0]
	v_pk_mul_f32 v[194:195], v[194:195], v[178:179] op_sel_hi:[1,0]
	v_pk_fma_f32 v[138:139], v[14:15], v[138:139], v[142:143]
	v_pk_fma_f32 v[136:137], v[12:13], v[136:137], v[140:141]
	v_lshl_add_u64 v[128:129], s[26:27], 1, v[128:129]
	v_mov_b32_e32 v169, v145
	v_pk_mul_f32 v[138:139], v[138:139], v[178:179] op_sel_hi:[1,0]
	v_pk_mul_f32 v[136:137], v[136:137], v[178:179] op_sel_hi:[1,0]
	v_pk_mul_f32 v[132:133], v[130:131], v[178:179] op_sel_hi:[1,0]
	v_lshl_add_u64 v[140:141], v[128:129], 0, v[168:169]
	v_cvt_pk_bf16_f32 v128, v180, v181
	v_cvt_pk_bf16_f32 v129, v174, v175
	v_cvt_pk_bf16_f32 v130, v194, v195
	v_cvt_pk_bf16_f32 v131, v192, v193
	global_store_dwordx4 v[140:141], v[128:131], off sc1
	v_add_u32_e32 v172, 0xb0, v166
	s_and_b64 vcc, exec, s[6:7]
	v_cvt_pk_bf16_f32 v128, v136, v137
	v_cvt_pk_bf16_f32 v129, v138, v139
	v_cvt_pk_bf16_f32 v130, v134, v135
	v_cvt_pk_bf16_f32 v131, v132, v133
	global_store_dwordx4 v[140:141], v[128:131], off offset:256 sc1
	s_nop 1
	v_lshlrev_b32_e32 v128, 9, v172
	v_and_b32_e32 v128, 0x1ffe00, v128
	v_mov_b32_e32 v129, v145
	v_lshl_add_u64 v[132:133], v[154:155], 0, v[128:129]
	v_lshl_add_u64 v[140:141], v[156:157], 0, v[128:129]
	global_load_dwordx4 v[128:131], v[132:133], off offset:16
	s_nop 0
	global_load_dwordx4 v[132:135], v[132:133], off
	s_nop 0
	global_load_dwordx4 v[136:139], v[140:141], off offset:16
	s_nop 0
	global_load_dwordx4 v[140:143], v[140:141], off
	s_cbranch_vccnz .LBB0_186
	v_mov_b32_e32 v177, v145
	v_lshl_add_u64 v[170:171], v[176:177], 2, s[8:9]
	global_load_dword v170, v[170:171], off
.LBB0_186:
	s_waitcnt vmcnt(1)
	v_pk_mul_f32 v[192:193], v[0:1], v[136:137]
	v_pk_mul_f32 v[136:137], v[16:17], v[136:137]
	v_ashrrev_i32_e32 v173, 31, v172
	s_waitcnt vmcnt(0)
	v_pk_mul_f32 v[174:175], v[6:7], v[142:143]
	v_pk_mul_f32 v[176:177], v[4:5], v[140:141]
	v_pk_mul_f32 v[180:181], v[2:3], v[138:139]
	v_pk_fma_f32 v[192:193], v[16:17], v[128:129], v[192:193] neg_lo:[0,0,1] neg_hi:[0,0,1]
	v_pk_fma_f32 v[128:129], v[0:1], v[128:129], v[136:137]
	v_lshlrev_b64 v[136:137], 12, v[172:173]
	v_pk_fma_f32 v[174:175], v[22:23], v[134:135], v[174:175] neg_lo:[0,0,1] neg_hi:[0,0,1]
	v_pk_fma_f32 v[176:177], v[20:21], v[132:133], v[176:177] neg_lo:[0,0,1] neg_hi:[0,0,1]
	v_pk_fma_f32 v[180:181], v[18:19], v[130:131], v[180:181] neg_lo:[0,0,1] neg_hi:[0,0,1]
	v_pk_mul_f32 v[142:143], v[22:23], v[142:143]
	v_pk_mul_f32 v[140:141], v[20:21], v[140:141]
	v_pk_mul_f32 v[138:139], v[18:19], v[138:139]
	v_lshl_add_u64 v[136:137], s[58:59], 0, v[136:137]
	v_pk_mul_f32 v[174:175], v[174:175], v[170:171] op_sel_hi:[1,0]
	v_pk_mul_f32 v[176:177], v[176:177], v[170:171] op_sel_hi:[1,0]
	v_pk_mul_f32 v[180:181], v[180:181], v[170:171] op_sel_hi:[1,0]
	v_pk_mul_f32 v[192:193], v[192:193], v[170:171] op_sel_hi:[1,0]
	v_pk_fma_f32 v[134:135], v[6:7], v[134:135], v[142:143]
	v_pk_fma_f32 v[132:133], v[4:5], v[132:133], v[140:141]
	v_pk_fma_f32 v[130:131], v[2:3], v[130:131], v[138:139]
	v_lshl_add_u64 v[136:137], s[26:27], 1, v[136:137]
	v_pk_mul_f32 v[132:133], v[132:133], v[170:171] op_sel_hi:[1,0]
	v_pk_mul_f32 v[134:135], v[134:135], v[170:171] op_sel_hi:[1,0]
	v_pk_mul_f32 v[130:131], v[130:131], v[170:171] op_sel_hi:[1,0]
	v_pk_mul_f32 v[128:129], v[128:129], v[170:171] op_sel_hi:[1,0]
	v_lshl_add_u64 v[136:137], v[136:137], 0, v[168:169]
	v_cvt_pk_bf16_f32 v138, v176, v177
	v_cvt_pk_bf16_f32 v139, v174, v175
	v_cvt_pk_bf16_f32 v140, v192, v193
	v_cvt_pk_bf16_f32 v141, v180, v181
	global_store_dwordx4 v[136:137], v[138:141], off sc1
	s_branch .LBB0_189
.LBB0_187:
	s_and_b64 vcc, exec, s[6:7]
	s_cbranch_vccz .LBB0_189
	v_ashrrev_i32_e32 v167, 31, v166
	v_lshl_add_u32 v128, s14, 8, v183
	v_mov_b32_e32 v129, v145
	v_lshlrev_b64 v[130:131], 12, v[166:167]
	v_lshl_add_u64 v[130:131], s[72:73], 0, v[130:131]
	v_lshlrev_b64 v[128:129], 1, v[128:129]
	v_lshl_add_u64 v[130:131], v[130:131], 0, v[128:129]
	s_mov_b64 s[6:7], 0x80000
	v_cvt_pk_bf16_f32 v68, v68, v69
	v_cvt_pk_bf16_f32 v69, v70, v71
	v_cvt_pk_bf16_f32 v70, v64, v65
	v_lshl_add_u64 v[64:65], v[130:131], 0, s[6:7]
	s_mov_b32 s6, 0x80000
	v_cvt_pk_bf16_f32 v60, v60, v61
	v_cvt_pk_bf16_f32 v61, v62, v63
	v_cvt_pk_bf16_f32 v62, v56, v57
	v_add_co_u32_e32 v56, vcc, s6, v130
	v_cvt_pk_bf16_f32 v44, v44, v45
	v_cvt_pk_bf16_f32 v45, v46, v47
	v_cvt_pk_bf16_f32 v46, v40, v41
	v_cvt_pk_bf16_f32 v47, v42, v43
	s_mov_b64 s[6:7], 0x90000
	v_cvt_pk_bf16_f32 v108, v108, v109
	v_cvt_pk_bf16_f32 v109, v110, v111
	v_cvt_pk_bf16_f32 v110, v104, v105
	v_or_b32_e32 v104, 16, v166
	v_addc_co_u32_e32 v57, vcc, 0, v131, vcc
	global_store_dwordx4 v[64:65], v[44:47], off offset:256 sc1
	v_ashrrev_i32_e32 v105, 31, v104
	v_cvt_pk_bf16_f32 v92, v92, v93
	v_lshl_add_u64 v[44:45], v[130:131], 0, s[6:7]
	s_mov_b32 s6, 0x90000
	v_cvt_pk_bf16_f32 v93, v94, v95
	v_cvt_pk_bf16_f32 v94, v88, v89
	v_or_b32_e32 v88, 32, v166
	v_add_co_u32_e32 v46, vcc, s6, v130
	v_cvt_pk_bf16_f32 v28, v28, v29
	v_cvt_pk_bf16_f32 v29, v30, v31
	v_cvt_pk_bf16_f32 v30, v24, v25
	v_cvt_pk_bf16_f32 v31, v26, v27
	s_mov_b64 s[6:7], 0xa0000
	v_lshlrev_b64 v[104:105], 12, v[104:105]
	v_ashrrev_i32_e32 v89, 31, v88
	v_cvt_pk_bf16_f32 v76, v76, v77
	v_cvt_pk_bf16_f32 v77, v78, v79
	v_cvt_pk_bf16_f32 v78, v72, v73
	v_or_b32_e32 v72, 48, v166
	v_addc_co_u32_e32 v47, vcc, 0, v131, vcc
	global_store_dwordx4 v[44:45], v[28:31], off offset:256 sc1
	v_cvt_pk_bf16_f32 v111, v106, v107
	v_lshl_add_u64 v[104:105], s[72:73], 0, v[104:105]
	v_lshl_add_u64 v[28:29], v[130:131], 0, s[6:7]
	s_mov_b32 s6, 0xa0000
	v_lshlrev_b64 v[88:89], 12, v[88:89]
	v_ashrrev_i32_e32 v73, 31, v72
	v_add_co_u32_e32 v30, vcc, s6, v130
	global_store_dwordx4 v[130:131], v[108:111], off offset:256 sc1
	v_cvt_pk_bf16_f32 v95, v90, v91
	v_lshl_add_u64 v[88:89], s[72:73], 0, v[88:89]
	v_lshl_add_u64 v[108:109], v[104:105], 0, v[128:129]
	v_lshlrev_b64 v[72:73], 12, v[72:73]
	v_addc_co_u32_e32 v31, vcc, 0, v131, vcc
	v_cvt_pk_bf16_f32 v12, v12, v13
	v_cvt_pk_bf16_f32 v13, v14, v15
	v_cvt_pk_bf16_f32 v14, v8, v9
	v_cvt_pk_bf16_f32 v15, v10, v11
	v_cvt_pk_bf16_f32 v124, v124, v125
	v_cvt_pk_bf16_f32 v125, v126, v127
	v_cvt_pk_bf16_f32 v126, v120, v121
	v_cvt_pk_bf16_f32 v127, v122, v123
	global_store_dwordx4 v[108:109], v[92:95], off offset:256 sc1
	v_cvt_pk_bf16_f32 v79, v74, v75
	v_lshl_add_u64 v[72:73], s[72:73], 0, v[72:73]
	v_lshl_add_u64 v[92:93], v[88:89], 0, v[128:129]
	global_store_dwordx4 v[28:29], v[12:15], off offset:256 sc1
	s_mov_b64 s[6:7], 0xb0000
	global_store_dwordx4 v[130:131], v[124:127], off sc1
	v_add_co_u32_e32 v12, vcc, 0xb0000, v130
	global_store_dwordx4 v[92:93], v[76:79], off offset:256 sc1
	v_lshl_add_u64 v[136:137], v[130:131], 0, s[6:7]
	v_addc_co_u32_e32 v13, vcc, 0, v131, vcc
	v_lshl_add_u64 v[76:77], v[72:73], 0, v[128:129]
	v_mov_b64_e32 v[134:135], v[6:7]
	v_mov_b64_e32 v[130:131], v[2:3]
	v_cvt_pk_bf16_f32 v104, v116, v117
	v_cvt_pk_bf16_f32 v105, v118, v119
	v_cvt_pk_bf16_f32 v106, v112, v113
	v_cvt_pk_bf16_f32 v107, v114, v115
	v_cvt_pk_bf16_f32 v88, v100, v101
	v_cvt_pk_bf16_f32 v89, v102, v103
	v_cvt_pk_bf16_f32 v90, v96, v97
	v_cvt_pk_bf16_f32 v91, v98, v99
	v_cvt_pk_bf16_f32 v72, v84, v85
	v_cvt_pk_bf16_f32 v73, v86, v87
	v_cvt_pk_bf16_f32 v74, v80, v81
	v_cvt_pk_bf16_f32 v75, v82, v83
	v_cvt_pk_bf16_f32 v71, v66, v67
	v_cvt_pk_bf16_f32 v63, v58, v59
	v_cvt_pk_bf16_f32 v40, v52, v53
	v_cvt_pk_bf16_f32 v41, v54, v55
	v_cvt_pk_bf16_f32 v42, v48, v49
	v_cvt_pk_bf16_f32 v43, v50, v51
	v_cvt_pk_bf16_f32 v24, v36, v37
	v_cvt_pk_bf16_f32 v25, v38, v39
	v_cvt_pk_bf16_f32 v26, v32, v33
	v_cvt_pk_bf16_f32 v27, v34, v35
	v_cvt_pk_bf16_f32 v8, v20, v21
	v_cvt_pk_bf16_f32 v9, v22, v23
	v_cvt_pk_bf16_f32 v10, v16, v17
	v_cvt_pk_bf16_f32 v11, v18, v19
	v_mov_b64_e32 v[132:133], v[4:5]
	v_mov_b64_e32 v[128:129], v[0:1]
	global_store_dwordx4 v[108:109], v[104:107], off sc1
	global_store_dwordx4 v[92:93], v[88:91], off sc1
	global_store_dwordx4 v[76:77], v[72:75], off sc1
	global_store_dwordx4 v[76:77], v[68:71], off offset:256 sc1
	global_store_dwordx4 v[56:57], v[60:63], off sc1
	global_store_dwordx4 v[46:47], v[40:43], off sc1
	global_store_dwordx4 v[30:31], v[24:27], off sc1
	global_store_dwordx4 v[12:13], v[8:11], off sc1
.LBB0_189:
	v_cvt_pk_bf16_f32 v0, v132, v133
	v_cvt_pk_bf16_f32 v1, v134, v135
	v_cvt_pk_bf16_f32 v2, v128, v129
	v_cvt_pk_bf16_f32 v3, v130, v131
	s_andn2_b64 vcc, exec, s[4:5]
	s_mov_b64 s[4:5], -1
	global_store_dwordx4 v[136:137], v[0:3], off offset:256 sc1
	s_cbranch_vccnz .LBB0_158
	s_andn2_b64 vcc, exec, s[0:1]
	s_cbranch_vccnz .LBB0_157
	s_barrier
	s_branch .LBB0_157

.LBB0_209:
	v_lshl_add_u32 v144, s16, 8, v140
	v_lshl_or_b32 v146, s48, 8, v141
	v_ashrrev_i32_e32 v145, 31, v144
	v_ashrrev_i32_e32 v147, 31, v146
	v_lshlrev_b64 v[148:149], 15, v[144:145]
	v_lshl_add_u64 v[148:149], s[10:11], 0, v[148:149]
	v_lshlrev_b64 v[146:147], 1, v[146:147]
	v_lshl_add_u64 v[148:149], v[148:149], 0, v[146:147]
	s_mov_b32 s13, 0x400000
	s_mov_b64 s[26:27], 0x400000
	v_cvt_pk_bf16_f32 v60, v60, v61
	v_cvt_pk_bf16_f32 v61, v62, v63
	v_cvt_pk_bf16_f32 v62, v56, v57
	v_add_co_u32_e32 v56, vcc, s13, v148
	v_cvt_pk_bf16_f32 v68, v68, v69
	v_cvt_pk_bf16_f32 v69, v70, v71
	v_cvt_pk_bf16_f32 v70, v64, v65
	v_lshl_add_u64 v[64:65], v[148:149], 0, s[26:27]
	v_addc_co_u32_e32 v57, vcc, 0, v149, vcc
	v_cvt_pk_bf16_f32 v44, v44, v45
	v_cvt_pk_bf16_f32 v45, v46, v47
	v_cvt_pk_bf16_f32 v46, v40, v41
	v_cvt_pk_bf16_f32 v47, v42, v43
	s_mov_b32 s13, 0x480000
	v_cvt_pk_bf16_f32 v108, v108, v109
	v_cvt_pk_bf16_f32 v109, v110, v111
	v_cvt_pk_bf16_f32 v110, v104, v105
	v_or_b32_e32 v104, 16, v144
	global_store_dwordx4 v[64:65], v[44:47], off offset:256 sc1
	s_mov_b64 s[26:27], 0x480000
	v_ashrrev_i32_e32 v105, 31, v104
	v_add_co_u32_e32 v46, vcc, s13, v148
	v_cvt_pk_bf16_f32 v92, v92, v93
	v_cvt_pk_bf16_f32 v93, v94, v95
	v_cvt_pk_bf16_f32 v94, v88, v89
	v_or_b32_e32 v88, 32, v144
	v_lshl_add_u64 v[44:45], v[148:149], 0, s[26:27]
	v_addc_co_u32_e32 v47, vcc, 0, v149, vcc
	v_cvt_pk_bf16_f32 v28, v28, v29
	v_cvt_pk_bf16_f32 v29, v30, v31
	v_cvt_pk_bf16_f32 v30, v24, v25
	v_cvt_pk_bf16_f32 v31, v26, v27
	s_mov_b32 s13, 0x500000
	v_lshlrev_b64 v[104:105], 15, v[104:105]
	v_ashrrev_i32_e32 v89, 31, v88
	v_cvt_pk_bf16_f32 v76, v76, v77
	v_cvt_pk_bf16_f32 v77, v78, v79
	v_cvt_pk_bf16_f32 v78, v72, v73
	v_or_b32_e32 v72, 48, v144
	global_store_dwordx4 v[44:45], v[28:31], off offset:256 sc1
	s_mov_b64 s[26:27], 0x500000
	v_cvt_pk_bf16_f32 v111, v106, v107
	v_add_co_u32_e32 v30, vcc, s13, v148
	v_lshl_add_u64 v[104:105], s[10:11], 0, v[104:105]
	v_lshlrev_b64 v[88:89], 15, v[88:89]
	v_ashrrev_i32_e32 v73, 31, v72
	v_lshl_add_u64 v[28:29], v[148:149], 0, s[26:27]
	v_addc_co_u32_e32 v31, vcc, 0, v149, vcc
	v_cvt_pk_bf16_f32 v12, v12, v13
	v_cvt_pk_bf16_f32 v13, v14, v15
	v_cvt_pk_bf16_f32 v14, v8, v9
	v_cvt_pk_bf16_f32 v15, v10, v11
	s_mov_b32 s13, 0x580000
	global_store_dwordx4 v[148:149], v[108:111], off offset:256 sc1
	v_cvt_pk_bf16_f32 v95, v90, v91
	v_lshl_add_u64 v[88:89], s[10:11], 0, v[88:89]
	v_lshl_add_u64 v[108:109], v[104:105], 0, v[146:147]
	v_lshlrev_b64 v[72:73], 15, v[72:73]
	global_store_dwordx4 v[28:29], v[12:15], off offset:256 sc1
	global_store_dwordx4 v[108:109], v[92:95], off offset:256 sc1
	v_cvt_pk_bf16_f32 v79, v74, v75
	v_add_co_u32_e32 v14, vcc, s13, v148
	v_lshl_add_u64 v[92:93], v[88:89], 0, v[146:147]
	v_lshl_add_u64 v[72:73], s[10:11], 0, v[72:73]
	s_mov_b64 s[26:27], 0x580000
	v_addc_co_u32_e32 v15, vcc, 0, v149, vcc
	v_cvt_pk_bf16_f32 v124, v124, v125
	v_cvt_pk_bf16_f32 v125, v126, v127
	v_cvt_pk_bf16_f32 v126, v120, v121
	v_cvt_pk_bf16_f32 v127, v122, v123
	v_cvt_pk_bf16_f32 v104, v116, v117
	v_cvt_pk_bf16_f32 v105, v118, v119
	v_cvt_pk_bf16_f32 v106, v112, v113
	v_cvt_pk_bf16_f32 v107, v114, v115
	v_cvt_pk_bf16_f32 v88, v100, v101
	v_cvt_pk_bf16_f32 v89, v102, v103
	v_cvt_pk_bf16_f32 v90, v96, v97
	v_cvt_pk_bf16_f32 v91, v98, v99
	global_store_dwordx4 v[92:93], v[76:79], off offset:256 sc1
	v_cvt_pk_bf16_f32 v74, v80, v81
	v_cvt_pk_bf16_f32 v75, v82, v83
	v_lshl_add_u64 v[76:77], v[72:73], 0, v[146:147]
	v_cvt_pk_bf16_f32 v72, v84, v85
	v_cvt_pk_bf16_f32 v73, v86, v87
	v_cvt_pk_bf16_f32 v71, v66, v67
	v_cvt_pk_bf16_f32 v63, v58, v59
	v_cvt_pk_bf16_f32 v40, v52, v53
	v_cvt_pk_bf16_f32 v41, v54, v55
	v_cvt_pk_bf16_f32 v42, v48, v49
	v_cvt_pk_bf16_f32 v43, v50, v51
	v_cvt_pk_bf16_f32 v24, v36, v37
	v_cvt_pk_bf16_f32 v25, v38, v39
	v_cvt_pk_bf16_f32 v26, v32, v33
	v_cvt_pk_bf16_f32 v27, v34, v35
	v_lshl_add_u64 v[12:13], v[148:149], 0, s[26:27]
	v_cvt_pk_bf16_f32 v8, v20, v21
	v_cvt_pk_bf16_f32 v9, v22, v23
	v_cvt_pk_bf16_f32 v10, v16, v17
	v_cvt_pk_bf16_f32 v11, v18, v19
	v_cvt_pk_bf16_f32 v4, v4, v5
	v_cvt_pk_bf16_f32 v5, v6, v7
	v_cvt_pk_bf16_f32 v6, v0, v1
	v_cvt_pk_bf16_f32 v7, v2, v3
	s_andn2_b64 vcc, exec, s[4:5]
	s_mov_b64 s[4:5], -1
	global_store_dwordx4 v[148:149], v[124:127], off sc1
	global_store_dwordx4 v[108:109], v[104:107], off sc1
	global_store_dwordx4 v[92:93], v[88:91], off sc1
	global_store_dwordx4 v[76:77], v[72:75], off sc1
	global_store_dwordx4 v[76:77], v[68:71], off offset:256 sc1
	global_store_dwordx4 v[56:57], v[60:63], off sc1
	global_store_dwordx4 v[46:47], v[40:43], off sc1
	global_store_dwordx4 v[30:31], v[24:27], off sc1
	global_store_dwordx4 v[14:15], v[8:11], off sc1
	global_store_dwordx4 v[12:13], v[4:7], off offset:256 sc1
	s_cbranch_vccnz .LBB0_198
	s_andn2_b64 vcc, exec, s[0:1]
	s_cbranch_vccnz .LBB0_197
	s_barrier
	s_branch .LBB0_197

.LBB0_391:
	global_load_dwordx4 v[0:3], v[12:13], off
	global_load_dwordx4 v[4:7], v[12:13], off offset:1024
	global_load_dwordx4 v[8:11], v[12:13], off offset:2048
	global_load_dwordx4 v[24:27], v[12:13], off offset:3072
	v_add_co_u32_e32 v40, vcc, 0xc000000, v12
	v_add_co_u32_e64 v14, s[0:1], s22, v12
	s_nop 0
	v_addc_co_u32_e32 v41, vcc, 0, v13, vcc
	global_load_dwordx4 v[28:31], v[40:41], off
	global_load_dwordx4 v[32:35], v[40:41], off offset:1024
	global_load_dwordx4 v[36:39], v[40:41], off offset:2048
	s_nop 0
	global_load_dwordx4 v[40:43], v[40:41], off offset:3072
	v_addc_co_u32_e64 v15, s[0:1], 0, v13, s[0:1]
	s_add_i32 s24, s24, s80
	v_lshl_add_u64 v[12:13], v[12:13], 0, s[20:21]
	s_cmpk_lt_i32 s24, 0x4000
	s_waitcnt vmcnt(7)
	v_lshlrev_b32_e32 v44, 16, v3
	v_and_b32_e32 v45, 0xffff0000, v3
	v_lshlrev_b32_e32 v46, 16, v2
	v_and_b32_e32 v47, 0xffff0000, v2
	v_lshlrev_b32_e32 v2, 16, v1
	v_and_b32_e32 v3, 0xffff0000, v1
	v_lshlrev_b32_e32 v48, 16, v0
	v_and_b32_e32 v49, 0xffff0000, v0
	s_waitcnt vmcnt(6)
	v_lshlrev_b32_e32 v0, 16, v7
	v_and_b32_e32 v1, 0xffff0000, v7
	v_lshlrev_b32_e32 v50, 16, v6
	v_and_b32_e32 v51, 0xffff0000, v6
	v_lshlrev_b32_e32 v6, 16, v5
	v_and_b32_e32 v7, 0xffff0000, v5
	v_lshlrev_b32_e32 v52, 16, v4
	v_and_b32_e32 v53, 0xffff0000, v4
	s_waitcnt vmcnt(5)
	v_lshlrev_b32_e32 v4, 16, v11
	v_and_b32_e32 v5, 0xffff0000, v11
	v_lshlrev_b32_e32 v54, 16, v10
	v_and_b32_e32 v55, 0xffff0000, v10
	v_lshlrev_b32_e32 v10, 16, v9
	v_and_b32_e32 v11, 0xffff0000, v9
	v_lshlrev_b32_e32 v56, 16, v8
	v_and_b32_e32 v57, 0xffff0000, v8
	s_waitcnt vmcnt(4)
	v_lshlrev_b32_e32 v8, 16, v27
	v_and_b32_e32 v9, 0xffff0000, v27
	v_lshlrev_b32_e32 v58, 16, v26
	v_and_b32_e32 v59, 0xffff0000, v26
	v_lshlrev_b32_e32 v26, 16, v25
	v_and_b32_e32 v27, 0xffff0000, v25
	v_lshlrev_b32_e32 v60, 16, v24
	v_and_b32_e32 v61, 0xffff0000, v24
	v_mul_f32_e32 v64, 0xbfb8aa3b, v46
	v_mul_f32_e32 v66, 0xbfb8aa3b, v2
	v_mul_f32_e32 v67, 0xbfb8aa3b, v3
	v_mul_f32_e32 v65, 0xbfb8aa3b, v47
	v_mul_f32_e32 v68, 0xbfb8aa3b, v48
	v_mul_f32_e32 v69, 0xbfb8aa3b, v49
	v_mul_f32_e32 v70, 0xbfb8aa3b, v44
	v_mul_f32_e32 v71, 0xbfb8aa3b, v45
	v_mul_f32_e32 v72, 0xbfb8aa3b, v50
	v_mul_f32_e32 v73, 0xbfb8aa3b, v51
	v_mul_f32_e32 v74, 0xbfb8aa3b, v6
	v_mul_f32_e32 v75, 0xbfb8aa3b, v7
	v_mul_f32_e32 v76, 0xbfb8aa3b, v52
	v_mul_f32_e32 v77, 0xbfb8aa3b, v53
	v_mul_f32_e32 v78, 0xbfb8aa3b, v0
	v_mul_f32_e32 v79, 0xbfb8aa3b, v1
	v_mul_f32_e32 v80, 0xbfb8aa3b, v54
	v_mul_f32_e32 v81, 0xbfb8aa3b, v55
	v_mul_f32_e32 v84, 0xbfb8aa3b, v56
	v_mul_f32_e32 v85, 0xbfb8aa3b, v57
	v_mul_f32_e32 v88, 0xbfb8aa3b, v58
	v_mul_f32_e32 v89, 0xbfb8aa3b, v59
	v_mul_f32_e32 v90, 0xbfb8aa3b, v26
	v_mul_f32_e32 v91, 0xbfb8aa3b, v27
	v_mul_f32_e32 v92, 0xbfb8aa3b, v60
	v_mul_f32_e32 v93, 0xbfb8aa3b, v61
	v_mul_f32_e32 v94, 0xbfb8aa3b, v8
	v_exp_f32_e32 v96, v64
	v_exp_f32_e32 v98, v66
	v_exp_f32_e32 v99, v67
	s_waitcnt vmcnt(3)
	v_lshlrev_b32_e32 v64, 16, v28
	v_mul_f32_e32 v95, 0xbfb8aa3b, v9
	v_lshlrev_b32_e32 v24, 16, v31
	v_and_b32_e32 v25, 0xffff0000, v31
	v_lshlrev_b32_e32 v62, 16, v30
	v_and_b32_e32 v63, 0xffff0000, v30
	v_exp_f32_e32 v97, v65
	v_lshlrev_b32_e32 v30, 16, v29
	v_and_b32_e32 v31, 0xffff0000, v29
	v_and_b32_e32 v65, 0xffff0000, v28
	v_exp_f32_e32 v100, v68
	v_exp_f32_e32 v101, v69
	v_exp_f32_e32 v102, v70
	v_exp_f32_e32 v103, v71
	s_waitcnt vmcnt(2)
	v_lshlrev_b32_e32 v28, 16, v35
	v_and_b32_e32 v29, 0xffff0000, v35
	v_lshlrev_b32_e32 v66, 16, v34
	v_and_b32_e32 v67, 0xffff0000, v34
	v_exp_f32_e32 v104, v72
	v_exp_f32_e32 v105, v73
	v_lshlrev_b32_e32 v34, 16, v33
	v_and_b32_e32 v35, 0xffff0000, v33
	v_exp_f32_e32 v106, v74
	v_exp_f32_e32 v107, v75
	v_lshlrev_b32_e32 v68, 16, v32
	v_and_b32_e32 v69, 0xffff0000, v32
	v_exp_f32_e32 v108, v76
	v_exp_f32_e32 v109, v77
	v_exp_f32_e32 v78, v78
	v_exp_f32_e32 v79, v79
	s_waitcnt vmcnt(1)
	v_lshlrev_b32_e32 v32, 16, v39
	v_and_b32_e32 v33, 0xffff0000, v39
	v_lshlrev_b32_e32 v70, 16, v38
	v_and_b32_e32 v71, 0xffff0000, v38
	v_exp_f32_e32 v80, v80
	v_exp_f32_e32 v81, v81
	v_lshlrev_b32_e32 v38, 16, v37
	v_and_b32_e32 v39, 0xffff0000, v37
	v_lshlrev_b32_e32 v72, 16, v36
	v_and_b32_e32 v73, 0xffff0000, v36
	v_exp_f32_e32 v84, v84
	v_exp_f32_e32 v85, v85
	s_waitcnt vmcnt(0)
	v_lshlrev_b32_e32 v36, 16, v43
	v_and_b32_e32 v37, 0xffff0000, v43
	v_lshlrev_b32_e32 v74, 16, v42
	v_and_b32_e32 v75, 0xffff0000, v42
	v_exp_f32_e32 v88, v88
	v_exp_f32_e32 v89, v89
	v_lshlrev_b32_e32 v42, 16, v41
	v_and_b32_e32 v43, 0xffff0000, v41
	v_exp_f32_e32 v41, v90
	v_exp_f32_e32 v90, v91
	v_lshlrev_b32_e32 v76, 16, v40
	v_and_b32_e32 v77, 0xffff0000, v40
	v_exp_f32_e32 v40, v92
	v_exp_f32_e32 v91, v93
	v_exp_f32_e32 v92, v94
	v_add_f32_e32 v94, 0, v64
	v_exp_f32_e32 v93, v95
	v_add_f32_e32 v95, 0, v68
	v_add_f32_e32 v110, 0, v72
	v_add_f32_e32 v111, 0, v76
	v_add_f32_e32 v94, v94, v65
	v_add_f32_e32 v95, v95, v69
	v_add_f32_e32 v110, v110, v73
	v_add_f32_e32 v111, v111, v77
	v_add_f32_e32 v94, v94, v30
	v_add_f32_e32 v95, v95, v34
	v_add_f32_e32 v110, v110, v38
	v_add_f32_e32 v111, v111, v42
	v_add_f32_e32 v98, 1.0, v98
	v_add_f32_e32 v99, 1.0, v99
	v_add_f32_e32 v94, v94, v31
	v_add_f32_e32 v96, 1.0, v96
	v_add_f32_e32 v97, 1.0, v97
	v_add_f32_e32 v100, 1.0, v100
	v_add_f32_e32 v101, 1.0, v101
	v_add_f32_e32 v104, 1.0, v104
	v_add_f32_e32 v105, 1.0, v105
	v_add_f32_e32 v108, 1.0, v108
	v_add_f32_e32 v109, 1.0, v109
	v_add_f32_e32 v95, v95, v35
	v_add_f32_e32 v112, 1.0, v78
	v_add_f32_e32 v113, 1.0, v79
	v_add_f32_e32 v114, 1.0, v80
	v_add_f32_e32 v115, 1.0, v81
	v_add_f32_e32 v118, 1.0, v84
	v_add_f32_e32 v119, 1.0, v85
	v_add_f32_e32 v110, v110, v39
	v_add_f32_e32 v122, 1.0, v88
	v_add_f32_e32 v123, 1.0, v89
	v_add_f32_e32 v126, 1.0, v40
	v_add_f32_e32 v127, 1.0, v91
	v_add_f32_e32 v111, v111, v43
	v_rcp_f32_e32 v78, v98
	v_rcp_f32_e32 v79, v99
	v_add_f32_e32 v130, v94, v62
	v_add_f32_e32 v124, 1.0, v41
	v_add_f32_e32 v128, 1.0, v92
	v_add_f32_e32 v129, 1.0, v93
	v_rcp_f32_e32 v40, v96
	v_rcp_f32_e32 v41, v97
	v_rcp_f32_e32 v80, v100
	v_rcp_f32_e32 v81, v101
	v_rcp_f32_e32 v84, v104
	v_rcp_f32_e32 v85, v105
	v_rcp_f32_e32 v88, v108
	v_rcp_f32_e32 v89, v109
	v_add_f32_e32 v108, v95, v66
	v_rcp_f32_e32 v92, v114
	v_rcp_f32_e32 v93, v115
	v_rcp_f32_e32 v96, v118
	v_rcp_f32_e32 v97, v119
	v_add_f32_e32 v109, v110, v70
	v_rcp_f32_e32 v100, v122
	v_rcp_f32_e32 v101, v123
	v_rcp_f32_e32 v104, v126
	v_rcp_f32_e32 v105, v127
	v_add_f32_e32 v110, v111, v74
	v_add_f32_e32 v111, v130, v63
	v_mul_f32_e32 v82, 0xbfb8aa3b, v10
	v_mul_f32_e32 v83, 0xbfb8aa3b, v11
	v_add_f32_e32 v108, v108, v67
	v_add_f32_e32 v109, v109, v71
	v_add_f32_e32 v110, v110, v75
	v_add_f32_e32 v111, v111, v24
	v_exp_f32_e32 v82, v82
	v_exp_f32_e32 v83, v83
	v_add_f32_e32 v108, v108, v28
	v_add_f32_e32 v109, v109, v32
	v_add_f32_e32 v110, v110, v36
	v_add_f32_e32 v111, v111, v25
	v_add_f32_e32 v108, v108, v29
	v_add_f32_e32 v109, v109, v33
	v_add_f32_e32 v110, v110, v37
	v_pk_mul_f32 v[2:3], v[78:79], v[2:3]
	ds_bpermute_b32 v78, v16, v111
	v_pk_mul_f32 v[40:41], v[40:41], v[46:47]
	v_pk_mul_f32 v[46:47], v[80:81], v[48:49]
	v_pk_mul_f32 v[48:49], v[84:85], v[50:51]
	v_pk_mul_f32 v[50:51], v[88:89], v[52:53]
	ds_bpermute_b32 v79, v16, v108
	v_pk_mul_f32 v[52:53], v[92:93], v[54:55]
	v_pk_mul_f32 v[54:55], v[96:97], v[56:57]
	ds_bpermute_b32 v80, v16, v109
	v_pk_mul_f32 v[56:57], v[100:101], v[58:59]
	v_pk_mul_f32 v[58:59], v[104:105], v[60:61]
	ds_bpermute_b32 v60, v16, v110
	v_add_f32_e32 v102, 1.0, v102
	v_add_f32_e32 v103, 1.0, v103
	v_add_f32_e32 v116, 1.0, v82
	v_add_f32_e32 v117, 1.0, v83
	v_rcp_f32_e32 v82, v102
	v_rcp_f32_e32 v83, v103
	s_waitcnt lgkmcnt(3)
	v_add_f32_e32 v61, v111, v78
	s_waitcnt lgkmcnt(2)
	v_add_f32_e32 v78, v108, v79
	s_waitcnt lgkmcnt(1)
	v_add_f32_e32 v79, v109, v80
	s_waitcnt lgkmcnt(0)
	v_add_f32_e32 v60, v110, v60
	ds_bpermute_b32 v80, v17, v61
	v_pk_mul_f32 v[44:45], v[82:83], v[44:45]
	ds_bpermute_b32 v81, v17, v78
	ds_bpermute_b32 v82, v17, v79
	ds_bpermute_b32 v83, v17, v60
	s_waitcnt lgkmcnt(3)
	v_add_f32_e32 v61, v61, v80
	ds_bpermute_b32 v80, v18, v61
	s_waitcnt lgkmcnt(3)
	v_add_f32_e32 v78, v78, v81
	s_waitcnt lgkmcnt(2)
	v_add_f32_e32 v79, v79, v82
	s_waitcnt lgkmcnt(1)
	v_add_f32_e32 v60, v60, v83
	ds_bpermute_b32 v81, v18, v78
	ds_bpermute_b32 v82, v18, v79
	ds_bpermute_b32 v83, v18, v60
	s_waitcnt lgkmcnt(3)
	v_add_f32_e32 v61, v61, v80
	ds_bpermute_b32 v80, v19, v61
	s_waitcnt lgkmcnt(3)
	v_add_f32_e32 v78, v78, v81
	s_waitcnt lgkmcnt(2)
	v_add_f32_e32 v79, v79, v82
	s_waitcnt lgkmcnt(1)
	v_add_f32_e32 v60, v60, v83
	ds_bpermute_b32 v81, v19, v78
	ds_bpermute_b32 v82, v19, v79
	ds_bpermute_b32 v83, v19, v60
	s_waitcnt lgkmcnt(3)
	v_add_f32_e32 v61, v61, v80
	ds_bpermute_b32 v80, v20, v61
	s_waitcnt lgkmcnt(3)
	v_add_f32_e32 v78, v78, v81
	s_waitcnt lgkmcnt(2)
	v_add_f32_e32 v79, v79, v82
	s_waitcnt lgkmcnt(1)
	v_add_f32_e32 v60, v60, v83
	ds_bpermute_b32 v81, v20, v78
	ds_bpermute_b32 v82, v20, v79
	ds_bpermute_b32 v83, v20, v60
	v_mul_f32_e32 v86, 0xbfb8aa3b, v4
	v_mul_f32_e32 v87, 0xbfb8aa3b, v5
	v_exp_f32_e32 v86, v86
	v_exp_f32_e32 v87, v87
	s_waitcnt lgkmcnt(3)
	v_add_f32_e32 v61, v61, v80
	s_waitcnt lgkmcnt(2)
	v_add_f32_e32 v78, v78, v81
	s_waitcnt lgkmcnt(1)
	v_add_f32_e32 v79, v79, v82
	s_waitcnt lgkmcnt(0)
	v_add_f32_e32 v60, v60, v83
	ds_bpermute_b32 v80, v21, v61
	ds_bpermute_b32 v81, v21, v78
	ds_bpermute_b32 v82, v21, v79
	ds_bpermute_b32 v83, v21, v60
	v_add_f32_e32 v106, 1.0, v106
	v_add_f32_e32 v107, 1.0, v107
	v_add_f32_e32 v120, 1.0, v86
	v_add_f32_e32 v121, 1.0, v87
	v_add_f32_e32 v125, 1.0, v90
	v_rcp_f32_e32 v86, v106
	v_rcp_f32_e32 v87, v107
	v_rcp_f32_e32 v90, v112
	v_rcp_f32_e32 v91, v113
	v_rcp_f32_e32 v94, v116
	v_rcp_f32_e32 v95, v117
	v_rcp_f32_e32 v98, v120
	v_rcp_f32_e32 v99, v121
	v_rcp_f32_e32 v106, v128
	v_rcp_f32_e32 v107, v129
	s_waitcnt lgkmcnt(3)
	v_add_f32_e32 v61, v61, v80
	s_waitcnt lgkmcnt(2)
	v_add_f32_e32 v78, v78, v81
	s_waitcnt lgkmcnt(1)
	v_add_f32_e32 v79, v79, v82
	s_waitcnt lgkmcnt(0)
	v_add_f32_e32 v81, v60, v83
	v_mul_f32_e32 v60, 0x3b000000, v61
	v_mul_f32_e32 v78, 0x3b000000, v78
	v_mul_f32_e32 v80, 0x3b000000, v79
	v_mul_f32_e32 v82, 0x3b000000, v81
	v_pk_add_f32 v[64:65], v[64:65], v[60:61] op_sel_hi:[1,0] neg_lo:[0,1] neg_hi:[0,1]
	v_pk_mul_f32 v[6:7], v[86:87], v[6:7]
	v_pk_mul_f32 v[0:1], v[90:91], v[0:1]
	v_pk_mul_f32 v[10:11], v[94:95], v[10:11]
	v_pk_mul_f32 v[4:5], v[98:99], v[4:5]
	v_pk_mul_f32 v[8:9], v[106:107], v[8:9]
	v_pk_add_f32 v[30:31], v[30:31], v[60:61] op_sel_hi:[1,0] neg_lo:[0,1] neg_hi:[0,1]
	v_pk_add_f32 v[62:63], v[62:63], v[60:61] op_sel_hi:[1,0] neg_lo:[0,1] neg_hi:[0,1]
	v_pk_add_f32 v[24:25], v[24:25], v[60:61] op_sel_hi:[1,0] neg_lo:[0,1] neg_hi:[0,1]
	v_pk_add_f32 v[60:61], v[68:69], v[78:79] op_sel_hi:[1,0] neg_lo:[0,1] neg_hi:[0,1]
	v_pk_add_f32 v[34:35], v[34:35], v[78:79] op_sel_hi:[1,0] neg_lo:[0,1] neg_hi:[0,1]
	v_pk_add_f32 v[66:67], v[66:67], v[78:79] op_sel_hi:[1,0] neg_lo:[0,1] neg_hi:[0,1]
	v_pk_add_f32 v[28:29], v[28:29], v[78:79] op_sel_hi:[1,0] neg_lo:[0,1] neg_hi:[0,1]
	v_pk_add_f32 v[68:69], v[72:73], v[80:81] op_sel_hi:[1,0] neg_lo:[0,1] neg_hi:[0,1]
	v_pk_add_f32 v[38:39], v[38:39], v[80:81] op_sel_hi:[1,0] neg_lo:[0,1] neg_hi:[0,1]
	v_pk_add_f32 v[70:71], v[70:71], v[80:81] op_sel_hi:[1,0] neg_lo:[0,1] neg_hi:[0,1]
	v_pk_add_f32 v[32:33], v[32:33], v[80:81] op_sel_hi:[1,0] neg_lo:[0,1] neg_hi:[0,1]
	v_pk_add_f32 v[72:73], v[76:77], v[82:83] op_sel_hi:[1,0] neg_lo:[0,1] neg_hi:[0,1]
	v_pk_add_f32 v[36:37], v[36:37], v[82:83] op_sel_hi:[1,0] neg_lo:[0,1] neg_hi:[0,1]
	v_pk_mul_f32 v[76:77], v[64:65], v[64:65]
	v_pk_add_f32 v[42:43], v[42:43], v[82:83] op_sel_hi:[1,0] neg_lo:[0,1] neg_hi:[0,1]
	v_pk_add_f32 v[74:75], v[74:75], v[82:83] op_sel_hi:[1,0] neg_lo:[0,1] neg_hi:[0,1]
	v_pk_mul_f32 v[78:79], v[30:31], v[30:31]
	v_pk_mul_f32 v[80:81], v[62:63], v[62:63]
	v_pk_mul_f32 v[82:83], v[24:25], v[24:25]
	v_pk_mul_f32 v[46:47], v[46:47], v[64:65]
	v_pk_mul_f32 v[2:3], v[2:3], v[30:31]
	v_pk_mul_f32 v[30:31], v[40:41], v[62:63]
	v_pk_mul_f32 v[24:25], v[44:45], v[24:25]
	v_pk_mul_f32 v[40:41], v[60:61], v[60:61]
	v_pk_mul_f32 v[44:45], v[34:35], v[34:35]
	v_pk_mul_f32 v[62:63], v[66:67], v[66:67]
	v_pk_mul_f32 v[64:65], v[28:29], v[28:29]
	v_pk_mul_f32 v[50:51], v[50:51], v[60:61]
	v_pk_mul_f32 v[6:7], v[6:7], v[34:35]
	v_pk_mul_f32 v[34:35], v[48:49], v[66:67]
	v_pk_mul_f32 v[28:29], v[0:1], v[28:29]
	v_pk_mul_f32 v[0:1], v[68:69], v[68:69]
	v_pk_mul_f32 v[48:49], v[38:39], v[38:39]
	v_pk_mul_f32 v[60:61], v[70:71], v[70:71]
	v_pk_mul_f32 v[66:67], v[32:33], v[32:33]
	v_pk_mul_f32 v[10:11], v[10:11], v[38:39]
	v_pk_mul_f32 v[38:39], v[52:53], v[70:71]
	v_pk_mul_f32 v[4:5], v[4:5], v[32:33]
	v_pk_mul_f32 v[32:33], v[72:73], v[72:73]
	v_pk_mul_f32 v[70:71], v[36:37], v[36:37]
	v_pk_mul_f32 v[8:9], v[8:9], v[36:37]
	v_add_f32_e32 v36, v76, v77
	v_add_f32_e32 v37, v40, v41
	v_add_f32_e32 v0, v0, v1
	v_add_f32_e32 v1, v32, v33
	v_add_f32_e32 v32, v78, v36
	v_add_f32_e32 v33, v44, v37
	v_add_f32_e32 v0, v48, v0
	v_add_f32_e32 v32, v79, v32
	v_pk_mul_f32 v[52:53], v[42:43], v[42:43]
	v_add_f32_e32 v33, v45, v33
	v_add_f32_e32 v0, v49, v0
	v_add_f32_e32 v32, v80, v32
	v_add_f32_e32 v1, v52, v1
	v_add_f32_e32 v33, v62, v33
	v_add_f32_e32 v0, v60, v0
	v_add_f32_e32 v32, v81, v32
	v_pk_mul_f32 v[54:55], v[54:55], v[68:69]
	v_pk_mul_f32 v[68:69], v[74:75], v[74:75]
	v_add_f32_e32 v1, v53, v1
	v_add_f32_e32 v33, v63, v33
	v_add_f32_e32 v0, v61, v0
	v_add_f32_e32 v32, v82, v32
	v_add_f32_e32 v1, v68, v1
	v_add_f32_e32 v33, v64, v33
	v_add_f32_e32 v0, v66, v0
	v_add_f32_e32 v32, v83, v32
	v_add_f32_e32 v1, v69, v1
	v_add_f32_e32 v33, v65, v33
	v_add_f32_e32 v0, v67, v0
	ds_bpermute_b32 v36, v16, v32
	v_add_f32_e32 v1, v70, v1
	ds_bpermute_b32 v37, v16, v33
	ds_bpermute_b32 v40, v16, v0
	v_add_f32_e32 v1, v71, v1
	ds_bpermute_b32 v41, v16, v1
	s_waitcnt lgkmcnt(3)
	v_add_f32_e32 v32, v32, v36
	s_waitcnt lgkmcnt(2)
	v_add_f32_e32 v33, v33, v37
	s_waitcnt lgkmcnt(1)
	v_add_f32_e32 v0, v0, v40
	ds_bpermute_b32 v36, v17, v32
	ds_bpermute_b32 v37, v17, v33
	ds_bpermute_b32 v40, v17, v0
	s_waitcnt lgkmcnt(3)
	v_add_f32_e32 v1, v1, v41
	ds_bpermute_b32 v41, v17, v1
	s_waitcnt lgkmcnt(3)
	v_add_f32_e32 v32, v32, v36
	s_waitcnt lgkmcnt(2)
	v_add_f32_e32 v33, v33, v37
	s_waitcnt lgkmcnt(1)
	v_add_f32_e32 v0, v0, v40
	ds_bpermute_b32 v36, v18, v32
	ds_bpermute_b32 v37, v18, v33
	ds_bpermute_b32 v40, v18, v0
	s_waitcnt lgkmcnt(3)
	v_add_f32_e32 v1, v1, v41
	ds_bpermute_b32 v41, v18, v1
	s_waitcnt lgkmcnt(3)
	v_add_f32_e32 v32, v32, v36
	s_waitcnt lgkmcnt(2)
	v_add_f32_e32 v33, v33, v37
	s_waitcnt lgkmcnt(1)
	v_add_f32_e32 v0, v0, v40
	ds_bpermute_b32 v36, v19, v32
	ds_bpermute_b32 v37, v19, v33
	ds_bpermute_b32 v40, v19, v0
	s_waitcnt lgkmcnt(3)
	v_add_f32_e32 v1, v1, v41
	ds_bpermute_b32 v41, v19, v1
	s_waitcnt lgkmcnt(3)
	v_add_f32_e32 v32, v32, v36
	s_waitcnt lgkmcnt(2)
	v_add_f32_e32 v33, v33, v37
	s_waitcnt lgkmcnt(1)
	v_add_f32_e32 v0, v0, v40
	ds_bpermute_b32 v36, v20, v32
	ds_bpermute_b32 v37, v20, v33
	ds_bpermute_b32 v40, v20, v0
	s_waitcnt lgkmcnt(3)
	v_add_f32_e32 v1, v1, v41
	ds_bpermute_b32 v41, v20, v1
	s_waitcnt lgkmcnt(3)
	v_add_f32_e32 v32, v32, v36
	s_waitcnt lgkmcnt(2)
	v_add_f32_e32 v33, v33, v37
	s_waitcnt lgkmcnt(1)
	v_add_f32_e32 v0, v0, v40
	ds_bpermute_b32 v36, v21, v32
	ds_bpermute_b32 v37, v21, v33
	ds_bpermute_b32 v40, v21, v0
	s_waitcnt lgkmcnt(3)
	v_add_f32_e32 v1, v1, v41
	ds_bpermute_b32 v41, v21, v1
	s_waitcnt lgkmcnt(3)
	v_add_f32_e32 v32, v32, v36
	s_waitcnt lgkmcnt(2)
	v_add_f32_e32 v33, v33, v37
	s_waitcnt lgkmcnt(1)
	v_add_f32_e32 v0, v0, v40
	v_fmamk_f32 v32, v32, 0x3b000000, v22
	v_fmamk_f32 v33, v33, 0x3b000000, v22
	v_fmamk_f32 v0, v0, 0x3b000000, v22
	v_mul_f32_e32 v36, 0x4f800000, v32
	v_cmp_gt_f32_e64 s[6:7], s3, v32
	s_waitcnt lgkmcnt(0)
	v_add_f32_e32 v1, v1, v41
	v_mul_f32_e32 v37, 0x4f800000, v33
	v_cmp_gt_f32_e32 vcc, s3, v33
	v_mul_f32_e32 v40, 0x4f800000, v0
	v_cmp_gt_f32_e64 s[0:1], s3, v0
	v_cndmask_b32_e64 v32, v32, v36, s[6:7]
	v_fmamk_f32 v1, v1, 0x3b000000, v22
	v_cndmask_b32_e32 v33, v33, v37, vcc
	v_cndmask_b32_e64 v0, v0, v40, s[0:1]
	v_sqrt_f32_e32 v36, v32
	v_mul_f32_e32 v41, 0x4f800000, v1
	v_cmp_gt_f32_e64 s[4:5], s3, v1
	v_sqrt_f32_e32 v37, v33
	v_sqrt_f32_e32 v40, v0
	v_rcp_f32_e32 v102, v124
	v_rcp_f32_e32 v103, v125
	v_cndmask_b32_e64 v1, v1, v41, s[4:5]
	v_sqrt_f32_e32 v41, v1
	v_add_u32_e32 v44, -1, v36
	v_add_u32_e32 v45, 1, v36
	v_add_u32_e32 v48, -1, v37
	v_add_u32_e32 v52, -1, v40
	v_fma_f32 v60, -v44, v36, v32
	v_pk_mul_f32 v[26:27], v[102:103], v[26:27]
	v_add_u32_e32 v49, 1, v37
	v_add_u32_e32 v53, 1, v40
	v_fma_f32 v61, -v45, v36, v32
	v_fma_f32 v62, -v48, v37, v33
	v_fma_f32 v64, -v52, v40, v0
	v_cmp_ge_f32_e64 s[8:9], 0, v60
	v_pk_mul_f32 v[26:27], v[26:27], v[42:43]
	v_pk_mul_f32 v[42:43], v[56:57], v[74:75]
	v_add_u32_e32 v56, -1, v41
	v_fma_f32 v63, -v49, v37, v33
	v_fma_f32 v65, -v53, v40, v0
	v_cndmask_b32_e64 v36, v36, v44, s[8:9]
	v_cmp_ge_f32_e64 s[8:9], 0, v62
	v_cmp_ge_f32_e64 s[10:11], 0, v64
	v_cmp_lt_f32_e64 s[14:15], 0, v61
	v_add_u32_e32 v57, 1, v41
	v_fma_f32 v66, -v56, v41, v1
	v_cndmask_b32_e64 v37, v37, v48, s[8:9]
	v_cmp_lt_f32_e64 s[8:9], 0, v63
	v_cndmask_b32_e64 v40, v40, v52, s[10:11]
	v_cmp_lt_f32_e64 s[10:11], 0, v65
	v_cndmask_b32_e64 v36, v36, v45, s[14:15]
	v_fma_f32 v67, -v57, v41, v1
	v_cmp_ge_f32_e64 s[12:13], 0, v66
	v_cndmask_b32_e64 v37, v37, v49, s[8:9]
	v_cndmask_b32_e64 v40, v40, v53, s[10:11]
	v_mul_f32_e32 v44, 0x37800000, v36
	v_cndmask_b32_e64 v41, v41, v56, s[12:13]
	v_cmp_lt_f32_e64 s[12:13], 0, v67
	v_mul_f32_e32 v45, 0x37800000, v37
	v_mul_f32_e32 v48, 0x37800000, v40
	v_cndmask_b32_e64 v36, v36, v44, s[6:7]
	v_cmp_class_f32_e64 s[6:7], v32, v23
	v_cndmask_b32_e64 v41, v41, v57, s[12:13]
	v_cndmask_b32_e32 v37, v37, v45, vcc
	v_cmp_class_f32_e32 vcc, v33, v23
	v_cndmask_b32_e64 v40, v40, v48, s[0:1]
	v_cmp_class_f32_e64 s[0:1], v0, v23
	v_cndmask_b32_e64 v32, v36, v32, s[6:7]
	v_mul_f32_e32 v49, 0x37800000, v41
	v_cndmask_b32_e32 v36, v37, v33, vcc
	v_cndmask_b32_e64 v37, v40, v0, s[0:1]
	v_div_scale_f32 v0, s[0:1], v32, v32, 1.0
	v_cndmask_b32_e64 v41, v41, v49, s[4:5]
	v_cmp_class_f32_e64 s[4:5], v1, v23
	v_div_scale_f32 v33, s[0:1], v36, v36, 1.0
	v_rcp_f32_e32 v52, v0
	v_cndmask_b32_e64 v40, v41, v1, s[4:5]
	v_div_scale_f32 v44, s[4:5], v37, v37, 1.0
	v_rcp_f32_e32 v53, v33
	v_div_scale_f32 v48, s[6:7], v40, v40, 1.0
	v_rcp_f32_e32 v56, v44
	v_rcp_f32_e32 v57, v48
	v_fma_f32 v60, -v0, v52, 1.0
	v_div_scale_f32 v1, vcc, 1.0, v32, 1.0
	v_fma_f32 v61, -v33, v53, 1.0
	v_fmac_f32_e32 v52, v60, v52
	v_div_scale_f32 v41, s[0:1], 1.0, v36, 1.0
	v_fma_f32 v62, -v44, v56, 1.0
	v_fmac_f32_e32 v53, v61, v53
	v_mul_f32_e32 v60, v1, v52
	v_div_scale_f32 v45, s[4:5], 1.0, v37, 1.0
	v_fma_f32 v63, -v48, v57, 1.0
	v_fmac_f32_e32 v56, v62, v56
	v_mul_f32_e32 v61, v41, v53
	v_fma_f32 v64, -v0, v60, v1
	v_div_scale_f32 v49, s[6:7], 1.0, v40, 1.0
	v_fmac_f32_e32 v57, v63, v57
	v_mul_f32_e32 v62, v45, v56
	v_fma_f32 v65, -v33, v61, v41
	v_fmac_f32_e32 v60, v64, v52
	v_mul_f32_e32 v63, v49, v57
	v_fma_f32 v66, -v44, v62, v45
	v_fmac_f32_e32 v61, v65, v53
	v_fma_f32 v0, -v0, v60, v1
	v_fma_f32 v67, -v48, v63, v49
	v_fmac_f32_e32 v62, v66, v56
	v_fma_f32 v1, -v33, v61, v41
	v_div_fmas_f32 v0, v0, v52, v60
	s_mov_b64 vcc, s[0:1]
	v_fmac_f32_e32 v63, v67, v57
	v_fma_f32 v41, -v44, v62, v45
	v_div_fixup_f32 v0, v0, v32, 1.0
	v_div_fmas_f32 v1, v1, v53, v61
	s_mov_b64 vcc, s[4:5]
	v_fma_f32 v44, -v48, v63, v49
	v_pk_mul_f32 v[32:33], v[46:47], v[0:1] op_sel_hi:[1,0]
	v_pk_mul_f32 v[2:3], v[2:3], v[0:1] op_sel_hi:[1,0]
	v_pk_mul_f32 v[30:31], v[30:31], v[0:1] op_sel_hi:[1,0]
	v_pk_mul_f32 v[24:25], v[24:25], v[0:1] op_sel_hi:[1,0]
	v_div_fixup_f32 v36, v1, v36, 1.0
	v_div_fmas_f32 v41, v41, v56, v62
	s_mov_b64 vcc, s[6:7]
	v_cvt_pk_bf16_f32 v0, v32, v33
	v_cvt_pk_bf16_f32 v1, v2, v3
	v_cvt_pk_bf16_f32 v2, v30, v31
	v_cvt_pk_bf16_f32 v3, v24, v25
	v_pk_mul_f32 v[24:25], v[50:51], v[36:37] op_sel_hi:[1,0]
	v_pk_mul_f32 v[6:7], v[6:7], v[36:37] op_sel_hi:[1,0]
	v_pk_mul_f32 v[30:31], v[34:35], v[36:37] op_sel_hi:[1,0]
	v_pk_mul_f32 v[28:29], v[28:29], v[36:37] op_sel_hi:[1,0]
	v_div_fixup_f32 v32, v41, v37, 1.0
	v_div_fmas_f32 v33, v44, v57, v63
	v_pk_mul_f32 v[58:59], v[58:59], v[72:73]
	global_store_dwordx4 v[14:15], v[0:3], off sc1
	v_pk_mul_f32 v[10:11], v[10:11], v[32:33] op_sel_hi:[1,0]
	v_pk_mul_f32 v[4:5], v[4:5], v[32:33] op_sel_hi:[1,0]
	v_cvt_pk_bf16_f32 v0, v24, v25
	v_cvt_pk_bf16_f32 v1, v6, v7
	v_cvt_pk_bf16_f32 v2, v30, v31
	v_cvt_pk_bf16_f32 v3, v28, v29
	v_pk_mul_f32 v[6:7], v[54:55], v[32:33] op_sel_hi:[1,0]
	v_pk_mul_f32 v[24:25], v[38:39], v[32:33] op_sel_hi:[1,0]
	v_div_fixup_f32 v28, v33, v40, 1.0
	global_store_dwordx4 v[14:15], v[0:3], off offset:1024 sc1
	v_pk_mul_f32 v[8:9], v[8:9], v[28:29] op_sel_hi:[1,0]
	s_nop 0
	v_cvt_pk_bf16_f32 v0, v6, v7
	v_cvt_pk_bf16_f32 v1, v10, v11
	v_cvt_pk_bf16_f32 v2, v24, v25
	v_cvt_pk_bf16_f32 v3, v4, v5
	v_pk_mul_f32 v[4:5], v[58:59], v[28:29] op_sel_hi:[1,0]
	v_pk_mul_f32 v[6:7], v[26:27], v[28:29] op_sel_hi:[1,0]
	v_pk_mul_f32 v[10:11], v[42:43], v[28:29] op_sel_hi:[1,0]
	global_store_dwordx4 v[14:15], v[0:3], off offset:2048 sc1
	s_nop 1
	v_cvt_pk_bf16_f32 v0, v4, v5
	v_cvt_pk_bf16_f32 v1, v6, v7
	v_cvt_pk_bf16_f32 v2, v10, v11
	v_cvt_pk_bf16_f32 v3, v8, v9
	global_store_dwordx4 v[14:15], v[0:3], off offset:3072 sc1
	s_cbranch_scc1 .LBB0_391
	v_readlane_b32 s81, v234, 49

.LBB0_462:
	v_lshl_add_u32 v144, s14, 8, v140
	v_lshl_or_b32 v146, s49, 8, v141
	v_ashrrev_i32_e32 v145, 31, v144
	v_ashrrev_i32_e32 v147, 31, v146
	v_lshlrev_b64 v[148:149], 11, v[144:145]
	v_lshl_add_u64 v[148:149], s[74:75], 0, v[148:149]
	v_lshlrev_b64 v[146:147], 1, v[146:147]
	v_lshl_add_u64 v[148:149], v[148:149], 0, v[146:147]
	s_mov_b32 s11, 0x40000
	s_mov_b64 s[26:27], 0x40000
	v_cvt_pk_bf16_f32 v60, v60, v61
	v_cvt_pk_bf16_f32 v61, v62, v63
	v_cvt_pk_bf16_f32 v62, v56, v57
	v_add_co_u32_e32 v56, vcc, s11, v148
	v_cvt_pk_bf16_f32 v68, v68, v69
	v_cvt_pk_bf16_f32 v69, v70, v71
	v_cvt_pk_bf16_f32 v70, v64, v65
	v_lshl_add_u64 v[64:65], v[148:149], 0, s[26:27]
	v_addc_co_u32_e32 v57, vcc, 0, v149, vcc
	v_cvt_pk_bf16_f32 v44, v44, v45
	v_cvt_pk_bf16_f32 v45, v46, v47
	v_cvt_pk_bf16_f32 v46, v40, v41
	v_cvt_pk_bf16_f32 v47, v42, v43
	s_mov_b32 s11, 0x48000
	v_cvt_pk_bf16_f32 v108, v108, v109
	v_cvt_pk_bf16_f32 v109, v110, v111
	v_cvt_pk_bf16_f32 v110, v104, v105
	v_or_b32_e32 v104, 16, v144
	global_store_dwordx4 v[64:65], v[44:47], off offset:256 sc1
	s_mov_b64 s[26:27], 0x48000
	v_ashrrev_i32_e32 v105, 31, v104
	v_add_co_u32_e32 v46, vcc, s11, v148
	v_cvt_pk_bf16_f32 v92, v92, v93
	v_cvt_pk_bf16_f32 v93, v94, v95
	v_cvt_pk_bf16_f32 v94, v88, v89
	v_or_b32_e32 v88, 32, v144
	v_lshl_add_u64 v[44:45], v[148:149], 0, s[26:27]
	v_addc_co_u32_e32 v47, vcc, 0, v149, vcc
	v_cvt_pk_bf16_f32 v28, v28, v29
	v_cvt_pk_bf16_f32 v29, v30, v31
	v_cvt_pk_bf16_f32 v30, v24, v25
	v_cvt_pk_bf16_f32 v31, v26, v27
	s_mov_b32 s11, 0x50000
	v_lshlrev_b64 v[104:105], 11, v[104:105]
	v_ashrrev_i32_e32 v89, 31, v88
	v_cvt_pk_bf16_f32 v76, v76, v77
	v_cvt_pk_bf16_f32 v77, v78, v79
	v_cvt_pk_bf16_f32 v78, v72, v73
	v_or_b32_e32 v72, 48, v144
	global_store_dwordx4 v[44:45], v[28:31], off offset:256 sc1
	s_mov_b64 s[26:27], 0x50000
	v_cvt_pk_bf16_f32 v111, v106, v107
	v_add_co_u32_e32 v30, vcc, s11, v148
	v_lshl_add_u64 v[104:105], s[74:75], 0, v[104:105]
	v_lshlrev_b64 v[88:89], 11, v[88:89]
	v_ashrrev_i32_e32 v73, 31, v72
	v_lshl_add_u64 v[28:29], v[148:149], 0, s[26:27]
	v_addc_co_u32_e32 v31, vcc, 0, v149, vcc
	v_cvt_pk_bf16_f32 v12, v12, v13
	v_cvt_pk_bf16_f32 v13, v14, v15
	v_cvt_pk_bf16_f32 v14, v8, v9
	v_cvt_pk_bf16_f32 v15, v10, v11
	s_mov_b32 s11, 0x58000
	global_store_dwordx4 v[148:149], v[108:111], off offset:256 sc1
	v_cvt_pk_bf16_f32 v95, v90, v91
	v_lshl_add_u64 v[88:89], s[74:75], 0, v[88:89]
	v_lshl_add_u64 v[108:109], v[104:105], 0, v[146:147]
	v_lshlrev_b64 v[72:73], 11, v[72:73]
	global_store_dwordx4 v[28:29], v[12:15], off offset:256 sc1
	global_store_dwordx4 v[108:109], v[92:95], off offset:256 sc1
	v_cvt_pk_bf16_f32 v79, v74, v75
	v_add_co_u32_e32 v14, vcc, s11, v148
	v_lshl_add_u64 v[92:93], v[88:89], 0, v[146:147]
	v_lshl_add_u64 v[72:73], s[74:75], 0, v[72:73]
	s_mov_b64 s[26:27], 0x58000
	v_addc_co_u32_e32 v15, vcc, 0, v149, vcc
	v_cvt_pk_bf16_f32 v124, v124, v125
	v_cvt_pk_bf16_f32 v125, v126, v127
	v_cvt_pk_bf16_f32 v126, v120, v121
	v_cvt_pk_bf16_f32 v127, v122, v123
	v_cvt_pk_bf16_f32 v104, v116, v117
	v_cvt_pk_bf16_f32 v105, v118, v119
	v_cvt_pk_bf16_f32 v106, v112, v113
	v_cvt_pk_bf16_f32 v107, v114, v115
	v_cvt_pk_bf16_f32 v88, v100, v101
	v_cvt_pk_bf16_f32 v89, v102, v103
	v_cvt_pk_bf16_f32 v90, v96, v97
	v_cvt_pk_bf16_f32 v91, v98, v99
	global_store_dwordx4 v[92:93], v[76:79], off offset:256 sc1
	v_cvt_pk_bf16_f32 v74, v80, v81
	v_cvt_pk_bf16_f32 v75, v82, v83
	v_lshl_add_u64 v[76:77], v[72:73], 0, v[146:147]
	v_cvt_pk_bf16_f32 v72, v84, v85
	v_cvt_pk_bf16_f32 v73, v86, v87
	v_cvt_pk_bf16_f32 v71, v66, v67
	v_cvt_pk_bf16_f32 v63, v58, v59
	v_cvt_pk_bf16_f32 v40, v52, v53
	v_cvt_pk_bf16_f32 v41, v54, v55
	v_cvt_pk_bf16_f32 v42, v48, v49
	v_cvt_pk_bf16_f32 v43, v50, v51
	v_cvt_pk_bf16_f32 v24, v36, v37
	v_cvt_pk_bf16_f32 v25, v38, v39
	v_cvt_pk_bf16_f32 v26, v32, v33
	v_cvt_pk_bf16_f32 v27, v34, v35
	v_lshl_add_u64 v[12:13], v[148:149], 0, s[26:27]
	v_cvt_pk_bf16_f32 v8, v20, v21
	v_cvt_pk_bf16_f32 v9, v22, v23
	v_cvt_pk_bf16_f32 v10, v16, v17
	v_cvt_pk_bf16_f32 v11, v18, v19
	v_cvt_pk_bf16_f32 v4, v4, v5
	v_cvt_pk_bf16_f32 v5, v6, v7
	v_cvt_pk_bf16_f32 v6, v0, v1
	v_cvt_pk_bf16_f32 v7, v2, v3
	s_andn2_b64 vcc, exec, s[4:5]
	s_mov_b64 s[4:5], -1
	global_store_dwordx4 v[148:149], v[124:127], off sc1
	global_store_dwordx4 v[108:109], v[104:107], off sc1
	global_store_dwordx4 v[92:93], v[88:91], off sc1
	global_store_dwordx4 v[76:77], v[72:75], off sc1
	global_store_dwordx4 v[76:77], v[68:71], off offset:256 sc1
	global_store_dwordx4 v[56:57], v[60:63], off sc1
	global_store_dwordx4 v[46:47], v[40:43], off sc1
	global_store_dwordx4 v[30:31], v[24:27], off sc1
	global_store_dwordx4 v[14:15], v[8:11], off sc1
	global_store_dwordx4 v[12:13], v[4:7], off offset:256 sc1
	s_cbranch_vccnz .LBB0_451
	s_andn2_b64 vcc, exec, s[0:1]
	s_cbranch_vccnz .LBB0_450
	s_barrier
	s_branch .LBB0_450

.LBB0_521:
	v_lshl_add_u64 v[46:47], s[84:85], 0, v[8:9]
	v_lshl_add_u64 v[10:11], s[16:17], 0, v[6:7]
	v_lshl_add_u64 v[48:49], s[84:85], 0, v[6:7]
	v_add_co_u32_e32 v46, vcc, 0x14400000, v46
	global_load_dwordx4 v[22:25], v[0:1], off
	global_load_dwordx4 v[26:29], v[2:3], off
	global_load_dwordx4 v[30:33], v[10:11], off
	global_load_dwordx4 v[34:37], v[10:11], off offset:1024
	global_load_dwordx4 v[38:41], v[10:11], off offset:2048
	global_load_dwordx4 v[42:45], v[10:11], off offset:3072
	v_add_co_u32_e64 v10, s[0:1], s11, v48
	v_addc_co_u32_e32 v47, vcc, 0, v47, vcc
	s_nop 0
	v_addc_co_u32_e64 v11, s[0:1], 0, v49, s[0:1]
	global_load_dwordx2 v[48:49], v[46:47], off
	global_load_dwordx2 v[50:51], v[46:47], off offset:512
	global_load_dwordx2 v[52:53], v[46:47], off offset:1024
	s_nop 0
	global_load_dwordx2 v[46:47], v[46:47], off offset:1536
	s_add_i32 s14, s14, s80
	v_lshl_add_u64 v[6:7], v[6:7], 0, s[6:7]
	v_lshl_add_u64 v[8:9], v[8:9], 0, s[8:9]
	s_cmpk_lt_i32 s14, 0x4000
	s_waitcnt vmcnt(3)
	v_lshlrev_b32_e32 v54, 16, v48
	v_and_b32_e32 v55, 0xffff0000, v48
	v_lshlrev_b32_e32 v48, 16, v49
	v_and_b32_e32 v49, 0xffff0000, v49
	s_waitcnt vmcnt(2)
	v_lshlrev_b32_e32 v56, 16, v50
	v_and_b32_e32 v57, 0xffff0000, v50
	v_lshlrev_b32_e32 v50, 16, v51
	v_and_b32_e32 v51, 0xffff0000, v51
	s_waitcnt vmcnt(1)
	v_lshlrev_b32_e32 v58, 16, v52
	v_and_b32_e32 v59, 0xffff0000, v52
	v_lshlrev_b32_e32 v52, 16, v53
	v_and_b32_e32 v53, 0xffff0000, v53
	s_waitcnt vmcnt(0)
	v_lshlrev_b32_e32 v60, 16, v46
	v_and_b32_e32 v61, 0xffff0000, v46
	v_lshlrev_b32_e32 v46, 16, v47
	v_and_b32_e32 v47, 0xffff0000, v47
	v_pk_fma_f32 v[32:33], v[32:33], s[10:11], v[48:49] op_sel_hi:[1,0,1]
	v_pk_fma_f32 v[30:31], v[30:31], s[10:11], v[54:55] op_sel_hi:[1,0,1]
	v_pk_fma_f32 v[36:37], v[36:37], s[10:11], v[50:51] op_sel_hi:[1,0,1]
	v_pk_fma_f32 v[34:35], v[34:35], s[10:11], v[56:57] op_sel_hi:[1,0,1]
	v_pk_fma_f32 v[40:41], v[40:41], s[10:11], v[52:53] op_sel_hi:[1,0,1]
	v_pk_fma_f32 v[44:45], v[44:45], s[10:11], v[46:47] op_sel_hi:[1,0,1]
	v_pk_mov_b32 v[46:47], v[30:31], v[32:33] op_sel:[1,0]
	v_mov_b32_e32 v48, v30
	v_mov_b32_e32 v49, v33
	v_pk_mov_b32 v[50:51], v[34:35], v[36:37] op_sel:[1,0]
	v_mov_b32_e32 v52, v34
	v_mov_b32_e32 v53, v37
	v_pk_add_f32 v[46:47], v[46:47], v[48:49]
	v_pk_add_f32 v[48:49], v[50:51], v[52:53]
	v_pk_fma_f32 v[38:39], v[38:39], s[10:11], v[58:59] op_sel_hi:[1,0,1]
	v_pk_fma_f32 v[42:43], v[42:43], s[10:11], v[60:61] op_sel_hi:[1,0,1]
	v_add_f32_e32 v21, v46, v47
	v_pk_add_f32 v[46:47], v[48:49], v[48:49] op_sel:[0,1] op_sel_hi:[1,0]
	v_add_f32_e32 v54, v38, v39
	v_add_f32_e32 v56, v40, v41
	v_mov_b32_e32 v59, v42
	v_mov_b32_e32 v55, v44
	v_mov_b32_e32 v57, v45
	v_add_f32_e32 v58, 0, v21
	v_mov_b32_e32 v47, v43
	v_pk_add_f32 v[50:51], v[54:55], v[56:57]
	v_pk_add_f32 v[46:47], v[58:59], v[46:47]
	s_nop 0
	v_pk_add_f32 v[46:47], v[46:47], v[50:51]
	s_nop 0
	v_add_f32_e32 v21, v46, v47
	ds_bpermute_b32 v46, v12, v21
	s_waitcnt lgkmcnt(0)
	v_add_f32_e32 v21, v21, v46
	ds_bpermute_b32 v46, v13, v21
	s_waitcnt lgkmcnt(0)
	v_add_f32_e32 v21, v21, v46
	ds_bpermute_b32 v46, v14, v21
	s_waitcnt lgkmcnt(0)
	v_add_f32_e32 v21, v21, v46
	ds_bpermute_b32 v46, v15, v21
	s_waitcnt lgkmcnt(0)
	v_add_f32_e32 v21, v21, v46
	ds_bpermute_b32 v46, v16, v21
	s_waitcnt lgkmcnt(0)
	v_add_f32_e32 v21, v21, v46
	ds_bpermute_b32 v46, v17, v21
	s_waitcnt lgkmcnt(0)
	v_add_f32_e32 v21, v21, v46
	v_fmamk_f32 v31, v21, 0xba800000, v31
	v_fmac_f32_e32 v30, 0xba800000, v21
	v_fmamk_f32 v33, v21, 0xba800000, v33
	v_fmac_f32_e32 v32, 0xba800000, v21
	v_fmamk_f32 v35, v21, 0xba800000, v35
	v_fmac_f32_e32 v34, 0xba800000, v21
	v_fmamk_f32 v37, v21, 0xba800000, v37
	v_fmac_f32_e32 v36, 0xba800000, v21
	v_pk_mul_f32 v[46:47], v[32:33], v[32:33]
	v_pk_mul_f32 v[48:49], v[30:31], v[30:31]
	v_pk_mul_f32 v[50:51], v[36:37], v[36:37]
	v_pk_mul_f32 v[52:53], v[34:35], v[34:35]
	v_fmac_f32_e32 v38, 0xba800000, v21
	v_fmac_f32_e32 v40, 0xba800000, v21
	v_pk_mov_b32 v[58:59], v[48:49], v[46:47] op_sel:[1,0]
	v_mov_b32_e32 v49, v47
	v_pk_mov_b32 v[46:47], v[52:53], v[50:51] op_sel:[1,0]
	v_mov_b32_e32 v53, v51
	v_fmamk_f32 v39, v21, 0xba800000, v39
	v_fmamk_f32 v41, v21, 0xba800000, v41
	v_mul_f32_e32 v54, v38, v38
	v_mul_f32_e32 v56, v40, v40
	v_pk_add_f32 v[48:49], v[58:59], v[48:49]
	v_pk_add_f32 v[46:47], v[46:47], v[52:53]
	v_fmamk_f32 v45, v21, 0xba800000, v45
	v_fmac_f32_e32 v44, 0xba800000, v21
	v_fmamk_f32 v43, v21, 0xba800000, v43
	v_fmac_f32_e32 v42, 0xba800000, v21
	v_pk_fma_f32 v[50:51], v[38:39], v[38:39], v[54:55] op_sel_hi:[1,1,0]
	v_pk_fma_f32 v[54:55], v[40:41], v[40:41], v[56:57] op_sel_hi:[1,1,0]
	v_pk_add_f32 v[48:49], v[48:49], v[48:49] op_sel_hi:[0,1]
	v_pk_add_f32 v[46:47], v[46:47], v[46:47] op_sel_hi:[0,1]
	v_mul_f32_e32 v50, v42, v42
	v_mul_f32_e32 v54, v43, v43
	v_mul_f32_e32 v48, v44, v44
	v_mul_f32_e32 v46, v45, v45
	v_pk_add_f32 v[50:51], v[50:51], v[54:55]
	v_pk_add_f32 v[46:47], v[48:49], v[46:47]
	s_nop 0
	v_pk_add_f32 v[46:47], v[50:51], v[46:47]
	v_mov_b32_e32 v51, 0
	v_add_f32_e32 v21, v46, v47
	ds_bpermute_b32 v46, v12, v21
	s_waitcnt lgkmcnt(0)
	v_add_f32_e32 v21, v21, v46
	ds_bpermute_b32 v46, v13, v21
	s_waitcnt lgkmcnt(0)
	v_add_f32_e32 v21, v21, v46
	ds_bpermute_b32 v46, v14, v21
	s_waitcnt lgkmcnt(0)
	v_add_f32_e32 v21, v21, v46
	ds_bpermute_b32 v46, v15, v21
	s_waitcnt lgkmcnt(0)
	v_add_f32_e32 v21, v21, v46
	ds_bpermute_b32 v46, v16, v21
	s_waitcnt lgkmcnt(0)
	v_add_f32_e32 v21, v21, v46
	ds_bpermute_b32 v46, v17, v21
	s_waitcnt lgkmcnt(0)
	v_add_f32_e32 v21, v21, v46
	v_fmamk_f32 v21, v21, 0x3a800000, v18
	v_mul_f32_e32 v46, 0x4f800000, v21
	v_cmp_gt_f32_e32 vcc, s3, v21
	s_nop 1
	v_cndmask_b32_e32 v21, v21, v46, vcc
	v_sqrt_f32_e32 v46, v21
	s_nop 0
	v_add_u32_e32 v47, -1, v46
	v_add_u32_e32 v48, 1, v46
	v_fma_f32 v49, -v47, v46, v21
	v_fma_f32 v50, -v48, v46, v21
	v_cmp_ge_f32_e64 s[0:1], 0, v49
	s_nop 1
	v_cndmask_b32_e64 v46, v46, v47, s[0:1]
	v_cmp_lt_f32_e64 s[0:1], 0, v50
	s_nop 1
	v_cndmask_b32_e64 v46, v46, v48, s[0:1]
	v_mul_f32_e32 v47, 0x37800000, v46
	v_cndmask_b32_e32 v46, v46, v47, vcc
	v_cmp_class_f32_e32 vcc, v21, v19
	s_nop 1
	v_cndmask_b32_e32 v21, v46, v21, vcc
	v_div_scale_f32 v46, s[0:1], v21, v21, 1.0
	v_rcp_f32_e32 v48, v46
	v_div_scale_f32 v47, vcc, 1.0, v21, 1.0
	v_fma_f32 v49, -v46, v48, 1.0
	v_fmac_f32_e32 v48, v49, v48
	v_mul_f32_e32 v49, v47, v48
	v_fma_f32 v50, -v46, v49, v47
	v_fmac_f32_e32 v49, v50, v48
	v_fma_f32 v46, -v46, v49, v47
	v_div_fmas_f32 v46, v46, v48, v49
	v_div_fixup_f32 v46, v46, v21, 1.0
	v_pk_mul_f32 v[30:31], v[30:31], v[46:47] op_sel_hi:[1,0]
	v_pk_mul_f32 v[32:33], v[32:33], v[46:47] op_sel_hi:[1,0]
	v_pk_fma_f32 v[22:23], v[22:23], v[30:31], v[26:27]
	v_pk_fma_f32 v[24:25], v[24:25], v[32:33], v[28:29]
	global_store_dwordx4 v[10:11], v[22:25], off sc1
	global_load_dwordx4 v[26:29], v[0:1], off offset:1024
	global_load_dwordx4 v[30:33], v[2:3], off offset:1024
	v_pk_mul_f32 v[34:35], v[34:35], v[46:47] op_sel_hi:[1,0]
	v_pk_mul_f32 v[36:37], v[36:37], v[46:47] op_sel_hi:[1,0]
	v_pk_mul_f32 v[38:39], v[38:39], v[46:47] op_sel_hi:[1,0]
	v_pk_mul_f32 v[40:41], v[40:41], v[46:47] op_sel_hi:[1,0]
	v_mov_b32_e32 v21, 0
	v_med3_f32 v22, v22, s12, v20
	v_med3_f32 v23, v23, s12, v20
	v_mov_b32_e32 v47, 0
	v_cvt_pk_fp8_f32 v21, v22, v23
	v_mov_b32_e32 v50, 0
	v_pk_mul_f32 v[42:43], v[42:43], v[46:47] op_sel_hi:[1,0]
	v_pk_mul_f32 v[44:45], v[44:45], v[46:47] op_sel_hi:[1,0]
	v_med3_f32 v24, v24, s12, v20
	v_med3_f32 v25, v25, s12, v20
	v_cvt_pk_fp8_f32 v21, v24, v25 op_sel:[0,0,1]
	v_lshl_add_u64 v[48:49], s[84:85], 0, v[4:5]
	v_add_co_u32_e32 v48, vcc, s13, v48
	v_lshl_add_u64 v[4:5], v[4:5], 0, s[4:5]
	s_nop 0
	v_addc_co_u32_e32 v49, vcc, 0, v49, vcc
	s_waitcnt vmcnt(0)
	v_pk_fma_f32 v[28:29], v[28:29], v[36:37], v[32:33]
	v_pk_fma_f32 v[26:27], v[26:27], v[34:35], v[30:31]
	global_store_dwordx4 v[10:11], v[26:29], off offset:1024 sc1
	global_load_dwordx4 v[30:33], v[0:1], off offset:2048
	global_load_dwordx4 v[34:37], v[2:3], off offset:2048
	v_med3_f32 v22, v26, s12, v20
	v_med3_f32 v23, v27, s12, v20
	v_cvt_pk_fp8_f32 v47, v22, v23
	v_med3_f32 v24, v28, s12, v20
	v_med3_f32 v25, v29, s12, v20
	v_cvt_pk_fp8_f32 v47, v24, v25 op_sel:[0,0,1]
	s_waitcnt vmcnt(0)
	v_pk_fma_f32 v[32:33], v[32:33], v[40:41], v[36:37]
	v_pk_fma_f32 v[30:31], v[30:31], v[38:39], v[34:35]
	global_store_dwordx4 v[10:11], v[30:33], off offset:2048 sc1
	global_load_dwordx4 v[34:37], v[0:1], off offset:3072
	global_load_dwordx4 v[38:41], v[2:3], off offset:3072
	v_med3_f32 v22, v30, s12, v20
	v_med3_f32 v23, v31, s12, v20
	v_cvt_pk_fp8_f32 v50, v22, v23
	v_med3_f32 v24, v32, s12, v20
	v_med3_f32 v25, v33, s12, v20
	v_cvt_pk_fp8_f32 v50, v24, v25 op_sel:[0,0,1]
	s_waitcnt vmcnt(0)
	v_pk_fma_f32 v[22:23], v[34:35], v[42:43], v[38:39]
	s_nop 0
	v_med3_f32 v26, v22, s12, v20
	v_med3_f32 v27, v23, s12, v20
	v_cvt_pk_fp8_f32 v51, v26, v27
	v_pk_fma_f32 v[24:25], v[36:37], v[44:45], v[40:41]
	global_store_dwordx4 v[10:11], v[22:25], off offset:3072 sc1
	v_med3_f32 v10, v24, s12, v20
	v_med3_f32 v11, v25, s12, v20
	v_cvt_pk_fp8_f32 v51, v10, v11 op_sel:[0,0,1]
	global_store_dword v[48:49], v21, off
	global_store_dword v[48:49], v47, off offset:256
	global_store_dword v[48:49], v50, off offset:512
	global_store_dword v[48:49], v51, off offset:768
	s_cbranch_scc1 .LBB0_521
	v_readlane_b32 s81, v234, 49

.LBB0_665:
	v_lshl_add_u32 v6, s43, 8, v187
	v_lshl_or_b32 v0, s44, 8, v188
	v_ashrrev_i32_e32 v7, 31, v6
	v_ashrrev_i32_e32 v1, 31, v0
	v_lshlrev_b64 v[2:3], 11, v[6:7]
	v_lshl_add_u64 v[2:3], s[74:75], 0, v[2:3]
	v_lshlrev_b64 v[8:9], 1, v[0:1]
	v_lshl_add_u64 v[0:1], v[2:3], 0, v[8:9]
	v_pk_mul_f32 v[4:5], v[158:159], s[12:13] op_sel_hi:[1,0]
	v_pk_mul_f32 v[2:3], v[156:157], s[12:13] op_sel_hi:[1,0]
	v_pk_mul_f32 v[10:11], v[154:155], s[12:13] op_sel_hi:[1,0]
	v_pk_mul_f32 v[12:13], v[152:153], s[12:13] op_sel_hi:[1,0]
	v_cvt_pk_bf16_f32 v2, v2, v3
	v_cvt_pk_bf16_f32 v3, v4, v5
	v_cvt_pk_bf16_f32 v4, v12, v13
	v_cvt_pk_bf16_f32 v5, v10, v11
	global_store_dwordx4 v[0:1], v[2:5], off sc1
	v_pk_mul_f32 v[10:11], v[138:139], s[12:13] op_sel_hi:[1,0]
	v_pk_mul_f32 v[12:13], v[136:137], s[12:13] op_sel_hi:[1,0]
	v_pk_mul_f32 v[4:5], v[146:147], s[12:13] op_sel_hi:[1,0]
	v_pk_mul_f32 v[2:3], v[144:145], s[12:13] op_sel_hi:[1,0]
	v_pk_mul_f32 v[14:15], v[140:141], s[12:13] op_sel_hi:[1,0]
	v_cvt_pk_bf16_f32 v2, v2, v3
	v_cvt_pk_bf16_f32 v3, v4, v5
	v_cvt_pk_bf16_f32 v4, v12, v13
	v_cvt_pk_bf16_f32 v5, v10, v11
	global_store_dwordx4 v[0:1], v[2:5], off offset:256 sc1
	v_pk_mul_f32 v[12:13], v[142:143], s[12:13] op_sel_hi:[1,0]
	s_mov_b64 s[20:21], 0x40000
	v_or_b32_e32 v2, 16, v6
	v_ashrrev_i32_e32 v3, 31, v2
	v_lshlrev_b64 v[2:3], 11, v[2:3]
	v_lshl_add_u64 v[2:3], s[74:75], 0, v[2:3]
	v_lshl_add_u64 v[10:11], v[2:3], 0, v[8:9]
	v_pk_mul_f32 v[4:5], v[150:151], s[12:13] op_sel_hi:[1,0]
	v_pk_mul_f32 v[2:3], v[148:149], s[12:13] op_sel_hi:[1,0]
	s_nop 0
	v_cvt_pk_bf16_f32 v2, v2, v3
	v_cvt_pk_bf16_f32 v3, v4, v5
	v_cvt_pk_bf16_f32 v4, v14, v15
	v_cvt_pk_bf16_f32 v5, v12, v13
	global_store_dwordx4 v[10:11], v[2:5], off sc1
	v_pk_mul_f32 v[12:13], v[122:123], s[12:13] op_sel_hi:[1,0]
	v_pk_mul_f32 v[14:15], v[120:121], s[12:13] op_sel_hi:[1,0]
	v_pk_mul_f32 v[4:5], v[130:131], s[12:13] op_sel_hi:[1,0]
	v_pk_mul_f32 v[2:3], v[128:129], s[12:13] op_sel_hi:[1,0]
	s_nop 0
	v_cvt_pk_bf16_f32 v2, v2, v3
	v_cvt_pk_bf16_f32 v3, v4, v5
	v_cvt_pk_bf16_f32 v4, v14, v15
	v_cvt_pk_bf16_f32 v5, v12, v13
	global_store_dwordx4 v[10:11], v[2:5], off offset:256 sc1
	v_pk_mul_f32 v[12:13], v[126:127], s[12:13] op_sel_hi:[1,0]
	v_pk_mul_f32 v[14:15], v[124:125], s[12:13] op_sel_hi:[1,0]
	v_or_b32_e32 v2, 32, v6
	v_ashrrev_i32_e32 v3, 31, v2
	v_lshlrev_b64 v[2:3], 11, v[2:3]
	v_lshl_add_u64 v[2:3], s[74:75], 0, v[2:3]
	v_lshl_add_u64 v[10:11], v[2:3], 0, v[8:9]
	v_pk_mul_f32 v[4:5], v[134:135], s[12:13] op_sel_hi:[1,0]
	v_pk_mul_f32 v[2:3], v[132:133], s[12:13] op_sel_hi:[1,0]
	s_nop 0
	v_cvt_pk_bf16_f32 v2, v2, v3
	v_cvt_pk_bf16_f32 v3, v4, v5
	v_cvt_pk_bf16_f32 v4, v14, v15
	v_cvt_pk_bf16_f32 v5, v12, v13
	global_store_dwordx4 v[10:11], v[2:5], off sc1
	v_pk_mul_f32 v[12:13], v[106:107], s[12:13] op_sel_hi:[1,0]
	v_pk_mul_f32 v[14:15], v[104:105], s[12:13] op_sel_hi:[1,0]
	v_pk_mul_f32 v[4:5], v[114:115], s[12:13] op_sel_hi:[1,0]
	v_pk_mul_f32 v[2:3], v[112:113], s[12:13] op_sel_hi:[1,0]
	s_nop 0
	v_cvt_pk_bf16_f32 v2, v2, v3
	v_cvt_pk_bf16_f32 v3, v4, v5
	v_cvt_pk_bf16_f32 v4, v14, v15
	v_cvt_pk_bf16_f32 v5, v12, v13
	global_store_dwordx4 v[10:11], v[2:5], off offset:256 sc1
	v_pk_mul_f32 v[10:11], v[108:109], s[12:13] op_sel_hi:[1,0]
	s_nop 0
	v_or_b32_e32 v2, 48, v6
	v_ashrrev_i32_e32 v3, 31, v2
	v_lshlrev_b64 v[2:3], 11, v[2:3]
	v_lshl_add_u64 v[2:3], s[74:75], 0, v[2:3]
	v_lshl_add_u64 v[6:7], v[2:3], 0, v[8:9]
	v_pk_mul_f32 v[4:5], v[118:119], s[12:13] op_sel_hi:[1,0]
	v_pk_mul_f32 v[2:3], v[116:117], s[12:13] op_sel_hi:[1,0]
	v_pk_mul_f32 v[8:9], v[110:111], s[12:13] op_sel_hi:[1,0]
	v_cvt_pk_bf16_f32 v2, v2, v3
	v_cvt_pk_bf16_f32 v3, v4, v5
	v_cvt_pk_bf16_f32 v4, v10, v11
	v_cvt_pk_bf16_f32 v5, v8, v9
	global_store_dwordx4 v[6:7], v[2:5], off sc1
	v_pk_mul_f32 v[8:9], v[98:99], s[12:13] op_sel_hi:[1,0]
	v_pk_mul_f32 v[10:11], v[96:97], s[12:13] op_sel_hi:[1,0]
	v_pk_mul_f32 v[4:5], v[102:103], s[12:13] op_sel_hi:[1,0]
	v_pk_mul_f32 v[2:3], v[100:101], s[12:13] op_sel_hi:[1,0]
	s_nop 0
	v_cvt_pk_bf16_f32 v2, v2, v3
	v_cvt_pk_bf16_f32 v3, v4, v5
	v_cvt_pk_bf16_f32 v4, v10, v11
	v_cvt_pk_bf16_f32 v5, v8, v9
	global_store_dwordx4 v[6:7], v[2:5], off offset:256 sc1
	v_lshl_add_u64 v[6:7], v[0:1], 0, s[20:21]
	v_pk_mul_f32 v[8:9], v[90:91], s[12:13] op_sel_hi:[1,0]
	v_pk_mul_f32 v[4:5], v[94:95], s[12:13] op_sel_hi:[1,0]
	v_pk_mul_f32 v[2:3], v[92:93], s[12:13] op_sel_hi:[1,0]
	s_mov_b32 s20, 0x40000
	v_pk_mul_f32 v[10:11], v[88:89], s[12:13] op_sel_hi:[1,0]
	v_cvt_pk_bf16_f32 v2, v2, v3
	v_cvt_pk_bf16_f32 v3, v4, v5
	v_cvt_pk_bf16_f32 v5, v8, v9
	v_add_co_u32_e32 v8, vcc, s20, v0
	v_cvt_pk_bf16_f32 v4, v10, v11
	s_nop 0
	v_addc_co_u32_e32 v9, vcc, 0, v1, vcc
	global_store_dwordx4 v[8:9], v[2:5], off sc1
	v_pk_mul_f32 v[8:9], v[74:75], s[12:13] op_sel_hi:[1,0]
	v_pk_mul_f32 v[10:11], v[72:73], s[12:13] op_sel_hi:[1,0]
	v_pk_mul_f32 v[4:5], v[82:83], s[12:13] op_sel_hi:[1,0]
	v_pk_mul_f32 v[2:3], v[80:81], s[12:13] op_sel_hi:[1,0]
	s_mov_b64 s[20:21], 0x48000
	v_cvt_pk_bf16_f32 v2, v2, v3
	v_cvt_pk_bf16_f32 v3, v4, v5
	v_cvt_pk_bf16_f32 v4, v10, v11
	v_cvt_pk_bf16_f32 v5, v8, v9
	global_store_dwordx4 v[6:7], v[2:5], off offset:256 sc1
	v_lshl_add_u64 v[6:7], v[0:1], 0, s[20:21]
	v_pk_mul_f32 v[8:9], v[78:79], s[12:13] op_sel_hi:[1,0]
	v_pk_mul_f32 v[4:5], v[86:87], s[12:13] op_sel_hi:[1,0]
	v_pk_mul_f32 v[2:3], v[84:85], s[12:13] op_sel_hi:[1,0]
	s_mov_b32 s20, 0x48000
	v_pk_mul_f32 v[10:11], v[76:77], s[12:13] op_sel_hi:[1,0]
	v_cvt_pk_bf16_f32 v2, v2, v3
	v_cvt_pk_bf16_f32 v3, v4, v5
	v_cvt_pk_bf16_f32 v5, v8, v9
	v_add_co_u32_e32 v8, vcc, s20, v0
	v_cvt_pk_bf16_f32 v4, v10, v11
	s_nop 0
	v_addc_co_u32_e32 v9, vcc, 0, v1, vcc
	global_store_dwordx4 v[8:9], v[2:5], off sc1
	v_pk_mul_f32 v[8:9], v[58:59], s[12:13] op_sel_hi:[1,0]
	v_pk_mul_f32 v[10:11], v[56:57], s[12:13] op_sel_hi:[1,0]
	v_pk_mul_f32 v[4:5], v[66:67], s[12:13] op_sel_hi:[1,0]
	v_pk_mul_f32 v[2:3], v[64:65], s[12:13] op_sel_hi:[1,0]
	s_mov_b64 s[20:21], 0x50000
	v_cvt_pk_bf16_f32 v2, v2, v3
	v_cvt_pk_bf16_f32 v3, v4, v5
	v_cvt_pk_bf16_f32 v4, v10, v11
	v_cvt_pk_bf16_f32 v5, v8, v9
	global_store_dwordx4 v[6:7], v[2:5], off offset:256 sc1
	v_lshl_add_u64 v[6:7], v[0:1], 0, s[20:21]
	v_pk_mul_f32 v[8:9], v[62:63], s[12:13] op_sel_hi:[1,0]
	v_pk_mul_f32 v[4:5], v[70:71], s[12:13] op_sel_hi:[1,0]
	v_pk_mul_f32 v[2:3], v[68:69], s[12:13] op_sel_hi:[1,0]
	s_mov_b32 s20, 0x50000
	v_pk_mul_f32 v[10:11], v[60:61], s[12:13] op_sel_hi:[1,0]
	v_cvt_pk_bf16_f32 v2, v2, v3
	v_cvt_pk_bf16_f32 v3, v4, v5
	v_cvt_pk_bf16_f32 v5, v8, v9
	v_add_co_u32_e32 v8, vcc, s20, v0
	v_cvt_pk_bf16_f32 v4, v10, v11
	s_nop 0
	v_addc_co_u32_e32 v9, vcc, 0, v1, vcc
	global_store_dwordx4 v[8:9], v[2:5], off sc1
	v_pk_mul_f32 v[8:9], v[42:43], s[12:13] op_sel_hi:[1,0]
	v_pk_mul_f32 v[10:11], v[40:41], s[12:13] op_sel_hi:[1,0]
	v_pk_mul_f32 v[4:5], v[50:51], s[12:13] op_sel_hi:[1,0]
	v_pk_mul_f32 v[2:3], v[48:49], s[12:13] op_sel_hi:[1,0]
	s_mov_b64 s[20:21], 0x58000
	v_cvt_pk_bf16_f32 v2, v2, v3
	v_cvt_pk_bf16_f32 v3, v4, v5
	v_cvt_pk_bf16_f32 v4, v10, v11
	v_cvt_pk_bf16_f32 v5, v8, v9
	global_store_dwordx4 v[6:7], v[2:5], off offset:256 sc1
	v_lshl_add_u64 v[6:7], v[0:1], 0, s[20:21]
	s_mov_b32 s20, 0x58000
	v_pk_mul_f32 v[4:5], v[54:55], s[12:13] op_sel_hi:[1,0]
	v_pk_mul_f32 v[2:3], v[52:53], s[12:13] op_sel_hi:[1,0]
	v_pk_mul_f32 v[8:9], v[46:47], s[12:13] op_sel_hi:[1,0]
	v_pk_mul_f32 v[10:11], v[44:45], s[12:13] op_sel_hi:[1,0]
	v_add_co_u32_e32 v0, vcc, s20, v0
	v_cvt_pk_bf16_f32 v2, v2, v3
	v_cvt_pk_bf16_f32 v3, v4, v5
	v_cvt_pk_bf16_f32 v4, v10, v11
	v_cvt_pk_bf16_f32 v5, v8, v9
	v_addc_co_u32_e32 v1, vcc, 0, v1, vcc
	global_store_dwordx4 v[0:1], v[2:5], off sc1
	v_pk_mul_f32 v[0:1], v[36:37], s[12:13] op_sel_hi:[1,0]
	v_pk_mul_f32 v[8:9], v[32:33], s[12:13] op_sel_hi:[1,0]
	v_pk_mul_f32 v[2:3], v[38:39], s[12:13] op_sel_hi:[1,0]
	v_pk_mul_f32 v[4:5], v[34:35], s[12:13] op_sel_hi:[1,0]
	v_cvt_pk_bf16_f32 v0, v0, v1
	v_cvt_pk_bf16_f32 v1, v2, v3
	v_cvt_pk_bf16_f32 v2, v8, v9
	v_cvt_pk_bf16_f32 v3, v4, v5
	s_and_b64 vcc, exec, s[4:5]
	s_mov_b64 s[4:5], -1
	global_store_dwordx4 v[6:7], v[0:3], off offset:256 sc1
	s_cbranch_vccnz .LBB0_650
	s_andn2_b64 vcc, exec, s[6:7]
	s_cbranch_vccnz .LBB0_649
	s_barrier
	s_branch .LBB0_649

.LBB0_724:
	v_lshl_add_u64 v[26:27], s[84:85], 0, v[4:5]
	v_add_co_u32_e32 v28, vcc, 0x14400000, v26
	v_lshl_add_u64 v[24:25], s[84:85], 0, v[6:7]
	s_nop 0
	v_addc_co_u32_e32 v29, vcc, 0, v27, vcc
	v_add_co_u32_e32 v42, vcc, 0x10400000, v24
	global_load_dwordx4 v[16:19], v[0:1], off
	global_load_dwordx4 v[20:23], v[2:3], off
	v_add_co_u32_e64 v40, s[0:1], s9, v26
	global_load_dwordx2 v[44:45], v[28:29], off
	global_load_dwordx2 v[46:47], v[28:29], off offset:512
	global_load_dwordx2 v[48:49], v[28:29], off offset:1024
	global_load_dwordx2 v[50:51], v[28:29], off offset:1536
	v_addc_co_u32_e32 v43, vcc, 0, v25, vcc
	v_addc_co_u32_e64 v41, s[0:1], 0, v27, s[0:1]
	global_load_dwordx4 v[24:27], v[42:43], off
	global_load_dwordx4 v[28:31], v[42:43], off offset:1024
	global_load_dwordx4 v[32:35], v[42:43], off offset:2048
	global_load_dwordx4 v[36:39], v[42:43], off offset:3072
	s_add_i32 s10, s10, s80
	v_lshl_add_u64 v[4:5], v[4:5], 0, s[4:5]
	v_lshl_add_u64 v[6:7], v[6:7], 0, s[6:7]
	s_cmpk_lt_i32 s10, 0x4000
	s_waitcnt vmcnt(7)
	v_lshlrev_b32_e32 v52, 16, v44
	v_and_b32_e32 v53, 0xffff0000, v44
	v_lshlrev_b32_e32 v44, 16, v45
	v_and_b32_e32 v45, 0xffff0000, v45
	s_waitcnt vmcnt(6)
	v_lshlrev_b32_e32 v54, 16, v46
	v_and_b32_e32 v55, 0xffff0000, v46
	v_lshlrev_b32_e32 v46, 16, v47
	v_and_b32_e32 v47, 0xffff0000, v47
	s_waitcnt vmcnt(5)
	v_lshlrev_b32_e32 v56, 16, v48
	v_and_b32_e32 v57, 0xffff0000, v48
	v_lshlrev_b32_e32 v48, 16, v49
	v_and_b32_e32 v49, 0xffff0000, v49
	s_waitcnt vmcnt(4)
	v_lshlrev_b32_e32 v58, 16, v50
	v_and_b32_e32 v59, 0xffff0000, v50
	v_lshlrev_b32_e32 v50, 16, v51
	v_and_b32_e32 v51, 0xffff0000, v51
	s_waitcnt vmcnt(3)
	v_pk_fma_f32 v[26:27], v[26:27], s[8:9], v[44:45] op_sel_hi:[1,0,1]
	v_pk_fma_f32 v[24:25], v[24:25], s[8:9], v[52:53] op_sel_hi:[1,0,1]
	s_waitcnt vmcnt(2)
	v_pk_fma_f32 v[30:31], v[30:31], s[8:9], v[46:47] op_sel_hi:[1,0,1]
	v_pk_fma_f32 v[28:29], v[28:29], s[8:9], v[54:55] op_sel_hi:[1,0,1]
	s_waitcnt vmcnt(1)
	v_pk_fma_f32 v[34:35], v[34:35], s[8:9], v[48:49] op_sel_hi:[1,0,1]
	s_waitcnt vmcnt(0)
	v_pk_fma_f32 v[38:39], v[38:39], s[8:9], v[50:51] op_sel_hi:[1,0,1]
	v_pk_mov_b32 v[44:45], v[24:25], v[26:27] op_sel:[1,0]
	v_mov_b32_e32 v46, v24
	v_mov_b32_e32 v47, v27
	v_pk_mov_b32 v[48:49], v[28:29], v[30:31] op_sel:[1,0]
	v_mov_b32_e32 v50, v28
	v_mov_b32_e32 v51, v31
	v_pk_add_f32 v[44:45], v[44:45], v[46:47]
	v_pk_add_f32 v[46:47], v[48:49], v[50:51]
	v_pk_fma_f32 v[32:33], v[32:33], s[8:9], v[56:57] op_sel_hi:[1,0,1]
	v_pk_fma_f32 v[36:37], v[36:37], s[8:9], v[58:59] op_sel_hi:[1,0,1]
	v_add_f32_e32 v50, v44, v45
	v_pk_add_f32 v[44:45], v[46:47], v[46:47] op_sel:[0,1] op_sel_hi:[1,0]
	v_add_f32_e32 v52, v32, v33
	v_add_f32_e32 v54, v34, v35
	v_mov_b32_e32 v57, v36
	v_mov_b32_e32 v53, v38
	v_mov_b32_e32 v55, v39
	v_add_f32_e32 v56, 0, v50
	v_mov_b32_e32 v45, v37
	v_pk_add_f32 v[48:49], v[52:53], v[54:55]
	v_pk_add_f32 v[44:45], v[56:57], v[44:45]
	s_nop 0
	v_pk_add_f32 v[44:45], v[44:45], v[48:49]
	s_nop 0
	v_add_f32_e32 v44, v44, v45
	ds_bpermute_b32 v45, v8, v44
	s_waitcnt lgkmcnt(0)
	v_add_f32_e32 v44, v44, v45
	ds_bpermute_b32 v45, v9, v44
	s_waitcnt lgkmcnt(0)
	v_add_f32_e32 v44, v44, v45
	ds_bpermute_b32 v45, v10, v44
	s_waitcnt lgkmcnt(0)
	v_add_f32_e32 v44, v44, v45
	ds_bpermute_b32 v45, v11, v44
	s_waitcnt lgkmcnt(0)
	v_add_f32_e32 v44, v44, v45
	ds_bpermute_b32 v45, v12, v44
	s_waitcnt lgkmcnt(0)
	v_add_f32_e32 v44, v44, v45
	ds_bpermute_b32 v45, v13, v44
	s_waitcnt lgkmcnt(0)
	v_add_f32_e32 v44, v44, v45
	v_fmamk_f32 v25, v44, 0xba800000, v25
	v_fmac_f32_e32 v24, 0xba800000, v44
	v_fmamk_f32 v27, v44, 0xba800000, v27
	v_fmac_f32_e32 v26, 0xba800000, v44
	v_fmamk_f32 v29, v44, 0xba800000, v29
	v_fmac_f32_e32 v28, 0xba800000, v44
	v_fmamk_f32 v31, v44, 0xba800000, v31
	v_fmac_f32_e32 v30, 0xba800000, v44
	v_fmamk_f32 v33, v44, 0xba800000, v33
	v_fmac_f32_e32 v32, 0xba800000, v44
	v_fmamk_f32 v35, v44, 0xba800000, v35
	v_fmac_f32_e32 v34, 0xba800000, v44
	v_fmamk_f32 v39, v44, 0xba800000, v39
	v_fmac_f32_e32 v38, 0xba800000, v44
	v_fmamk_f32 v37, v44, 0xba800000, v37
	v_fmac_f32_e32 v36, 0xba800000, v44
	v_pk_mul_f32 v[44:45], v[26:27], v[26:27]
	v_pk_mul_f32 v[46:47], v[24:25], v[24:25]
	v_pk_mul_f32 v[48:49], v[30:31], v[30:31]
	v_pk_mul_f32 v[50:51], v[28:29], v[28:29]
	v_pk_mov_b32 v[56:57], v[46:47], v[44:45] op_sel:[1,0]
	v_mov_b32_e32 v47, v45
	v_pk_mov_b32 v[44:45], v[50:51], v[48:49] op_sel:[1,0]
	v_mov_b32_e32 v51, v49
	v_mul_f32_e32 v52, v32, v32
	v_mul_f32_e32 v54, v34, v34
	v_pk_add_f32 v[46:47], v[56:57], v[46:47]
	v_pk_add_f32 v[44:45], v[44:45], v[50:51]
	v_pk_fma_f32 v[48:49], v[32:33], v[32:33], v[52:53] op_sel_hi:[1,1,0]
	v_pk_fma_f32 v[52:53], v[34:35], v[34:35], v[54:55] op_sel_hi:[1,1,0]
	v_pk_add_f32 v[46:47], v[46:47], v[46:47] op_sel_hi:[0,1]
	v_pk_add_f32 v[44:45], v[44:45], v[44:45] op_sel_hi:[0,1]
	v_mul_f32_e32 v48, v36, v36
	v_mul_f32_e32 v52, v37, v37
	v_mul_f32_e32 v46, v38, v38
	v_mul_f32_e32 v44, v39, v39
	v_pk_add_f32 v[48:49], v[48:49], v[52:53]
	v_pk_add_f32 v[44:45], v[46:47], v[44:45]
	s_nop 0
	v_pk_add_f32 v[44:45], v[48:49], v[44:45]
	s_nop 0
	v_add_f32_e32 v44, v44, v45
	ds_bpermute_b32 v45, v8, v44
	s_waitcnt lgkmcnt(0)
	v_add_f32_e32 v44, v44, v45
	ds_bpermute_b32 v45, v9, v44
	s_waitcnt lgkmcnt(0)
	v_add_f32_e32 v44, v44, v45
	ds_bpermute_b32 v45, v10, v44
	s_waitcnt lgkmcnt(0)
	v_add_f32_e32 v44, v44, v45
	ds_bpermute_b32 v45, v11, v44
	s_waitcnt lgkmcnt(0)
	v_add_f32_e32 v44, v44, v45
	ds_bpermute_b32 v45, v12, v44
	s_waitcnt lgkmcnt(0)
	v_add_f32_e32 v44, v44, v45
	ds_bpermute_b32 v45, v13, v44
	s_waitcnt lgkmcnt(0)
	v_add_f32_e32 v44, v44, v45
	v_fmamk_f32 v44, v44, 0x3a800000, v14
	v_mul_f32_e32 v45, 0x4f800000, v44
	v_cmp_gt_f32_e32 vcc, s3, v44
	s_nop 1
	v_cndmask_b32_e32 v44, v44, v45, vcc
	v_sqrt_f32_e32 v45, v44
	s_nop 0
	v_add_u32_e32 v46, -1, v45
	v_add_u32_e32 v47, 1, v45
	v_fma_f32 v48, -v46, v45, v44
	v_fma_f32 v49, -v47, v45, v44
	v_cmp_ge_f32_e64 s[0:1], 0, v48
	s_nop 1
	v_cndmask_b32_e64 v45, v45, v46, s[0:1]
	v_cmp_lt_f32_e64 s[0:1], 0, v49
	s_nop 1
	v_cndmask_b32_e64 v45, v45, v47, s[0:1]
	v_mul_f32_e32 v46, 0x37800000, v45
	v_cndmask_b32_e32 v45, v45, v46, vcc
	v_cmp_class_f32_e32 vcc, v44, v15
	s_nop 1
	v_cndmask_b32_e32 v44, v45, v44, vcc
	v_div_scale_f32 v45, s[0:1], v44, v44, 1.0
	v_rcp_f32_e32 v47, v45
	v_div_scale_f32 v46, vcc, 1.0, v44, 1.0
	v_fma_f32 v48, -v45, v47, 1.0
	v_fmac_f32_e32 v47, v48, v47
	v_mul_f32_e32 v48, v46, v47
	v_fma_f32 v49, -v45, v48, v46
	v_fmac_f32_e32 v48, v49, v47
	v_fma_f32 v45, -v45, v48, v46
	v_div_fmas_f32 v45, v45, v47, v48
	v_div_fixup_f32 v44, v45, v44, 1.0
	v_pk_mul_f32 v[24:25], v[24:25], v[44:45] op_sel_hi:[1,0]
	v_pk_mul_f32 v[26:27], v[26:27], v[44:45] op_sel_hi:[1,0]
	v_pk_fma_f32 v[16:17], v[16:17], v[24:25], v[20:21]
	v_pk_fma_f32 v[18:19], v[18:19], v[26:27], v[22:23]
	global_store_dwordx4 v[42:43], v[16:19], off sc1
	v_pk_mul_f32 v[24:25], v[30:31], v[44:45] op_sel_hi:[1,0]
	v_pk_mul_f32 v[26:27], v[28:29], v[44:45] op_sel_hi:[1,0]
	v_cvt_pk_bf16_f32 v16, v16, v17
	v_cvt_pk_bf16_f32 v17, v18, v19
	global_store_dwordx2 v[40:41], v[16:17], off
	global_load_dwordx4 v[16:19], v[0:1], off offset:1024
	s_nop 0
	global_load_dwordx4 v[20:23], v[2:3], off offset:1024
	s_waitcnt vmcnt(0)
	v_pk_fma_f32 v[16:17], v[16:17], v[26:27], v[20:21]
	v_pk_fma_f32 v[18:19], v[18:19], v[24:25], v[22:23]
	global_store_dwordx4 v[42:43], v[16:19], off offset:1024 sc1
	v_pk_mul_f32 v[24:25], v[34:35], v[44:45] op_sel_hi:[1,0]
	v_pk_mul_f32 v[26:27], v[32:33], v[44:45] op_sel_hi:[1,0]
	v_cvt_pk_bf16_f32 v16, v16, v17
	v_cvt_pk_bf16_f32 v17, v18, v19
	global_store_dwordx2 v[40:41], v[16:17], off offset:512
	global_load_dwordx4 v[16:19], v[0:1], off offset:2048
	s_nop 0
	global_load_dwordx4 v[20:23], v[2:3], off offset:2048
	s_waitcnt vmcnt(0)
	v_pk_fma_f32 v[16:17], v[16:17], v[26:27], v[20:21]
	v_pk_fma_f32 v[18:19], v[18:19], v[24:25], v[22:23]
	global_store_dwordx4 v[42:43], v[16:19], off offset:2048 sc1
	v_pk_mul_f32 v[24:25], v[38:39], v[44:45] op_sel_hi:[1,0]
	v_pk_mul_f32 v[26:27], v[36:37], v[44:45] op_sel_hi:[1,0]
	v_cvt_pk_bf16_f32 v16, v16, v17
	v_cvt_pk_bf16_f32 v17, v18, v19
	global_store_dwordx2 v[40:41], v[16:17], off offset:1024
	global_load_dwordx4 v[16:19], v[0:1], off offset:3072
	s_nop 0
	global_load_dwordx4 v[20:23], v[2:3], off offset:3072
	s_waitcnt vmcnt(0)
	v_pk_fma_f32 v[16:17], v[16:17], v[26:27], v[20:21]
	v_pk_fma_f32 v[18:19], v[18:19], v[24:25], v[22:23]
	global_store_dwordx4 v[42:43], v[16:19], off offset:3072 sc1
	s_nop 1
	v_cvt_pk_bf16_f32 v16, v16, v17
	v_cvt_pk_bf16_f32 v17, v18, v19
	global_store_dwordx2 v[40:41], v[16:17], off offset:1536
	s_cbranch_scc1 .LBB0_724
	v_readlane_b32 s81, v234, 49

.LBB0_795:
	v_lshl_add_u32 v144, s14, 8, v140
	v_lshl_or_b32 v146, s43, 8, v141
	v_ashrrev_i32_e32 v145, 31, v144
	v_ashrrev_i32_e32 v147, 31, v146
	v_lshlrev_b64 v[148:149], 12, v[144:145]
	v_lshl_add_u64 v[148:149], s[58:59], 0, v[148:149]
	v_lshlrev_b64 v[146:147], 1, v[146:147]
	v_lshl_add_u64 v[148:149], v[148:149], 0, v[146:147]
	s_mov_b32 s11, 0x80000
	s_mov_b64 s[24:25], 0x80000
	v_cvt_pk_bf16_f32 v60, v60, v61
	v_cvt_pk_bf16_f32 v61, v62, v63
	v_cvt_pk_bf16_f32 v62, v56, v57
	v_add_co_u32_e32 v56, vcc, s11, v148
	v_cvt_pk_bf16_f32 v68, v68, v69
	v_cvt_pk_bf16_f32 v69, v70, v71
	v_cvt_pk_bf16_f32 v70, v64, v65
	v_lshl_add_u64 v[64:65], v[148:149], 0, s[24:25]
	v_addc_co_u32_e32 v57, vcc, 0, v149, vcc
	v_cvt_pk_bf16_f32 v44, v44, v45
	v_cvt_pk_bf16_f32 v45, v46, v47
	v_cvt_pk_bf16_f32 v46, v40, v41
	v_cvt_pk_bf16_f32 v47, v42, v43
	s_mov_b32 s11, 0x90000
	v_cvt_pk_bf16_f32 v108, v108, v109
	v_cvt_pk_bf16_f32 v109, v110, v111
	v_cvt_pk_bf16_f32 v110, v104, v105
	v_or_b32_e32 v104, 16, v144
	global_store_dwordx4 v[64:65], v[44:47], off offset:256 sc1
	s_mov_b64 s[24:25], 0x90000
	v_ashrrev_i32_e32 v105, 31, v104
	v_add_co_u32_e32 v46, vcc, s11, v148
	v_cvt_pk_bf16_f32 v92, v92, v93
	v_cvt_pk_bf16_f32 v93, v94, v95
	v_cvt_pk_bf16_f32 v94, v88, v89
	v_or_b32_e32 v88, 32, v144
	v_lshl_add_u64 v[44:45], v[148:149], 0, s[24:25]
	v_addc_co_u32_e32 v47, vcc, 0, v149, vcc
	v_cvt_pk_bf16_f32 v28, v28, v29
	v_cvt_pk_bf16_f32 v29, v30, v31
	v_cvt_pk_bf16_f32 v30, v24, v25
	v_cvt_pk_bf16_f32 v31, v26, v27
	s_mov_b32 s11, 0xa0000
	v_lshlrev_b64 v[104:105], 12, v[104:105]
	v_ashrrev_i32_e32 v89, 31, v88
	v_cvt_pk_bf16_f32 v76, v76, v77
	v_cvt_pk_bf16_f32 v77, v78, v79
	v_cvt_pk_bf16_f32 v78, v72, v73
	v_or_b32_e32 v72, 48, v144
	global_store_dwordx4 v[44:45], v[28:31], off offset:256 sc1
	s_mov_b64 s[24:25], 0xa0000
	v_cvt_pk_bf16_f32 v111, v106, v107
	v_add_co_u32_e32 v30, vcc, s11, v148
	v_lshl_add_u64 v[104:105], s[58:59], 0, v[104:105]
	v_lshlrev_b64 v[88:89], 12, v[88:89]
	v_ashrrev_i32_e32 v73, 31, v72
	v_lshl_add_u64 v[28:29], v[148:149], 0, s[24:25]
	v_addc_co_u32_e32 v31, vcc, 0, v149, vcc
	v_cvt_pk_bf16_f32 v12, v12, v13
	v_cvt_pk_bf16_f32 v13, v14, v15
	v_cvt_pk_bf16_f32 v14, v8, v9
	v_cvt_pk_bf16_f32 v15, v10, v11
	s_mov_b32 s11, 0xb0000
	global_store_dwordx4 v[148:149], v[108:111], off offset:256 sc1
	v_cvt_pk_bf16_f32 v95, v90, v91
	v_lshl_add_u64 v[88:89], s[58:59], 0, v[88:89]
	v_lshl_add_u64 v[108:109], v[104:105], 0, v[146:147]
	v_lshlrev_b64 v[72:73], 12, v[72:73]
	global_store_dwordx4 v[28:29], v[12:15], off offset:256 sc1
	global_store_dwordx4 v[108:109], v[92:95], off offset:256 sc1
	v_cvt_pk_bf16_f32 v79, v74, v75
	v_add_co_u32_e32 v14, vcc, s11, v148
	v_lshl_add_u64 v[92:93], v[88:89], 0, v[146:147]
	v_lshl_add_u64 v[72:73], s[58:59], 0, v[72:73]
	s_mov_b64 s[24:25], 0xb0000
	v_addc_co_u32_e32 v15, vcc, 0, v149, vcc
	v_cvt_pk_bf16_f32 v124, v124, v125
	v_cvt_pk_bf16_f32 v125, v126, v127
	v_cvt_pk_bf16_f32 v126, v120, v121
	v_cvt_pk_bf16_f32 v127, v122, v123
	v_cvt_pk_bf16_f32 v104, v116, v117
	v_cvt_pk_bf16_f32 v105, v118, v119
	v_cvt_pk_bf16_f32 v106, v112, v113
	v_cvt_pk_bf16_f32 v107, v114, v115
	v_cvt_pk_bf16_f32 v88, v100, v101
	v_cvt_pk_bf16_f32 v89, v102, v103
	v_cvt_pk_bf16_f32 v90, v96, v97
	v_cvt_pk_bf16_f32 v91, v98, v99
	global_store_dwordx4 v[92:93], v[76:79], off offset:256 sc1
	v_cvt_pk_bf16_f32 v74, v80, v81
	v_cvt_pk_bf16_f32 v75, v82, v83
	v_lshl_add_u64 v[76:77], v[72:73], 0, v[146:147]
	v_cvt_pk_bf16_f32 v72, v84, v85
	v_cvt_pk_bf16_f32 v73, v86, v87
	v_cvt_pk_bf16_f32 v71, v66, v67
	v_cvt_pk_bf16_f32 v63, v58, v59
	v_cvt_pk_bf16_f32 v40, v52, v53
	v_cvt_pk_bf16_f32 v41, v54, v55
	v_cvt_pk_bf16_f32 v42, v48, v49
	v_cvt_pk_bf16_f32 v43, v50, v51
	v_cvt_pk_bf16_f32 v24, v36, v37
	v_cvt_pk_bf16_f32 v25, v38, v39
	v_cvt_pk_bf16_f32 v26, v32, v33
	v_cvt_pk_bf16_f32 v27, v34, v35
	v_lshl_add_u64 v[12:13], v[148:149], 0, s[24:25]
	v_cvt_pk_bf16_f32 v8, v20, v21
	v_cvt_pk_bf16_f32 v9, v22, v23
	v_cvt_pk_bf16_f32 v10, v16, v17
	v_cvt_pk_bf16_f32 v11, v18, v19
	v_cvt_pk_bf16_f32 v4, v4, v5
	v_cvt_pk_bf16_f32 v5, v6, v7
	v_cvt_pk_bf16_f32 v6, v0, v1
	v_cvt_pk_bf16_f32 v7, v2, v3
	s_andn2_b64 vcc, exec, s[4:5]
	s_mov_b64 s[4:5], -1
	global_store_dwordx4 v[148:149], v[124:127], off sc1
	global_store_dwordx4 v[108:109], v[104:107], off sc1
	global_store_dwordx4 v[92:93], v[88:91], off sc1
	global_store_dwordx4 v[76:77], v[72:75], off sc1
	global_store_dwordx4 v[76:77], v[68:71], off offset:256 sc1
	global_store_dwordx4 v[56:57], v[60:63], off sc1
	global_store_dwordx4 v[46:47], v[40:43], off sc1
	global_store_dwordx4 v[30:31], v[24:27], off sc1
	global_store_dwordx4 v[14:15], v[8:11], off sc1
	global_store_dwordx4 v[12:13], v[4:7], off offset:256 sc1
	s_cbranch_vccnz .LBB0_784
	s_andn2_b64 vcc, exec, s[0:1]
	s_cbranch_vccnz .LBB0_783
	s_barrier
	s_branch .LBB0_783

.LBB0_815:
	v_lshl_add_u32 v144, s14, 8, v140
	v_lshl_or_b32 v146, s43, 8, v141
	v_ashrrev_i32_e32 v145, 31, v144
	v_ashrrev_i32_e32 v147, 31, v146
	v_lshlrev_b64 v[148:149], 15, v[144:145]
	v_lshl_add_u64 v[148:149], s[72:73], 0, v[148:149]
	v_lshlrev_b64 v[146:147], 1, v[146:147]
	v_lshl_add_u64 v[148:149], v[148:149], 0, v[146:147]
	s_mov_b32 s11, 0x400000
	s_mov_b64 s[24:25], 0x400000
	v_cvt_pk_bf16_f32 v60, v60, v61
	v_cvt_pk_bf16_f32 v61, v62, v63
	v_cvt_pk_bf16_f32 v62, v56, v57
	v_add_co_u32_e32 v56, vcc, s11, v148
	v_cvt_pk_bf16_f32 v68, v68, v69
	v_cvt_pk_bf16_f32 v69, v70, v71
	v_cvt_pk_bf16_f32 v70, v64, v65
	v_lshl_add_u64 v[64:65], v[148:149], 0, s[24:25]
	v_addc_co_u32_e32 v57, vcc, 0, v149, vcc
	v_cvt_pk_bf16_f32 v44, v44, v45
	v_cvt_pk_bf16_f32 v45, v46, v47
	v_cvt_pk_bf16_f32 v46, v40, v41
	v_cvt_pk_bf16_f32 v47, v42, v43
	s_mov_b32 s11, 0x480000
	v_cvt_pk_bf16_f32 v108, v108, v109
	v_cvt_pk_bf16_f32 v109, v110, v111
	v_cvt_pk_bf16_f32 v110, v104, v105
	v_or_b32_e32 v104, 16, v144
	global_store_dwordx4 v[64:65], v[44:47], off offset:256 sc1
	s_mov_b64 s[24:25], 0x480000
	v_ashrrev_i32_e32 v105, 31, v104
	v_add_co_u32_e32 v46, vcc, s11, v148
	v_cvt_pk_bf16_f32 v92, v92, v93
	v_cvt_pk_bf16_f32 v93, v94, v95
	v_cvt_pk_bf16_f32 v94, v88, v89
	v_or_b32_e32 v88, 32, v144
	v_lshl_add_u64 v[44:45], v[148:149], 0, s[24:25]
	v_addc_co_u32_e32 v47, vcc, 0, v149, vcc
	v_cvt_pk_bf16_f32 v28, v28, v29
	v_cvt_pk_bf16_f32 v29, v30, v31
	v_cvt_pk_bf16_f32 v30, v24, v25
	v_cvt_pk_bf16_f32 v31, v26, v27
	s_mov_b32 s11, 0x500000
	v_lshlrev_b64 v[104:105], 15, v[104:105]
	v_ashrrev_i32_e32 v89, 31, v88
	v_cvt_pk_bf16_f32 v76, v76, v77
	v_cvt_pk_bf16_f32 v77, v78, v79
	v_cvt_pk_bf16_f32 v78, v72, v73
	v_or_b32_e32 v72, 48, v144
	global_store_dwordx4 v[44:45], v[28:31], off offset:256 sc1
	s_mov_b64 s[24:25], 0x500000
	v_cvt_pk_bf16_f32 v111, v106, v107
	v_add_co_u32_e32 v30, vcc, s11, v148
	v_lshl_add_u64 v[104:105], s[72:73], 0, v[104:105]
	v_lshlrev_b64 v[88:89], 15, v[88:89]
	v_ashrrev_i32_e32 v73, 31, v72
	v_lshl_add_u64 v[28:29], v[148:149], 0, s[24:25]
	v_addc_co_u32_e32 v31, vcc, 0, v149, vcc
	v_cvt_pk_bf16_f32 v12, v12, v13
	v_cvt_pk_bf16_f32 v13, v14, v15
	v_cvt_pk_bf16_f32 v14, v8, v9
	v_cvt_pk_bf16_f32 v15, v10, v11
	s_mov_b32 s11, 0x580000
	global_store_dwordx4 v[148:149], v[108:111], off offset:256 sc1
	v_cvt_pk_bf16_f32 v95, v90, v91
	v_lshl_add_u64 v[88:89], s[72:73], 0, v[88:89]
	v_lshl_add_u64 v[108:109], v[104:105], 0, v[146:147]
	v_lshlrev_b64 v[72:73], 15, v[72:73]
	global_store_dwordx4 v[28:29], v[12:15], off offset:256 sc1
	global_store_dwordx4 v[108:109], v[92:95], off offset:256 sc1
	v_cvt_pk_bf16_f32 v79, v74, v75
	v_add_co_u32_e32 v14, vcc, s11, v148
	v_lshl_add_u64 v[92:93], v[88:89], 0, v[146:147]
	v_lshl_add_u64 v[72:73], s[72:73], 0, v[72:73]
	s_mov_b64 s[24:25], 0x580000
	v_addc_co_u32_e32 v15, vcc, 0, v149, vcc
	v_cvt_pk_bf16_f32 v124, v124, v125
	v_cvt_pk_bf16_f32 v125, v126, v127
	v_cvt_pk_bf16_f32 v126, v120, v121
	v_cvt_pk_bf16_f32 v127, v122, v123
	v_cvt_pk_bf16_f32 v104, v116, v117
	v_cvt_pk_bf16_f32 v105, v118, v119
	v_cvt_pk_bf16_f32 v106, v112, v113
	v_cvt_pk_bf16_f32 v107, v114, v115
	v_cvt_pk_bf16_f32 v88, v100, v101
	v_cvt_pk_bf16_f32 v89, v102, v103
	v_cvt_pk_bf16_f32 v90, v96, v97
	v_cvt_pk_bf16_f32 v91, v98, v99
	global_store_dwordx4 v[92:93], v[76:79], off offset:256 sc1
	v_cvt_pk_bf16_f32 v74, v80, v81
	v_cvt_pk_bf16_f32 v75, v82, v83
	v_lshl_add_u64 v[76:77], v[72:73], 0, v[146:147]
	v_cvt_pk_bf16_f32 v72, v84, v85
	v_cvt_pk_bf16_f32 v73, v86, v87
	v_cvt_pk_bf16_f32 v71, v66, v67
	v_cvt_pk_bf16_f32 v63, v58, v59
	v_cvt_pk_bf16_f32 v40, v52, v53
	v_cvt_pk_bf16_f32 v41, v54, v55
	v_cvt_pk_bf16_f32 v42, v48, v49
	v_cvt_pk_bf16_f32 v43, v50, v51
	v_cvt_pk_bf16_f32 v24, v36, v37
	v_cvt_pk_bf16_f32 v25, v38, v39
	v_cvt_pk_bf16_f32 v26, v32, v33
	v_cvt_pk_bf16_f32 v27, v34, v35
	v_lshl_add_u64 v[12:13], v[148:149], 0, s[24:25]
	v_cvt_pk_bf16_f32 v8, v20, v21
	v_cvt_pk_bf16_f32 v9, v22, v23
	v_cvt_pk_bf16_f32 v10, v16, v17
	v_cvt_pk_bf16_f32 v11, v18, v19
	v_cvt_pk_bf16_f32 v4, v4, v5
	v_cvt_pk_bf16_f32 v5, v6, v7
	v_cvt_pk_bf16_f32 v6, v0, v1
	v_cvt_pk_bf16_f32 v7, v2, v3
	s_andn2_b64 vcc, exec, s[4:5]
	s_mov_b64 s[4:5], -1
	global_store_dwordx4 v[148:149], v[124:127], off sc1
	global_store_dwordx4 v[108:109], v[104:107], off sc1
	global_store_dwordx4 v[92:93], v[88:91], off sc1
	global_store_dwordx4 v[76:77], v[72:75], off sc1
	global_store_dwordx4 v[76:77], v[68:71], off offset:256 sc1
	global_store_dwordx4 v[56:57], v[60:63], off sc1
	global_store_dwordx4 v[46:47], v[40:43], off sc1
	global_store_dwordx4 v[30:31], v[24:27], off sc1
	global_store_dwordx4 v[14:15], v[8:11], off sc1
	global_store_dwordx4 v[12:13], v[4:7], off offset:256 sc1
	s_cbranch_vccnz .LBB0_804
	s_andn2_b64 vcc, exec, s[0:1]
	s_cbranch_vccnz .LBB0_803
	s_barrier
	s_branch .LBB0_803

.LBB0_996:
	v_lshl_add_u32 v144, s18, 8, v140
	v_lshl_or_b32 v146, s49, 8, v141
	v_ashrrev_i32_e32 v145, 31, v144
	v_ashrrev_i32_e32 v147, 31, v146
	v_lshlrev_b64 v[148:149], 11, v[144:145]
	v_lshl_add_u64 v[148:149], s[74:75], 0, v[148:149]
	v_lshlrev_b64 v[146:147], 1, v[146:147]
	v_lshl_add_u64 v[148:149], v[148:149], 0, v[146:147]
	s_mov_b32 s15, 0x40000
	s_mov_b64 s[26:27], 0x40000
	v_cvt_pk_bf16_f32 v60, v60, v61
	v_cvt_pk_bf16_f32 v61, v62, v63
	v_cvt_pk_bf16_f32 v62, v56, v57
	v_add_co_u32_e32 v56, vcc, s15, v148
	v_cvt_pk_bf16_f32 v68, v68, v69
	v_cvt_pk_bf16_f32 v69, v70, v71
	v_cvt_pk_bf16_f32 v70, v64, v65
	v_lshl_add_u64 v[64:65], v[148:149], 0, s[26:27]
	v_addc_co_u32_e32 v57, vcc, 0, v149, vcc
	v_cvt_pk_bf16_f32 v44, v44, v45
	v_cvt_pk_bf16_f32 v45, v46, v47
	v_cvt_pk_bf16_f32 v46, v40, v41
	v_cvt_pk_bf16_f32 v47, v42, v43
	v_cvt_pk_bf16_f32 v108, v108, v109
	v_cvt_pk_bf16_f32 v109, v110, v111
	v_cvt_pk_bf16_f32 v110, v104, v105
	v_or_b32_e32 v104, 16, v144
	global_store_dwordx4 v[64:65], v[44:47], off offset:256 sc1
	s_mov_b64 s[26:27], 0x48000
	v_ashrrev_i32_e32 v105, 31, v104
	v_add_co_u32_e32 v46, vcc, s45, v148
	v_cvt_pk_bf16_f32 v92, v92, v93
	v_cvt_pk_bf16_f32 v93, v94, v95
	v_cvt_pk_bf16_f32 v94, v88, v89
	v_or_b32_e32 v88, 32, v144
	v_lshl_add_u64 v[44:45], v[148:149], 0, s[26:27]
	v_addc_co_u32_e32 v47, vcc, 0, v149, vcc
	v_cvt_pk_bf16_f32 v28, v28, v29
	v_cvt_pk_bf16_f32 v29, v30, v31
	v_cvt_pk_bf16_f32 v30, v24, v25
	v_cvt_pk_bf16_f32 v31, v26, v27
	v_lshlrev_b64 v[104:105], 11, v[104:105]
	v_ashrrev_i32_e32 v89, 31, v88
	v_cvt_pk_bf16_f32 v76, v76, v77
	v_cvt_pk_bf16_f32 v77, v78, v79
	v_cvt_pk_bf16_f32 v78, v72, v73
	v_or_b32_e32 v72, 48, v144
	global_store_dwordx4 v[44:45], v[28:31], off offset:256 sc1
	v_cvt_pk_bf16_f32 v111, v106, v107
	v_lshl_add_u64 v[104:105], s[74:75], 0, v[104:105]
	v_add_co_u32_e32 v30, vcc, s47, v148
	v_lshlrev_b64 v[88:89], 11, v[88:89]
	v_ashrrev_i32_e32 v73, 31, v72
	v_lshl_add_u64 v[28:29], v[148:149], 0, s[10:11]
	v_addc_co_u32_e32 v31, vcc, 0, v149, vcc
	v_cvt_pk_bf16_f32 v12, v12, v13
	v_cvt_pk_bf16_f32 v13, v14, v15
	v_cvt_pk_bf16_f32 v14, v8, v9
	v_cvt_pk_bf16_f32 v15, v10, v11
	global_store_dwordx4 v[148:149], v[108:111], off offset:256 sc1
	v_cvt_pk_bf16_f32 v95, v90, v91
	v_lshl_add_u64 v[88:89], s[74:75], 0, v[88:89]
	v_lshl_add_u64 v[108:109], v[104:105], 0, v[146:147]
	v_lshlrev_b64 v[72:73], 11, v[72:73]
	global_store_dwordx4 v[28:29], v[12:15], off offset:256 sc1
	global_store_dwordx4 v[108:109], v[92:95], off offset:256 sc1
	v_cvt_pk_bf16_f32 v79, v74, v75
	v_add_co_u32_e32 v14, vcc, s48, v148
	v_lshl_add_u64 v[92:93], v[88:89], 0, v[146:147]
	v_lshl_add_u64 v[72:73], s[74:75], 0, v[72:73]
	v_addc_co_u32_e32 v15, vcc, 0, v149, vcc
	v_cvt_pk_bf16_f32 v124, v124, v125
	v_cvt_pk_bf16_f32 v125, v126, v127
	v_cvt_pk_bf16_f32 v126, v120, v121
	v_cvt_pk_bf16_f32 v127, v122, v123
	v_cvt_pk_bf16_f32 v104, v116, v117
	v_cvt_pk_bf16_f32 v105, v118, v119
	v_cvt_pk_bf16_f32 v106, v112, v113
	v_cvt_pk_bf16_f32 v107, v114, v115
	v_cvt_pk_bf16_f32 v88, v100, v101
	v_cvt_pk_bf16_f32 v89, v102, v103
	v_cvt_pk_bf16_f32 v90, v96, v97
	v_cvt_pk_bf16_f32 v91, v98, v99
	global_store_dwordx4 v[92:93], v[76:79], off offset:256 sc1
	v_cvt_pk_bf16_f32 v74, v80, v81
	v_cvt_pk_bf16_f32 v75, v82, v83
	v_lshl_add_u64 v[76:77], v[72:73], 0, v[146:147]
	v_cvt_pk_bf16_f32 v72, v84, v85
	v_cvt_pk_bf16_f32 v73, v86, v87
	v_cvt_pk_bf16_f32 v71, v66, v67
	v_cvt_pk_bf16_f32 v63, v58, v59
	v_cvt_pk_bf16_f32 v40, v52, v53
	v_cvt_pk_bf16_f32 v41, v54, v55
	v_cvt_pk_bf16_f32 v42, v48, v49
	v_cvt_pk_bf16_f32 v43, v50, v51
	v_cvt_pk_bf16_f32 v24, v36, v37
	v_cvt_pk_bf16_f32 v25, v38, v39
	v_cvt_pk_bf16_f32 v26, v32, v33
	v_cvt_pk_bf16_f32 v27, v34, v35
	v_lshl_add_u64 v[12:13], v[148:149], 0, s[12:13]
	v_cvt_pk_bf16_f32 v8, v20, v21
	v_cvt_pk_bf16_f32 v9, v22, v23
	v_cvt_pk_bf16_f32 v10, v16, v17
	v_cvt_pk_bf16_f32 v11, v18, v19
	v_cvt_pk_bf16_f32 v4, v4, v5
	v_cvt_pk_bf16_f32 v5, v6, v7
	v_cvt_pk_bf16_f32 v6, v0, v1
	v_cvt_pk_bf16_f32 v7, v2, v3
	s_andn2_b64 vcc, exec, s[4:5]
	s_mov_b64 s[4:5], -1
	global_store_dwordx4 v[148:149], v[124:127], off sc1
	global_store_dwordx4 v[108:109], v[104:107], off sc1
	global_store_dwordx4 v[92:93], v[88:91], off sc1
	global_store_dwordx4 v[76:77], v[72:75], off sc1
	global_store_dwordx4 v[76:77], v[68:71], off offset:256 sc1
	global_store_dwordx4 v[56:57], v[60:63], off sc1
	global_store_dwordx4 v[46:47], v[40:43], off sc1
	global_store_dwordx4 v[30:31], v[24:27], off sc1
	global_store_dwordx4 v[14:15], v[8:11], off sc1
	global_store_dwordx4 v[12:13], v[4:7], off offset:256 sc1
	s_cbranch_vccnz .LBB0_985
	s_andn2_b64 vcc, exec, s[0:1]
	s_cbranch_vccnz .LBB0_984
	s_barrier
	s_branch .LBB0_984

.LBB0_1060:
	v_lshl_add_u64 v[0:1], s[84:85], 0, v[24:25]
	v_add_co_u32_e32 v0, vcc, 0x14400000, v0
	s_waitcnt lgkmcnt(6)
	v_lshl_add_u64 v[2:3], s[84:85], 0, v[22:23]
	v_addc_co_u32_e32 v1, vcc, 0, v1, vcc
	global_load_dwordx2 v[4:5], v[0:1], off
	s_waitcnt lgkmcnt(0)
	global_load_dwordx2 v[14:15], v[0:1], off offset:512
	global_load_dwordx2 v[28:29], v[0:1], off offset:1024
	v_add_co_u32_e32 v26, vcc, 0x10400000, v2
	global_load_dwordx2 v[30:31], v[0:1], off offset:1536
	s_nop 0
	v_addc_co_u32_e32 v27, vcc, 0, v3, vcc
	global_load_dwordx4 v[0:3], v[26:27], off
	global_load_dwordx4 v[6:9], v[26:27], off offset:1024
	global_load_dwordx4 v[10:13], v[26:27], off offset:2048
	global_load_dwordx4 v[56:59], v[26:27], off offset:3072
	s_waitcnt vmcnt(7)
	v_lshlrev_b32_e32 v32, 16, v4
	v_and_b32_e32 v33, 0xffff0000, v4
	v_lshlrev_b32_e32 v4, 16, v5
	v_and_b32_e32 v5, 0xffff0000, v5
	s_waitcnt vmcnt(6)
	v_lshlrev_b32_e32 v34, 16, v14
	v_and_b32_e32 v35, 0xffff0000, v14
	v_lshlrev_b32_e32 v14, 16, v15
	v_and_b32_e32 v15, 0xffff0000, v15
	s_waitcnt vmcnt(5)
	v_lshlrev_b32_e32 v38, 16, v28
	v_and_b32_e32 v39, 0xffff0000, v28
	v_lshlrev_b32_e32 v28, 16, v29
	v_and_b32_e32 v29, 0xffff0000, v29
	s_waitcnt vmcnt(3)
	v_pk_fma_f32 v[4:5], v[2:3], s[30:31], v[4:5] op_sel_hi:[1,0,1]
	v_pk_fma_f32 v[64:65], v[0:1], s[30:31], v[32:33] op_sel_hi:[1,0,1]
	s_waitcnt vmcnt(2)
	v_pk_fma_f32 v[0:1], v[8:9], s[30:31], v[14:15] op_sel_hi:[1,0,1]
	v_pk_fma_f32 v[2:3], v[6:7], s[30:31], v[34:35] op_sel_hi:[1,0,1]
	v_lshlrev_b32_e32 v60, 16, v30
	v_and_b32_e32 v61, 0xffff0000, v30
	v_lshlrev_b32_e32 v62, 16, v31
	v_and_b32_e32 v63, 0xffff0000, v31
	s_waitcnt vmcnt(1)
	v_pk_fma_f32 v[28:29], v[12:13], s[30:31], v[28:29] op_sel_hi:[1,0,1]
	v_pk_fma_f32 v[30:31], v[10:11], s[30:31], v[38:39] op_sel_hi:[1,0,1]
	v_pk_mov_b32 v[6:7], v[64:65], v[4:5] op_sel:[1,0]
	v_mov_b32_e32 v8, v64
	v_mov_b32_e32 v9, v5
	v_pk_mov_b32 v[10:11], v[2:3], v[0:1] op_sel:[1,0]
	v_mov_b32_e32 v12, v2
	v_mov_b32_e32 v13, v1
	v_pk_add_f32 v[6:7], v[6:7], v[8:9]
	v_pk_add_f32 v[8:9], v[10:11], v[12:13]
	s_waitcnt vmcnt(0)
	v_pk_fma_f32 v[32:33], v[58:59], s[30:31], v[62:63] op_sel_hi:[1,0,1]
	v_pk_fma_f32 v[34:35], v[56:57], s[30:31], v[60:61] op_sel_hi:[1,0,1]
	v_add_f32_e32 v12, v6, v7
	v_pk_add_f32 v[6:7], v[8:9], v[8:9] op_sel:[0,1] op_sel_hi:[1,0]
	v_add_f32_e32 v14, v30, v31
	v_add_f32_e32 v38, v28, v29
	v_mov_b32_e32 v57, v34
	v_mov_b32_e32 v15, v32
	v_mov_b32_e32 v39, v33
	v_add_f32_e32 v56, 0, v12
	v_mov_b32_e32 v7, v35
	v_pk_add_f32 v[10:11], v[14:15], v[38:39]
	v_pk_add_f32 v[6:7], v[56:57], v[6:7]
	s_nop 0
	v_pk_add_f32 v[6:7], v[6:7], v[10:11]
	global_load_dwordx4 v[8:11], v[16:17], off
	global_load_dwordx4 v[12:15], v[18:19], off
	v_add_f32_e32 v6, v6, v7
	ds_bpermute_b32 v7, v40, v6
	s_waitcnt lgkmcnt(0)
	v_add_f32_e32 v6, v6, v7
	ds_bpermute_b32 v7, v41, v6
	s_waitcnt lgkmcnt(0)
	v_add_f32_e32 v6, v6, v7
	ds_bpermute_b32 v7, v42, v6
	s_waitcnt lgkmcnt(0)
	v_add_f32_e32 v6, v6, v7
	ds_bpermute_b32 v7, v43, v6
	s_waitcnt lgkmcnt(0)
	v_add_f32_e32 v6, v6, v7
	ds_bpermute_b32 v7, v44, v6
	s_waitcnt lgkmcnt(0)
	v_add_f32_e32 v6, v6, v7
	ds_bpermute_b32 v7, v45, v6
	s_waitcnt lgkmcnt(0)
	v_add_f32_e32 v6, v6, v7
	v_fmamk_f32 v65, v6, 0xba800000, v65
	v_fmac_f32_e32 v64, 0xba800000, v6
	v_fmamk_f32 v5, v6, 0xba800000, v5
	v_fmac_f32_e32 v4, 0xba800000, v6
	v_fmamk_f32 v3, v6, 0xba800000, v3
	v_fmac_f32_e32 v2, 0xba800000, v6
	v_fmamk_f32 v1, v6, 0xba800000, v1
	v_fmac_f32_e32 v0, 0xba800000, v6
	v_fmamk_f32 v31, v6, 0xba800000, v31
	v_fmac_f32_e32 v30, 0xba800000, v6
	v_fmamk_f32 v29, v6, 0xba800000, v29
	v_fmac_f32_e32 v28, 0xba800000, v6
	v_fmamk_f32 v33, v6, 0xba800000, v33
	v_fmac_f32_e32 v32, 0xba800000, v6
	v_fmamk_f32 v35, v6, 0xba800000, v35
	v_fmac_f32_e32 v34, 0xba800000, v6
	v_pk_mul_f32 v[6:7], v[4:5], v[4:5]
	v_pk_mul_f32 v[38:39], v[64:65], v[64:65]
	v_pk_mul_f32 v[56:57], v[0:1], v[0:1]
	v_pk_mul_f32 v[58:59], v[2:3], v[2:3]
	v_pk_mov_b32 v[62:63], v[38:39], v[6:7] op_sel:[1,0]
	v_mov_b32_e32 v39, v7
	v_pk_mov_b32 v[6:7], v[58:59], v[56:57] op_sel:[1,0]
	v_mov_b32_e32 v59, v57
	v_mul_f32_e32 v36, v30, v30
	v_mul_f32_e32 v60, v28, v28
	v_pk_add_f32 v[38:39], v[62:63], v[38:39]
	v_pk_add_f32 v[6:7], v[6:7], v[58:59]
	v_pk_fma_f32 v[56:57], v[30:31], v[30:31], v[36:37] op_sel_hi:[1,1,0]
	v_pk_fma_f32 v[60:61], v[28:29], v[28:29], v[60:61] op_sel_hi:[1,1,0]
	v_pk_add_f32 v[38:39], v[38:39], v[38:39] op_sel_hi:[0,1]
	v_pk_add_f32 v[6:7], v[6:7], v[6:7] op_sel_hi:[0,1]
	v_mul_f32_e32 v56, v34, v34
	v_mul_f32_e32 v60, v35, v35
	v_mul_f32_e32 v38, v32, v32
	v_mul_f32_e32 v6, v33, v33
	v_pk_add_f32 v[56:57], v[56:57], v[60:61]
	v_pk_add_f32 v[6:7], v[38:39], v[6:7]
	v_mov_b32_e32 v58, 0
	v_pk_add_f32 v[6:7], v[56:57], v[6:7]
	v_mov_b32_e32 v57, 0
	v_add_f32_e32 v6, v6, v7
	ds_bpermute_b32 v7, v40, v6
	v_mov_b32_e32 v56, 0
	s_waitcnt lgkmcnt(0)
	v_add_f32_e32 v6, v6, v7
	ds_bpermute_b32 v7, v41, v6
	s_waitcnt lgkmcnt(0)
	v_add_f32_e32 v6, v6, v7
	ds_bpermute_b32 v7, v42, v6
	s_waitcnt lgkmcnt(0)
	v_add_f32_e32 v6, v6, v7
	ds_bpermute_b32 v7, v43, v6
	s_waitcnt lgkmcnt(0)
	v_add_f32_e32 v6, v6, v7
	ds_bpermute_b32 v7, v44, v6
	s_waitcnt lgkmcnt(0)
	v_add_f32_e32 v6, v6, v7
	ds_bpermute_b32 v7, v45, v6
	s_waitcnt lgkmcnt(0)
	v_add_f32_e32 v6, v6, v7
	v_fmamk_f32 v6, v6, 0x3a800000, v48
	v_mul_f32_e32 v7, 0x4f800000, v6
	v_cmp_gt_f32_e32 vcc, s23, v6
	s_nop 1
	v_cndmask_b32_e32 v6, v6, v7, vcc
	v_sqrt_f32_e32 v7, v6
	s_nop 0
	v_add_u32_e32 v36, -1, v7
	v_add_u32_e32 v38, 1, v7
	v_fma_f32 v39, -v36, v7, v6
	v_fma_f32 v55, -v38, v7, v6
	v_cmp_ge_f32_e64 s[6:7], 0, v39
	s_nop 1
	v_cndmask_b32_e64 v7, v7, v36, s[6:7]
	v_cmp_lt_f32_e64 s[6:7], 0, v55
	s_nop 1
	v_cndmask_b32_e64 v7, v7, v38, s[6:7]
	v_mul_f32_e32 v36, 0x37800000, v7
	v_cndmask_b32_e32 v7, v7, v36, vcc
	v_cmp_class_f32_e32 vcc, v6, v49
	s_nop 1
	v_cndmask_b32_e32 v6, v7, v6, vcc
	v_div_scale_f32 v7, s[6:7], v6, v6, 1.0
	v_rcp_f32_e32 v36, v7
	v_div_scale_f32 v38, vcc, 1.0, v6, 1.0
	v_fma_f32 v39, -v7, v36, 1.0
	v_fmac_f32_e32 v36, v39, v36
	v_mul_f32_e32 v39, v38, v36
	v_fma_f32 v55, -v7, v39, v38
	v_fmac_f32_e32 v39, v55, v36
	v_fma_f32 v7, -v7, v39, v38
	v_div_fmas_f32 v7, v7, v36, v39
	v_div_fixup_f32 v36, v7, v6, 1.0
	v_pk_mul_f32 v[38:39], v[64:65], v[36:37] op_sel_hi:[1,0]
	v_pk_mul_f32 v[4:5], v[4:5], v[36:37] op_sel_hi:[1,0]
	v_pk_mul_f32 v[0:1], v[0:1], v[36:37] op_sel_hi:[1,0]
	s_waitcnt vmcnt(0)
	v_pk_fma_f32 v[6:7], v[10:11], v[4:5], v[14:15]
	v_pk_fma_f32 v[4:5], v[8:9], v[38:39], v[12:13]
	global_store_dwordx4 v[26:27], v[4:7], off sc1
	global_load_dwordx4 v[8:11], v[16:17], off offset:1024
	global_load_dwordx4 v[12:15], v[18:19], off offset:1024
	v_pk_mul_f32 v[38:39], v[2:3], v[36:37] op_sel_hi:[1,0]
	v_pk_mul_f32 v[30:31], v[30:31], v[36:37] op_sel_hi:[1,0]
	v_pk_mul_f32 v[28:29], v[28:29], v[36:37] op_sel_hi:[1,0]
	v_pk_mul_f32 v[34:35], v[34:35], v[36:37] op_sel_hi:[1,0]
	v_pk_mul_f32 v[32:33], v[32:33], v[36:37] op_sel_hi:[1,0]
	v_med3_f32 v36, v4, s31, v50
	v_med3_f32 v59, v5, s31, v50
	v_med3_f32 v187, v6, s31, v50
	v_med3_f32 v196, v7, s31, v50
	v_mov_b32_e32 v55, 0
	v_cvt_pk_fp8_f32 v55, v36, v59
	v_cvt_pk_fp8_f32 v55, v187, v196 op_sel:[0,0,1]
	s_waitcnt vmcnt(0)
	v_pk_fma_f32 v[2:3], v[10:11], v[0:1], v[14:15]
	v_pk_fma_f32 v[0:1], v[8:9], v[38:39], v[12:13]
	global_store_dwordx4 v[26:27], v[0:3], off offset:1024 sc1
	global_load_dwordx4 v[8:11], v[16:17], off offset:2048
	global_load_dwordx4 v[12:15], v[18:19], off offset:2048
	ds_read_b128 v[60:63], v51
	ds_read_b128 v[64:67], v51 offset:16
	ds_read_b128 v[68:71], v51 offset:32
	ds_read_b128 v[72:75], v51 offset:48
	ds_read_b128 v[76:79], v51 offset:64
	ds_read_b128 v[80:83], v51 offset:80
	ds_read_b128 v[84:87], v51 offset:96
	ds_read_b128 v[88:91], v51 offset:112
	ds_read_b128 v[92:95], v51 offset:8192
	ds_read_b128 v[96:99], v51 offset:8208
	ds_read_b128 v[100:103], v51 offset:8224
	ds_read_b128 v[104:107], v51 offset:8240
	ds_read_b128 v[108:111], v51 offset:8256
	ds_read_b128 v[112:115], v51 offset:8272
	ds_read_b128 v[116:119], v51 offset:8288
	ds_read_b128 v[120:123], v51 offset:8304
	ds_read_b128 v[124:127], v51 offset:16384
	ds_read_b128 v[128:131], v51 offset:16400
	ds_read_b128 v[132:135], v51 offset:16416
	ds_read_b128 v[136:139], v51 offset:16432
	ds_read_b128 v[140:143], v51 offset:16448
	ds_read_b128 v[144:147], v51 offset:16464
	ds_read_b128 v[148:151], v51 offset:16480
	ds_read_b128 v[152:155], v51 offset:16496
	ds_read_b128 v[156:159], v51 offset:24576
	ds_read_b128 v[164:167], v51 offset:24592
	ds_read_b128 v[168:171], v51 offset:24608
	ds_read_b128 v[172:175], v51 offset:24624
	ds_read_b128 v[176:179], v51 offset:24640
	ds_read_b128 v[180:183], v51 offset:24656
	ds_read_b128 v[188:191], v51 offset:24672
	ds_read_b128 v[192:195], v51 offset:24688
	s_waitcnt lgkmcnt(14)
	v_fma_f32 v62, v62, v4, 0
	v_fma_f32 v63, v63, v4, 0
	v_fma_f32 v64, v64, v4, 0
	v_fma_f32 v65, v65, v4, 0
	v_fma_f32 v66, v66, v4, 0
	v_fma_f32 v67, v67, v4, 0
	v_pk_fma_f32 v[60:61], v[60:61], v[4:5], 0 op_sel_hi:[1,0,0]
	v_fmac_f32_e32 v62, v70, v5
	v_fmac_f32_e32 v63, v71, v5
	v_fmac_f32_e32 v64, v72, v5
	v_fmac_f32_e32 v65, v73, v5
	v_fmac_f32_e32 v66, v74, v5
	v_fmac_f32_e32 v67, v75, v5
	v_pk_fma_f32 v[4:5], v[68:69], v[4:5], v[60:61] op_sel:[0,1,0]
	v_fmac_f32_e32 v62, v78, v6
	v_fmac_f32_e32 v63, v79, v6
	v_fmac_f32_e32 v64, v80, v6
	v_fmac_f32_e32 v65, v81, v6
	v_fmac_f32_e32 v66, v82, v6
	v_fmac_f32_e32 v67, v83, v6
	v_pk_fma_f32 v[4:5], v[76:77], v[6:7], v[4:5] op_sel_hi:[1,0,1]
	v_fmac_f32_e32 v62, v7, v86
	v_fmac_f32_e32 v63, v7, v87
	v_fmac_f32_e32 v64, v7, v88
	v_fmac_f32_e32 v65, v7, v89
	v_fmac_f32_e32 v66, v7, v90
	v_fmac_f32_e32 v67, v7, v91
	v_pk_fma_f32 v[4:5], v[6:7], v[84:85], v[4:5] op_sel:[1,0,0]
	v_fmac_f32_e32 v62, v0, v94
	v_fmac_f32_e32 v63, v0, v95
	v_fmac_f32_e32 v64, v0, v96
	v_fmac_f32_e32 v65, v0, v97
	v_fmac_f32_e32 v66, v0, v98
	v_fmac_f32_e32 v67, v0, v99
	v_pk_fma_f32 v[4:5], v[0:1], v[92:93], v[4:5] op_sel_hi:[0,1,1]
	v_med3_f32 v6, v0, s31, v50
	v_med3_f32 v7, v1, s31, v50
	v_fmac_f32_e32 v62, v1, v102
	v_fmac_f32_e32 v63, v1, v103
	v_fmac_f32_e32 v64, v1, v104
	v_fmac_f32_e32 v65, v1, v105
	v_fmac_f32_e32 v66, v1, v106
	v_fmac_f32_e32 v67, v1, v107
	v_pk_fma_f32 v[0:1], v[0:1], v[100:101], v[4:5] op_sel:[1,0,0]
	v_fmac_f32_e32 v62, v2, v110
	v_fmac_f32_e32 v63, v2, v111
	v_fmac_f32_e32 v64, v2, v112
	v_fmac_f32_e32 v65, v2, v113
	v_fmac_f32_e32 v66, v2, v114
	v_fmac_f32_e32 v67, v2, v115
	v_pk_fma_f32 v[0:1], v[2:3], v[108:109], v[0:1] op_sel_hi:[0,1,1]
	v_fmac_f32_e32 v62, v3, v118
	v_fmac_f32_e32 v63, v3, v119
	v_fmac_f32_e32 v64, v3, v120
	v_fmac_f32_e32 v65, v3, v121
	v_fmac_f32_e32 v66, v3, v122
	v_fmac_f32_e32 v67, v3, v123
	v_pk_fma_f32 v[0:1], v[2:3], v[116:117], v[0:1] op_sel:[1,0,0]
	v_med3_f32 v36, v2, s31, v50
	v_med3_f32 v59, v3, s31, v50
	v_cvt_pk_fp8_f32 v56, v6, v7
	v_lshl_add_u64 v[38:39], s[84:85], 0, v[20:21]
	v_add_co_u32_e32 v38, vcc, s36, v38
	v_cvt_pk_fp8_f32 v56, v36, v59 op_sel:[0,0,1]
	s_nop 0
	v_addc_co_u32_e32 v39, vcc, 0, v39, vcc
	s_waitcnt vmcnt(0)
	v_pk_fma_f32 v[10:11], v[10:11], v[28:29], v[14:15]
	v_pk_fma_f32 v[8:9], v[8:9], v[30:31], v[12:13]
	global_store_dwordx4 v[26:27], v[8:11], off offset:2048 sc1
	global_load_dwordx4 v[12:15], v[16:17], off offset:3072
	global_load_dwordx4 v[28:31], v[18:19], off offset:3072
	v_med3_f32 v2, v8, s31, v50
	v_med3_f32 v3, v9, s31, v50
	v_fmac_f32_e32 v62, v8, v126
	v_fmac_f32_e32 v63, v8, v127
	v_fmac_f32_e32 v64, v8, v128
	v_fmac_f32_e32 v65, v8, v129
	v_fmac_f32_e32 v66, v8, v130
	v_fmac_f32_e32 v67, v8, v131
	v_pk_fma_f32 v[0:1], v[8:9], v[124:125], v[0:1] op_sel_hi:[0,1,1]
	v_cvt_pk_fp8_f32 v57, v2, v3
	s_waitcnt lgkmcnt(13)
	v_pk_fma_f32 v[0:1], v[8:9], v[132:133], v[0:1] op_sel:[1,0,0]
	v_fmac_f32_e32 v62, v9, v134
	v_fmac_f32_e32 v63, v9, v135
	s_waitcnt lgkmcnt(12)
	v_fmac_f32_e32 v64, v9, v136
	v_fmac_f32_e32 v65, v9, v137
	v_fmac_f32_e32 v66, v9, v138
	v_fmac_f32_e32 v67, v9, v139
	s_waitcnt lgkmcnt(11)
	v_fmac_f32_e32 v62, v10, v142
	v_fmac_f32_e32 v63, v10, v143
	s_waitcnt lgkmcnt(10)
	v_fmac_f32_e32 v64, v10, v144
	v_fmac_f32_e32 v65, v10, v145
	v_fmac_f32_e32 v66, v10, v146
	v_fmac_f32_e32 v67, v10, v147
	v_pk_fma_f32 v[0:1], v[10:11], v[140:141], v[0:1] op_sel_hi:[0,1,1]
	s_waitcnt lgkmcnt(9)
	v_fmac_f32_e32 v62, v11, v150
	v_fmac_f32_e32 v63, v11, v151
	s_waitcnt lgkmcnt(8)
	v_fmac_f32_e32 v64, v11, v152
	v_fmac_f32_e32 v65, v11, v153
	v_fmac_f32_e32 v66, v11, v154
	v_fmac_f32_e32 v67, v11, v155
	v_pk_fma_f32 v[4:5], v[10:11], v[148:149], v[0:1] op_sel:[1,0,0]
	v_med3_f32 v6, v10, s31, v50
	v_med3_f32 v7, v11, s31, v50
	v_cvt_pk_fp8_f32 v57, v6, v7 op_sel:[0,0,1]
	s_waitcnt vmcnt(0)
	v_pk_fma_f32 v[0:1], v[12:13], v[34:35], v[28:29]
	v_pk_fma_f32 v[2:3], v[14:15], v[32:33], v[30:31]
	s_waitcnt lgkmcnt(7)
	v_fmac_f32_e32 v62, v0, v158
	v_fmac_f32_e32 v63, v0, v159
	s_waitcnt lgkmcnt(6)
	v_fmac_f32_e32 v64, v0, v164
	v_fmac_f32_e32 v65, v0, v165
	v_fmac_f32_e32 v66, v0, v166
	v_fmac_f32_e32 v67, v0, v167
	v_pk_fma_f32 v[4:5], v[0:1], v[156:157], v[4:5] op_sel_hi:[0,1,1]
	global_store_dwordx4 v[26:27], v[0:3], off offset:3072 sc1
	v_med3_f32 v6, v0, s31, v50
	v_med3_f32 v7, v1, s31, v50
	s_waitcnt lgkmcnt(5)
	v_fmac_f32_e32 v62, v1, v170
	v_fmac_f32_e32 v63, v1, v171
	s_waitcnt lgkmcnt(4)
	v_fmac_f32_e32 v64, v1, v172
	v_fmac_f32_e32 v65, v1, v173
	v_fmac_f32_e32 v66, v1, v174
	v_fmac_f32_e32 v67, v1, v175
	v_pk_fma_f32 v[0:1], v[0:1], v[168:169], v[4:5] op_sel:[1,0,0]
	s_waitcnt lgkmcnt(3)
	v_fmac_f32_e32 v62, v2, v178
	v_fmac_f32_e32 v63, v2, v179
	s_waitcnt lgkmcnt(2)
	v_fmac_f32_e32 v64, v2, v180
	v_fmac_f32_e32 v65, v2, v181
	v_fmac_f32_e32 v66, v2, v182
	v_fmac_f32_e32 v67, v2, v183
	v_pk_fma_f32 v[0:1], v[2:3], v[176:177], v[0:1] op_sel_hi:[0,1,1]
	s_waitcnt lgkmcnt(1)
	v_fmac_f32_e32 v62, v3, v190
	v_fmac_f32_e32 v63, v3, v191
	s_waitcnt lgkmcnt(0)
	v_fmac_f32_e32 v64, v3, v192
	v_fmac_f32_e32 v65, v3, v193
	v_fmac_f32_e32 v66, v3, v194
	v_fmac_f32_e32 v67, v3, v195
	v_pk_fma_f32 v[0:1], v[2:3], v[188:189], v[0:1] op_sel:[1,0,0]
	v_med3_f32 v8, v2, s31, v50
	v_med3_f32 v9, v3, s31, v50
	v_cvt_pk_fp8_f32 v58, v6, v7
	ds_bpermute_b32 v2, v40, v0
	ds_bpermute_b32 v3, v40, v1
	ds_bpermute_b32 v4, v40, v62
	ds_bpermute_b32 v5, v40, v63
	ds_bpermute_b32 v6, v40, v64
	ds_bpermute_b32 v7, v40, v65
	ds_bpermute_b32 v10, v40, v66
	ds_bpermute_b32 v11, v40, v67
	v_cvt_pk_fp8_f32 v58, v8, v9 op_sel:[0,0,1]
	s_waitcnt lgkmcnt(6)
	v_pk_add_f32 v[0:1], v[0:1], v[2:3]
	s_waitcnt lgkmcnt(5)
	v_add_f32_e32 v4, v62, v4
	s_waitcnt lgkmcnt(4)
	v_add_f32_e32 v5, v63, v5
	s_waitcnt lgkmcnt(3)
	v_add_f32_e32 v6, v64, v6
	s_waitcnt lgkmcnt(2)
	v_add_f32_e32 v7, v65, v7
	s_waitcnt lgkmcnt(1)
	v_add_f32_e32 v8, v66, v10
	s_waitcnt lgkmcnt(0)
	v_add_f32_e32 v9, v67, v11
	ds_bpermute_b32 v2, v41, v0
	ds_bpermute_b32 v3, v41, v1
	ds_bpermute_b32 v10, v41, v4
	ds_bpermute_b32 v11, v41, v5
	ds_bpermute_b32 v12, v41, v6
	ds_bpermute_b32 v13, v41, v7
	ds_bpermute_b32 v14, v41, v8
	ds_bpermute_b32 v15, v41, v9
	s_waitcnt lgkmcnt(6)
	v_pk_add_f32 v[0:1], v[0:1], v[2:3]
	s_waitcnt lgkmcnt(5)
	v_add_f32_e32 v4, v4, v10
	s_waitcnt lgkmcnt(4)
	v_add_f32_e32 v5, v5, v11
	s_waitcnt lgkmcnt(3)
	v_add_f32_e32 v6, v6, v12
	s_waitcnt lgkmcnt(2)
	v_add_f32_e32 v7, v7, v13
	s_waitcnt lgkmcnt(1)
	v_add_f32_e32 v8, v8, v14
	s_waitcnt lgkmcnt(0)
	v_add_f32_e32 v9, v9, v15
	ds_bpermute_b32 v2, v42, v0
	ds_bpermute_b32 v3, v42, v1
	ds_bpermute_b32 v10, v42, v4
	ds_bpermute_b32 v11, v42, v5
	ds_bpermute_b32 v12, v42, v6
	ds_bpermute_b32 v13, v42, v7
	ds_bpermute_b32 v14, v42, v8
	ds_bpermute_b32 v15, v42, v9
	s_waitcnt lgkmcnt(6)
	v_pk_add_f32 v[0:1], v[0:1], v[2:3]
	s_waitcnt lgkmcnt(5)
	v_add_f32_e32 v4, v4, v10
	s_waitcnt lgkmcnt(4)
	v_add_f32_e32 v5, v5, v11
	s_waitcnt lgkmcnt(3)
	v_add_f32_e32 v6, v6, v12
	s_waitcnt lgkmcnt(2)
	v_add_f32_e32 v7, v7, v13
	s_waitcnt lgkmcnt(1)
	v_add_f32_e32 v8, v8, v14
	s_waitcnt lgkmcnt(0)
	v_add_f32_e32 v9, v9, v15
	ds_bpermute_b32 v2, v43, v0
	ds_bpermute_b32 v3, v43, v1
	ds_bpermute_b32 v10, v43, v4
	ds_bpermute_b32 v11, v43, v5
	ds_bpermute_b32 v12, v43, v6
	ds_bpermute_b32 v13, v43, v7
	ds_bpermute_b32 v14, v43, v8
	ds_bpermute_b32 v15, v43, v9
	s_waitcnt lgkmcnt(6)
	v_pk_add_f32 v[0:1], v[0:1], v[2:3]
	s_waitcnt lgkmcnt(5)
	v_add_f32_e32 v4, v4, v10
	s_waitcnt lgkmcnt(4)
	v_add_f32_e32 v5, v5, v11
	s_waitcnt lgkmcnt(3)
	v_add_f32_e32 v6, v6, v12
	s_waitcnt lgkmcnt(2)
	v_add_f32_e32 v7, v7, v13
	s_waitcnt lgkmcnt(1)
	v_add_f32_e32 v8, v8, v14
	s_waitcnt lgkmcnt(0)
	v_add_f32_e32 v10, v9, v15
	ds_bpermute_b32 v2, v44, v0
	ds_bpermute_b32 v3, v44, v1
	ds_bpermute_b32 v9, v44, v4
	ds_bpermute_b32 v11, v44, v5
	ds_bpermute_b32 v12, v44, v6
	ds_bpermute_b32 v13, v44, v7
	ds_bpermute_b32 v14, v44, v8
	ds_bpermute_b32 v15, v44, v10
	s_waitcnt lgkmcnt(6)
	v_pk_add_f32 v[0:1], v[0:1], v[2:3]
	s_waitcnt lgkmcnt(5)
	v_add_f32_e32 v4, v4, v9
	s_waitcnt lgkmcnt(4)
	v_add_f32_e32 v5, v5, v11
	s_waitcnt lgkmcnt(3)
	v_add_f32_e32 v6, v6, v12
	s_waitcnt lgkmcnt(2)
	v_add_f32_e32 v7, v7, v13
	s_waitcnt lgkmcnt(1)
	v_add_f32_e32 v9, v8, v14
	s_waitcnt lgkmcnt(0)
	v_add_f32_e32 v11, v10, v15
	ds_bpermute_b32 v2, v45, v0
	ds_bpermute_b32 v3, v45, v1
	ds_bpermute_b32 v8, v45, v4
	ds_bpermute_b32 v10, v45, v5
	ds_bpermute_b32 v12, v45, v6
	ds_bpermute_b32 v13, v45, v7
	ds_bpermute_b32 v14, v45, v9
	ds_bpermute_b32 v15, v45, v11
	global_store_dword v[38:39], v55, off
	global_store_dword v[38:39], v56, off offset:256
	global_store_dword v[38:39], v57, off offset:512
	global_store_dword v[38:39], v58, off offset:768
	s_and_saveexec_b64 s[34:35], s[4:5]
	s_cbranch_execz .LBB0_1059
	s_waitcnt lgkmcnt(6)
	v_pk_add_f32 v[2:3], v[0:1], v[2:3]
	s_waitcnt lgkmcnt(5)
	v_add_f32_e32 v4, v4, v8
	v_cmp_gt_f32_e32 vcc, v3, v2
	s_waitcnt lgkmcnt(4)
	v_add_f32_e32 v5, v5, v10
	s_waitcnt lgkmcnt(3)
	v_add_f32_e32 v6, v6, v12
	v_cndmask_b32_e32 v0, v2, v3, vcc
	v_cmp_gt_f32_e64 s[6:7], v4, v0
	s_waitcnt lgkmcnt(2)
	v_add_f32_e32 v7, v7, v13
	s_waitcnt lgkmcnt(1)
	v_add_f32_e32 v9, v9, v14
	v_cndmask_b32_e64 v0, v0, v4, s[6:7]
	v_cmp_gt_f32_e64 s[8:9], v5, v0
	s_waitcnt lgkmcnt(0)
	v_add_f32_e32 v11, v11, v15
	v_cmp_lt_f32_e64 s[18:19], s37, v2
	v_cndmask_b32_e64 v0, v0, v5, s[8:9]
	v_cmp_gt_f32_e64 s[10:11], v6, v0
	s_ashr_i32 s21, s20, 31
	s_nop 0
	v_cndmask_b32_e64 v0, v0, v6, s[10:11]
	v_cmp_gt_f32_e64 s[12:13], v7, v0
	s_nop 1
	v_cndmask_b32_e64 v0, v0, v7, s[12:13]
	v_cmp_gt_f32_e64 s[14:15], v9, v0
	s_nop 1
	v_cndmask_b32_e64 v1, v0, v9, s[14:15]
	v_cndmask_b32_e64 v0, 0, 1, vcc
	v_cndmask_b32_e64 v0, v0, 2, s[6:7]
	v_cndmask_b32_e64 v0, v0, 3, s[8:9]
	v_cndmask_b32_e64 v0, v0, 4, s[10:11]
	v_cndmask_b32_e64 v0, v0, 5, s[12:13]
	v_cndmask_b32_e64 v0, v0, 6, s[14:15]
	v_cmp_ngt_f32_e32 vcc, v11, v1
	s_and_b64 s[42:43], s[14:15], vcc
	s_nop 0
	v_cndmask_b32_e32 v0, 7, v0, vcc
	v_cmp_ne_u32_e64 s[16:17], 0, v0
	s_and_b64 s[16:17], s[16:17], s[18:19]
	v_cmp_ne_u32_e64 s[14:15], 1, v0
	v_cndmask_b32_e64 v2, v53, v2, s[16:17]
	v_cmp_gt_f32_e64 s[16:17], v3, v2
	s_and_b64 s[14:15], s[14:15], s[16:17]
	v_cndmask_b32_e64 v2, v2, v3, s[14:15]
	v_cmp_ne_u32_e64 s[12:13], 2, v0
	v_cmp_gt_f32_e64 s[16:17], v4, v2
	s_and_b64 s[12:13], s[12:13], s[16:17]
	v_cndmask_b32_e64 v2, v2, v4, s[12:13]
	v_cmp_ne_u32_e64 s[10:11], 3, v0
	v_cmp_gt_f32_e64 s[16:17], v5, v2
	s_and_b64 s[10:11], s[10:11], s[16:17]
	v_cndmask_b32_e64 v2, v2, v5, s[10:11]
	v_cmp_ne_u32_e64 s[8:9], 4, v0
	v_cmp_gt_f32_e64 s[16:17], v6, v2
	s_and_b64 s[8:9], s[8:9], s[16:17]
	v_cndmask_b32_e64 v2, v2, v6, s[8:9]
	v_cmp_ne_u32_e64 s[6:7], 5, v0
	v_cmp_gt_f32_e64 s[16:17], v7, v2
	s_and_b64 s[6:7], s[6:7], s[16:17]
	v_cndmask_b32_e64 v2, v2, v7, s[6:7]
	v_cmp_ngt_f32_e64 s[16:17], v9, v2
	s_or_b64 s[16:17], s[42:43], s[16:17]
	v_cndmask_b32_e32 v1, v11, v1, vcc
	v_cndmask_b32_e64 v2, v9, v2, s[16:17]
	v_cmp_gt_f32_e64 s[18:19], v11, v2
	s_and_b64 s[18:19], vcc, s[18:19]
	v_cndmask_b32_e64 v3, 0, 1, s[14:15]
	v_cndmask_b32_e64 v2, v2, v11, s[18:19]
	v_sub_f32_e32 v4, v2, v1
	v_mul_f32_e32 v1, 0x3fb8aa3b, v4
	v_fma_f32 v2, v4, s38, -v1
	v_rndne_f32_e32 v5, v1
	v_fmac_f32_e32 v2, 0x32a5705f, v4
	v_sub_f32_e32 v1, v1, v5
	v_add_f32_e32 v1, v1, v2
	v_cndmask_b32_e64 v3, v3, 2, s[12:13]
	v_exp_f32_e32 v1, v1
	v_cvt_i32_f32_e32 v5, v5
	v_cndmask_b32_e64 v3, v3, 3, s[10:11]
	v_cndmask_b32_e64 v3, v3, 4, s[8:9]
	v_cndmask_b32_e64 v2, v3, 5, s[6:7]
	v_cndmask_b32_e64 v2, 6, v2, s[16:17]
	v_ldexp_f32 v1, v1, v5
	v_cmp_ngt_f32_e32 vcc, s39, v4
	v_cndmask_b32_e64 v2, v2, 7, s[18:19]
	v_lshl_add_u32 v3, v2, 2, 0
	v_cndmask_b32_e32 v5, 0, v1, vcc
	v_lshl_add_u32 v1, v0, 2, 0
	ds_add_rtn_u32 v1, v1, v52 offset:32768
	ds_add_rtn_u32 v3, v3, v52 offset:32768
	v_cmp_nlt_f32_e32 vcc, s40, v4
	s_and_b32 s6, s3, 60
	v_lshl_add_u32 v6, s6, 2, v46
	v_cndmask_b32_e32 v4, v54, v5, vcc
	v_add_f32_e32 v5, 1.0, v4
	s_waitcnt lgkmcnt(0)
	ds_write_b128 v6, v[0:3] offset:32832
	v_div_scale_f32 v0, s[6:7], v5, v5, v4
	v_rcp_f32_e32 v1, v0
	s_lshl_b64 s[6:7], s[20:21], 2
	s_add_u32 s6, s54, s6
	s_addc_u32 s7, s55, s7
	v_fma_f32 v2, -v0, v1, 1.0
	v_fmac_f32_e32 v1, v2, v1
	v_div_scale_f32 v2, vcc, v4, v5, v4
	v_mul_f32_e32 v3, v2, v1
	v_fma_f32 v6, -v0, v3, v2
	v_fmac_f32_e32 v3, v6, v1
	v_fma_f32 v0, -v0, v3, v2
	v_div_scale_f32 v2, s[8:9], v5, v5, 1.0
	v_rcp_f32_e32 v6, v2
	v_div_fmas_f32 v0, v0, v1, v3
	v_div_fixup_f32 v1, v0, v5, v4
	v_fma_f32 v0, -v2, v6, 1.0
	v_fmac_f32_e32 v6, v0, v6
	v_div_scale_f32 v0, vcc, 1.0, v5, 1.0
	v_mul_f32_e32 v3, v0, v6
	v_fma_f32 v4, -v2, v3, v0
	v_fmac_f32_e32 v3, v4, v6
	v_fma_f32 v0, -v2, v3, v0
	v_div_fmas_f32 v0, v0, v6, v3
	v_div_fixup_f32 v0, v0, v5, 1.0
	global_store_dwordx2 v47, v[0:1], s[6:7]
	s_branch .LBB0_1059

.LBB0_1064:
	s_or_b64 exec, exec, s[4:5]
	v_and_b32_e32 v0, 15, v161
	v_lshrrev_b32_e32 v1, 4, v161
	s_movk_i32 s3, 0x80
	v_mul_lo_u32 v0, s80, v0
	v_sub_u32_e32 v1, v1, v185
	v_cmp_gt_u32_e32 vcc, s3, v161
	v_add3_u32 v0, v1, v0, s46
	s_movk_i32 s3, 0x4000
	s_add_u32 s6, s84, 0x900000
	v_cmp_gt_i32_e64 s[4:5], s3, v0
	s_addc_u32 s7, s85, 0
	s_and_b64 s[8:9], vcc, s[4:5]
	s_waitcnt lgkmcnt(0)
	s_barrier
	s_and_saveexec_b64 s[4:5], s[8:9]
	s_cbranch_execz .LBB0_1066
	ds_read_b128 v[2:5], v37 offset:32832
	v_lshlrev_b32_e32 v0, 2, v0
	s_waitcnt lgkmcnt(0)
	v_lshl_add_u32 v1, v2, 2, 0
	v_lshl_add_u32 v6, v4, 2, 0
	ds_read_b32 v7, v1 offset:32800
	ds_read_b32 v6, v6 offset:32800
	v_ashrrev_i32_e32 v1, 31, v0
	v_lshl_add_u64 v[0:1], v[0:1], 2, s[6:7]
	s_waitcnt lgkmcnt(1)
	v_add_u32_e32 v3, v3, v7
	s_waitcnt lgkmcnt(0)
	v_add_u32_e32 v5, v5, v6
	global_store_dwordx4 v[0:1], v[2:5], off sc1

.Lgat4_top:
	s_add_i32 s18, s13, s16
	s_cmpk_lt_i32 s18, 0x4000
	s_cbranch_scc0 .Lgat4_done
	s_ashr_i32 s9, s8, 31
	s_lshl_b64 s[10:11], s[8:9], 2
	s_add_u32 s10, s6, s10
	s_addc_u32 s11, s7, s11
	s_add_u32 s20, s10, s17
	s_addc_u32 s21, s11, 0
	s_add_u32 s22, s20, s17
	s_addc_u32 s23, s21, 0
	s_add_u32 s24, s22, s17
	s_addc_u32 s25, s23, 0
	v_lshl_add_u64 v[42:43], v[0:1], 0, s[4:5]
	v_lshl_add_u64 v[44:45], v[42:43], 0, s[4:5]
	v_lshl_add_u64 v[46:47], v[44:45], 0, s[4:5]
	global_load_dwordx4 v[4:7], v8, s[10:11]
	global_load_dwordx4 v[18:21], v8, s[20:21]
	global_load_dwordx4 v[22:25], v8, s[22:23]
	global_load_dwordx4 v[26:29], v8, s[24:25]
	global_load_dwordx4 v[10:13], v[0:1], off
	global_load_dwordx4 v[30:33], v[42:43], off
	global_load_dwordx4 v[34:37], v[44:45], off
	global_load_dwordx4 v[38:41], v[46:47], off
	s_waitcnt vmcnt(4)
	v_lshlrev_b32_e32 v4, 2, v4
	v_lshlrev_b32_e32 v6, 2, v6
	ds_read_b32 v6, v6
	ds_read_b32 v4, v4
	v_lshlrev_b32_e32 v18, 2, v18
	v_lshlrev_b32_e32 v20, 2, v20
	ds_read_b32 v20, v20
	ds_read_b32 v18, v18
	v_lshlrev_b32_e32 v22, 2, v22
	v_lshlrev_b32_e32 v24, 2, v24
	ds_read_b32 v24, v24
	ds_read_b32 v22, v22
	v_lshlrev_b32_e32 v26, 2, v26
	v_lshlrev_b32_e32 v28, 2, v28
	ds_read_b32 v28, v28
	ds_read_b32 v26, v26
	s_waitcnt lgkmcnt(0)
	v_add_u32_e32 v6, v6, v7
	v_add_u32_e32 v4, v4, v5
	v_add_u32_e32 v20, v20, v21
	v_add_u32_e32 v18, v18, v19
	v_add_u32_e32 v24, v24, v25
	v_add_u32_e32 v22, v22, v23
	v_add_u32_e32 v28, v28, v29
	v_add_u32_e32 v26, v26, v27
	s_waitcnt vmcnt(0)
	v_ashrrev_i32_e32 v5, 31, v4
	v_ashrrev_i32_e32 v7, 31, v6
	v_lshlrev_b64 v[14:15], 10, v[4:5]
	v_lshlrev_b64 v[16:17], 10, v[6:7]
	v_lshl_add_u64 v[14:15], v[2:3], 0, v[14:15]
	v_lshl_add_u64 v[16:17], v[2:3], 0, v[16:17]
	global_store_dwordx4 v[14:15], v[10:13], off sc1
	global_store_dwordx4 v[16:17], v[10:13], off sc1
	s_ashr_i32 s1, s0, 31
	s_lshl_b64 s[14:15], s[0:1], 2
	s_add_u32 s14, s50, s14
	s_addc_u32 s15, s51, s15
	v_mov_b32_e32 v5, v6
	s_and_saveexec_b64 s[26:27], vcc
	global_store_dwordx2 v8, v[4:5], s[14:15]
	s_or_b64 exec, exec, s[26:27]
	s_add_i32 s0, s0, s3
	s_add_i32 s8, s8, s12
	s_add_i32 s13, s13, s80
	v_ashrrev_i32_e32 v19, 31, v18
	v_ashrrev_i32_e32 v21, 31, v20
	v_lshlrev_b64 v[14:15], 10, v[18:19]
	v_lshlrev_b64 v[16:17], 10, v[20:21]
	v_lshl_add_u64 v[14:15], v[2:3], 0, v[14:15]
	v_lshl_add_u64 v[16:17], v[2:3], 0, v[16:17]
	global_store_dwordx4 v[14:15], v[30:33], off sc1
	global_store_dwordx4 v[16:17], v[30:33], off sc1
	s_ashr_i32 s1, s0, 31
	s_lshl_b64 s[14:15], s[0:1], 2
	s_add_u32 s14, s50, s14
	s_addc_u32 s15, s51, s15
	v_mov_b32_e32 v19, v20
	s_and_saveexec_b64 s[26:27], vcc
	global_store_dwordx2 v8, v[18:19], s[14:15]
	s_or_b64 exec, exec, s[26:27]
	s_add_i32 s0, s0, s3
	s_add_i32 s8, s8, s12
	s_add_i32 s13, s13, s80
	v_ashrrev_i32_e32 v23, 31, v22
	v_ashrrev_i32_e32 v25, 31, v24
	v_lshlrev_b64 v[14:15], 10, v[22:23]
	v_lshlrev_b64 v[16:17], 10, v[24:25]
	v_lshl_add_u64 v[14:15], v[2:3], 0, v[14:15]
	v_lshl_add_u64 v[16:17], v[2:3], 0, v[16:17]
	global_store_dwordx4 v[14:15], v[34:37], off sc1
	global_store_dwordx4 v[16:17], v[34:37], off sc1
	s_ashr_i32 s1, s0, 31
	s_lshl_b64 s[14:15], s[0:1], 2
	s_add_u32 s14, s50, s14
	s_addc_u32 s15, s51, s15
	v_mov_b32_e32 v23, v24
	s_and_saveexec_b64 s[26:27], vcc
	global_store_dwordx2 v8, v[22:23], s[14:15]
	s_or_b64 exec, exec, s[26:27]
	s_add_i32 s0, s0, s3
	s_add_i32 s8, s8, s12
	s_add_i32 s13, s13, s80
	v_ashrrev_i32_e32 v27, 31, v26
	v_ashrrev_i32_e32 v29, 31, v28
	v_lshlrev_b64 v[14:15], 10, v[26:27]
	v_lshlrev_b64 v[16:17], 10, v[28:29]
	v_lshl_add_u64 v[14:15], v[2:3], 0, v[14:15]
	v_lshl_add_u64 v[16:17], v[2:3], 0, v[16:17]
	global_store_dwordx4 v[14:15], v[38:41], off sc1
	global_store_dwordx4 v[16:17], v[38:41], off sc1
	s_ashr_i32 s1, s0, 31
	s_lshl_b64 s[14:15], s[0:1], 2
	s_add_u32 s14, s50, s14
	s_addc_u32 s15, s51, s15
	v_mov_b32_e32 v27, v28
	s_and_saveexec_b64 s[26:27], vcc
	global_store_dwordx2 v8, v[26:27], s[14:15]
	s_or_b64 exec, exec, s[26:27]
	s_add_i32 s0, s0, s3
	s_add_i32 s8, s8, s12
	s_add_i32 s13, s13, s80
	v_lshl_add_u64 v[0:1], v[46:47], 0, s[4:5]
	s_branch .Lgat4_top

.LBB0_1202:
	s_ashr_i32 s9, s8, 31
	s_lshl_b64 s[10:11], s[8:9], 2
	s_add_u32 s10, s6, s10
	s_addc_u32 s11, s7, s11
	global_load_dwordx4 v[4:7], v8, s[10:11]
	global_load_dwordx4 v[10:13], v[0:1], off
	s_waitcnt vmcnt(1)
	v_lshlrev_b32_e32 v4, 2, v4
	v_lshlrev_b32_e32 v6, 2, v6
	v_add_u32_e32 v4, 0, v4
	v_add_u32_e32 v6, 0, v6
	ds_read_b32 v6, v6
	ds_read_b32 v4, v4
	s_waitcnt lgkmcnt(1)
	v_add_u32_e32 v6, v6, v7
	s_waitcnt lgkmcnt(0)
	v_add_u32_e32 v4, v4, v5
	v_ashrrev_i32_e32 v5, 31, v4
	v_ashrrev_i32_e32 v7, 31, v6
	v_lshlrev_b64 v[14:15], 10, v[4:5]
	v_lshlrev_b64 v[16:17], 10, v[6:7]
	v_lshl_add_u64 v[14:15], v[2:3], 0, v[14:15]
	v_lshl_add_u64 v[16:17], v[2:3], 0, v[16:17]
	s_waitcnt vmcnt(0)
	global_store_dwordx4 v[14:15], v[10:13], off sc1
	global_store_dwordx4 v[16:17], v[10:13], off sc1
	s_and_saveexec_b64 s[10:11], vcc
	s_cbranch_execz .LBB0_1201
	s_ashr_i32 s1, s0, 31
	s_lshl_b64 s[14:15], s[0:1], 2
	s_add_u32 s14, s50, s14
	v_mov_b32_e32 v5, v6
	s_addc_u32 s15, s51, s15
	global_store_dwordx2 v8, v[4:5], s[14:15]
	s_branch .LBB0_1201

.LBB0_1352:
	s_ashr_i32 s30, s67, 31
	s_lshr_b32 s30, s30, 30
	s_add_i32 s30, s67, s30
	s_and_b32 s30, s30, 0xfffffc
	s_sub_i32 s30, s67, s30
	v_lshl_add_u32 v6, s28, 8, v161
	v_lshl_or_b32 v0, s30, 8, v180
	v_ashrrev_i32_e32 v7, 31, v6
	v_ashrrev_i32_e32 v1, 31, v0
	v_lshlrev_b64 v[2:3], 11, v[6:7]
	v_lshl_add_u64 v[2:3], s[68:69], 0, v[2:3]
	v_lshlrev_b64 v[8:9], 1, v[0:1]
	v_lshl_add_u64 v[0:1], v[2:3], 0, v[8:9]
	v_pk_mul_f32 v[4:5], v[158:159], s[12:13] op_sel_hi:[1,0]
	v_pk_mul_f32 v[2:3], v[156:157], s[12:13] op_sel_hi:[1,0]
	v_pk_mul_f32 v[10:11], v[154:155], s[12:13] op_sel_hi:[1,0]
	v_pk_mul_f32 v[12:13], v[152:153], s[12:13] op_sel_hi:[1,0]
	v_cvt_pk_bf16_f32 v2, v2, v3
	v_cvt_pk_bf16_f32 v3, v4, v5
	v_cvt_pk_bf16_f32 v4, v12, v13
	v_cvt_pk_bf16_f32 v5, v10, v11
	global_store_dwordx4 v[0:1], v[2:5], off sc1
	v_pk_mul_f32 v[10:11], v[138:139], s[12:13] op_sel_hi:[1,0]
	v_pk_mul_f32 v[12:13], v[136:137], s[12:13] op_sel_hi:[1,0]
	v_pk_mul_f32 v[4:5], v[146:147], s[12:13] op_sel_hi:[1,0]
	v_pk_mul_f32 v[2:3], v[144:145], s[12:13] op_sel_hi:[1,0]
	v_pk_mul_f32 v[14:15], v[140:141], s[12:13] op_sel_hi:[1,0]
	v_cvt_pk_bf16_f32 v2, v2, v3
	v_cvt_pk_bf16_f32 v3, v4, v5
	v_cvt_pk_bf16_f32 v4, v12, v13
	v_cvt_pk_bf16_f32 v5, v10, v11
	global_store_dwordx4 v[0:1], v[2:5], off offset:256 sc1
	v_pk_mul_f32 v[12:13], v[142:143], s[12:13] op_sel_hi:[1,0]
	s_nop 0
	v_or_b32_e32 v2, 16, v6
	v_ashrrev_i32_e32 v3, 31, v2
	v_lshlrev_b64 v[2:3], 11, v[2:3]
	v_lshl_add_u64 v[2:3], s[68:69], 0, v[2:3]
	v_lshl_add_u64 v[10:11], v[2:3], 0, v[8:9]
	v_pk_mul_f32 v[4:5], v[150:151], s[12:13] op_sel_hi:[1,0]
	v_pk_mul_f32 v[2:3], v[148:149], s[12:13] op_sel_hi:[1,0]
	s_nop 0
	v_cvt_pk_bf16_f32 v2, v2, v3
	v_cvt_pk_bf16_f32 v3, v4, v5
	v_cvt_pk_bf16_f32 v4, v14, v15
	v_cvt_pk_bf16_f32 v5, v12, v13
	global_store_dwordx4 v[10:11], v[2:5], off sc1
	v_pk_mul_f32 v[12:13], v[122:123], s[12:13] op_sel_hi:[1,0]
	v_pk_mul_f32 v[14:15], v[120:121], s[12:13] op_sel_hi:[1,0]
	v_pk_mul_f32 v[4:5], v[130:131], s[12:13] op_sel_hi:[1,0]
	v_pk_mul_f32 v[2:3], v[128:129], s[12:13] op_sel_hi:[1,0]
	s_nop 0
	v_cvt_pk_bf16_f32 v2, v2, v3
	v_cvt_pk_bf16_f32 v3, v4, v5
	v_cvt_pk_bf16_f32 v4, v14, v15
	v_cvt_pk_bf16_f32 v5, v12, v13
	global_store_dwordx4 v[10:11], v[2:5], off offset:256 sc1
	v_pk_mul_f32 v[12:13], v[126:127], s[12:13] op_sel_hi:[1,0]
	v_pk_mul_f32 v[14:15], v[124:125], s[12:13] op_sel_hi:[1,0]
	v_or_b32_e32 v2, 32, v6
	v_ashrrev_i32_e32 v3, 31, v2
	v_lshlrev_b64 v[2:3], 11, v[2:3]
	v_lshl_add_u64 v[2:3], s[68:69], 0, v[2:3]
	v_lshl_add_u64 v[10:11], v[2:3], 0, v[8:9]
	v_pk_mul_f32 v[4:5], v[134:135], s[12:13] op_sel_hi:[1,0]
	v_pk_mul_f32 v[2:3], v[132:133], s[12:13] op_sel_hi:[1,0]
	s_nop 0
	v_cvt_pk_bf16_f32 v2, v2, v3
	v_cvt_pk_bf16_f32 v3, v4, v5
	v_cvt_pk_bf16_f32 v4, v14, v15
	v_cvt_pk_bf16_f32 v5, v12, v13
	global_store_dwordx4 v[10:11], v[2:5], off sc1
	v_pk_mul_f32 v[12:13], v[106:107], s[12:13] op_sel_hi:[1,0]
	v_pk_mul_f32 v[14:15], v[104:105], s[12:13] op_sel_hi:[1,0]
	v_pk_mul_f32 v[4:5], v[114:115], s[12:13] op_sel_hi:[1,0]
	v_pk_mul_f32 v[2:3], v[112:113], s[12:13] op_sel_hi:[1,0]
	s_nop 0
	v_cvt_pk_bf16_f32 v2, v2, v3
	v_cvt_pk_bf16_f32 v3, v4, v5
	v_cvt_pk_bf16_f32 v4, v14, v15
	v_cvt_pk_bf16_f32 v5, v12, v13
	global_store_dwordx4 v[10:11], v[2:5], off offset:256 sc1
	v_pk_mul_f32 v[10:11], v[108:109], s[12:13] op_sel_hi:[1,0]
	s_nop 0
	v_or_b32_e32 v2, 48, v6
	v_ashrrev_i32_e32 v3, 31, v2
	v_lshlrev_b64 v[2:3], 11, v[2:3]
	v_lshl_add_u64 v[2:3], s[68:69], 0, v[2:3]
	v_lshl_add_u64 v[6:7], v[2:3], 0, v[8:9]
	v_pk_mul_f32 v[4:5], v[118:119], s[12:13] op_sel_hi:[1,0]
	v_pk_mul_f32 v[2:3], v[116:117], s[12:13] op_sel_hi:[1,0]
	v_pk_mul_f32 v[8:9], v[110:111], s[12:13] op_sel_hi:[1,0]
	v_cvt_pk_bf16_f32 v2, v2, v3
	v_cvt_pk_bf16_f32 v3, v4, v5
	v_cvt_pk_bf16_f32 v4, v10, v11
	v_cvt_pk_bf16_f32 v5, v8, v9
	global_store_dwordx4 v[6:7], v[2:5], off sc1
	v_pk_mul_f32 v[8:9], v[98:99], s[12:13] op_sel_hi:[1,0]
	v_pk_mul_f32 v[10:11], v[96:97], s[12:13] op_sel_hi:[1,0]
	v_pk_mul_f32 v[4:5], v[102:103], s[12:13] op_sel_hi:[1,0]
	v_pk_mul_f32 v[2:3], v[100:101], s[12:13] op_sel_hi:[1,0]
	s_nop 0
	v_cvt_pk_bf16_f32 v2, v2, v3
	v_cvt_pk_bf16_f32 v3, v4, v5
	v_cvt_pk_bf16_f32 v4, v10, v11
	v_cvt_pk_bf16_f32 v5, v8, v9
	global_store_dwordx4 v[6:7], v[2:5], off offset:256 sc1
	v_pk_mul_f32 v[8:9], v[90:91], s[12:13] op_sel_hi:[1,0]
	v_pk_mul_f32 v[10:11], v[88:89], s[12:13] op_sel_hi:[1,0]
	v_pk_mul_f32 v[4:5], v[94:95], s[12:13] op_sel_hi:[1,0]
	v_pk_mul_f32 v[2:3], v[92:93], s[12:13] op_sel_hi:[1,0]
	v_lshl_add_u64 v[6:7], v[0:1], 0, s[14:15]
	v_cvt_pk_bf16_f32 v2, v2, v3
	v_cvt_pk_bf16_f32 v3, v4, v5
	v_cvt_pk_bf16_f32 v5, v8, v9
	v_add_co_u32_e32 v8, vcc, s63, v0
	v_cvt_pk_bf16_f32 v4, v10, v11
	s_nop 0
	v_addc_co_u32_e32 v9, vcc, 0, v1, vcc
	global_store_dwordx4 v[8:9], v[2:5], off sc1
	v_pk_mul_f32 v[8:9], v[74:75], s[12:13] op_sel_hi:[1,0]
	v_pk_mul_f32 v[10:11], v[72:73], s[12:13] op_sel_hi:[1,0]
	v_pk_mul_f32 v[4:5], v[82:83], s[12:13] op_sel_hi:[1,0]
	v_pk_mul_f32 v[2:3], v[80:81], s[12:13] op_sel_hi:[1,0]
	s_nop 0
	v_cvt_pk_bf16_f32 v2, v2, v3
	v_cvt_pk_bf16_f32 v3, v4, v5
	v_cvt_pk_bf16_f32 v4, v10, v11
	v_cvt_pk_bf16_f32 v5, v8, v9
	global_store_dwordx4 v[6:7], v[2:5], off offset:256 sc1
	v_pk_mul_f32 v[8:9], v[78:79], s[12:13] op_sel_hi:[1,0]
	v_pk_mul_f32 v[10:11], v[76:77], s[12:13] op_sel_hi:[1,0]
	v_pk_mul_f32 v[4:5], v[86:87], s[12:13] op_sel_hi:[1,0]
	v_pk_mul_f32 v[2:3], v[84:85], s[12:13] op_sel_hi:[1,0]
	v_lshl_add_u64 v[6:7], v[0:1], 0, s[16:17]
	v_cvt_pk_bf16_f32 v2, v2, v3
	v_cvt_pk_bf16_f32 v3, v4, v5
	v_cvt_pk_bf16_f32 v5, v8, v9
	v_add_co_u32_e32 v8, vcc, s64, v0
	v_cvt_pk_bf16_f32 v4, v10, v11
	s_nop 0
	v_addc_co_u32_e32 v9, vcc, 0, v1, vcc
	global_store_dwordx4 v[8:9], v[2:5], off sc1
	v_pk_mul_f32 v[8:9], v[58:59], s[12:13] op_sel_hi:[1,0]
	v_pk_mul_f32 v[10:11], v[56:57], s[12:13] op_sel_hi:[1,0]
	v_pk_mul_f32 v[4:5], v[66:67], s[12:13] op_sel_hi:[1,0]
	v_pk_mul_f32 v[2:3], v[64:65], s[12:13] op_sel_hi:[1,0]
	s_nop 0
	v_cvt_pk_bf16_f32 v2, v2, v3
	v_cvt_pk_bf16_f32 v3, v4, v5
	v_cvt_pk_bf16_f32 v4, v10, v11
	v_cvt_pk_bf16_f32 v5, v8, v9
	global_store_dwordx4 v[6:7], v[2:5], off offset:256 sc1
	v_pk_mul_f32 v[8:9], v[62:63], s[12:13] op_sel_hi:[1,0]
	v_pk_mul_f32 v[10:11], v[60:61], s[12:13] op_sel_hi:[1,0]
	v_pk_mul_f32 v[4:5], v[70:71], s[12:13] op_sel_hi:[1,0]
	v_pk_mul_f32 v[2:3], v[68:69], s[12:13] op_sel_hi:[1,0]
	v_lshl_add_u64 v[6:7], v[0:1], 0, s[18:19]
	v_cvt_pk_bf16_f32 v2, v2, v3
	v_cvt_pk_bf16_f32 v3, v4, v5
	v_cvt_pk_bf16_f32 v5, v8, v9
	v_add_co_u32_e32 v8, vcc, s65, v0
	v_cvt_pk_bf16_f32 v4, v10, v11
	s_nop 0
	v_addc_co_u32_e32 v9, vcc, 0, v1, vcc
	global_store_dwordx4 v[8:9], v[2:5], off sc1
	v_pk_mul_f32 v[8:9], v[42:43], s[12:13] op_sel_hi:[1,0]
	v_pk_mul_f32 v[10:11], v[40:41], s[12:13] op_sel_hi:[1,0]
	v_pk_mul_f32 v[4:5], v[50:51], s[12:13] op_sel_hi:[1,0]
	v_pk_mul_f32 v[2:3], v[48:49], s[12:13] op_sel_hi:[1,0]
	s_nop 0
	v_cvt_pk_bf16_f32 v2, v2, v3
	v_cvt_pk_bf16_f32 v3, v4, v5
	v_cvt_pk_bf16_f32 v4, v10, v11
	v_cvt_pk_bf16_f32 v5, v8, v9
	global_store_dwordx4 v[6:7], v[2:5], off offset:256 sc1
	v_lshl_add_u64 v[6:7], v[0:1], 0, s[20:21]
	v_pk_mul_f32 v[8:9], v[46:47], s[12:13] op_sel_hi:[1,0]
	v_pk_mul_f32 v[4:5], v[54:55], s[12:13] op_sel_hi:[1,0]
	v_pk_mul_f32 v[2:3], v[52:53], s[12:13] op_sel_hi:[1,0]
	v_pk_mul_f32 v[10:11], v[44:45], s[12:13] op_sel_hi:[1,0]
	v_add_co_u32_e32 v0, vcc, s66, v0
	v_cvt_pk_bf16_f32 v2, v2, v3
	v_cvt_pk_bf16_f32 v3, v4, v5
	v_cvt_pk_bf16_f32 v4, v10, v11
	v_cvt_pk_bf16_f32 v5, v8, v9
	v_addc_co_u32_e32 v1, vcc, 0, v1, vcc
	global_store_dwordx4 v[0:1], v[2:5], off sc1
	v_pk_mul_f32 v[0:1], v[36:37], s[12:13] op_sel_hi:[1,0]
	v_pk_mul_f32 v[8:9], v[32:33], s[12:13] op_sel_hi:[1,0]
	v_pk_mul_f32 v[2:3], v[38:39], s[12:13] op_sel_hi:[1,0]
	v_pk_mul_f32 v[4:5], v[34:35], s[12:13] op_sel_hi:[1,0]
	v_cvt_pk_bf16_f32 v0, v0, v1
	v_cvt_pk_bf16_f32 v1, v2, v3
	v_cvt_pk_bf16_f32 v2, v8, v9
	v_cvt_pk_bf16_f32 v3, v4, v5
	s_and_b64 vcc, exec, s[4:5]
	s_mov_b64 s[4:5], -1
	global_store_dwordx4 v[6:7], v[0:3], off offset:256 sc1
	s_cbranch_vccnz .LBB0_1337
	s_andn2_b64 vcc, exec, s[6:7]
	s_cbranch_vccnz .LBB0_1336
	s_barrier
	s_branch .LBB0_1336

.LBB0_1411:
	s_ashr_i32 s3, s2, 31
	v_lshl_add_u64 v[8:9], s[8:9], 0, v[2:3]
	s_lshl_b64 s[0:1], s[2:3], 2
	v_add_co_u32_e32 v8, vcc, s12, v8
	s_add_u32 s14, s50, s0
	s_nop 0
	v_addc_co_u32_e32 v9, vcc, 0, v9, vcc
	s_addc_u32 s15, s51, s1
	global_load_dwordx4 v[22:25], v[4:5], off
	global_load_dwordx4 v[26:29], v[6:7], off
	global_load_dwordx4 v[30:33], v[8:9], off
	global_load_dwordx4 v[34:37], v[8:9], off offset:1024
	global_load_dwordx4 v[38:41], v[8:9], off offset:2048
	global_load_dwordx4 v[42:45], v[8:9], off offset:3072
	s_add_u32 s0, s54, s0
	global_load_dwordx2 v[8:9], v18, s[14:15]
	s_addc_u32 s1, s55, s1
	global_load_dwordx2 v[46:47], v18, s[0:1]
	v_lshl_add_u64 v[10:11], s[4:5], 0, v[2:3]
	s_add_i32 s46, s46, s80
	s_add_i32 s2, s2, s11
	s_add_u32 s4, s4, s6
	s_addc_u32 s5, s5, s7
	s_add_u32 s8, s8, s6
	s_addc_u32 s9, s9, s7
	s_cmpk_lt_i32 s46, 0x4000
	s_waitcnt vmcnt(1)
	v_ashrrev_i32_e32 v49, 31, v8
	v_mov_b32_e32 v48, v8
	v_ashrrev_i32_e32 v51, 31, v9
	v_mov_b32_e32 v50, v9
	v_lshlrev_b64 v[8:9], 11, v[48:49]
	v_lshlrev_b64 v[48:49], 11, v[50:51]
	v_lshl_add_u64 v[8:9], v[0:1], 0, v[8:9]
	v_lshl_add_u64 v[48:49], v[0:1], 0, v[48:49]
	global_load_dwordx2 v[50:51], v[8:9], off
	global_load_dwordx2 v[52:53], v[48:49], off
	global_load_dwordx2 v[54:55], v[8:9], off offset:512
	global_load_dwordx2 v[56:57], v[48:49], off offset:512
	global_load_dwordx2 v[58:59], v[8:9], off offset:1024
	global_load_dwordx2 v[60:61], v[48:49], off offset:1024
	global_load_dwordx2 v[62:63], v[8:9], off offset:1536
	global_load_dwordx2 v[64:65], v[48:49], off offset:1536
	s_waitcnt vmcnt(7)
	v_lshlrev_b32_e32 v8, 16, v50
	v_and_b32_e32 v9, 0xffff0000, v50
	v_lshlrev_b32_e32 v48, 16, v51
	v_and_b32_e32 v49, 0xffff0000, v51
	s_waitcnt vmcnt(6)
	v_lshlrev_b32_e32 v50, 16, v52
	v_and_b32_e32 v51, 0xffff0000, v52
	v_lshlrev_b32_e32 v52, 16, v53
	v_and_b32_e32 v53, 0xffff0000, v53
	s_waitcnt vmcnt(4)
	v_lshlrev_b32_e32 v68, 16, v56
	v_and_b32_e32 v69, 0xffff0000, v56
	v_lshlrev_b32_e32 v56, 16, v57
	v_and_b32_e32 v57, 0xffff0000, v57
	v_lshlrev_b32_e32 v66, 16, v54
	v_and_b32_e32 v67, 0xffff0000, v54
	v_lshlrev_b32_e32 v54, 16, v55
	v_and_b32_e32 v55, 0xffff0000, v55
	s_waitcnt vmcnt(2)
	v_lshlrev_b32_e32 v72, 16, v60
	v_and_b32_e32 v73, 0xffff0000, v60
	v_lshlrev_b32_e32 v60, 16, v61
	v_and_b32_e32 v61, 0xffff0000, v61
	s_waitcnt vmcnt(0)
	v_lshlrev_b32_e32 v76, 16, v64
	v_and_b32_e32 v77, 0xffff0000, v64
	v_lshlrev_b32_e32 v64, 16, v65
	v_and_b32_e32 v65, 0xffff0000, v65
	v_pk_mul_f32 v[52:53], v[46:47], v[52:53] op_sel:[1,0]
	v_pk_mul_f32 v[50:51], v[46:47], v[50:51] op_sel:[1,0]
	v_pk_mul_f32 v[56:57], v[46:47], v[56:57] op_sel:[1,0]
	v_pk_mul_f32 v[68:69], v[46:47], v[68:69] op_sel:[1,0]
	v_lshlrev_b32_e32 v70, 16, v58
	v_and_b32_e32 v71, 0xffff0000, v58
	v_lshlrev_b32_e32 v58, 16, v59
	v_and_b32_e32 v59, 0xffff0000, v59
	v_lshlrev_b32_e32 v74, 16, v62
	v_and_b32_e32 v75, 0xffff0000, v62
	v_lshlrev_b32_e32 v62, 16, v63
	v_and_b32_e32 v63, 0xffff0000, v63
	v_pk_mul_f32 v[60:61], v[46:47], v[60:61] op_sel:[1,0]
	v_pk_mul_f32 v[72:73], v[46:47], v[72:73] op_sel:[1,0]
	v_pk_mul_f32 v[64:65], v[46:47], v[64:65] op_sel:[1,0]
	v_pk_mul_f32 v[76:77], v[46:47], v[76:77] op_sel:[1,0]
	v_pk_fma_f32 v[8:9], v[46:47], v[8:9], v[50:51] op_sel_hi:[0,1,1]
	v_pk_fma_f32 v[48:49], v[46:47], v[48:49], v[52:53] op_sel_hi:[0,1,1]
	v_pk_fma_f32 v[50:51], v[46:47], v[66:67], v[68:69] op_sel_hi:[0,1,1]
	v_pk_fma_f32 v[52:53], v[46:47], v[54:55], v[56:57] op_sel_hi:[0,1,1]
	v_pk_fma_f32 v[54:55], v[46:47], v[70:71], v[72:73] op_sel_hi:[0,1,1]
	v_pk_fma_f32 v[56:57], v[46:47], v[58:59], v[60:61] op_sel_hi:[0,1,1]
	v_pk_fma_f32 v[58:59], v[46:47], v[74:75], v[76:77] op_sel_hi:[0,1,1]
	v_pk_fma_f32 v[46:47], v[46:47], v[62:63], v[64:65] op_sel_hi:[0,1,1]
	v_pk_fma_f32 v[32:33], v[32:33], s[10:11], v[48:49] op_sel_hi:[1,0,1]
	v_pk_fma_f32 v[8:9], v[30:31], s[10:11], v[8:9] op_sel_hi:[1,0,1]
	v_pk_fma_f32 v[30:31], v[36:37], s[10:11], v[52:53] op_sel_hi:[1,0,1]
	v_pk_fma_f32 v[34:35], v[34:35], s[10:11], v[50:51] op_sel_hi:[1,0,1]
	v_pk_fma_f32 v[36:37], v[40:41], s[10:11], v[56:57] op_sel_hi:[1,0,1]
	v_pk_fma_f32 v[40:41], v[44:45], s[10:11], v[46:47] op_sel_hi:[1,0,1]
	v_pk_mov_b32 v[44:45], v[8:9], v[32:33] op_sel:[1,0]
	v_mov_b32_e32 v46, v8
	v_mov_b32_e32 v47, v33
	v_pk_mov_b32 v[48:49], v[34:35], v[30:31] op_sel:[1,0]
	v_mov_b32_e32 v50, v34
	v_mov_b32_e32 v51, v31
	v_pk_add_f32 v[44:45], v[44:45], v[46:47]
	v_pk_add_f32 v[46:47], v[48:49], v[50:51]
	v_pk_fma_f32 v[38:39], v[38:39], s[10:11], v[54:55] op_sel_hi:[1,0,1]
	v_pk_fma_f32 v[42:43], v[42:43], s[10:11], v[58:59] op_sel_hi:[1,0,1]
	v_add_f32_e32 v21, v44, v45
	v_pk_add_f32 v[44:45], v[46:47], v[46:47] op_sel:[0,1] op_sel_hi:[1,0]
	v_add_f32_e32 v52, v38, v39
	v_add_f32_e32 v54, v36, v37
	v_mov_b32_e32 v57, v42
	v_mov_b32_e32 v53, v40
	v_mov_b32_e32 v55, v41
	v_add_f32_e32 v56, 0, v21
	v_mov_b32_e32 v45, v43
	v_pk_add_f32 v[48:49], v[52:53], v[54:55]
	v_pk_add_f32 v[44:45], v[56:57], v[44:45]
	s_nop 0
	v_pk_add_f32 v[44:45], v[44:45], v[48:49]
	s_nop 0
	v_add_f32_e32 v21, v44, v45
	ds_bpermute_b32 v44, v12, v21
	s_waitcnt lgkmcnt(0)
	v_add_f32_e32 v21, v21, v44
	ds_bpermute_b32 v44, v13, v21
	s_waitcnt lgkmcnt(0)
	v_add_f32_e32 v21, v21, v44
	ds_bpermute_b32 v44, v14, v21
	s_waitcnt lgkmcnt(0)
	v_add_f32_e32 v21, v21, v44
	ds_bpermute_b32 v44, v15, v21
	s_waitcnt lgkmcnt(0)
	v_add_f32_e32 v21, v21, v44
	ds_bpermute_b32 v44, v16, v21
	s_waitcnt lgkmcnt(0)
	v_add_f32_e32 v21, v21, v44
	ds_bpermute_b32 v44, v17, v21
	s_waitcnt lgkmcnt(0)
	v_add_f32_e32 v21, v21, v44
	v_fmamk_f32 v9, v21, 0xba800000, v9
	v_fmac_f32_e32 v8, 0xba800000, v21
	v_fmamk_f32 v33, v21, 0xba800000, v33
	v_fmac_f32_e32 v32, 0xba800000, v21
	v_fmamk_f32 v35, v21, 0xba800000, v35
	v_fmac_f32_e32 v34, 0xba800000, v21
	v_fmamk_f32 v31, v21, 0xba800000, v31
	v_fmac_f32_e32 v30, 0xba800000, v21
	v_pk_mul_f32 v[44:45], v[32:33], v[32:33]
	v_pk_mul_f32 v[46:47], v[8:9], v[8:9]
	v_pk_mul_f32 v[48:49], v[30:31], v[30:31]
	v_pk_mul_f32 v[50:51], v[34:35], v[34:35]
	v_fmac_f32_e32 v38, 0xba800000, v21
	v_fmac_f32_e32 v36, 0xba800000, v21
	v_pk_mov_b32 v[56:57], v[46:47], v[44:45] op_sel:[1,0]
	v_mov_b32_e32 v47, v45
	v_pk_mov_b32 v[44:45], v[50:51], v[48:49] op_sel:[1,0]
	v_mov_b32_e32 v51, v49
	v_fmamk_f32 v39, v21, 0xba800000, v39
	v_fmamk_f32 v37, v21, 0xba800000, v37
	v_mul_f32_e32 v52, v38, v38
	v_mul_f32_e32 v54, v36, v36
	v_pk_add_f32 v[46:47], v[56:57], v[46:47]
	v_pk_add_f32 v[44:45], v[44:45], v[50:51]
	v_fmamk_f32 v41, v21, 0xba800000, v41
	v_fmac_f32_e32 v40, 0xba800000, v21
	v_fmamk_f32 v43, v21, 0xba800000, v43
	v_fmac_f32_e32 v42, 0xba800000, v21
	v_pk_fma_f32 v[48:49], v[38:39], v[38:39], v[52:53] op_sel_hi:[1,1,0]
	v_pk_fma_f32 v[52:53], v[36:37], v[36:37], v[54:55] op_sel_hi:[1,1,0]
	v_pk_add_f32 v[46:47], v[46:47], v[46:47] op_sel_hi:[0,1]
	v_pk_add_f32 v[44:45], v[44:45], v[44:45] op_sel_hi:[0,1]
	v_mul_f32_e32 v48, v42, v42
	v_mul_f32_e32 v52, v43, v43
	v_mul_f32_e32 v46, v40, v40
	v_mul_f32_e32 v44, v41, v41
	v_pk_add_f32 v[48:49], v[48:49], v[52:53]
	v_pk_add_f32 v[44:45], v[46:47], v[44:45]
	s_nop 0
	v_pk_add_f32 v[44:45], v[48:49], v[44:45]
	s_nop 0
	v_add_f32_e32 v21, v44, v45
	ds_bpermute_b32 v44, v12, v21
	s_waitcnt lgkmcnt(0)
	v_add_f32_e32 v21, v21, v44
	ds_bpermute_b32 v44, v13, v21
	s_waitcnt lgkmcnt(0)
	v_add_f32_e32 v21, v21, v44
	ds_bpermute_b32 v44, v14, v21
	s_waitcnt lgkmcnt(0)
	v_add_f32_e32 v21, v21, v44
	ds_bpermute_b32 v44, v15, v21
	s_waitcnt lgkmcnt(0)
	v_add_f32_e32 v21, v21, v44
	ds_bpermute_b32 v44, v16, v21
	s_waitcnt lgkmcnt(0)
	v_add_f32_e32 v21, v21, v44
	ds_bpermute_b32 v44, v17, v21
	s_waitcnt lgkmcnt(0)
	v_add_f32_e32 v21, v21, v44
	v_fmamk_f32 v21, v21, 0x3a800000, v19
	v_mul_f32_e32 v44, 0x4f800000, v21
	v_cmp_gt_f32_e32 vcc, s13, v21
	s_nop 1
	v_cndmask_b32_e32 v21, v21, v44, vcc
	v_sqrt_f32_e32 v44, v21
	s_nop 0
	v_add_u32_e32 v45, -1, v44
	v_add_u32_e32 v46, 1, v44
	v_fma_f32 v47, -v45, v44, v21
	v_fma_f32 v48, -v46, v44, v21
	v_cmp_ge_f32_e64 s[0:1], 0, v47
	s_nop 1
	v_cndmask_b32_e64 v44, v44, v45, s[0:1]
	v_cmp_lt_f32_e64 s[0:1], 0, v48
	s_nop 1
	v_cndmask_b32_e64 v44, v44, v46, s[0:1]
	v_mul_f32_e32 v45, 0x37800000, v44
	v_cndmask_b32_e32 v44, v44, v45, vcc
	v_cmp_class_f32_e32 vcc, v21, v20
	s_nop 1
	v_cndmask_b32_e32 v21, v44, v21, vcc
	v_div_scale_f32 v44, s[0:1], v21, v21, 1.0
	v_rcp_f32_e32 v46, v44
	v_div_scale_f32 v45, vcc, 1.0, v21, 1.0
	v_fma_f32 v47, -v44, v46, 1.0
	v_fmac_f32_e32 v46, v47, v46
	v_mul_f32_e32 v47, v45, v46
	v_fma_f32 v48, -v44, v47, v45
	v_fmac_f32_e32 v47, v48, v46
	v_fma_f32 v44, -v44, v47, v45
	v_div_fmas_f32 v44, v44, v46, v47
	v_div_fixup_f32 v44, v44, v21, 1.0
	v_pk_mul_f32 v[8:9], v[8:9], v[44:45] op_sel_hi:[1,0]
	v_pk_mul_f32 v[32:33], v[32:33], v[44:45] op_sel_hi:[1,0]
	v_pk_fma_f32 v[22:23], v[22:23], v[8:9], v[26:27]
	v_pk_fma_f32 v[24:25], v[24:25], v[32:33], v[28:29]
	global_store_dwordx4 v[10:11], v[22:25], off sc1
	global_load_dwordx4 v[22:25], v[4:5], off offset:1024
	s_nop 0
	global_load_dwordx4 v[26:29], v[6:7], off offset:1024
	v_pk_mul_f32 v[8:9], v[30:31], v[44:45] op_sel_hi:[1,0]
	v_pk_mul_f32 v[30:31], v[34:35], v[44:45] op_sel_hi:[1,0]
	s_waitcnt vmcnt(0)
	v_pk_fma_f32 v[24:25], v[24:25], v[8:9], v[28:29]
	v_pk_fma_f32 v[22:23], v[22:23], v[30:31], v[26:27]
	global_store_dwordx4 v[10:11], v[22:25], off offset:1024 sc1
	global_load_dwordx4 v[22:25], v[4:5], off offset:2048
	s_nop 0
	global_load_dwordx4 v[26:29], v[6:7], off offset:2048
	v_pk_mul_f32 v[8:9], v[36:37], v[44:45] op_sel_hi:[1,0]
	v_pk_mul_f32 v[30:31], v[38:39], v[44:45] op_sel_hi:[1,0]
	s_waitcnt vmcnt(0)
	v_pk_fma_f32 v[24:25], v[24:25], v[8:9], v[28:29]
	v_pk_fma_f32 v[22:23], v[22:23], v[30:31], v[26:27]
	global_store_dwordx4 v[10:11], v[22:25], off offset:2048 sc1
	global_load_dwordx4 v[22:25], v[4:5], off offset:3072
	s_nop 0
	global_load_dwordx4 v[26:29], v[6:7], off offset:3072
	v_pk_mul_f32 v[8:9], v[40:41], v[44:45] op_sel_hi:[1,0]
	v_pk_mul_f32 v[30:31], v[42:43], v[44:45] op_sel_hi:[1,0]
	s_waitcnt vmcnt(0)
	v_pk_fma_f32 v[24:25], v[24:25], v[8:9], v[28:29]
	v_pk_fma_f32 v[22:23], v[22:23], v[30:31], v[26:27]
	global_store_dwordx4 v[10:11], v[22:25], off offset:3072 sc1
	s_cbranch_scc1 .LBB0_1411
